# v68 + GEMM unit seams: the trailing half-workgroup takes its extra offset-restoring barrier after the next-unit header and accumulator zeroing instead of before (15 GEMM instances)
# speedup vs baseline: 1.0011x; 1.0011x over previous
.LBB0_120:
	s_add_u32 s10, s4, 0x11800000
	s_addc_u32 s11, s5, 0
	s_lshl_b32 s4, s12, 5
	s_mov_b64 s[12:13], 0x80
	s_and_b32 s17, s4, 0x60
	s_add_i32 m0, s31, 0x18000
	v_lshl_add_u64 v[6:7], v[6:7], 0, s[12:13]
	s_lshl_b32 s16, s15, 13
	s_lshl_b32 s18, s17, 7
	s_waitcnt vmcnt(2)
	s_barrier
	global_load_lds_dwordx4 v[6:7], off
	v_lshl_add_u64 v[4:5], v[4:5], 0, s[12:13]
	s_add_i32 m0, s31, 0x1a000
	s_add_i32 s36, s31, 0x8000
	s_add_i32 s37, s31, 0xa000
	global_load_lds_dwordx4 v[4:5], off
	v_lshl_add_u64 v[0:1], v[0:1], 0, s[12:13]
	s_mov_b32 m0, s36
	s_add_u32 s4, s24, 0x40080
	global_load_lds_dwordx4 v[0:1], off
	v_lshl_add_u64 v[0:1], v[2:3], 0, s[12:13]
	s_mov_b32 m0, s37
	s_addc_u32 s5, s25, 0
	global_load_lds_dwordx4 v[0:1], off
	s_add_i32 m0, s31, 0x1c000
	v_lshl_add_u64 v[0:1], s[4:5], 0, v[132:133]
	global_load_lds_dwordx4 v[0:1], off
	v_lshl_add_u64 v[0:1], s[4:5], 0, v[128:129]
	s_add_i32 m0, s31, 0x1e000
	s_cmpk_lt_u32 s14, 0x100
	global_load_lds_dwordx4 v[0:1], off
	v_lshrrev_b32_e32 v1, 1, v8
	v_and_b32_e32 v1, 24, v1
	v_and_b32_e32 v0, 15, v8
	v_lshlrev_b32_e32 v2, 1, v1
	v_lshl_or_b32 v146, s15, 6, v0
	v_lshl_or_b32 v0, v0, 6, v2
	v_lshlrev_b32_e32 v2, 2, v8
	v_and_b32_e32 v2, 32, v2
	v_bitop3_b32 v3, v0, s16, v2 bitop3:0xde
	v_bitop3_b32 v147, s18, v0, v2 bitop3:0xf6
	v_lshlrev_b32_e32 v0, 14, v9
	v_and_b32_e32 v0, 0xffff8000, v0
	v_or_b32_e32 v148, s17, v1
	v_lshl_add_u32 v0, v10, 11, v0
	v_and_b32_e32 v1, 1, v9
	v_lshl_or_b32 v0, v1, 6, v0
	v_lshl_add_u32 v136, v11, 1, v0
	v_lshlrev_b32_e32 v0, 14, v13
	v_and_b32_e32 v0, 0xffff8000, v0
	s_waitcnt vmcnt(6)
	v_lshl_add_u32 v0, v12, 11, v0
	v_and_b32_e32 v1, 1, v13
	s_cselect_b64 s[14:15], -1, 0
	v_lshl_or_b32 v0, v1, 6, v0
	s_add_i32 s40, 0, 0x10000
	s_add_i32 s41, 0, 0x14000
	s_mov_b32 s38, 0
	v_mov_b32_e32 v137, v133
	v_lshl_add_u32 v138, v14, 1, v0
	v_mov_b32_e32 v139, v133
	v_mov_b64_e32 v[140:141], 0xb00
	v_mov_b64_e32 v[142:143], 0xaff
	s_movk_i32 s39, 0x161
	v_add_u32_e32 v149, s40, v147
	v_add_u32_e32 v150, s41, v147
	v_add_u32_e32 v151, 0, v3
	s_movk_i32 s42, 0x1600
	s_mov_b32 s43, s86
	s_mov_b32 s44, s88
	s_barrier
	s_mov_b32 s100, 0
	s_branch .LBB0_123

.LBB0_125:
	s_ashr_i32 s19, s18, 31
	s_lshl_b64 s[20:21], s[18:19], 19
	s_add_u32 s20, s0, s20
	s_addc_u32 s21, s1, s21
	s_and_b64 s[22:23], s[4:5], exec
	s_cselect_b32 s19, s21, s27
	s_cselect_b32 s45, s20, s26
	s_ashr_i32 s17, s16, 31
	s_lshl_b64 s[22:23], s[16:17], 19
	s_add_u32 s22, s6, s22
	s_addc_u32 s23, s7, s23
	s_and_b64 s[28:29], s[4:5], exec
	s_cselect_b32 s17, s23, s25
	s_cselect_b32 s46, s22, s24
	s_add_u32 s47, s24, 0x100
	s_addc_u32 s48, s25, 0
	s_add_u32 s24, s26, 0x40080
	v_mov_b32_e32 v0, 0
	s_addc_u32 s25, s27, 0
	s_mov_b32 s49, -2
	v_mov_b32_e32 v1, v0
	v_mov_b32_e32 v2, v0
	v_mov_b32_e32 v3, v0
	v_mov_b32_e32 v4, v0
	v_mov_b32_e32 v5, v0
	v_mov_b32_e32 v6, v0
	v_mov_b32_e32 v7, v0
	v_mov_b32_e32 v16, v0
	v_mov_b32_e32 v17, v0
	v_mov_b32_e32 v18, v0
	v_mov_b32_e32 v19, v0
	v_mov_b32_e32 v20, v0
	v_mov_b32_e32 v21, v0
	v_mov_b32_e32 v22, v0
	v_mov_b32_e32 v23, v0
	v_mov_b32_e32 v32, v0
	v_mov_b32_e32 v33, v0
	v_mov_b32_e32 v34, v0
	v_mov_b32_e32 v35, v0
	v_mov_b32_e32 v36, v0
	v_mov_b32_e32 v37, v0
	v_mov_b32_e32 v38, v0
	v_mov_b32_e32 v39, v0
	v_mov_b32_e32 v48, v0
	v_mov_b32_e32 v49, v0
	v_mov_b32_e32 v50, v0
	v_mov_b32_e32 v51, v0
	v_mov_b32_e32 v52, v0
	v_mov_b32_e32 v53, v0
	v_mov_b32_e32 v54, v0
	v_mov_b32_e32 v55, v0
	v_mov_b32_e32 v8, v0
	v_mov_b32_e32 v9, v0
	v_mov_b32_e32 v10, v0
	v_mov_b32_e32 v11, v0
	v_mov_b32_e32 v12, v0
	v_mov_b32_e32 v13, v0
	v_mov_b32_e32 v14, v0
	v_mov_b32_e32 v15, v0
	v_mov_b32_e32 v24, v0
	v_mov_b32_e32 v25, v0
	v_mov_b32_e32 v26, v0
	v_mov_b32_e32 v27, v0
	v_mov_b32_e32 v28, v0
	v_mov_b32_e32 v29, v0
	v_mov_b32_e32 v30, v0
	v_mov_b32_e32 v31, v0
	v_mov_b32_e32 v40, v0
	v_mov_b32_e32 v41, v0
	v_mov_b32_e32 v42, v0
	v_mov_b32_e32 v43, v0
	v_mov_b32_e32 v44, v0
	v_mov_b32_e32 v45, v0
	v_mov_b32_e32 v46, v0
	v_mov_b32_e32 v47, v0
	v_mov_b32_e32 v56, v0
	v_mov_b32_e32 v57, v0
	v_mov_b32_e32 v58, v0
	v_mov_b32_e32 v59, v0
	v_mov_b32_e32 v60, v0
	v_mov_b32_e32 v61, v0
	v_mov_b32_e32 v62, v0
	v_mov_b32_e32 v63, v0
	v_mov_b32_e32 v64, v0
	v_mov_b32_e32 v65, v0
	v_mov_b32_e32 v66, v0
	v_mov_b32_e32 v67, v0
	v_mov_b32_e32 v68, v0
	v_mov_b32_e32 v69, v0
	v_mov_b32_e32 v70, v0
	v_mov_b32_e32 v71, v0
	v_mov_b32_e32 v80, v0
	v_mov_b32_e32 v81, v0
	v_mov_b32_e32 v82, v0
	v_mov_b32_e32 v83, v0
	v_mov_b32_e32 v84, v0
	v_mov_b32_e32 v85, v0
	v_mov_b32_e32 v86, v0
	v_mov_b32_e32 v87, v0
	v_mov_b32_e32 v96, v0
	v_mov_b32_e32 v97, v0
	v_mov_b32_e32 v98, v0
	v_mov_b32_e32 v99, v0
	v_mov_b32_e32 v100, v0
	v_mov_b32_e32 v101, v0
	v_mov_b32_e32 v102, v0
	v_mov_b32_e32 v103, v0
	v_mov_b32_e32 v112, v0
	v_mov_b32_e32 v113, v0
	v_mov_b32_e32 v114, v0
	v_mov_b32_e32 v115, v0
	v_mov_b32_e32 v116, v0
	v_mov_b32_e32 v117, v0
	v_mov_b32_e32 v118, v0
	v_mov_b32_e32 v119, v0
	v_mov_b32_e32 v72, v0
	v_mov_b32_e32 v73, v0
	v_mov_b32_e32 v74, v0
	v_mov_b32_e32 v75, v0
	v_mov_b32_e32 v76, v0
	v_mov_b32_e32 v77, v0
	v_mov_b32_e32 v78, v0
	v_mov_b32_e32 v79, v0
	v_mov_b32_e32 v88, v0
	v_mov_b32_e32 v89, v0
	v_mov_b32_e32 v90, v0
	v_mov_b32_e32 v91, v0
	v_mov_b32_e32 v92, v0
	v_mov_b32_e32 v93, v0
	v_mov_b32_e32 v94, v0
	v_mov_b32_e32 v95, v0
	v_mov_b32_e32 v104, v0
	v_mov_b32_e32 v105, v0
	v_mov_b32_e32 v106, v0
	v_mov_b32_e32 v107, v0
	v_mov_b32_e32 v108, v0
	v_mov_b32_e32 v109, v0
	v_mov_b32_e32 v110, v0
	v_mov_b32_e32 v111, v0
	v_mov_b32_e32 v120, v0
	v_mov_b32_e32 v121, v0
	v_mov_b32_e32 v122, v0
	v_mov_b32_e32 v123, v0
	v_mov_b32_e32 v124, v0
	v_mov_b32_e32 v125, v0
	v_mov_b32_e32 v126, v0
	v_mov_b32_e32 v127, v0
	s_cmp_eq_u32 s100, 1
	s_cbranch_scc0 .Lgemm_nobar_121
	s_mov_b32 s100, 0
	s_barrier
.Lgemm_nobar_121:
.LBB0_126:
	ds_read_b128 v[152:155], v149
	ds_read_b128 v[156:159], v149 offset:1024
	ds_read_b128 v[160:163], v149 offset:2048
	ds_read_b128 v[164:167], v149 offset:3072
	ds_read_b128 v[168:171], v150
	ds_read_b128 v[172:175], v150 offset:1024
	ds_read_b128 v[176:179], v150 offset:2048
	ds_read_b128 v[180:183], v150 offset:3072
	s_add_u32 s26, s24, 0xfffc0080
	s_addc_u32 s27, s25, -1
	s_cmp_eq_u32 s49, 12
	s_cselect_b32 s29, s19, s27
	s_cselect_b32 s28, s45, s26
	s_cselect_b32 s27, s17, s48
	s_cselect_b32 s26, s46, s47
	v_lshl_add_u64 v[144:145], s[24:25], 0, v[138:139]
	s_add_i32 m0, s31, 0xc000
	ds_read_b128 v[184:187], v151
	ds_read_b128 v[188:191], v151 offset:1024
	ds_read_b128 v[192:195], v151 offset:2048
	ds_read_b128 v[196:199], v151 offset:3072
	ds_read_b128 v[200:203], v151 offset:4096
	ds_read_b128 v[204:207], v151 offset:5120
	ds_read_b128 v[208:211], v151 offset:6144
	ds_read_b128 v[212:215], v151 offset:7168
	global_load_lds_dwordx4 v[144:145], off
	v_lshl_add_u64 v[144:145], s[24:25], 0, v[136:137]
	s_add_i32 m0, s31, 0xe000
	s_nop 0
	global_load_lds_dwordx4 v[144:145], off
	s_waitcnt vmcnt(8)
	s_waitcnt lgkmcnt(0)
	s_barrier
	s_setprio 1
	s_waitcnt lgkmcnt(0)
	v_mfma_f32_16x16x32_bf16 v[124:127], v[152:155], v[184:187], v[124:127]
	v_mfma_f32_16x16x32_bf16 v[120:123], v[160:163], v[184:187], v[120:123]
	v_mfma_f32_16x16x32_bf16 v[108:111], v[152:155], v[192:195], v[108:111]
	v_mfma_f32_16x16x32_bf16 v[104:107], v[160:163], v[192:195], v[104:107]
	v_mfma_f32_16x16x32_bf16 v[92:95], v[152:155], v[200:203], v[92:95]
	v_mfma_f32_16x16x32_bf16 v[88:91], v[160:163], v[200:203], v[88:91]
	v_mfma_f32_16x16x32_bf16 v[76:79], v[152:155], v[208:211], v[76:79]
	v_mfma_f32_16x16x32_bf16 v[72:75], v[160:163], v[208:211], v[72:75]
	v_mfma_f32_16x16x32_bf16 v[124:127], v[156:159], v[188:191], v[124:127]
	v_mfma_f32_16x16x32_bf16 v[120:123], v[164:167], v[188:191], v[120:123]
	v_mfma_f32_16x16x32_bf16 v[108:111], v[156:159], v[196:199], v[108:111]
	v_mfma_f32_16x16x32_bf16 v[104:107], v[164:167], v[196:199], v[104:107]
	v_mfma_f32_16x16x32_bf16 v[92:95], v[156:159], v[204:207], v[92:95]
	v_mfma_f32_16x16x32_bf16 v[88:91], v[164:167], v[204:207], v[88:91]
	v_mfma_f32_16x16x32_bf16 v[76:79], v[156:159], v[212:215], v[76:79]
	v_mfma_f32_16x16x32_bf16 v[72:75], v[164:167], v[212:215], v[72:75]
	s_setprio 0
	s_setprio 1
	v_mfma_f32_16x16x32_bf16 v[116:119], v[168:171], v[184:187], v[116:119]
	v_mfma_f32_16x16x32_bf16 v[112:115], v[176:179], v[184:187], v[112:115]
	v_mfma_f32_16x16x32_bf16 v[100:103], v[168:171], v[192:195], v[100:103]
	v_mfma_f32_16x16x32_bf16 v[96:99], v[176:179], v[192:195], v[96:99]
	v_mfma_f32_16x16x32_bf16 v[84:87], v[168:171], v[200:203], v[84:87]
	v_mfma_f32_16x16x32_bf16 v[80:83], v[176:179], v[200:203], v[80:83]
	v_mfma_f32_16x16x32_bf16 v[68:71], v[168:171], v[208:211], v[68:71]
	v_mfma_f32_16x16x32_bf16 v[64:67], v[176:179], v[208:211], v[64:67]
	v_mfma_f32_16x16x32_bf16 v[116:119], v[172:175], v[188:191], v[116:119]
	v_mfma_f32_16x16x32_bf16 v[112:115], v[180:183], v[188:191], v[112:115]
	v_mfma_f32_16x16x32_bf16 v[100:103], v[172:175], v[196:199], v[100:103]
	v_mfma_f32_16x16x32_bf16 v[96:99], v[180:183], v[196:199], v[96:99]
	v_mfma_f32_16x16x32_bf16 v[84:87], v[172:175], v[204:207], v[84:87]
	v_mfma_f32_16x16x32_bf16 v[80:83], v[180:183], v[204:207], v[80:83]
	v_mfma_f32_16x16x32_bf16 v[68:71], v[172:175], v[212:215], v[68:71]
	v_mfma_f32_16x16x32_bf16 v[64:67], v[180:183], v[212:215], v[64:67]
	s_setprio 0
	s_barrier
	s_add_i32 s50, s40, s30
	v_lshl_add_u64 v[144:145], s[26:27], 0, v[132:133]
	s_mov_b32 m0, s50
	ds_read_b128 v[184:187], v151 offset:16384
	ds_read_b128 v[188:191], v151 offset:17408
	ds_read_b128 v[192:195], v151 offset:18432
	ds_read_b128 v[196:199], v151 offset:19456
	ds_read_b128 v[200:203], v151 offset:20480
	ds_read_b128 v[204:207], v151 offset:21504
	ds_read_b128 v[208:211], v151 offset:22528
	ds_read_b128 v[212:215], v151 offset:23552
	global_load_lds_dwordx4 v[144:145], off
	s_add_i32 m0, s50, 0x2000
	s_add_u32 s50, s26, 0x40000
	v_lshl_add_u64 v[216:217], s[26:27], 0, v[128:129]
	s_addc_u32 s51, s27, 0
	s_add_i32 s52, s41, s30
	global_load_lds_dwordx4 v[216:217], off
	v_lshl_add_u64 v[218:219], s[50:51], 0, v[132:133]
	s_mov_b32 m0, s52
	v_lshl_add_u64 v[220:221], s[28:29], 0, v[130:131]
	global_load_lds_dwordx4 v[218:219], off
	v_lshl_add_u64 v[218:219], s[50:51], 0, v[128:129]
	s_add_i32 m0, s52, 0x2000
	s_nop 0
	global_load_lds_dwordx4 v[218:219], off
	v_lshl_add_u64 v[218:219], s[28:29], 0, v[134:135]
	s_mov_b32 m0, s31
	s_nop 0
	global_load_lds_dwordx4 v[218:219], off
	s_mov_b32 m0, s33
	s_nop 0
	global_load_lds_dwordx4 v[220:221], off
	s_waitcnt vmcnt(8)
	s_waitcnt lgkmcnt(0)
	s_barrier
	s_setprio 1
	s_waitcnt lgkmcnt(0)
	v_mfma_f32_16x16x32_bf16 v[60:63], v[152:155], v[184:187], v[60:63]
	v_mfma_f32_16x16x32_bf16 v[56:59], v[160:163], v[184:187], v[56:59]
	v_mfma_f32_16x16x32_bf16 v[44:47], v[152:155], v[192:195], v[44:47]
	v_mfma_f32_16x16x32_bf16 v[40:43], v[160:163], v[192:195], v[40:43]
	v_mfma_f32_16x16x32_bf16 v[28:31], v[152:155], v[200:203], v[28:31]
	v_mfma_f32_16x16x32_bf16 v[24:27], v[160:163], v[200:203], v[24:27]
	v_mfma_f32_16x16x32_bf16 v[12:15], v[152:155], v[208:211], v[12:15]
	v_mfma_f32_16x16x32_bf16 v[8:11], v[160:163], v[208:211], v[8:11]
	v_mfma_f32_16x16x32_bf16 v[60:63], v[156:159], v[188:191], v[60:63]
	v_mfma_f32_16x16x32_bf16 v[56:59], v[164:167], v[188:191], v[56:59]
	v_mfma_f32_16x16x32_bf16 v[44:47], v[156:159], v[196:199], v[44:47]
	v_mfma_f32_16x16x32_bf16 v[40:43], v[164:167], v[196:199], v[40:43]
	v_mfma_f32_16x16x32_bf16 v[28:31], v[156:159], v[204:207], v[28:31]
	v_mfma_f32_16x16x32_bf16 v[24:27], v[164:167], v[204:207], v[24:27]
	v_mfma_f32_16x16x32_bf16 v[12:15], v[156:159], v[212:215], v[12:15]
	v_mfma_f32_16x16x32_bf16 v[8:11], v[164:167], v[212:215], v[8:11]
	s_setprio 0
	s_setprio 1
	v_mfma_f32_16x16x32_bf16 v[52:55], v[168:171], v[184:187], v[52:55]
	v_mfma_f32_16x16x32_bf16 v[48:51], v[176:179], v[184:187], v[48:51]
	v_mfma_f32_16x16x32_bf16 v[36:39], v[168:171], v[192:195], v[36:39]
	v_mfma_f32_16x16x32_bf16 v[32:35], v[176:179], v[192:195], v[32:35]
	v_mfma_f32_16x16x32_bf16 v[20:23], v[168:171], v[200:203], v[20:23]
	v_mfma_f32_16x16x32_bf16 v[16:19], v[176:179], v[200:203], v[16:19]
	v_mfma_f32_16x16x32_bf16 v[4:7], v[168:171], v[208:211], v[4:7]
	v_mfma_f32_16x16x32_bf16 v[0:3], v[176:179], v[208:211], v[0:3]
	v_mfma_f32_16x16x32_bf16 v[52:55], v[172:175], v[188:191], v[52:55]
	v_mfma_f32_16x16x32_bf16 v[48:51], v[180:183], v[188:191], v[48:51]
	v_mfma_f32_16x16x32_bf16 v[36:39], v[172:175], v[196:199], v[36:39]
	v_mfma_f32_16x16x32_bf16 v[32:35], v[180:183], v[196:199], v[32:35]
	v_mfma_f32_16x16x32_bf16 v[20:23], v[172:175], v[204:207], v[20:23]
	v_mfma_f32_16x16x32_bf16 v[16:19], v[180:183], v[204:207], v[16:19]
	v_mfma_f32_16x16x32_bf16 v[4:7], v[172:175], v[212:215], v[4:7]
	v_mfma_f32_16x16x32_bf16 v[0:3], v[180:183], v[212:215], v[0:3]
	s_setprio 0
	s_barrier
	s_add_i32 s50, 0, 0x18000
	s_add_i32 s51, 0, 0x1c000
	v_add_u32_e32 v164, s50, v147
	v_add_u32_e32 v180, s51, v147
	ds_read_b128 v[152:155], v164
	ds_read_b128 v[156:159], v164 offset:1024
	ds_read_b128 v[160:163], v164 offset:2048
	ds_read_b128 v[164:167], v164 offset:3072
	ds_read_b128 v[168:171], v180
	ds_read_b128 v[172:175], v180 offset:1024
	ds_read_b128 v[176:179], v180 offset:2048
	ds_read_b128 v[180:183], v180 offset:3072
	s_add_u32 s28, s28, 0x40000
	s_addc_u32 s29, s29, 0
	s_mov_b32 m0, s34
	v_lshl_add_u64 v[222:223], s[28:29], 0, v[134:135]
	ds_read_b128 v[184:187], v151 offset:32768
	ds_read_b128 v[188:191], v151 offset:33792
	ds_read_b128 v[192:195], v151 offset:34816
	ds_read_b128 v[196:199], v151 offset:35840
	ds_read_b128 v[200:203], v151 offset:36864
	ds_read_b128 v[204:207], v151 offset:37888
	ds_read_b128 v[208:211], v151 offset:38912
	ds_read_b128 v[212:215], v151 offset:39936
	global_load_lds_dwordx4 v[222:223], off
	v_lshl_add_u64 v[222:223], s[28:29], 0, v[130:131]
	s_mov_b32 m0, s35
	s_nop 0
	global_load_lds_dwordx4 v[222:223], off
	s_waitcnt vmcnt(8)
	s_waitcnt lgkmcnt(0)
	s_barrier
	s_setprio 1
	s_waitcnt lgkmcnt(0)
	v_mfma_f32_16x16x32_bf16 v[124:127], v[152:155], v[184:187], v[124:127]
	v_mfma_f32_16x16x32_bf16 v[120:123], v[160:163], v[184:187], v[120:123]
	v_mfma_f32_16x16x32_bf16 v[108:111], v[152:155], v[192:195], v[108:111]
	v_mfma_f32_16x16x32_bf16 v[104:107], v[160:163], v[192:195], v[104:107]
	v_mfma_f32_16x16x32_bf16 v[92:95], v[152:155], v[200:203], v[92:95]
	v_mfma_f32_16x16x32_bf16 v[88:91], v[160:163], v[200:203], v[88:91]
	v_mfma_f32_16x16x32_bf16 v[76:79], v[152:155], v[208:211], v[76:79]
	v_mfma_f32_16x16x32_bf16 v[72:75], v[160:163], v[208:211], v[72:75]
	v_mfma_f32_16x16x32_bf16 v[124:127], v[156:159], v[188:191], v[124:127]
	v_mfma_f32_16x16x32_bf16 v[120:123], v[164:167], v[188:191], v[120:123]
	v_mfma_f32_16x16x32_bf16 v[108:111], v[156:159], v[196:199], v[108:111]
	v_mfma_f32_16x16x32_bf16 v[104:107], v[164:167], v[196:199], v[104:107]
	v_mfma_f32_16x16x32_bf16 v[92:95], v[156:159], v[204:207], v[92:95]
	v_mfma_f32_16x16x32_bf16 v[88:91], v[164:167], v[204:207], v[88:91]
	v_mfma_f32_16x16x32_bf16 v[76:79], v[156:159], v[212:215], v[76:79]
	v_mfma_f32_16x16x32_bf16 v[72:75], v[164:167], v[212:215], v[72:75]
	s_setprio 0
	s_setprio 1
	v_mfma_f32_16x16x32_bf16 v[116:119], v[168:171], v[184:187], v[116:119]
	v_mfma_f32_16x16x32_bf16 v[112:115], v[176:179], v[184:187], v[112:115]
	v_mfma_f32_16x16x32_bf16 v[100:103], v[168:171], v[192:195], v[100:103]
	v_mfma_f32_16x16x32_bf16 v[96:99], v[176:179], v[192:195], v[96:99]
	v_mfma_f32_16x16x32_bf16 v[84:87], v[168:171], v[200:203], v[84:87]
	v_mfma_f32_16x16x32_bf16 v[80:83], v[176:179], v[200:203], v[80:83]
	v_mfma_f32_16x16x32_bf16 v[68:71], v[168:171], v[208:211], v[68:71]
	v_mfma_f32_16x16x32_bf16 v[64:67], v[176:179], v[208:211], v[64:67]
	v_mfma_f32_16x16x32_bf16 v[116:119], v[172:175], v[188:191], v[116:119]
	v_mfma_f32_16x16x32_bf16 v[112:115], v[180:183], v[188:191], v[112:115]
	v_mfma_f32_16x16x32_bf16 v[100:103], v[172:175], v[196:199], v[100:103]
	v_mfma_f32_16x16x32_bf16 v[96:99], v[180:183], v[196:199], v[96:99]
	v_mfma_f32_16x16x32_bf16 v[84:87], v[172:175], v[204:207], v[84:87]
	v_mfma_f32_16x16x32_bf16 v[80:83], v[180:183], v[204:207], v[80:83]
	v_mfma_f32_16x16x32_bf16 v[68:71], v[172:175], v[212:215], v[68:71]
	v_mfma_f32_16x16x32_bf16 v[64:67], v[180:183], v[212:215], v[64:67]
	s_setprio 0
	s_barrier
	s_add_i32 s28, s50, s30
	v_lshl_add_u64 v[144:145], v[144:145], 0, s[12:13]
	s_mov_b32 m0, s28
	ds_read_b128 v[184:187], v151 offset:49152
	ds_read_b128 v[188:191], v151 offset:50176
	ds_read_b128 v[192:195], v151 offset:51200
	ds_read_b128 v[196:199], v151 offset:52224
	ds_read_b128 v[200:203], v151 offset:53248
	ds_read_b128 v[204:207], v151 offset:54272
	ds_read_b128 v[208:211], v151 offset:55296
	ds_read_b128 v[212:215], v151 offset:56320
	global_load_lds_dwordx4 v[144:145], off
	s_add_i32 m0, s28, 0x2000
	s_add_u32 s26, s26, 0x40080
	v_lshl_add_u64 v[144:145], v[216:217], 0, s[12:13]
	s_addc_u32 s27, s27, 0
	s_add_i32 s28, s51, s30
	global_load_lds_dwordx4 v[144:145], off
	v_lshl_add_u64 v[144:145], s[26:27], 0, v[132:133]
	s_mov_b32 m0, s28
	s_nop 0
	global_load_lds_dwordx4 v[144:145], off
	v_lshl_add_u64 v[144:145], s[26:27], 0, v[128:129]
	s_add_i32 m0, s28, 0x2000
	s_nop 0
	global_load_lds_dwordx4 v[144:145], off
	v_lshl_add_u64 v[144:145], v[218:219], 0, s[12:13]
	s_mov_b32 m0, s36
	s_nop 0
	global_load_lds_dwordx4 v[144:145], off
	v_lshl_add_u64 v[144:145], v[220:221], 0, s[12:13]
	s_mov_b32 m0, s37
	s_nop 0
	global_load_lds_dwordx4 v[144:145], off
	s_waitcnt vmcnt(8)
	s_waitcnt lgkmcnt(0)
	s_barrier
	s_setprio 1
	s_waitcnt lgkmcnt(0)
	v_mfma_f32_16x16x32_bf16 v[60:63], v[152:155], v[184:187], v[60:63]
	v_mfma_f32_16x16x32_bf16 v[56:59], v[160:163], v[184:187], v[56:59]
	v_mfma_f32_16x16x32_bf16 v[44:47], v[152:155], v[192:195], v[44:47]
	v_mfma_f32_16x16x32_bf16 v[40:43], v[160:163], v[192:195], v[40:43]
	v_mfma_f32_16x16x32_bf16 v[28:31], v[152:155], v[200:203], v[28:31]
	v_mfma_f32_16x16x32_bf16 v[24:27], v[160:163], v[200:203], v[24:27]
	v_mfma_f32_16x16x32_bf16 v[12:15], v[152:155], v[208:211], v[12:15]
	v_mfma_f32_16x16x32_bf16 v[8:11], v[160:163], v[208:211], v[8:11]
	v_mfma_f32_16x16x32_bf16 v[60:63], v[156:159], v[188:191], v[60:63]
	v_mfma_f32_16x16x32_bf16 v[56:59], v[164:167], v[188:191], v[56:59]
	v_mfma_f32_16x16x32_bf16 v[44:47], v[156:159], v[196:199], v[44:47]
	v_mfma_f32_16x16x32_bf16 v[40:43], v[164:167], v[196:199], v[40:43]
	v_mfma_f32_16x16x32_bf16 v[28:31], v[156:159], v[204:207], v[28:31]
	v_mfma_f32_16x16x32_bf16 v[24:27], v[164:167], v[204:207], v[24:27]
	v_mfma_f32_16x16x32_bf16 v[12:15], v[156:159], v[212:215], v[12:15]
	v_mfma_f32_16x16x32_bf16 v[8:11], v[164:167], v[212:215], v[8:11]
	s_setprio 0
	s_setprio 1
	v_mfma_f32_16x16x32_bf16 v[52:55], v[168:171], v[184:187], v[52:55]
	v_mfma_f32_16x16x32_bf16 v[48:51], v[176:179], v[184:187], v[48:51]
	v_mfma_f32_16x16x32_bf16 v[36:39], v[168:171], v[192:195], v[36:39]
	v_mfma_f32_16x16x32_bf16 v[32:35], v[176:179], v[192:195], v[32:35]
	v_mfma_f32_16x16x32_bf16 v[20:23], v[168:171], v[200:203], v[20:23]
	v_mfma_f32_16x16x32_bf16 v[16:19], v[176:179], v[200:203], v[16:19]
	v_mfma_f32_16x16x32_bf16 v[4:7], v[168:171], v[208:211], v[4:7]
	v_mfma_f32_16x16x32_bf16 v[0:3], v[176:179], v[208:211], v[0:3]
	v_mfma_f32_16x16x32_bf16 v[52:55], v[172:175], v[188:191], v[52:55]
	v_mfma_f32_16x16x32_bf16 v[48:51], v[180:183], v[188:191], v[48:51]
	v_mfma_f32_16x16x32_bf16 v[36:39], v[172:175], v[196:199], v[36:39]
	v_mfma_f32_16x16x32_bf16 v[32:35], v[180:183], v[196:199], v[32:35]
	v_mfma_f32_16x16x32_bf16 v[20:23], v[172:175], v[204:207], v[20:23]
	v_mfma_f32_16x16x32_bf16 v[16:19], v[180:183], v[204:207], v[16:19]
	v_mfma_f32_16x16x32_bf16 v[4:7], v[172:175], v[212:215], v[4:7]
	v_mfma_f32_16x16x32_bf16 v[0:3], v[180:183], v[212:215], v[0:3]
	s_setprio 0
	s_barrier
	s_add_i32 s49, s49, 2
	s_add_u32 s47, s47, 0x100
	s_addc_u32 s48, s48, 0
	s_add_u32 s24, s24, 0x100
	s_addc_u32 s25, s25, 0
	s_cmp_gt_u32 s49, 13
	s_cbranch_scc0 .LBB0_126
	s_and_b64 vcc, exec, s[14:15]
	s_cbranch_vccz .LBB0_129
	s_barrier
.LBB0_129:
	v_mul_f32_e32 v153, 0xbfb8aa3b, v124
	v_mul_f32_e32 v154, 0xbfb8aa3b, v120
	v_exp_f32_e32 v153, v153
	v_exp_f32_e32 v155, v154
	v_mul_f32_e32 v154, 0xbfb8aa3b, v125
	v_exp_f32_e32 v156, v154
	v_add_f32_e32 v153, 1.0, v153
	v_rcp_f32_e32 v154, v153
	v_add_f32_e32 v153, 1.0, v155
	v_add_f32_e32 v155, 1.0, v156
	v_rcp_f32_e32 v155, v155
	v_mul_f32_e32 v156, 0xbfb8aa3b, v121
	v_exp_f32_e32 v157, v156
	v_rcp_f32_e32 v156, v153
	v_pk_mul_f32 v[124:125], v[124:125], v[154:155]
	v_mul_f32_e32 v153, 0xbfb8aa3b, v127
	v_pk_mul_f32 v[116:117], v[124:125], v[116:117]
	v_add_f32_e32 v124, 1.0, v157
	v_mul_f32_e32 v125, 0xbfb8aa3b, v122
	v_rcp_f32_e32 v157, v124
	v_mul_f32_e32 v124, 0xbfb8aa3b, v126
	v_exp_f32_e32 v125, v125
	v_exp_f32_e32 v124, v124
	v_exp_f32_e32 v153, v153
	v_mul_f32_e32 v154, 0xbfb8aa3b, v123
	v_exp_f32_e32 v155, v154
	v_add_f32_e32 v125, 1.0, v125
	v_add_f32_e32 v124, 1.0, v124
	v_rcp_f32_e32 v154, v125
	v_add_f32_e32 v125, 1.0, v153
	v_rcp_f32_e32 v124, v124
	v_rcp_f32_e32 v125, v125
	v_add_f32_e32 v153, 1.0, v155
	v_rcp_f32_e32 v155, v153
	v_pk_mul_f32 v[120:121], v[120:121], v[156:157]
	v_lshl_or_b32 v144, s43, 7, v148
	v_pk_mul_f32 v[120:121], v[120:121], v[112:113]
	v_pk_mul_f32 v[112:113], v[126:127], v[124:125]
	s_mov_b64 s[24:25], s[10:11]
	v_ashrrev_i32_e32 v145, 31, v144
	v_pk_mul_f32 v[118:119], v[112:113], v[118:119]
	v_pk_mul_f32 v[112:113], v[122:123], v[154:155]
	v_lshl_add_u32 v152, s44, 8, v146
	v_lshl_add_u64 v[144:145], v[144:145], 1, s[24:25]
	v_pk_mul_f32 v[122:123], v[112:113], v[114:115]
	v_mad_i64_i32 v[124:125], s[24:25], v152, s42, v[144:145]
	v_cvt_pk_bf16_f32 v112, v116, v117
	v_cvt_pk_bf16_f32 v113, v118, v119
	v_cvt_pk_bf16_f32 v114, v120, v121
	v_cvt_pk_bf16_f32 v115, v122, v123
	global_store_dwordx4 v[124:125], v[112:115], off
	v_or_b32_e32 v116, 16, v152
	s_andn2_b64 vcc, exec, s[4:5]
	v_mul_f32_e32 v112, 0xbfb8aa3b, v108
	v_mul_f32_e32 v113, 0xbfb8aa3b, v104
	v_mul_f32_e32 v114, 0xbfb8aa3b, v109
	v_exp_f32_e32 v112, v112
	v_exp_f32_e32 v113, v113
	v_exp_f32_e32 v114, v114
	s_mov_b64 s[4:5], -1
	v_add_f32_e32 v112, 1.0, v112
	v_add_f32_e32 v115, 1.0, v113
	v_add_f32_e32 v113, 1.0, v114
	v_rcp_f32_e32 v112, v112
	v_rcp_f32_e32 v113, v113
	v_mul_f32_e32 v114, 0xbfb8aa3b, v105
	v_exp_f32_e32 v117, v114
	v_rcp_f32_e32 v114, v115
	v_pk_mul_f32 v[108:109], v[108:109], v[112:113]
	v_mul_f32_e32 v112, 0xbfb8aa3b, v111
	v_pk_mul_f32 v[100:101], v[108:109], v[100:101]
	v_add_f32_e32 v108, 1.0, v117
	v_rcp_f32_e32 v115, v108
	v_mul_f32_e32 v109, 0xbfb8aa3b, v106
	v_mul_f32_e32 v108, 0xbfb8aa3b, v110
	v_exp_f32_e32 v109, v109
	v_exp_f32_e32 v108, v108
	v_exp_f32_e32 v113, v112
	v_mul_f32_e32 v112, 0xbfb8aa3b, v107
	v_pk_mul_f32 v[104:105], v[104:105], v[114:115]
	v_exp_f32_e32 v114, v112
	v_add_f32_e32 v109, 1.0, v109
	v_add_f32_e32 v108, 1.0, v108
	v_rcp_f32_e32 v112, v109
	v_add_f32_e32 v109, 1.0, v113
	v_rcp_f32_e32 v108, v108
	v_rcp_f32_e32 v109, v109
	v_add_f32_e32 v113, 1.0, v114
	v_rcp_f32_e32 v113, v113
	v_pk_mul_f32 v[104:105], v[104:105], v[96:97]
	v_pk_mul_f32 v[96:97], v[110:111], v[108:109]
	v_mad_i64_i32 v[108:109], s[24:25], v116, s42, v[144:145]
	v_pk_mul_f32 v[102:103], v[96:97], v[102:103]
	v_pk_mul_f32 v[96:97], v[106:107], v[112:113]
	s_nop 0
	v_pk_mul_f32 v[106:107], v[96:97], v[98:99]
	v_cvt_pk_bf16_f32 v96, v100, v101
	v_cvt_pk_bf16_f32 v97, v102, v103
	v_cvt_pk_bf16_f32 v98, v104, v105
	v_cvt_pk_bf16_f32 v99, v106, v107
	global_store_dwordx4 v[108:109], v[96:99], off
	v_or_b32_e32 v100, 32, v152
	s_nop 0
	v_mul_f32_e32 v96, 0xbfb8aa3b, v92
	v_mul_f32_e32 v97, 0xbfb8aa3b, v88
	v_mul_f32_e32 v98, 0xbfb8aa3b, v93
	v_exp_f32_e32 v96, v96
	v_exp_f32_e32 v97, v97
	v_exp_f32_e32 v98, v98
	v_add_f32_e32 v96, 1.0, v96
	v_add_f32_e32 v99, 1.0, v97
	v_add_f32_e32 v97, 1.0, v98
	v_rcp_f32_e32 v96, v96
	v_rcp_f32_e32 v97, v97
	v_mul_f32_e32 v98, 0xbfb8aa3b, v89
	v_exp_f32_e32 v101, v98
	v_rcp_f32_e32 v98, v99
	v_pk_mul_f32 v[92:93], v[92:93], v[96:97]
	v_mul_f32_e32 v96, 0xbfb8aa3b, v95
	v_pk_mul_f32 v[84:85], v[92:93], v[84:85]
	v_add_f32_e32 v92, 1.0, v101
	v_rcp_f32_e32 v99, v92
	v_mul_f32_e32 v93, 0xbfb8aa3b, v90
	v_mul_f32_e32 v92, 0xbfb8aa3b, v94
	v_exp_f32_e32 v93, v93
	v_exp_f32_e32 v92, v92
	v_exp_f32_e32 v97, v96
	v_mul_f32_e32 v96, 0xbfb8aa3b, v91
	v_pk_mul_f32 v[88:89], v[88:89], v[98:99]
	v_exp_f32_e32 v98, v96
	v_add_f32_e32 v93, 1.0, v93
	v_add_f32_e32 v92, 1.0, v92
	v_rcp_f32_e32 v96, v93
	v_add_f32_e32 v93, 1.0, v97
	v_rcp_f32_e32 v92, v92
	v_rcp_f32_e32 v93, v93
	v_add_f32_e32 v97, 1.0, v98
	v_rcp_f32_e32 v97, v97
	v_pk_mul_f32 v[88:89], v[88:89], v[80:81]
	v_pk_mul_f32 v[80:81], v[94:95], v[92:93]
	v_mad_i64_i32 v[92:93], s[24:25], v100, s42, v[144:145]
	v_pk_mul_f32 v[86:87], v[80:81], v[86:87]
	v_pk_mul_f32 v[80:81], v[90:91], v[96:97]
	s_nop 0
	v_pk_mul_f32 v[90:91], v[80:81], v[82:83]
	v_cvt_pk_bf16_f32 v80, v84, v85
	v_cvt_pk_bf16_f32 v81, v86, v87
	v_cvt_pk_bf16_f32 v82, v88, v89
	v_cvt_pk_bf16_f32 v83, v90, v91
	global_store_dwordx4 v[92:93], v[80:83], off
	v_or_b32_e32 v84, 48, v152
	s_nop 0
	v_mul_f32_e32 v80, 0xbfb8aa3b, v76
	v_mul_f32_e32 v81, 0xbfb8aa3b, v72
	v_mul_f32_e32 v82, 0xbfb8aa3b, v77
	v_exp_f32_e32 v80, v80
	v_exp_f32_e32 v81, v81
	v_exp_f32_e32 v82, v82
	v_add_f32_e32 v80, 1.0, v80
	v_add_f32_e32 v83, 1.0, v81
	v_add_f32_e32 v81, 1.0, v82
	v_rcp_f32_e32 v80, v80
	v_rcp_f32_e32 v81, v81
	v_mul_f32_e32 v82, 0xbfb8aa3b, v73
	v_exp_f32_e32 v85, v82
	v_rcp_f32_e32 v82, v83
	v_pk_mul_f32 v[76:77], v[76:77], v[80:81]
	v_mul_f32_e32 v80, 0xbfb8aa3b, v79
	v_pk_mul_f32 v[68:69], v[76:77], v[68:69]
	v_add_f32_e32 v76, 1.0, v85
	v_rcp_f32_e32 v83, v76
	v_mul_f32_e32 v77, 0xbfb8aa3b, v74
	v_mul_f32_e32 v76, 0xbfb8aa3b, v78
	v_exp_f32_e32 v77, v77
	v_exp_f32_e32 v76, v76
	v_exp_f32_e32 v81, v80
	v_mul_f32_e32 v80, 0xbfb8aa3b, v75
	v_pk_mul_f32 v[72:73], v[72:73], v[82:83]
	v_exp_f32_e32 v82, v80
	v_add_f32_e32 v77, 1.0, v77
	v_add_f32_e32 v76, 1.0, v76
	v_rcp_f32_e32 v80, v77
	v_add_f32_e32 v77, 1.0, v81
	v_rcp_f32_e32 v76, v76
	v_rcp_f32_e32 v77, v77
	v_add_f32_e32 v81, 1.0, v82
	v_rcp_f32_e32 v81, v81
	v_pk_mul_f32 v[72:73], v[72:73], v[64:65]
	v_pk_mul_f32 v[64:65], v[78:79], v[76:77]
	v_mad_i64_i32 v[76:77], s[24:25], v84, s42, v[144:145]
	v_pk_mul_f32 v[70:71], v[64:65], v[70:71]
	v_pk_mul_f32 v[64:65], v[74:75], v[80:81]
	s_nop 0
	v_pk_mul_f32 v[74:75], v[64:65], v[66:67]
	v_cvt_pk_bf16_f32 v64, v68, v69
	v_cvt_pk_bf16_f32 v65, v70, v71
	v_cvt_pk_bf16_f32 v66, v72, v73
	v_cvt_pk_bf16_f32 v67, v74, v75
	global_store_dwordx4 v[76:77], v[64:67], off
	v_add_u32_e32 v68, 0x80, v152
	s_nop 0
	v_mul_f32_e32 v64, 0xbfb8aa3b, v60
	v_mul_f32_e32 v65, 0xbfb8aa3b, v56
	v_mul_f32_e32 v66, 0xbfb8aa3b, v61
	v_exp_f32_e32 v64, v64
	v_exp_f32_e32 v65, v65
	v_exp_f32_e32 v66, v66
	v_add_f32_e32 v64, 1.0, v64
	v_add_f32_e32 v67, 1.0, v65
	v_add_f32_e32 v65, 1.0, v66
	v_rcp_f32_e32 v64, v64
	v_rcp_f32_e32 v65, v65
	v_mul_f32_e32 v66, 0xbfb8aa3b, v57
	v_exp_f32_e32 v69, v66
	v_rcp_f32_e32 v66, v67
	v_pk_mul_f32 v[60:61], v[60:61], v[64:65]
	v_mul_f32_e32 v64, 0xbfb8aa3b, v63
	v_pk_mul_f32 v[52:53], v[60:61], v[52:53]
	v_add_f32_e32 v60, 1.0, v69
	v_rcp_f32_e32 v67, v60
	v_mul_f32_e32 v61, 0xbfb8aa3b, v58
	v_mul_f32_e32 v60, 0xbfb8aa3b, v62
	v_exp_f32_e32 v61, v61
	v_exp_f32_e32 v60, v60
	v_exp_f32_e32 v65, v64
	v_mul_f32_e32 v64, 0xbfb8aa3b, v59
	v_pk_mul_f32 v[56:57], v[56:57], v[66:67]
	v_exp_f32_e32 v66, v64
	v_add_f32_e32 v61, 1.0, v61
	v_add_f32_e32 v60, 1.0, v60
	v_rcp_f32_e32 v64, v61
	v_add_f32_e32 v61, 1.0, v65
	v_rcp_f32_e32 v60, v60
	v_rcp_f32_e32 v61, v61
	v_add_f32_e32 v65, 1.0, v66
	v_rcp_f32_e32 v65, v65
	v_pk_mul_f32 v[56:57], v[56:57], v[48:49]
	v_pk_mul_f32 v[48:49], v[62:63], v[60:61]
	v_mad_i64_i32 v[60:61], s[24:25], v68, s42, v[144:145]
	v_pk_mul_f32 v[54:55], v[48:49], v[54:55]
	v_pk_mul_f32 v[48:49], v[58:59], v[64:65]
	s_nop 0
	v_pk_mul_f32 v[58:59], v[48:49], v[50:51]
	v_cvt_pk_bf16_f32 v48, v52, v53
	v_cvt_pk_bf16_f32 v49, v54, v55
	v_cvt_pk_bf16_f32 v50, v56, v57
	v_cvt_pk_bf16_f32 v51, v58, v59
	global_store_dwordx4 v[60:61], v[48:51], off
	v_add_u32_e32 v52, 0x90, v152
	s_nop 0
	v_mul_f32_e32 v48, 0xbfb8aa3b, v44
	v_mul_f32_e32 v49, 0xbfb8aa3b, v40
	v_mul_f32_e32 v50, 0xbfb8aa3b, v45
	v_exp_f32_e32 v48, v48
	v_exp_f32_e32 v49, v49
	v_exp_f32_e32 v50, v50
	v_add_f32_e32 v48, 1.0, v48
	v_add_f32_e32 v51, 1.0, v49
	v_add_f32_e32 v49, 1.0, v50
	v_rcp_f32_e32 v48, v48
	v_rcp_f32_e32 v49, v49
	v_mul_f32_e32 v50, 0xbfb8aa3b, v41
	v_exp_f32_e32 v53, v50
	v_rcp_f32_e32 v50, v51
	v_pk_mul_f32 v[44:45], v[44:45], v[48:49]
	v_mul_f32_e32 v48, 0xbfb8aa3b, v47
	v_pk_mul_f32 v[36:37], v[44:45], v[36:37]
	v_add_f32_e32 v44, 1.0, v53
	v_rcp_f32_e32 v51, v44
	v_mul_f32_e32 v45, 0xbfb8aa3b, v42
	v_mul_f32_e32 v44, 0xbfb8aa3b, v46
	v_exp_f32_e32 v45, v45
	v_exp_f32_e32 v44, v44
	v_exp_f32_e32 v49, v48
	v_mul_f32_e32 v48, 0xbfb8aa3b, v43
	v_pk_mul_f32 v[40:41], v[40:41], v[50:51]
	v_exp_f32_e32 v50, v48
	v_add_f32_e32 v45, 1.0, v45
	v_add_f32_e32 v44, 1.0, v44
	v_rcp_f32_e32 v48, v45
	v_add_f32_e32 v45, 1.0, v49
	v_rcp_f32_e32 v44, v44
	v_rcp_f32_e32 v45, v45
	v_add_f32_e32 v49, 1.0, v50
	v_rcp_f32_e32 v49, v49
	v_pk_mul_f32 v[40:41], v[40:41], v[32:33]
	v_pk_mul_f32 v[32:33], v[46:47], v[44:45]
	v_mad_i64_i32 v[44:45], s[24:25], v52, s42, v[144:145]
	v_pk_mul_f32 v[38:39], v[32:33], v[38:39]
	v_pk_mul_f32 v[32:33], v[42:43], v[48:49]
	s_nop 0
	v_pk_mul_f32 v[42:43], v[32:33], v[34:35]
	v_cvt_pk_bf16_f32 v32, v36, v37
	v_cvt_pk_bf16_f32 v33, v38, v39
	v_cvt_pk_bf16_f32 v34, v40, v41
	v_cvt_pk_bf16_f32 v35, v42, v43
	global_store_dwordx4 v[44:45], v[32:35], off
	v_add_u32_e32 v36, 0xa0, v152
	s_nop 0
	v_mul_f32_e32 v32, 0xbfb8aa3b, v28
	v_mul_f32_e32 v33, 0xbfb8aa3b, v24
	v_mul_f32_e32 v34, 0xbfb8aa3b, v29
	v_exp_f32_e32 v32, v32
	v_exp_f32_e32 v33, v33
	v_exp_f32_e32 v34, v34
	v_add_f32_e32 v32, 1.0, v32
	v_add_f32_e32 v35, 1.0, v33
	v_add_f32_e32 v33, 1.0, v34
	v_rcp_f32_e32 v32, v32
	v_rcp_f32_e32 v33, v33
	v_mul_f32_e32 v34, 0xbfb8aa3b, v25
	v_exp_f32_e32 v37, v34
	v_rcp_f32_e32 v34, v35
	v_pk_mul_f32 v[28:29], v[28:29], v[32:33]
	v_mul_f32_e32 v32, 0xbfb8aa3b, v31
	v_pk_mul_f32 v[20:21], v[28:29], v[20:21]
	v_add_f32_e32 v28, 1.0, v37
	v_rcp_f32_e32 v35, v28
	v_mul_f32_e32 v29, 0xbfb8aa3b, v26
	v_mul_f32_e32 v28, 0xbfb8aa3b, v30
	v_exp_f32_e32 v29, v29
	v_exp_f32_e32 v28, v28
	v_exp_f32_e32 v33, v32
	v_mul_f32_e32 v32, 0xbfb8aa3b, v27
	v_pk_mul_f32 v[24:25], v[24:25], v[34:35]
	v_exp_f32_e32 v34, v32
	v_add_f32_e32 v29, 1.0, v29
	v_add_f32_e32 v28, 1.0, v28
	v_rcp_f32_e32 v32, v29
	v_add_f32_e32 v29, 1.0, v33
	v_rcp_f32_e32 v28, v28
	v_rcp_f32_e32 v29, v29
	v_add_f32_e32 v33, 1.0, v34
	v_rcp_f32_e32 v33, v33
	v_pk_mul_f32 v[24:25], v[24:25], v[16:17]
	v_pk_mul_f32 v[16:17], v[30:31], v[28:29]
	v_mad_i64_i32 v[28:29], s[24:25], v36, s42, v[144:145]
	v_pk_mul_f32 v[22:23], v[16:17], v[22:23]
	v_pk_mul_f32 v[16:17], v[26:27], v[32:33]
	s_nop 0
	v_pk_mul_f32 v[26:27], v[16:17], v[18:19]
	v_cvt_pk_bf16_f32 v16, v20, v21
	v_cvt_pk_bf16_f32 v17, v22, v23
	v_cvt_pk_bf16_f32 v18, v24, v25
	v_cvt_pk_bf16_f32 v19, v26, v27
	global_store_dwordx4 v[28:29], v[16:19], off
	v_add_u32_e32 v20, 0xb0, v152
	s_nop 0
	v_mul_f32_e32 v16, 0xbfb8aa3b, v12
	v_mul_f32_e32 v17, 0xbfb8aa3b, v8
	v_mul_f32_e32 v18, 0xbfb8aa3b, v13
	v_exp_f32_e32 v16, v16
	v_exp_f32_e32 v17, v17
	v_exp_f32_e32 v18, v18
	v_add_f32_e32 v16, 1.0, v16
	v_add_f32_e32 v19, 1.0, v17
	v_add_f32_e32 v17, 1.0, v18
	v_rcp_f32_e32 v16, v16
	v_rcp_f32_e32 v17, v17
	v_mul_f32_e32 v18, 0xbfb8aa3b, v9
	v_exp_f32_e32 v21, v18
	v_rcp_f32_e32 v18, v19
	v_pk_mul_f32 v[12:13], v[12:13], v[16:17]
	v_mul_f32_e32 v16, 0xbfb8aa3b, v15
	v_pk_mul_f32 v[4:5], v[12:13], v[4:5]
	v_add_f32_e32 v12, 1.0, v21
	v_rcp_f32_e32 v19, v12
	v_mul_f32_e32 v13, 0xbfb8aa3b, v10
	v_mul_f32_e32 v12, 0xbfb8aa3b, v14
	v_exp_f32_e32 v13, v13
	v_exp_f32_e32 v12, v12
	v_exp_f32_e32 v17, v16
	v_mul_f32_e32 v16, 0xbfb8aa3b, v11
	v_pk_mul_f32 v[8:9], v[8:9], v[18:19]
	v_exp_f32_e32 v18, v16
	v_add_f32_e32 v13, 1.0, v13
	v_add_f32_e32 v12, 1.0, v12
	v_rcp_f32_e32 v16, v13
	v_add_f32_e32 v13, 1.0, v17
	v_rcp_f32_e32 v12, v12
	v_rcp_f32_e32 v13, v13
	v_add_f32_e32 v17, 1.0, v18
	v_rcp_f32_e32 v17, v17
	v_pk_mul_f32 v[8:9], v[8:9], v[0:1]
	v_pk_mul_f32 v[0:1], v[14:15], v[12:13]
	v_mad_i64_i32 v[12:13], s[24:25], v20, s42, v[144:145]
	v_pk_mul_f32 v[6:7], v[0:1], v[6:7]
	v_pk_mul_f32 v[0:1], v[10:11], v[16:17]
	s_nop 0
	v_pk_mul_f32 v[10:11], v[0:1], v[2:3]
	v_cvt_pk_bf16_f32 v0, v4, v5
	v_cvt_pk_bf16_f32 v1, v6, v7
	v_cvt_pk_bf16_f32 v2, v8, v9
	v_cvt_pk_bf16_f32 v3, v10, v11
	global_store_dwordx4 v[12:13], v[0:3], off
	s_cbranch_vccnz .LBB0_122
	s_andn2_b64 vcc, exec, s[8:9]
	s_cbranch_vccnz .LBB0_121
	s_mov_b32 s100, 1
	s_branch .LBB0_121

.LBB0_188:
	s_add_u32 s14, s4, 0xd800000
	s_addc_u32 s15, s5, 0
	s_lshl_b32 s4, s16, 5
	s_mov_b64 s[16:17], 0x80
	s_and_b32 s21, s4, 0x60
	s_add_i32 m0, s33, 0x18000
	v_lshl_add_u64 v[6:7], v[6:7], 0, s[16:17]
	s_lshl_b32 s18, s7, 13
	s_lshl_b32 s19, s21, 7
	s_waitcnt vmcnt(2)
	s_barrier
	global_load_lds_dwordx4 v[6:7], off
	v_lshl_add_u64 v[4:5], v[4:5], 0, s[16:17]
	s_add_i32 m0, s33, 0x1a000
	s_add_i32 s44, s33, 0x8000
	s_add_i32 s45, s33, 0xa000
	global_load_lds_dwordx4 v[4:5], off
	v_lshl_add_u64 v[0:1], v[0:1], 0, s[16:17]
	s_mov_b32 m0, s44
	s_add_u32 s4, s34, 0xb0080
	global_load_lds_dwordx4 v[0:1], off
	v_lshl_add_u64 v[0:1], v[2:3], 0, s[16:17]
	s_mov_b32 m0, s45
	s_addc_u32 s5, s35, 0
	global_load_lds_dwordx4 v[0:1], off
	s_add_i32 m0, s33, 0x1c000
	v_lshl_add_u64 v[0:1], s[4:5], 0, v[132:133]
	global_load_lds_dwordx4 v[0:1], off
	v_lshl_add_u64 v[0:1], s[4:5], 0, v[128:129]
	s_add_i32 m0, s33, 0x1e000
	s_cmpk_lt_u32 s6, 0x100
	global_load_lds_dwordx4 v[0:1], off
	v_lshrrev_b32_e32 v1, 1, v8
	v_and_b32_e32 v1, 24, v1
	v_and_b32_e32 v0, 15, v8
	v_lshlrev_b32_e32 v2, 1, v1
	v_lshl_or_b32 v144, s7, 6, v0
	v_lshl_or_b32 v0, v0, 6, v2
	v_lshlrev_b32_e32 v2, 2, v8
	v_and_b32_e32 v2, 32, v2
	v_bitop3_b32 v3, v0, s18, v2 bitop3:0xde
	v_bitop3_b32 v145, s19, v0, v2 bitop3:0xf6
	v_or_b32_e32 v146, s21, v1
	v_lshrrev_b32_e32 v1, 1, v9
	v_mul_lo_u32 v0, v10, s20
	s_mov_b32 s21, 0xb000
	v_mad_u64_u32 v[0:1], s[6:7], v1, s21, v[0:1]
	v_or_b32_e32 v0, v0, v11
	s_mov_b64 s[4:5], 0xb0080
	v_add_lshl_u32 v0, v0, v12, 1
	v_mov_b32_e32 v1, v133
	v_lshl_add_u64 v[136:137], v[0:1], 0, s[4:5]
	v_lshrrev_b32_e32 v1, 1, v14
	v_mul_lo_u32 v0, v13, s20
	v_mad_u64_u32 v[0:1], s[6:7], v1, s21, v[0:1]
	s_waitcnt vmcnt(6)
	v_or_b32_e32 v0, v0, v15
	s_cselect_b64 s[18:19], -1, 0
	v_add_lshl_u32 v0, v0, v16, 1
	v_mov_b32_e32 v1, v133
	s_add_i32 s46, 0, 0x10000
	s_add_i32 s47, 0, 0x14000
	v_lshl_add_u64 v[138:139], v[0:1], 0, s[4:5]
	v_mov_b64_e32 v[140:141], 0x200
	v_mov_b64_e32 v[142:143], 0x1ff
	v_add_u32_e32 v147, s46, v145
	v_add_u32_e32 v148, s47, v145
	v_add_u32_e32 v149, 0, v3
	s_mov_b64 s[20:21], 0x40000
	s_mov_b32 s48, 0x40000
	s_mov_b64 s[22:23], 0x48000
	s_mov_b32 s49, 0x48000
	s_mov_b64 s[24:25], 0x50000
	s_mov_b32 s50, 0x50000
	s_mov_b64 s[26:27], 0x58000
	s_mov_b32 s51, 0x58000
	s_mov_b32 s54, s61
	s_mov_b32 s55, s92
	s_barrier
	s_mov_b32 s100, 0
	s_branch .LBB0_191

.LBB0_197:
	s_add_u32 s56, s34, 0x100
	v_mov_b32_e32 v0, 0
	s_addc_u32 s57, s35, 0
	s_mov_b32 s58, -2
	v_mov_b32_e32 v1, v0
	v_mov_b32_e32 v2, v0
	v_mov_b32_e32 v3, v0
	v_mov_b32_e32 v4, v0
	v_mov_b32_e32 v5, v0
	v_mov_b32_e32 v6, v0
	v_mov_b32_e32 v7, v0
	v_mov_b32_e32 v8, v0
	v_mov_b32_e32 v9, v0
	v_mov_b32_e32 v10, v0
	v_mov_b32_e32 v11, v0
	v_mov_b32_e32 v12, v0
	v_mov_b32_e32 v13, v0
	v_mov_b32_e32 v14, v0
	v_mov_b32_e32 v15, v0
	v_mov_b32_e32 v24, v0
	v_mov_b32_e32 v25, v0
	v_mov_b32_e32 v26, v0
	v_mov_b32_e32 v27, v0
	v_mov_b32_e32 v28, v0
	v_mov_b32_e32 v29, v0
	v_mov_b32_e32 v30, v0
	v_mov_b32_e32 v31, v0
	v_mov_b32_e32 v40, v0
	v_mov_b32_e32 v41, v0
	v_mov_b32_e32 v42, v0
	v_mov_b32_e32 v43, v0
	v_mov_b32_e32 v44, v0
	v_mov_b32_e32 v45, v0
	v_mov_b32_e32 v46, v0
	v_mov_b32_e32 v47, v0
	v_mov_b32_e32 v16, v0
	v_mov_b32_e32 v17, v0
	v_mov_b32_e32 v18, v0
	v_mov_b32_e32 v19, v0
	v_mov_b32_e32 v20, v0
	v_mov_b32_e32 v21, v0
	v_mov_b32_e32 v22, v0
	v_mov_b32_e32 v23, v0
	v_mov_b32_e32 v32, v0
	v_mov_b32_e32 v33, v0
	v_mov_b32_e32 v34, v0
	v_mov_b32_e32 v35, v0
	v_mov_b32_e32 v36, v0
	v_mov_b32_e32 v37, v0
	v_mov_b32_e32 v38, v0
	v_mov_b32_e32 v39, v0
	v_mov_b32_e32 v48, v0
	v_mov_b32_e32 v49, v0
	v_mov_b32_e32 v50, v0
	v_mov_b32_e32 v51, v0
	v_mov_b32_e32 v52, v0
	v_mov_b32_e32 v53, v0
	v_mov_b32_e32 v54, v0
	v_mov_b32_e32 v55, v0
	v_mov_b32_e32 v56, v0
	v_mov_b32_e32 v57, v0
	v_mov_b32_e32 v58, v0
	v_mov_b32_e32 v59, v0
	v_mov_b32_e32 v60, v0
	v_mov_b32_e32 v61, v0
	v_mov_b32_e32 v62, v0
	v_mov_b32_e32 v63, v0
	v_mov_b32_e32 v64, v0
	v_mov_b32_e32 v65, v0
	v_mov_b32_e32 v66, v0
	v_mov_b32_e32 v67, v0
	v_mov_b32_e32 v68, v0
	v_mov_b32_e32 v69, v0
	v_mov_b32_e32 v70, v0
	v_mov_b32_e32 v71, v0
	v_mov_b32_e32 v72, v0
	v_mov_b32_e32 v73, v0
	v_mov_b32_e32 v74, v0
	v_mov_b32_e32 v75, v0
	v_mov_b32_e32 v76, v0
	v_mov_b32_e32 v77, v0
	v_mov_b32_e32 v78, v0
	v_mov_b32_e32 v79, v0
	v_mov_b32_e32 v88, v0
	v_mov_b32_e32 v89, v0
	v_mov_b32_e32 v90, v0
	v_mov_b32_e32 v91, v0
	v_mov_b32_e32 v92, v0
	v_mov_b32_e32 v93, v0
	v_mov_b32_e32 v94, v0
	v_mov_b32_e32 v95, v0
	v_mov_b32_e32 v104, v0
	v_mov_b32_e32 v105, v0
	v_mov_b32_e32 v106, v0
	v_mov_b32_e32 v107, v0
	v_mov_b32_e32 v108, v0
	v_mov_b32_e32 v109, v0
	v_mov_b32_e32 v110, v0
	v_mov_b32_e32 v111, v0
	v_mov_b32_e32 v80, v0
	v_mov_b32_e32 v81, v0
	v_mov_b32_e32 v82, v0
	v_mov_b32_e32 v83, v0
	v_mov_b32_e32 v84, v0
	v_mov_b32_e32 v85, v0
	v_mov_b32_e32 v86, v0
	v_mov_b32_e32 v87, v0
	v_mov_b32_e32 v96, v0
	v_mov_b32_e32 v97, v0
	v_mov_b32_e32 v98, v0
	v_mov_b32_e32 v99, v0
	v_mov_b32_e32 v100, v0
	v_mov_b32_e32 v101, v0
	v_mov_b32_e32 v102, v0
	v_mov_b32_e32 v103, v0
	v_mov_b32_e32 v112, v0
	v_mov_b32_e32 v113, v0
	v_mov_b32_e32 v114, v0
	v_mov_b32_e32 v115, v0
	v_mov_b32_e32 v116, v0
	v_mov_b32_e32 v117, v0
	v_mov_b32_e32 v118, v0
	v_mov_b32_e32 v119, v0
	v_mov_b32_e32 v120, v0
	v_mov_b32_e32 v121, v0
	v_mov_b32_e32 v122, v0
	v_mov_b32_e32 v123, v0
	v_mov_b32_e32 v124, v0
	v_mov_b32_e32 v125, v0
	v_mov_b32_e32 v126, v0
	v_mov_b32_e32 v127, v0
	s_cmp_eq_u32 s100, 1
	s_cbranch_scc0 .Lgemm_nobar_189
	s_mov_b32 s100, 0
	s_barrier
.Lgemm_nobar_189:
.LBB0_198:
	ds_read_b128 v[150:153], v147
	ds_read_b128 v[154:157], v147 offset:1024
	ds_read_b128 v[158:161], v147 offset:2048
	ds_read_b128 v[162:165], v147 offset:3072
	ds_read_b128 v[166:169], v148
	ds_read_b128 v[170:173], v148 offset:1024
	ds_read_b128 v[174:177], v148 offset:2048
	ds_read_b128 v[178:181], v148 offset:3072
	s_add_u32 s34, s30, 0x100
	s_addc_u32 s35, s31, 0
	s_cmp_eq_u32 s58, 40
	s_cselect_b32 s39, s7, s35
	s_cselect_b32 s38, s6, s34
	s_cselect_b32 s37, s29, s57
	s_cselect_b32 s36, s28, s56
	v_lshl_add_u64 v[214:215], s[30:31], 0, v[138:139]
	s_add_i32 m0, s33, 0xc000
	ds_read_b128 v[182:185], v149
	ds_read_b128 v[186:189], v149 offset:1024
	ds_read_b128 v[190:193], v149 offset:2048
	ds_read_b128 v[194:197], v149 offset:3072
	ds_read_b128 v[198:201], v149 offset:4096
	ds_read_b128 v[202:205], v149 offset:5120
	ds_read_b128 v[206:209], v149 offset:6144
	ds_read_b128 v[210:213], v149 offset:7168
	global_load_lds_dwordx4 v[214:215], off
	v_lshl_add_u64 v[214:215], s[30:31], 0, v[136:137]
	s_add_i32 m0, s33, 0xe000
	s_nop 0
	global_load_lds_dwordx4 v[214:215], off
	s_waitcnt vmcnt(8)
	s_waitcnt lgkmcnt(0)
	s_barrier
	s_setprio 1
	s_waitcnt lgkmcnt(0)
	v_mfma_f32_16x16x32_bf16 v[124:127], v[150:153], v[182:185], v[124:127]
	v_mfma_f32_16x16x32_bf16 v[120:123], v[158:161], v[182:185], v[120:123]
	v_mfma_f32_16x16x32_bf16 v[116:119], v[150:153], v[190:193], v[116:119]
	v_mfma_f32_16x16x32_bf16 v[112:115], v[158:161], v[190:193], v[112:115]
	v_mfma_f32_16x16x32_bf16 v[100:103], v[150:153], v[198:201], v[100:103]
	v_mfma_f32_16x16x32_bf16 v[96:99], v[158:161], v[198:201], v[96:99]
	v_mfma_f32_16x16x32_bf16 v[84:87], v[150:153], v[206:209], v[84:87]
	v_mfma_f32_16x16x32_bf16 v[80:83], v[158:161], v[206:209], v[80:83]
	v_mfma_f32_16x16x32_bf16 v[124:127], v[154:157], v[186:189], v[124:127]
	v_mfma_f32_16x16x32_bf16 v[120:123], v[162:165], v[186:189], v[120:123]
	v_mfma_f32_16x16x32_bf16 v[116:119], v[154:157], v[194:197], v[116:119]
	v_mfma_f32_16x16x32_bf16 v[112:115], v[162:165], v[194:197], v[112:115]
	v_mfma_f32_16x16x32_bf16 v[100:103], v[154:157], v[202:205], v[100:103]
	v_mfma_f32_16x16x32_bf16 v[96:99], v[162:165], v[202:205], v[96:99]
	v_mfma_f32_16x16x32_bf16 v[84:87], v[154:157], v[210:213], v[84:87]
	v_mfma_f32_16x16x32_bf16 v[80:83], v[162:165], v[210:213], v[80:83]
	s_setprio 0
	s_setprio 1
	v_mfma_f32_16x16x32_bf16 v[108:111], v[166:169], v[182:185], v[108:111]
	v_mfma_f32_16x16x32_bf16 v[104:107], v[174:177], v[182:185], v[104:107]
	v_mfma_f32_16x16x32_bf16 v[92:95], v[166:169], v[190:193], v[92:95]
	v_mfma_f32_16x16x32_bf16 v[88:91], v[174:177], v[190:193], v[88:91]
	v_mfma_f32_16x16x32_bf16 v[76:79], v[166:169], v[198:201], v[76:79]
	v_mfma_f32_16x16x32_bf16 v[72:75], v[174:177], v[198:201], v[72:75]
	v_mfma_f32_16x16x32_bf16 v[68:71], v[166:169], v[206:209], v[68:71]
	v_mfma_f32_16x16x32_bf16 v[64:67], v[174:177], v[206:209], v[64:67]
	v_mfma_f32_16x16x32_bf16 v[108:111], v[170:173], v[186:189], v[108:111]
	v_mfma_f32_16x16x32_bf16 v[104:107], v[178:181], v[186:189], v[104:107]
	v_mfma_f32_16x16x32_bf16 v[92:95], v[170:173], v[194:197], v[92:95]
	v_mfma_f32_16x16x32_bf16 v[88:91], v[178:181], v[194:197], v[88:91]
	v_mfma_f32_16x16x32_bf16 v[76:79], v[170:173], v[202:205], v[76:79]
	v_mfma_f32_16x16x32_bf16 v[72:75], v[178:181], v[202:205], v[72:75]
	v_mfma_f32_16x16x32_bf16 v[68:71], v[170:173], v[210:213], v[68:71]
	v_mfma_f32_16x16x32_bf16 v[64:67], v[178:181], v[210:213], v[64:67]
	s_setprio 0
	s_barrier
	s_add_i32 s30, s46, s1
	v_lshl_add_u64 v[214:215], s[36:37], 0, v[132:133]
	s_mov_b32 m0, s30
	ds_read_b128 v[182:185], v149 offset:16384
	ds_read_b128 v[186:189], v149 offset:17408
	ds_read_b128 v[190:193], v149 offset:18432
	ds_read_b128 v[194:197], v149 offset:19456
	ds_read_b128 v[198:201], v149 offset:20480
	ds_read_b128 v[202:205], v149 offset:21504
	ds_read_b128 v[206:209], v149 offset:22528
	ds_read_b128 v[210:213], v149 offset:23552
	global_load_lds_dwordx4 v[214:215], off
	s_add_i32 m0, s30, 0x2000
	s_add_u32 s30, s36, 0xb0000
	v_lshl_add_u64 v[216:217], s[36:37], 0, v[128:129]
	s_addc_u32 s31, s37, 0
	s_add_i32 s59, s47, s1
	global_load_lds_dwordx4 v[216:217], off
	v_lshl_add_u64 v[218:219], s[30:31], 0, v[132:133]
	s_mov_b32 m0, s59
	v_lshl_add_u64 v[220:221], s[38:39], 0, v[130:131]
	global_load_lds_dwordx4 v[218:219], off
	v_lshl_add_u64 v[218:219], s[30:31], 0, v[128:129]
	s_add_i32 m0, s59, 0x2000
	s_nop 0
	global_load_lds_dwordx4 v[218:219], off
	v_lshl_add_u64 v[218:219], s[38:39], 0, v[134:135]
	s_mov_b32 m0, s33
	s_nop 0
	global_load_lds_dwordx4 v[218:219], off
	s_mov_b32 m0, s40
	s_nop 0
	global_load_lds_dwordx4 v[220:221], off
	s_waitcnt vmcnt(8)
	s_waitcnt lgkmcnt(0)
	s_barrier
	s_setprio 1
	s_waitcnt lgkmcnt(0)
	v_mfma_f32_16x16x32_bf16 v[60:63], v[150:153], v[182:185], v[60:63]
	v_mfma_f32_16x16x32_bf16 v[56:59], v[158:161], v[182:185], v[56:59]
	v_mfma_f32_16x16x32_bf16 v[52:55], v[150:153], v[190:193], v[52:55]
	v_mfma_f32_16x16x32_bf16 v[48:51], v[158:161], v[190:193], v[48:51]
	v_mfma_f32_16x16x32_bf16 v[36:39], v[150:153], v[198:201], v[36:39]
	v_mfma_f32_16x16x32_bf16 v[32:35], v[158:161], v[198:201], v[32:35]
	v_mfma_f32_16x16x32_bf16 v[20:23], v[150:153], v[206:209], v[20:23]
	v_mfma_f32_16x16x32_bf16 v[16:19], v[158:161], v[206:209], v[16:19]
	v_mfma_f32_16x16x32_bf16 v[60:63], v[154:157], v[186:189], v[60:63]
	v_mfma_f32_16x16x32_bf16 v[56:59], v[162:165], v[186:189], v[56:59]
	v_mfma_f32_16x16x32_bf16 v[52:55], v[154:157], v[194:197], v[52:55]
	v_mfma_f32_16x16x32_bf16 v[48:51], v[162:165], v[194:197], v[48:51]
	v_mfma_f32_16x16x32_bf16 v[36:39], v[154:157], v[202:205], v[36:39]
	v_mfma_f32_16x16x32_bf16 v[32:35], v[162:165], v[202:205], v[32:35]
	v_mfma_f32_16x16x32_bf16 v[20:23], v[154:157], v[210:213], v[20:23]
	v_mfma_f32_16x16x32_bf16 v[16:19], v[162:165], v[210:213], v[16:19]
	s_setprio 0
	s_setprio 1
	v_mfma_f32_16x16x32_bf16 v[44:47], v[166:169], v[182:185], v[44:47]
	v_mfma_f32_16x16x32_bf16 v[40:43], v[174:177], v[182:185], v[40:43]
	v_mfma_f32_16x16x32_bf16 v[28:31], v[166:169], v[190:193], v[28:31]
	v_mfma_f32_16x16x32_bf16 v[24:27], v[174:177], v[190:193], v[24:27]
	v_mfma_f32_16x16x32_bf16 v[12:15], v[166:169], v[198:201], v[12:15]
	v_mfma_f32_16x16x32_bf16 v[8:11], v[174:177], v[198:201], v[8:11]
	v_mfma_f32_16x16x32_bf16 v[4:7], v[166:169], v[206:209], v[4:7]
	v_mfma_f32_16x16x32_bf16 v[0:3], v[174:177], v[206:209], v[0:3]
	v_mfma_f32_16x16x32_bf16 v[44:47], v[170:173], v[186:189], v[44:47]
	v_mfma_f32_16x16x32_bf16 v[40:43], v[178:181], v[186:189], v[40:43]
	v_mfma_f32_16x16x32_bf16 v[28:31], v[170:173], v[194:197], v[28:31]
	v_mfma_f32_16x16x32_bf16 v[24:27], v[178:181], v[194:197], v[24:27]
	v_mfma_f32_16x16x32_bf16 v[12:15], v[170:173], v[202:205], v[12:15]
	v_mfma_f32_16x16x32_bf16 v[8:11], v[178:181], v[202:205], v[8:11]
	v_mfma_f32_16x16x32_bf16 v[4:7], v[170:173], v[210:213], v[4:7]
	v_mfma_f32_16x16x32_bf16 v[0:3], v[178:181], v[210:213], v[0:3]
	s_setprio 0
	s_barrier
	s_add_i32 s59, 0, 0x18000
	s_add_i32 s60, 0, 0x1c000
	v_add_u32_e32 v162, s59, v145
	v_add_u32_e32 v178, s60, v145
	ds_read_b128 v[150:153], v162
	ds_read_b128 v[154:157], v162 offset:1024
	ds_read_b128 v[158:161], v162 offset:2048
	ds_read_b128 v[162:165], v162 offset:3072
	ds_read_b128 v[166:169], v178
	ds_read_b128 v[170:173], v178 offset:1024
	ds_read_b128 v[174:177], v178 offset:2048
	ds_read_b128 v[178:181], v178 offset:3072
	s_add_u32 s30, s38, 0xb0000
	s_addc_u32 s31, s39, 0
	s_mov_b32 m0, s41
	v_lshl_add_u64 v[222:223], s[30:31], 0, v[134:135]
	ds_read_b128 v[182:185], v149 offset:32768
	ds_read_b128 v[186:189], v149 offset:33792
	ds_read_b128 v[190:193], v149 offset:34816
	ds_read_b128 v[194:197], v149 offset:35840
	ds_read_b128 v[198:201], v149 offset:36864
	ds_read_b128 v[202:205], v149 offset:37888
	ds_read_b128 v[206:209], v149 offset:38912
	ds_read_b128 v[210:213], v149 offset:39936
	global_load_lds_dwordx4 v[222:223], off
	v_lshl_add_u64 v[222:223], s[30:31], 0, v[130:131]
	s_mov_b32 m0, s42
	s_nop 0
	global_load_lds_dwordx4 v[222:223], off
	s_waitcnt vmcnt(8)
	s_waitcnt lgkmcnt(0)
	s_barrier
	s_setprio 1
	s_waitcnt lgkmcnt(0)
	v_mfma_f32_16x16x32_bf16 v[124:127], v[150:153], v[182:185], v[124:127]
	v_mfma_f32_16x16x32_bf16 v[120:123], v[158:161], v[182:185], v[120:123]
	v_mfma_f32_16x16x32_bf16 v[116:119], v[150:153], v[190:193], v[116:119]
	v_mfma_f32_16x16x32_bf16 v[112:115], v[158:161], v[190:193], v[112:115]
	v_mfma_f32_16x16x32_bf16 v[100:103], v[150:153], v[198:201], v[100:103]
	v_mfma_f32_16x16x32_bf16 v[96:99], v[158:161], v[198:201], v[96:99]
	v_mfma_f32_16x16x32_bf16 v[84:87], v[150:153], v[206:209], v[84:87]
	v_mfma_f32_16x16x32_bf16 v[80:83], v[158:161], v[206:209], v[80:83]
	v_mfma_f32_16x16x32_bf16 v[124:127], v[154:157], v[186:189], v[124:127]
	v_mfma_f32_16x16x32_bf16 v[120:123], v[162:165], v[186:189], v[120:123]
	v_mfma_f32_16x16x32_bf16 v[116:119], v[154:157], v[194:197], v[116:119]
	v_mfma_f32_16x16x32_bf16 v[112:115], v[162:165], v[194:197], v[112:115]
	v_mfma_f32_16x16x32_bf16 v[100:103], v[154:157], v[202:205], v[100:103]
	v_mfma_f32_16x16x32_bf16 v[96:99], v[162:165], v[202:205], v[96:99]
	v_mfma_f32_16x16x32_bf16 v[84:87], v[154:157], v[210:213], v[84:87]
	v_mfma_f32_16x16x32_bf16 v[80:83], v[162:165], v[210:213], v[80:83]
	s_setprio 0
	s_setprio 1
	v_mfma_f32_16x16x32_bf16 v[108:111], v[166:169], v[182:185], v[108:111]
	v_mfma_f32_16x16x32_bf16 v[104:107], v[174:177], v[182:185], v[104:107]
	v_mfma_f32_16x16x32_bf16 v[92:95], v[166:169], v[190:193], v[92:95]
	v_mfma_f32_16x16x32_bf16 v[88:91], v[174:177], v[190:193], v[88:91]
	v_mfma_f32_16x16x32_bf16 v[76:79], v[166:169], v[198:201], v[76:79]
	v_mfma_f32_16x16x32_bf16 v[72:75], v[174:177], v[198:201], v[72:75]
	v_mfma_f32_16x16x32_bf16 v[68:71], v[166:169], v[206:209], v[68:71]
	v_mfma_f32_16x16x32_bf16 v[64:67], v[174:177], v[206:209], v[64:67]
	v_mfma_f32_16x16x32_bf16 v[108:111], v[170:173], v[186:189], v[108:111]
	v_mfma_f32_16x16x32_bf16 v[104:107], v[178:181], v[186:189], v[104:107]
	v_mfma_f32_16x16x32_bf16 v[92:95], v[170:173], v[194:197], v[92:95]
	v_mfma_f32_16x16x32_bf16 v[88:91], v[178:181], v[194:197], v[88:91]
	v_mfma_f32_16x16x32_bf16 v[76:79], v[170:173], v[202:205], v[76:79]
	v_mfma_f32_16x16x32_bf16 v[72:75], v[178:181], v[202:205], v[72:75]
	v_mfma_f32_16x16x32_bf16 v[68:71], v[170:173], v[210:213], v[68:71]
	v_mfma_f32_16x16x32_bf16 v[64:67], v[178:181], v[210:213], v[64:67]
	s_setprio 0
	s_barrier
	s_add_i32 s30, s59, s1
	v_lshl_add_u64 v[214:215], v[214:215], 0, s[16:17]
	s_mov_b32 m0, s30
	ds_read_b128 v[182:185], v149 offset:49152
	ds_read_b128 v[186:189], v149 offset:50176
	ds_read_b128 v[190:193], v149 offset:51200
	ds_read_b128 v[194:197], v149 offset:52224
	ds_read_b128 v[198:201], v149 offset:53248
	ds_read_b128 v[202:205], v149 offset:54272
	ds_read_b128 v[206:209], v149 offset:55296
	ds_read_b128 v[210:213], v149 offset:56320
	global_load_lds_dwordx4 v[214:215], off
	s_add_i32 m0, s30, 0x2000
	s_add_u32 s30, s36, 0xb0080
	v_lshl_add_u64 v[214:215], v[216:217], 0, s[16:17]
	s_addc_u32 s31, s37, 0
	s_add_i32 s36, s60, s1
	global_load_lds_dwordx4 v[214:215], off
	v_lshl_add_u64 v[214:215], s[30:31], 0, v[132:133]
	s_mov_b32 m0, s36
	s_nop 0
	global_load_lds_dwordx4 v[214:215], off
	v_lshl_add_u64 v[214:215], s[30:31], 0, v[128:129]
	s_add_i32 m0, s36, 0x2000
	s_nop 0
	global_load_lds_dwordx4 v[214:215], off
	v_lshl_add_u64 v[214:215], v[218:219], 0, s[16:17]
	s_mov_b32 m0, s44
	s_nop 0
	global_load_lds_dwordx4 v[214:215], off
	v_lshl_add_u64 v[214:215], v[220:221], 0, s[16:17]
	s_mov_b32 m0, s45
	s_nop 0
	global_load_lds_dwordx4 v[214:215], off
	s_waitcnt vmcnt(8)
	s_waitcnt lgkmcnt(0)
	s_barrier
	s_setprio 1
	s_waitcnt lgkmcnt(0)
	v_mfma_f32_16x16x32_bf16 v[60:63], v[150:153], v[182:185], v[60:63]
	v_mfma_f32_16x16x32_bf16 v[56:59], v[158:161], v[182:185], v[56:59]
	v_mfma_f32_16x16x32_bf16 v[52:55], v[150:153], v[190:193], v[52:55]
	v_mfma_f32_16x16x32_bf16 v[48:51], v[158:161], v[190:193], v[48:51]
	v_mfma_f32_16x16x32_bf16 v[36:39], v[150:153], v[198:201], v[36:39]
	v_mfma_f32_16x16x32_bf16 v[32:35], v[158:161], v[198:201], v[32:35]
	v_mfma_f32_16x16x32_bf16 v[20:23], v[150:153], v[206:209], v[20:23]
	v_mfma_f32_16x16x32_bf16 v[16:19], v[158:161], v[206:209], v[16:19]
	v_mfma_f32_16x16x32_bf16 v[60:63], v[154:157], v[186:189], v[60:63]
	v_mfma_f32_16x16x32_bf16 v[56:59], v[162:165], v[186:189], v[56:59]
	v_mfma_f32_16x16x32_bf16 v[52:55], v[154:157], v[194:197], v[52:55]
	v_mfma_f32_16x16x32_bf16 v[48:51], v[162:165], v[194:197], v[48:51]
	v_mfma_f32_16x16x32_bf16 v[36:39], v[154:157], v[202:205], v[36:39]
	v_mfma_f32_16x16x32_bf16 v[32:35], v[162:165], v[202:205], v[32:35]
	v_mfma_f32_16x16x32_bf16 v[20:23], v[154:157], v[210:213], v[20:23]
	v_mfma_f32_16x16x32_bf16 v[16:19], v[162:165], v[210:213], v[16:19]
	s_setprio 0
	s_setprio 1
	v_mfma_f32_16x16x32_bf16 v[44:47], v[166:169], v[182:185], v[44:47]
	v_mfma_f32_16x16x32_bf16 v[40:43], v[174:177], v[182:185], v[40:43]
	v_mfma_f32_16x16x32_bf16 v[28:31], v[166:169], v[190:193], v[28:31]
	v_mfma_f32_16x16x32_bf16 v[24:27], v[174:177], v[190:193], v[24:27]
	v_mfma_f32_16x16x32_bf16 v[12:15], v[166:169], v[198:201], v[12:15]
	v_mfma_f32_16x16x32_bf16 v[8:11], v[174:177], v[198:201], v[8:11]
	v_mfma_f32_16x16x32_bf16 v[4:7], v[166:169], v[206:209], v[4:7]
	v_mfma_f32_16x16x32_bf16 v[0:3], v[174:177], v[206:209], v[0:3]
	v_mfma_f32_16x16x32_bf16 v[44:47], v[170:173], v[186:189], v[44:47]
	v_mfma_f32_16x16x32_bf16 v[40:43], v[178:181], v[186:189], v[40:43]
	v_mfma_f32_16x16x32_bf16 v[28:31], v[170:173], v[194:197], v[28:31]
	v_mfma_f32_16x16x32_bf16 v[24:27], v[178:181], v[194:197], v[24:27]
	v_mfma_f32_16x16x32_bf16 v[12:15], v[170:173], v[202:205], v[12:15]
	v_mfma_f32_16x16x32_bf16 v[8:11], v[178:181], v[202:205], v[8:11]
	v_mfma_f32_16x16x32_bf16 v[4:7], v[170:173], v[210:213], v[4:7]
	v_mfma_f32_16x16x32_bf16 v[0:3], v[178:181], v[210:213], v[0:3]
	s_setprio 0
	s_barrier
	s_add_i32 s58, s58, 2
	s_add_u32 s56, s56, 0x100
	s_addc_u32 s57, s57, 0
	s_cmp_gt_u32 s58, 41
	s_mov_b64 s[30:31], s[34:35]
	s_cbranch_scc0 .LBB0_198
	s_and_b64 vcc, exec, s[18:19]
	s_cbranch_vccz .LBB0_201
	s_barrier
.LBB0_201:
	v_lshl_or_b32 v150, s54, 8, v146
	v_lshl_add_u32 v152, s55, 8, v144
	s_mov_b64 s[30:31], s[14:15]
	v_ashrrev_i32_e32 v151, 31, v150
	v_ashrrev_i32_e32 v153, 31, v152
	v_lshlrev_b64 v[154:155], 11, v[152:153]
	v_lshl_add_u64 v[150:151], v[150:151], 1, s[30:31]
	v_lshl_add_u64 v[154:155], v[150:151], 0, v[154:155]
	v_cvt_pk_bf16_f32 v60, v60, v61
	v_cvt_pk_bf16_f32 v61, v62, v63
	v_cvt_pk_bf16_f32 v62, v56, v57
	v_add_co_u32_e32 v56, vcc, s48, v154
	v_cvt_pk_bf16_f32 v68, v68, v69
	v_cvt_pk_bf16_f32 v69, v70, v71
	v_cvt_pk_bf16_f32 v70, v64, v65
	v_lshl_add_u64 v[64:65], v[154:155], 0, s[20:21]
	v_addc_co_u32_e32 v57, vcc, 0, v155, vcc
	v_cvt_pk_bf16_f32 v44, v44, v45
	v_cvt_pk_bf16_f32 v45, v46, v47
	v_cvt_pk_bf16_f32 v46, v40, v41
	v_cvt_pk_bf16_f32 v47, v42, v43
	global_store_dwordx4 v[64:65], v[44:47], off offset:256
	v_cvt_pk_bf16_f32 v108, v108, v109
	v_cvt_pk_bf16_f32 v109, v110, v111
	v_add_co_u32_e32 v46, vcc, s49, v154
	v_cvt_pk_bf16_f32 v110, v104, v105
	v_or_b32_e32 v104, 16, v152
	v_lshl_add_u64 v[44:45], v[154:155], 0, s[22:23]
	v_addc_co_u32_e32 v47, vcc, 0, v155, vcc
	v_cvt_pk_bf16_f32 v28, v28, v29
	v_cvt_pk_bf16_f32 v29, v30, v31
	v_cvt_pk_bf16_f32 v30, v24, v25
	v_cvt_pk_bf16_f32 v31, v26, v27
	v_ashrrev_i32_e32 v105, 31, v104
	v_cvt_pk_bf16_f32 v92, v92, v93
	v_cvt_pk_bf16_f32 v93, v94, v95
	v_cvt_pk_bf16_f32 v94, v88, v89
	v_or_b32_e32 v88, 32, v152
	global_store_dwordx4 v[44:45], v[28:31], off offset:256
	v_cvt_pk_bf16_f32 v111, v106, v107
	v_lshlrev_b64 v[104:105], 11, v[104:105]
	v_add_co_u32_e32 v30, vcc, s50, v154
	v_ashrrev_i32_e32 v89, 31, v88
	v_cvt_pk_bf16_f32 v76, v76, v77
	v_cvt_pk_bf16_f32 v77, v78, v79
	v_cvt_pk_bf16_f32 v78, v72, v73
	v_or_b32_e32 v72, 48, v152
	v_lshl_add_u64 v[28:29], v[154:155], 0, s[24:25]
	v_addc_co_u32_e32 v31, vcc, 0, v155, vcc
	v_cvt_pk_bf16_f32 v12, v12, v13
	v_cvt_pk_bf16_f32 v13, v14, v15
	v_cvt_pk_bf16_f32 v14, v8, v9
	v_cvt_pk_bf16_f32 v15, v10, v11
	global_store_dwordx4 v[154:155], v[108:111], off offset:256
	v_cvt_pk_bf16_f32 v95, v90, v91
	v_lshlrev_b64 v[88:89], 11, v[88:89]
	v_lshl_add_u64 v[108:109], v[150:151], 0, v[104:105]
	v_ashrrev_i32_e32 v73, 31, v72
	global_store_dwordx4 v[28:29], v[12:15], off offset:256
	global_store_dwordx4 v[108:109], v[92:95], off offset:256
	v_cvt_pk_bf16_f32 v79, v74, v75
	v_add_co_u32_e32 v14, vcc, s51, v154
	v_lshl_add_u64 v[92:93], v[150:151], 0, v[88:89]
	v_lshlrev_b64 v[72:73], 11, v[72:73]
	v_addc_co_u32_e32 v15, vcc, 0, v155, vcc
	v_cvt_pk_bf16_f32 v124, v124, v125
	v_cvt_pk_bf16_f32 v125, v126, v127
	v_cvt_pk_bf16_f32 v126, v120, v121
	v_cvt_pk_bf16_f32 v127, v122, v123
	v_cvt_pk_bf16_f32 v104, v116, v117
	v_cvt_pk_bf16_f32 v105, v118, v119
	v_cvt_pk_bf16_f32 v106, v112, v113
	v_cvt_pk_bf16_f32 v107, v114, v115
	v_cvt_pk_bf16_f32 v88, v100, v101
	v_cvt_pk_bf16_f32 v89, v102, v103
	v_cvt_pk_bf16_f32 v90, v96, v97
	v_cvt_pk_bf16_f32 v91, v98, v99
	global_store_dwordx4 v[92:93], v[76:79], off offset:256
	v_cvt_pk_bf16_f32 v74, v80, v81
	v_cvt_pk_bf16_f32 v75, v82, v83
	v_lshl_add_u64 v[76:77], v[150:151], 0, v[72:73]
	v_cvt_pk_bf16_f32 v72, v84, v85
	v_cvt_pk_bf16_f32 v73, v86, v87
	v_cvt_pk_bf16_f32 v71, v66, v67
	v_cvt_pk_bf16_f32 v63, v58, v59
	v_cvt_pk_bf16_f32 v40, v52, v53
	v_cvt_pk_bf16_f32 v41, v54, v55
	v_cvt_pk_bf16_f32 v42, v48, v49
	v_cvt_pk_bf16_f32 v43, v50, v51
	v_cvt_pk_bf16_f32 v24, v36, v37
	v_cvt_pk_bf16_f32 v25, v38, v39
	v_cvt_pk_bf16_f32 v26, v32, v33
	v_cvt_pk_bf16_f32 v27, v34, v35
	v_lshl_add_u64 v[12:13], v[154:155], 0, s[26:27]
	v_cvt_pk_bf16_f32 v8, v20, v21
	v_cvt_pk_bf16_f32 v9, v22, v23
	v_cvt_pk_bf16_f32 v10, v16, v17
	v_cvt_pk_bf16_f32 v11, v18, v19
	v_cvt_pk_bf16_f32 v4, v4, v5
	v_cvt_pk_bf16_f32 v5, v6, v7
	v_cvt_pk_bf16_f32 v6, v0, v1
	v_cvt_pk_bf16_f32 v7, v2, v3
	s_and_b64 vcc, exec, s[4:5]
	s_mov_b64 s[4:5], -1
	global_store_dwordx4 v[154:155], v[124:127], off
	global_store_dwordx4 v[108:109], v[104:107], off
	global_store_dwordx4 v[92:93], v[88:91], off
	global_store_dwordx4 v[76:77], v[72:75], off
	global_store_dwordx4 v[76:77], v[68:71], off offset:256
	global_store_dwordx4 v[56:57], v[60:63], off
	global_store_dwordx4 v[46:47], v[40:43], off
	global_store_dwordx4 v[30:31], v[24:27], off
	global_store_dwordx4 v[14:15], v[8:11], off
	global_store_dwordx4 v[12:13], v[4:7], off offset:256
	s_cbranch_vccnz .LBB0_190
	s_andn2_b64 vcc, exec, s[12:13]
	s_cbranch_vccnz .LBB0_189
	s_mov_b32 s100, 1
	s_branch .LBB0_189

.LBB0_350:
	s_add_u32 s10, s4, 0x11800000
	s_addc_u32 s11, s5, 0
	s_lshl_b32 s4, s12, 5
	s_mov_b64 s[12:13], 0x80
	s_and_b32 s18, s4, 0x60
	s_add_i32 m0, s25, 0x18000
	v_lshl_add_u64 v[6:7], v[6:7], 0, s[12:13]
	s_lshl_b32 s17, s16, 13
	s_lshl_b32 s19, s18, 7
	s_waitcnt vmcnt(2)
	s_barrier
	global_load_lds_dwordx4 v[6:7], off
	v_lshl_add_u64 v[4:5], v[4:5], 0, s[12:13]
	s_add_i32 m0, s25, 0x1a000
	s_add_i32 s39, s25, 0x8000
	s_add_i32 s40, s25, 0xa000
	global_load_lds_dwordx4 v[4:5], off
	v_lshl_add_u64 v[0:1], v[0:1], 0, s[12:13]
	s_mov_b32 m0, s39
	s_add_u32 s4, s26, 0x40080
	global_load_lds_dwordx4 v[0:1], off
	v_lshl_add_u64 v[0:1], v[2:3], 0, s[12:13]
	s_mov_b32 m0, s40
	s_addc_u32 s5, s27, 0
	global_load_lds_dwordx4 v[0:1], off
	s_add_i32 m0, s25, 0x1c000
	v_lshl_add_u64 v[0:1], s[4:5], 0, v[132:133]
	global_load_lds_dwordx4 v[0:1], off
	v_lshl_add_u64 v[0:1], s[4:5], 0, v[128:129]
	s_add_i32 m0, s25, 0x1e000
	s_cmpk_lt_u32 s15, 0x100
	global_load_lds_dwordx4 v[0:1], off
	v_lshrrev_b32_e32 v1, 1, v8
	v_and_b32_e32 v1, 24, v1
	v_and_b32_e32 v0, 15, v8
	v_lshlrev_b32_e32 v2, 1, v1
	v_lshl_or_b32 v145, s16, 6, v0
	v_lshl_or_b32 v0, v0, 6, v2
	v_lshlrev_b32_e32 v2, 2, v8
	v_and_b32_e32 v2, 32, v2
	v_bitop3_b32 v3, v0, s17, v2 bitop3:0xde
	v_bitop3_b32 v146, s19, v0, v2 bitop3:0xf6
	v_lshlrev_b32_e32 v0, 14, v9
	v_and_b32_e32 v0, 0xffff8000, v0
	v_or_b32_e32 v147, s18, v1
	v_lshl_add_u32 v0, v10, 11, v0
	v_and_b32_e32 v1, 1, v9
	v_lshl_or_b32 v0, v1, 6, v0
	v_lshl_add_u32 v136, v11, 1, v0
	v_lshlrev_b32_e32 v0, 14, v13
	v_and_b32_e32 v0, 0xffff8000, v0
	s_waitcnt vmcnt(6)
	v_lshl_add_u32 v0, v12, 11, v0
	v_and_b32_e32 v1, 1, v13
	s_sext_i32_i8 s44, s14
	s_cselect_b64 s[14:15], -1, 0
	v_lshl_or_b32 v0, v1, 6, v0
	s_add_i32 s41, 0, 0x10000
	s_add_i32 s42, 0, 0x14000
	v_mov_b32_e32 v137, v133
	v_lshl_add_u32 v138, v14, 1, v0
	v_mov_b32_e32 v139, v133
	v_mov_b64_e32 v[140:141], 0x600
	v_mov_b64_e32 v[142:143], 0x5ff
	v_add_u32_e32 v148, s41, v146
	v_add_u32_e32 v149, s42, v146
	v_add_u32_e32 v150, 0, v3
	s_movk_i32 s43, 0x1800
	v_mov_b32_e32 v151, 0x3db504f3
	s_barrier
	s_mov_b32 s100, 0
	s_branch .LBB0_353

.LBB0_355:
	s_ashr_i32 s19, s18, 31
	s_lshl_b64 s[20:21], s[18:19], 19
	s_add_u32 s20, s0, s20
	s_addc_u32 s21, s1, s21
	s_and_b64 s[22:23], s[4:5], exec
	s_cselect_b32 s19, s21, s29
	s_cselect_b32 s45, s20, s28
	s_ashr_i32 s17, s16, 31
	s_lshl_b64 s[22:23], s[16:17], 19
	s_add_u32 s22, s6, s22
	s_addc_u32 s23, s7, s23
	s_and_b64 s[30:31], s[4:5], exec
	s_cselect_b32 s17, s23, s27
	s_cselect_b32 s46, s22, s26
	s_add_u32 s47, s26, 0x100
	s_addc_u32 s48, s27, 0
	s_add_u32 s26, s28, 0x40080
	v_mov_b32_e32 v0, 0
	s_addc_u32 s27, s29, 0
	s_mov_b32 s49, -2
	v_mov_b32_e32 v1, v0
	v_mov_b32_e32 v2, v0
	v_mov_b32_e32 v3, v0
	v_mov_b32_e32 v4, v0
	v_mov_b32_e32 v5, v0
	v_mov_b32_e32 v6, v0
	v_mov_b32_e32 v7, v0
	v_mov_b32_e32 v8, v0
	v_mov_b32_e32 v9, v0
	v_mov_b32_e32 v10, v0
	v_mov_b32_e32 v11, v0
	v_mov_b32_e32 v16, v0
	v_mov_b32_e32 v17, v0
	v_mov_b32_e32 v18, v0
	v_mov_b32_e32 v19, v0
	v_mov_b32_e32 v24, v0
	v_mov_b32_e32 v25, v0
	v_mov_b32_e32 v26, v0
	v_mov_b32_e32 v27, v0
	v_mov_b32_e32 v32, v0
	v_mov_b32_e32 v33, v0
	v_mov_b32_e32 v34, v0
	v_mov_b32_e32 v35, v0
	v_mov_b32_e32 v40, v0
	v_mov_b32_e32 v41, v0
	v_mov_b32_e32 v42, v0
	v_mov_b32_e32 v43, v0
	v_mov_b32_e32 v48, v0
	v_mov_b32_e32 v49, v0
	v_mov_b32_e32 v50, v0
	v_mov_b32_e32 v51, v0
	v_mov_b32_e32 v12, v0
	v_mov_b32_e32 v13, v0
	v_mov_b32_e32 v14, v0
	v_mov_b32_e32 v15, v0
	v_mov_b32_e32 v20, v0
	v_mov_b32_e32 v21, v0
	v_mov_b32_e32 v22, v0
	v_mov_b32_e32 v23, v0
	v_mov_b32_e32 v28, v0
	v_mov_b32_e32 v29, v0
	v_mov_b32_e32 v30, v0
	v_mov_b32_e32 v31, v0
	v_mov_b32_e32 v36, v0
	v_mov_b32_e32 v37, v0
	v_mov_b32_e32 v38, v0
	v_mov_b32_e32 v39, v0
	v_mov_b32_e32 v44, v0
	v_mov_b32_e32 v45, v0
	v_mov_b32_e32 v46, v0
	v_mov_b32_e32 v47, v0
	v_mov_b32_e32 v52, v0
	v_mov_b32_e32 v53, v0
	v_mov_b32_e32 v54, v0
	v_mov_b32_e32 v55, v0
	v_mov_b32_e32 v56, v0
	v_mov_b32_e32 v57, v0
	v_mov_b32_e32 v58, v0
	v_mov_b32_e32 v59, v0
	v_mov_b32_e32 v60, v0
	v_mov_b32_e32 v61, v0
	v_mov_b32_e32 v62, v0
	v_mov_b32_e32 v63, v0
	v_mov_b32_e32 v64, v0
	v_mov_b32_e32 v65, v0
	v_mov_b32_e32 v66, v0
	v_mov_b32_e32 v67, v0
	v_mov_b32_e32 v68, v0
	v_mov_b32_e32 v69, v0
	v_mov_b32_e32 v70, v0
	v_mov_b32_e32 v71, v0
	v_mov_b32_e32 v72, v0
	v_mov_b32_e32 v73, v0
	v_mov_b32_e32 v74, v0
	v_mov_b32_e32 v75, v0
	v_mov_b32_e32 v80, v0
	v_mov_b32_e32 v81, v0
	v_mov_b32_e32 v82, v0
	v_mov_b32_e32 v83, v0
	v_mov_b32_e32 v88, v0
	v_mov_b32_e32 v89, v0
	v_mov_b32_e32 v90, v0
	v_mov_b32_e32 v91, v0
	v_mov_b32_e32 v96, v0
	v_mov_b32_e32 v97, v0
	v_mov_b32_e32 v98, v0
	v_mov_b32_e32 v99, v0
	v_mov_b32_e32 v104, v0
	v_mov_b32_e32 v105, v0
	v_mov_b32_e32 v106, v0
	v_mov_b32_e32 v107, v0
	v_mov_b32_e32 v112, v0
	v_mov_b32_e32 v113, v0
	v_mov_b32_e32 v114, v0
	v_mov_b32_e32 v115, v0
	v_mov_b32_e32 v76, v0
	v_mov_b32_e32 v77, v0
	v_mov_b32_e32 v78, v0
	v_mov_b32_e32 v79, v0
	v_mov_b32_e32 v84, v0
	v_mov_b32_e32 v85, v0
	v_mov_b32_e32 v86, v0
	v_mov_b32_e32 v87, v0
	v_mov_b32_e32 v92, v0
	v_mov_b32_e32 v93, v0
	v_mov_b32_e32 v94, v0
	v_mov_b32_e32 v95, v0
	v_mov_b32_e32 v100, v0
	v_mov_b32_e32 v101, v0
	v_mov_b32_e32 v102, v0
	v_mov_b32_e32 v103, v0
	v_mov_b32_e32 v108, v0
	v_mov_b32_e32 v109, v0
	v_mov_b32_e32 v110, v0
	v_mov_b32_e32 v111, v0
	v_mov_b32_e32 v116, v0
	v_mov_b32_e32 v117, v0
	v_mov_b32_e32 v118, v0
	v_mov_b32_e32 v119, v0
	v_mov_b32_e32 v120, v0
	v_mov_b32_e32 v121, v0
	v_mov_b32_e32 v122, v0
	v_mov_b32_e32 v123, v0
	v_mov_b32_e32 v124, v0
	v_mov_b32_e32 v125, v0
	v_mov_b32_e32 v126, v0
	v_mov_b32_e32 v127, v0
	s_cmp_eq_u32 s100, 1
	s_cbranch_scc0 .Lgemm_nobar_351
	s_mov_b32 s100, 0
	s_barrier
.Lgemm_nobar_351:
.LBB0_356:
	ds_read_b128 v[152:155], v148
	ds_read_b128 v[156:159], v148 offset:1024
	ds_read_b128 v[160:163], v148 offset:2048
	ds_read_b128 v[164:167], v148 offset:3072
	ds_read_b128 v[168:171], v149
	ds_read_b128 v[172:175], v149 offset:1024
	ds_read_b128 v[176:179], v149 offset:2048
	ds_read_b128 v[180:183], v149 offset:3072
	s_add_u32 s28, s26, 0xfffc0080
	s_addc_u32 s29, s27, -1
	s_cmp_eq_u32 s49, 12
	s_cselect_b32 s31, s19, s29
	s_cselect_b32 s30, s45, s28
	s_cselect_b32 s29, s17, s48
	s_cselect_b32 s28, s46, s47
	v_lshl_add_u64 v[216:217], s[26:27], 0, v[138:139]
	s_add_i32 m0, s25, 0xc000
	ds_read_b128 v[184:187], v150
	ds_read_b128 v[188:191], v150 offset:1024
	ds_read_b128 v[192:195], v150 offset:2048
	ds_read_b128 v[196:199], v150 offset:3072
	ds_read_b128 v[200:203], v150 offset:4096
	ds_read_b128 v[204:207], v150 offset:5120
	ds_read_b128 v[208:211], v150 offset:6144
	ds_read_b128 v[212:215], v150 offset:7168
	global_load_lds_dwordx4 v[216:217], off
	v_lshl_add_u64 v[216:217], s[26:27], 0, v[136:137]
	s_add_i32 m0, s25, 0xe000
	s_nop 0
	global_load_lds_dwordx4 v[216:217], off
	s_waitcnt vmcnt(8)
	s_waitcnt lgkmcnt(0)
	s_barrier
	s_setprio 1
	s_waitcnt lgkmcnt(0)
	v_mfma_f32_16x16x32_bf16 v[124:127], v[152:155], v[184:187], v[124:127]
	v_mfma_f32_16x16x32_bf16 v[120:123], v[160:163], v[184:187], v[120:123]
	v_mfma_f32_16x16x32_bf16 v[116:119], v[152:155], v[192:195], v[116:119]
	v_mfma_f32_16x16x32_bf16 v[108:111], v[160:163], v[192:195], v[108:111]
	v_mfma_f32_16x16x32_bf16 v[100:103], v[152:155], v[200:203], v[100:103]
	v_mfma_f32_16x16x32_bf16 v[92:95], v[160:163], v[200:203], v[92:95]
	v_mfma_f32_16x16x32_bf16 v[84:87], v[152:155], v[208:211], v[84:87]
	v_mfma_f32_16x16x32_bf16 v[76:79], v[160:163], v[208:211], v[76:79]
	v_mfma_f32_16x16x32_bf16 v[124:127], v[156:159], v[188:191], v[124:127]
	v_mfma_f32_16x16x32_bf16 v[120:123], v[164:167], v[188:191], v[120:123]
	v_mfma_f32_16x16x32_bf16 v[116:119], v[156:159], v[196:199], v[116:119]
	v_mfma_f32_16x16x32_bf16 v[108:111], v[164:167], v[196:199], v[108:111]
	v_mfma_f32_16x16x32_bf16 v[100:103], v[156:159], v[204:207], v[100:103]
	v_mfma_f32_16x16x32_bf16 v[92:95], v[164:167], v[204:207], v[92:95]
	v_mfma_f32_16x16x32_bf16 v[84:87], v[156:159], v[212:215], v[84:87]
	v_mfma_f32_16x16x32_bf16 v[76:79], v[164:167], v[212:215], v[76:79]
	s_setprio 0
	s_setprio 1
	v_mfma_f32_16x16x32_bf16 v[112:115], v[168:171], v[184:187], v[112:115]
	v_mfma_f32_16x16x32_bf16 v[104:107], v[176:179], v[184:187], v[104:107]
	v_mfma_f32_16x16x32_bf16 v[96:99], v[168:171], v[192:195], v[96:99]
	v_mfma_f32_16x16x32_bf16 v[88:91], v[176:179], v[192:195], v[88:91]
	v_mfma_f32_16x16x32_bf16 v[80:83], v[168:171], v[200:203], v[80:83]
	v_mfma_f32_16x16x32_bf16 v[72:75], v[176:179], v[200:203], v[72:75]
	v_mfma_f32_16x16x32_bf16 v[68:71], v[168:171], v[208:211], v[68:71]
	v_mfma_f32_16x16x32_bf16 v[64:67], v[176:179], v[208:211], v[64:67]
	v_mfma_f32_16x16x32_bf16 v[112:115], v[172:175], v[188:191], v[112:115]
	v_mfma_f32_16x16x32_bf16 v[104:107], v[180:183], v[188:191], v[104:107]
	v_mfma_f32_16x16x32_bf16 v[96:99], v[172:175], v[196:199], v[96:99]
	v_mfma_f32_16x16x32_bf16 v[88:91], v[180:183], v[196:199], v[88:91]
	v_mfma_f32_16x16x32_bf16 v[80:83], v[172:175], v[204:207], v[80:83]
	v_mfma_f32_16x16x32_bf16 v[72:75], v[180:183], v[204:207], v[72:75]
	v_mfma_f32_16x16x32_bf16 v[68:71], v[172:175], v[212:215], v[68:71]
	v_mfma_f32_16x16x32_bf16 v[64:67], v[180:183], v[212:215], v[64:67]
	s_setprio 0
	s_barrier
	s_add_i32 s50, s41, s33
	v_lshl_add_u64 v[216:217], s[28:29], 0, v[132:133]
	s_mov_b32 m0, s50
	ds_read_b128 v[184:187], v150 offset:16384
	ds_read_b128 v[188:191], v150 offset:17408
	ds_read_b128 v[192:195], v150 offset:18432
	ds_read_b128 v[196:199], v150 offset:19456
	ds_read_b128 v[200:203], v150 offset:20480
	ds_read_b128 v[204:207], v150 offset:21504
	ds_read_b128 v[208:211], v150 offset:22528
	ds_read_b128 v[212:215], v150 offset:23552
	global_load_lds_dwordx4 v[216:217], off
	s_add_i32 m0, s50, 0x2000
	s_add_u32 s50, s28, 0x40000
	v_lshl_add_u64 v[218:219], s[28:29], 0, v[128:129]
	s_addc_u32 s51, s29, 0
	s_add_i32 s52, s42, s33
	global_load_lds_dwordx4 v[218:219], off
	v_lshl_add_u64 v[220:221], s[50:51], 0, v[132:133]
	s_mov_b32 m0, s52
	v_lshl_add_u64 v[222:223], s[30:31], 0, v[130:131]
	global_load_lds_dwordx4 v[220:221], off
	v_lshl_add_u64 v[220:221], s[50:51], 0, v[128:129]
	s_add_i32 m0, s52, 0x2000
	s_nop 0
	global_load_lds_dwordx4 v[220:221], off
	v_lshl_add_u64 v[220:221], s[30:31], 0, v[134:135]
	s_mov_b32 m0, s25
	s_nop 0
	global_load_lds_dwordx4 v[220:221], off
	s_mov_b32 m0, s35
	s_nop 0
	global_load_lds_dwordx4 v[222:223], off
	s_waitcnt vmcnt(8)
	s_waitcnt lgkmcnt(0)
	s_barrier
	s_setprio 1
	s_waitcnt lgkmcnt(0)
	v_mfma_f32_16x16x32_bf16 v[60:63], v[152:155], v[184:187], v[60:63]
	v_mfma_f32_16x16x32_bf16 v[56:59], v[160:163], v[184:187], v[56:59]
	v_mfma_f32_16x16x32_bf16 v[52:55], v[152:155], v[192:195], v[52:55]
	v_mfma_f32_16x16x32_bf16 v[44:47], v[160:163], v[192:195], v[44:47]
	v_mfma_f32_16x16x32_bf16 v[36:39], v[152:155], v[200:203], v[36:39]
	v_mfma_f32_16x16x32_bf16 v[28:31], v[160:163], v[200:203], v[28:31]
	v_mfma_f32_16x16x32_bf16 v[20:23], v[152:155], v[208:211], v[20:23]
	v_mfma_f32_16x16x32_bf16 v[12:15], v[160:163], v[208:211], v[12:15]
	v_mfma_f32_16x16x32_bf16 v[60:63], v[156:159], v[188:191], v[60:63]
	v_mfma_f32_16x16x32_bf16 v[56:59], v[164:167], v[188:191], v[56:59]
	v_mfma_f32_16x16x32_bf16 v[52:55], v[156:159], v[196:199], v[52:55]
	v_mfma_f32_16x16x32_bf16 v[44:47], v[164:167], v[196:199], v[44:47]
	v_mfma_f32_16x16x32_bf16 v[36:39], v[156:159], v[204:207], v[36:39]
	v_mfma_f32_16x16x32_bf16 v[28:31], v[164:167], v[204:207], v[28:31]
	v_mfma_f32_16x16x32_bf16 v[20:23], v[156:159], v[212:215], v[20:23]
	v_mfma_f32_16x16x32_bf16 v[12:15], v[164:167], v[212:215], v[12:15]
	s_setprio 0
	s_setprio 1
	v_mfma_f32_16x16x32_bf16 v[48:51], v[168:171], v[184:187], v[48:51]
	v_mfma_f32_16x16x32_bf16 v[40:43], v[176:179], v[184:187], v[40:43]
	v_mfma_f32_16x16x32_bf16 v[32:35], v[168:171], v[192:195], v[32:35]
	v_mfma_f32_16x16x32_bf16 v[24:27], v[176:179], v[192:195], v[24:27]
	v_mfma_f32_16x16x32_bf16 v[16:19], v[168:171], v[200:203], v[16:19]
	v_mfma_f32_16x16x32_bf16 v[8:11], v[176:179], v[200:203], v[8:11]
	v_mfma_f32_16x16x32_bf16 v[4:7], v[168:171], v[208:211], v[4:7]
	v_mfma_f32_16x16x32_bf16 v[0:3], v[176:179], v[208:211], v[0:3]
	v_mfma_f32_16x16x32_bf16 v[48:51], v[172:175], v[188:191], v[48:51]
	v_mfma_f32_16x16x32_bf16 v[40:43], v[180:183], v[188:191], v[40:43]
	v_mfma_f32_16x16x32_bf16 v[32:35], v[172:175], v[196:199], v[32:35]
	v_mfma_f32_16x16x32_bf16 v[24:27], v[180:183], v[196:199], v[24:27]
	v_mfma_f32_16x16x32_bf16 v[16:19], v[172:175], v[204:207], v[16:19]
	v_mfma_f32_16x16x32_bf16 v[8:11], v[180:183], v[204:207], v[8:11]
	v_mfma_f32_16x16x32_bf16 v[4:7], v[172:175], v[212:215], v[4:7]
	v_mfma_f32_16x16x32_bf16 v[0:3], v[180:183], v[212:215], v[0:3]
	s_setprio 0
	s_barrier
	s_add_i32 s50, 0, 0x18000
	v_add_u32_e32 v144, s50, v146
	s_add_i32 s51, 0, 0x1c000
	ds_read_b128 v[152:155], v144
	ds_read_b128 v[156:159], v144 offset:1024
	ds_read_b128 v[160:163], v144 offset:2048
	ds_read_b128 v[164:167], v144 offset:3072
	v_add_u32_e32 v144, s51, v146
	ds_read_b128 v[168:171], v144
	ds_read_b128 v[172:175], v144 offset:1024
	ds_read_b128 v[176:179], v144 offset:2048
	ds_read_b128 v[180:183], v144 offset:3072
	s_add_u32 s30, s30, 0x40000
	s_addc_u32 s31, s31, 0
	s_mov_b32 m0, s36
	v_lshl_add_u64 v[224:225], s[30:31], 0, v[134:135]
	ds_read_b128 v[184:187], v150 offset:32768
	ds_read_b128 v[188:191], v150 offset:33792
	ds_read_b128 v[192:195], v150 offset:34816
	ds_read_b128 v[196:199], v150 offset:35840
	ds_read_b128 v[200:203], v150 offset:36864
	ds_read_b128 v[204:207], v150 offset:37888
	ds_read_b128 v[208:211], v150 offset:38912
	ds_read_b128 v[212:215], v150 offset:39936
	global_load_lds_dwordx4 v[224:225], off
	v_lshl_add_u64 v[224:225], s[30:31], 0, v[130:131]
	s_mov_b32 m0, s37
	s_nop 0
	global_load_lds_dwordx4 v[224:225], off
	s_waitcnt vmcnt(8)
	s_waitcnt lgkmcnt(0)
	s_barrier
	s_setprio 1
	s_waitcnt lgkmcnt(0)
	v_mfma_f32_16x16x32_bf16 v[124:127], v[152:155], v[184:187], v[124:127]
	v_mfma_f32_16x16x32_bf16 v[120:123], v[160:163], v[184:187], v[120:123]
	v_mfma_f32_16x16x32_bf16 v[116:119], v[152:155], v[192:195], v[116:119]
	v_mfma_f32_16x16x32_bf16 v[108:111], v[160:163], v[192:195], v[108:111]
	v_mfma_f32_16x16x32_bf16 v[100:103], v[152:155], v[200:203], v[100:103]
	v_mfma_f32_16x16x32_bf16 v[92:95], v[160:163], v[200:203], v[92:95]
	v_mfma_f32_16x16x32_bf16 v[84:87], v[152:155], v[208:211], v[84:87]
	v_mfma_f32_16x16x32_bf16 v[76:79], v[160:163], v[208:211], v[76:79]
	v_mfma_f32_16x16x32_bf16 v[124:127], v[156:159], v[188:191], v[124:127]
	v_mfma_f32_16x16x32_bf16 v[120:123], v[164:167], v[188:191], v[120:123]
	v_mfma_f32_16x16x32_bf16 v[116:119], v[156:159], v[196:199], v[116:119]
	v_mfma_f32_16x16x32_bf16 v[108:111], v[164:167], v[196:199], v[108:111]
	v_mfma_f32_16x16x32_bf16 v[100:103], v[156:159], v[204:207], v[100:103]
	v_mfma_f32_16x16x32_bf16 v[92:95], v[164:167], v[204:207], v[92:95]
	v_mfma_f32_16x16x32_bf16 v[84:87], v[156:159], v[212:215], v[84:87]
	v_mfma_f32_16x16x32_bf16 v[76:79], v[164:167], v[212:215], v[76:79]
	s_setprio 0
	s_setprio 1
	v_mfma_f32_16x16x32_bf16 v[112:115], v[168:171], v[184:187], v[112:115]
	v_mfma_f32_16x16x32_bf16 v[104:107], v[176:179], v[184:187], v[104:107]
	v_mfma_f32_16x16x32_bf16 v[96:99], v[168:171], v[192:195], v[96:99]
	v_mfma_f32_16x16x32_bf16 v[88:91], v[176:179], v[192:195], v[88:91]
	v_mfma_f32_16x16x32_bf16 v[80:83], v[168:171], v[200:203], v[80:83]
	v_mfma_f32_16x16x32_bf16 v[72:75], v[176:179], v[200:203], v[72:75]
	v_mfma_f32_16x16x32_bf16 v[68:71], v[168:171], v[208:211], v[68:71]
	v_mfma_f32_16x16x32_bf16 v[64:67], v[176:179], v[208:211], v[64:67]
	v_mfma_f32_16x16x32_bf16 v[112:115], v[172:175], v[188:191], v[112:115]
	v_mfma_f32_16x16x32_bf16 v[104:107], v[180:183], v[188:191], v[104:107]
	v_mfma_f32_16x16x32_bf16 v[96:99], v[172:175], v[196:199], v[96:99]
	v_mfma_f32_16x16x32_bf16 v[88:91], v[180:183], v[196:199], v[88:91]
	v_mfma_f32_16x16x32_bf16 v[80:83], v[172:175], v[204:207], v[80:83]
	v_mfma_f32_16x16x32_bf16 v[72:75], v[180:183], v[204:207], v[72:75]
	v_mfma_f32_16x16x32_bf16 v[68:71], v[172:175], v[212:215], v[68:71]
	v_mfma_f32_16x16x32_bf16 v[64:67], v[180:183], v[212:215], v[64:67]
	s_setprio 0
	s_barrier
	s_add_i32 s30, s50, s33
	v_lshl_add_u64 v[216:217], v[216:217], 0, s[12:13]
	s_mov_b32 m0, s30
	ds_read_b128 v[184:187], v150 offset:49152
	ds_read_b128 v[188:191], v150 offset:50176
	ds_read_b128 v[192:195], v150 offset:51200
	ds_read_b128 v[196:199], v150 offset:52224
	ds_read_b128 v[200:203], v150 offset:53248
	ds_read_b128 v[204:207], v150 offset:54272
	ds_read_b128 v[208:211], v150 offset:55296
	ds_read_b128 v[212:215], v150 offset:56320
	global_load_lds_dwordx4 v[216:217], off
	s_add_i32 m0, s30, 0x2000
	s_add_u32 s28, s28, 0x40080
	v_lshl_add_u64 v[216:217], v[218:219], 0, s[12:13]
	s_addc_u32 s29, s29, 0
	s_add_i32 s30, s51, s33
	global_load_lds_dwordx4 v[216:217], off
	v_lshl_add_u64 v[216:217], s[28:29], 0, v[132:133]
	s_mov_b32 m0, s30
	s_nop 0
	global_load_lds_dwordx4 v[216:217], off
	v_lshl_add_u64 v[216:217], s[28:29], 0, v[128:129]
	s_add_i32 m0, s30, 0x2000
	s_nop 0
	global_load_lds_dwordx4 v[216:217], off
	v_lshl_add_u64 v[216:217], v[220:221], 0, s[12:13]
	s_mov_b32 m0, s39
	s_nop 0
	global_load_lds_dwordx4 v[216:217], off
	v_lshl_add_u64 v[216:217], v[222:223], 0, s[12:13]
	s_mov_b32 m0, s40
	s_nop 0
	global_load_lds_dwordx4 v[216:217], off
	s_waitcnt vmcnt(8)
	s_waitcnt lgkmcnt(0)
	s_barrier
	s_setprio 1
	s_waitcnt lgkmcnt(0)
	v_mfma_f32_16x16x32_bf16 v[60:63], v[152:155], v[184:187], v[60:63]
	v_mfma_f32_16x16x32_bf16 v[56:59], v[160:163], v[184:187], v[56:59]
	v_mfma_f32_16x16x32_bf16 v[52:55], v[152:155], v[192:195], v[52:55]
	v_mfma_f32_16x16x32_bf16 v[44:47], v[160:163], v[192:195], v[44:47]
	v_mfma_f32_16x16x32_bf16 v[36:39], v[152:155], v[200:203], v[36:39]
	v_mfma_f32_16x16x32_bf16 v[28:31], v[160:163], v[200:203], v[28:31]
	v_mfma_f32_16x16x32_bf16 v[20:23], v[152:155], v[208:211], v[20:23]
	v_mfma_f32_16x16x32_bf16 v[12:15], v[160:163], v[208:211], v[12:15]
	v_mfma_f32_16x16x32_bf16 v[60:63], v[156:159], v[188:191], v[60:63]
	v_mfma_f32_16x16x32_bf16 v[56:59], v[164:167], v[188:191], v[56:59]
	v_mfma_f32_16x16x32_bf16 v[52:55], v[156:159], v[196:199], v[52:55]
	v_mfma_f32_16x16x32_bf16 v[44:47], v[164:167], v[196:199], v[44:47]
	v_mfma_f32_16x16x32_bf16 v[36:39], v[156:159], v[204:207], v[36:39]
	v_mfma_f32_16x16x32_bf16 v[28:31], v[164:167], v[204:207], v[28:31]
	v_mfma_f32_16x16x32_bf16 v[20:23], v[156:159], v[212:215], v[20:23]
	v_mfma_f32_16x16x32_bf16 v[12:15], v[164:167], v[212:215], v[12:15]
	s_setprio 0
	s_setprio 1
	v_mfma_f32_16x16x32_bf16 v[48:51], v[168:171], v[184:187], v[48:51]
	v_mfma_f32_16x16x32_bf16 v[40:43], v[176:179], v[184:187], v[40:43]
	v_mfma_f32_16x16x32_bf16 v[32:35], v[168:171], v[192:195], v[32:35]
	v_mfma_f32_16x16x32_bf16 v[24:27], v[176:179], v[192:195], v[24:27]
	v_mfma_f32_16x16x32_bf16 v[16:19], v[168:171], v[200:203], v[16:19]
	v_mfma_f32_16x16x32_bf16 v[8:11], v[176:179], v[200:203], v[8:11]
	v_mfma_f32_16x16x32_bf16 v[4:7], v[168:171], v[208:211], v[4:7]
	v_mfma_f32_16x16x32_bf16 v[0:3], v[176:179], v[208:211], v[0:3]
	v_mfma_f32_16x16x32_bf16 v[48:51], v[172:175], v[188:191], v[48:51]
	v_mfma_f32_16x16x32_bf16 v[40:43], v[180:183], v[188:191], v[40:43]
	v_mfma_f32_16x16x32_bf16 v[32:35], v[172:175], v[196:199], v[32:35]
	v_mfma_f32_16x16x32_bf16 v[24:27], v[180:183], v[196:199], v[24:27]
	v_mfma_f32_16x16x32_bf16 v[16:19], v[172:175], v[204:207], v[16:19]
	v_mfma_f32_16x16x32_bf16 v[8:11], v[180:183], v[204:207], v[8:11]
	v_mfma_f32_16x16x32_bf16 v[4:7], v[172:175], v[212:215], v[4:7]
	v_mfma_f32_16x16x32_bf16 v[0:3], v[180:183], v[212:215], v[0:3]
	s_setprio 0
	s_barrier
	s_add_i32 s49, s49, 2
	s_add_u32 s47, s47, 0x100
	s_addc_u32 s48, s48, 0
	s_add_u32 s26, s26, 0x100
	s_addc_u32 s27, s27, 0
	s_cmp_gt_u32 s49, 13
	s_cbranch_scc0 .LBB0_356
	s_and_b64 vcc, exec, s[14:15]
	s_cbranch_vccz .LBB0_359
	s_barrier
.LBB0_359:
	s_and_b32 s17, s44, -2
	s_cmp_eq_u32 s17, 2
	s_cselect_b64 vcc, -1, 0
	v_lshl_or_b32 v152, s44, 8, v147
	s_mov_b64 s[26:27], s[10:11]
	v_cndmask_b32_e32 v144, 1.0, v151, vcc
	v_ashrrev_i32_e32 v153, 31, v152
	v_lshl_add_u32 v158, s24, 8, v145
	v_lshl_add_u64 v[152:153], v[152:153], 1, s[26:27]
	v_pk_mul_f32 v[126:127], v[144:145], v[126:127] op_sel_hi:[0,1]
	v_pk_mul_f32 v[124:125], v[144:145], v[124:125] op_sel_hi:[0,1]
	v_pk_mul_f32 v[156:157], v[144:145], v[122:123] op_sel_hi:[0,1]
	v_pk_mul_f32 v[122:123], v[144:145], v[120:121] op_sel_hi:[0,1]
	v_mad_i64_i32 v[154:155], s[26:27], v158, s43, v[152:153]
	v_cvt_pk_bf16_f32 v120, v124, v125
	v_cvt_pk_bf16_f32 v121, v126, v127
	v_cvt_pk_bf16_f32 v122, v122, v123
	v_cvt_pk_bf16_f32 v123, v156, v157
	global_store_dwordx4 v[154:155], v[120:123], off
	v_pk_mul_f32 v[114:115], v[144:145], v[114:115] op_sel_hi:[0,1]
	v_pk_mul_f32 v[112:113], v[144:145], v[112:113] op_sel_hi:[0,1]
	v_pk_mul_f32 v[120:121], v[144:145], v[106:107] op_sel_hi:[0,1]
	v_pk_mul_f32 v[106:107], v[144:145], v[104:105] op_sel_hi:[0,1]
	v_cvt_pk_bf16_f32 v104, v112, v113
	v_cvt_pk_bf16_f32 v105, v114, v115
	v_cvt_pk_bf16_f32 v106, v106, v107
	v_cvt_pk_bf16_f32 v107, v120, v121
	global_store_dwordx4 v[154:155], v[104:107], off offset:256
	v_pk_mul_f32 v[110:111], v[144:145], v[110:111] op_sel_hi:[0,1]
	v_pk_mul_f32 v[108:109], v[144:145], v[108:109] op_sel_hi:[0,1]
	v_or_b32_e32 v104, 16, v158
	v_mad_i64_i32 v[112:113], s[26:27], v104, s43, v[152:153]
	v_pk_mul_f32 v[106:107], v[144:145], v[118:119] op_sel_hi:[0,1]
	v_pk_mul_f32 v[104:105], v[144:145], v[116:117] op_sel_hi:[0,1]
	v_cvt_pk_bf16_f32 v104, v104, v105
	v_cvt_pk_bf16_f32 v105, v106, v107
	v_cvt_pk_bf16_f32 v106, v108, v109
	v_cvt_pk_bf16_f32 v107, v110, v111
	global_store_dwordx4 v[112:113], v[104:107], off
	v_pk_mul_f32 v[98:99], v[144:145], v[98:99] op_sel_hi:[0,1]
	v_pk_mul_f32 v[96:97], v[144:145], v[96:97] op_sel_hi:[0,1]
	v_pk_mul_f32 v[104:105], v[144:145], v[90:91] op_sel_hi:[0,1]
	v_pk_mul_f32 v[90:91], v[144:145], v[88:89] op_sel_hi:[0,1]
	v_cvt_pk_bf16_f32 v88, v96, v97
	v_cvt_pk_bf16_f32 v89, v98, v99
	v_cvt_pk_bf16_f32 v90, v90, v91
	v_cvt_pk_bf16_f32 v91, v104, v105
	global_store_dwordx4 v[112:113], v[88:91], off offset:256
	v_pk_mul_f32 v[94:95], v[144:145], v[94:95] op_sel_hi:[0,1]
	v_pk_mul_f32 v[92:93], v[144:145], v[92:93] op_sel_hi:[0,1]
	v_or_b32_e32 v88, 32, v158
	v_mad_i64_i32 v[96:97], s[26:27], v88, s43, v[152:153]
	v_pk_mul_f32 v[90:91], v[144:145], v[102:103] op_sel_hi:[0,1]
	v_pk_mul_f32 v[88:89], v[144:145], v[100:101] op_sel_hi:[0,1]
	v_cvt_pk_bf16_f32 v88, v88, v89
	v_cvt_pk_bf16_f32 v89, v90, v91
	v_cvt_pk_bf16_f32 v90, v92, v93
	v_cvt_pk_bf16_f32 v91, v94, v95
	global_store_dwordx4 v[96:97], v[88:91], off
	v_pk_mul_f32 v[82:83], v[144:145], v[82:83] op_sel_hi:[0,1]
	v_pk_mul_f32 v[80:81], v[144:145], v[80:81] op_sel_hi:[0,1]
	v_pk_mul_f32 v[88:89], v[144:145], v[74:75] op_sel_hi:[0,1]
	v_pk_mul_f32 v[74:75], v[144:145], v[72:73] op_sel_hi:[0,1]
	v_cvt_pk_bf16_f32 v72, v80, v81
	v_cvt_pk_bf16_f32 v73, v82, v83
	v_cvt_pk_bf16_f32 v74, v74, v75
	v_cvt_pk_bf16_f32 v75, v88, v89
	global_store_dwordx4 v[96:97], v[72:75], off offset:256
	v_pk_mul_f32 v[78:79], v[144:145], v[78:79] op_sel_hi:[0,1]
	v_pk_mul_f32 v[76:77], v[144:145], v[76:77] op_sel_hi:[0,1]
	v_or_b32_e32 v72, 48, v158
	v_mad_i64_i32 v[80:81], s[26:27], v72, s43, v[152:153]
	v_pk_mul_f32 v[74:75], v[144:145], v[86:87] op_sel_hi:[0,1]
	v_pk_mul_f32 v[72:73], v[144:145], v[84:85] op_sel_hi:[0,1]
	v_cvt_pk_bf16_f32 v72, v72, v73
	v_cvt_pk_bf16_f32 v73, v74, v75
	v_cvt_pk_bf16_f32 v74, v76, v77
	v_cvt_pk_bf16_f32 v75, v78, v79
	global_store_dwordx4 v[80:81], v[72:75], off
	v_pk_mul_f32 v[70:71], v[144:145], v[70:71] op_sel_hi:[0,1]
	v_pk_mul_f32 v[68:69], v[144:145], v[68:69] op_sel_hi:[0,1]
	v_pk_mul_f32 v[72:73], v[144:145], v[66:67] op_sel_hi:[0,1]
	v_pk_mul_f32 v[66:67], v[144:145], v[64:65] op_sel_hi:[0,1]
	v_cvt_pk_bf16_f32 v64, v68, v69
	v_cvt_pk_bf16_f32 v65, v70, v71
	v_cvt_pk_bf16_f32 v66, v66, v67
	v_cvt_pk_bf16_f32 v67, v72, v73
	global_store_dwordx4 v[80:81], v[64:67], off offset:256
	v_pk_mul_f32 v[62:63], v[144:145], v[62:63] op_sel_hi:[0,1]
	v_pk_mul_f32 v[60:61], v[144:145], v[60:61] op_sel_hi:[0,1]
	v_add_u32_e32 v64, 0x80, v158
	v_pk_mul_f32 v[66:67], v[144:145], v[58:59] op_sel_hi:[0,1]
	v_pk_mul_f32 v[58:59], v[144:145], v[56:57] op_sel_hi:[0,1]
	v_mad_i64_i32 v[64:65], s[26:27], v64, s43, v[152:153]
	v_cvt_pk_bf16_f32 v56, v60, v61
	v_cvt_pk_bf16_f32 v57, v62, v63
	v_cvt_pk_bf16_f32 v58, v58, v59
	v_cvt_pk_bf16_f32 v59, v66, v67
	global_store_dwordx4 v[64:65], v[56:59], off
	v_pk_mul_f32 v[50:51], v[144:145], v[50:51] op_sel_hi:[0,1]
	v_pk_mul_f32 v[48:49], v[144:145], v[48:49] op_sel_hi:[0,1]
	v_pk_mul_f32 v[56:57], v[144:145], v[42:43] op_sel_hi:[0,1]
	v_pk_mul_f32 v[42:43], v[144:145], v[40:41] op_sel_hi:[0,1]
	v_cvt_pk_bf16_f32 v40, v48, v49
	v_cvt_pk_bf16_f32 v41, v50, v51
	v_cvt_pk_bf16_f32 v42, v42, v43
	v_cvt_pk_bf16_f32 v43, v56, v57
	global_store_dwordx4 v[64:65], v[40:43], off offset:256
	v_pk_mul_f32 v[46:47], v[144:145], v[46:47] op_sel_hi:[0,1]
	v_pk_mul_f32 v[44:45], v[144:145], v[44:45] op_sel_hi:[0,1]
	v_add_u32_e32 v40, 0x90, v158
	v_mad_i64_i32 v[48:49], s[26:27], v40, s43, v[152:153]
	v_pk_mul_f32 v[42:43], v[144:145], v[54:55] op_sel_hi:[0,1]
	v_pk_mul_f32 v[40:41], v[144:145], v[52:53] op_sel_hi:[0,1]
	v_cvt_pk_bf16_f32 v40, v40, v41
	v_cvt_pk_bf16_f32 v41, v42, v43
	v_cvt_pk_bf16_f32 v42, v44, v45
	v_cvt_pk_bf16_f32 v43, v46, v47
	global_store_dwordx4 v[48:49], v[40:43], off
	v_pk_mul_f32 v[34:35], v[144:145], v[34:35] op_sel_hi:[0,1]
	v_pk_mul_f32 v[32:33], v[144:145], v[32:33] op_sel_hi:[0,1]
	v_pk_mul_f32 v[40:41], v[144:145], v[26:27] op_sel_hi:[0,1]
	v_pk_mul_f32 v[26:27], v[144:145], v[24:25] op_sel_hi:[0,1]
	v_cvt_pk_bf16_f32 v24, v32, v33
	v_cvt_pk_bf16_f32 v25, v34, v35
	v_cvt_pk_bf16_f32 v26, v26, v27
	v_cvt_pk_bf16_f32 v27, v40, v41
	global_store_dwordx4 v[48:49], v[24:27], off offset:256
	v_pk_mul_f32 v[30:31], v[144:145], v[30:31] op_sel_hi:[0,1]
	v_pk_mul_f32 v[28:29], v[144:145], v[28:29] op_sel_hi:[0,1]
	v_add_u32_e32 v24, 0xa0, v158
	v_mad_i64_i32 v[32:33], s[26:27], v24, s43, v[152:153]
	v_pk_mul_f32 v[26:27], v[144:145], v[38:39] op_sel_hi:[0,1]
	v_pk_mul_f32 v[24:25], v[144:145], v[36:37] op_sel_hi:[0,1]
	v_cvt_pk_bf16_f32 v24, v24, v25
	v_cvt_pk_bf16_f32 v25, v26, v27
	v_cvt_pk_bf16_f32 v26, v28, v29
	v_cvt_pk_bf16_f32 v27, v30, v31
	global_store_dwordx4 v[32:33], v[24:27], off
	v_pk_mul_f32 v[18:19], v[144:145], v[18:19] op_sel_hi:[0,1]
	v_pk_mul_f32 v[16:17], v[144:145], v[16:17] op_sel_hi:[0,1]
	v_pk_mul_f32 v[24:25], v[144:145], v[10:11] op_sel_hi:[0,1]
	v_pk_mul_f32 v[10:11], v[144:145], v[8:9] op_sel_hi:[0,1]
	v_cvt_pk_bf16_f32 v8, v16, v17
	v_cvt_pk_bf16_f32 v9, v18, v19
	v_cvt_pk_bf16_f32 v10, v10, v11
	v_cvt_pk_bf16_f32 v11, v24, v25
	global_store_dwordx4 v[32:33], v[8:11], off offset:256
	v_pk_mul_f32 v[14:15], v[144:145], v[14:15] op_sel_hi:[0,1]
	v_pk_mul_f32 v[12:13], v[144:145], v[12:13] op_sel_hi:[0,1]
	v_add_u32_e32 v8, 0xb0, v158
	v_mad_i64_i32 v[16:17], s[26:27], v8, s43, v[152:153]
	v_pk_mul_f32 v[10:11], v[144:145], v[22:23] op_sel_hi:[0,1]
	v_pk_mul_f32 v[8:9], v[144:145], v[20:21] op_sel_hi:[0,1]
	v_cvt_pk_bf16_f32 v8, v8, v9
	v_cvt_pk_bf16_f32 v9, v10, v11
	v_cvt_pk_bf16_f32 v10, v12, v13
	v_cvt_pk_bf16_f32 v11, v14, v15
	global_store_dwordx4 v[16:17], v[8:11], off
	v_pk_mul_f32 v[6:7], v[144:145], v[6:7] op_sel_hi:[0,1]
	v_pk_mul_f32 v[4:5], v[144:145], v[4:5] op_sel_hi:[0,1]
	v_pk_mul_f32 v[8:9], v[144:145], v[2:3] op_sel_hi:[0,1]
	v_pk_mul_f32 v[2:3], v[144:145], v[0:1] op_sel_hi:[0,1]
	v_cvt_pk_bf16_f32 v0, v4, v5
	v_cvt_pk_bf16_f32 v1, v6, v7
	v_cvt_pk_bf16_f32 v2, v2, v3
	v_cvt_pk_bf16_f32 v3, v8, v9
	s_andn2_b64 vcc, exec, s[4:5]
	s_mov_b64 s[4:5], -1
	global_store_dwordx4 v[16:17], v[0:3], off offset:256
	s_cbranch_vccnz .LBB0_352
	s_andn2_b64 vcc, exec, s[8:9]
	s_cbranch_vccnz .LBB0_351
	s_mov_b32 s100, 1
	s_branch .LBB0_351

.LBB0_723:
	s_add_u32 s10, s10, 0xd800000
	s_addc_u32 s11, s11, 0
	s_lshl_b32 s14, s14, 5
	s_and_b32 s19, s14, 0x60
	s_mov_b64 s[14:15], 0x80
	s_add_i32 m0, s40, 0x18000
	v_lshl_add_u64 v[6:7], v[6:7], 0, s[14:15]
	s_lshl_b32 s18, s7, 13
	s_lshl_b32 s20, s19, 7
	s_waitcnt vmcnt(2)
	s_barrier
	global_load_lds_dwordx4 v[6:7], off
	v_lshl_add_u64 v[2:3], v[2:3], 0, s[14:15]
	s_add_i32 m0, s40, 0x1a000
	s_add_i32 s45, s40, 0x8000
	s_add_i32 s46, s40, 0xa000
	global_load_lds_dwordx4 v[2:3], off
	v_lshl_add_u64 v[0:1], v[0:1], 0, s[14:15]
	s_mov_b32 m0, s45
	s_add_u32 s16, s34, 0x40080
	global_load_lds_dwordx4 v[0:1], off
	v_lshl_add_u64 v[0:1], v[4:5], 0, s[14:15]
	s_mov_b32 m0, s46
	s_addc_u32 s17, s35, 0
	global_load_lds_dwordx4 v[0:1], off
	s_add_i32 m0, s40, 0x1c000
	v_lshl_add_u64 v[0:1], s[16:17], 0, v[132:133]
	global_load_lds_dwordx4 v[0:1], off
	v_lshl_add_u64 v[0:1], s[16:17], 0, v[128:129]
	s_add_i32 m0, s40, 0x1e000
	s_cmpk_lt_u32 s6, 0x100
	global_load_lds_dwordx4 v[0:1], off
	v_lshrrev_b32_e32 v1, 1, v8
	v_and_b32_e32 v1, 24, v1
	v_and_b32_e32 v0, 15, v8
	v_lshlrev_b32_e32 v2, 1, v1
	v_lshl_or_b32 v144, s7, 6, v0
	v_lshl_or_b32 v0, v0, 6, v2
	v_lshlrev_b32_e32 v2, 2, v8
	v_and_b32_e32 v2, 32, v2
	v_bitop3_b32 v3, v0, s18, v2 bitop3:0xde
	v_bitop3_b32 v145, s20, v0, v2 bitop3:0xf6
	v_lshlrev_b32_e32 v0, 14, v9
	v_and_b32_e32 v0, 0xffff8000, v0
	v_or_b32_e32 v146, s19, v1
	v_lshl_add_u32 v0, v10, 11, v0
	v_and_b32_e32 v1, 1, v9
	v_lshl_or_b32 v0, v1, 6, v0
	v_lshl_add_u32 v136, v11, 1, v0
	v_lshlrev_b32_e32 v0, 14, v13
	v_and_b32_e32 v0, 0xffff8000, v0
	s_waitcnt vmcnt(6)
	v_lshl_add_u32 v0, v12, 11, v0
	v_and_b32_e32 v1, 1, v13
	s_cselect_b64 s[16:17], -1, 0
	v_lshl_or_b32 v0, v1, 6, v0
	s_add_i32 s47, 0, 0x10000
	s_add_i32 s48, 0, 0x14000
	v_mov_b32_e32 v137, v133
	v_lshl_add_u32 v138, v14, 1, v0
	v_mov_b32_e32 v139, v133
	v_mov_b64_e32 v[140:141], 0x200
	v_mov_b64_e32 v[142:143], 0x1ff
	v_add_u32_e32 v147, s47, v145
	v_add_u32_e32 v148, s48, v145
	v_add_u32_e32 v149, 0, v3
	s_mov_b32 s49, 0x40000
	s_mov_b64 s[18:19], 0x48000
	s_mov_b32 s50, 0x48000
	s_mov_b64 s[20:21], 0x50000
	s_mov_b32 s51, 0x50000
	s_mov_b64 s[22:23], 0x58000
	s_mov_b32 s52, 0x58000
	v_readlane_b32 s53, v254, 11
	s_mov_b32 s54, s92
	s_barrier
	s_mov_b32 s100, 0
	s_branch .LBB0_726

.LBB0_728:
	s_ashr_i32 s27, s26, 31
	s_lshl_b64 s[28:29], s[26:27], 19
	s_add_u32 s28, s8, s28
	s_addc_u32 s29, s9, s29
	s_and_b64 s[30:31], s[6:7], exec
	s_cselect_b32 s27, s29, s37
	s_cselect_b32 s55, s28, s36
	s_ashr_i32 s25, s24, 31
	s_lshl_b64 s[30:31], s[24:25], 19
	s_add_u32 s30, s0, s30
	s_addc_u32 s31, s1, s31
	s_and_b64 s[38:39], s[6:7], exec
	s_cselect_b32 s25, s31, s35
	s_cselect_b32 s56, s30, s34
	s_add_u32 s57, s34, 0x100
	s_addc_u32 s58, s35, 0
	s_add_u32 s34, s36, 0x40080
	v_mov_b32_e32 v0, 0
	s_addc_u32 s35, s37, 0
	s_mov_b32 s59, -2
	v_mov_b32_e32 v1, v0
	v_mov_b32_e32 v2, v0
	v_mov_b32_e32 v3, v0
	v_mov_b32_e32 v4, v0
	v_mov_b32_e32 v5, v0
	v_mov_b32_e32 v6, v0
	v_mov_b32_e32 v7, v0
	v_mov_b32_e32 v8, v0
	v_mov_b32_e32 v9, v0
	v_mov_b32_e32 v10, v0
	v_mov_b32_e32 v11, v0
	v_mov_b32_e32 v12, v0
	v_mov_b32_e32 v13, v0
	v_mov_b32_e32 v14, v0
	v_mov_b32_e32 v15, v0
	v_mov_b32_e32 v24, v0
	v_mov_b32_e32 v25, v0
	v_mov_b32_e32 v26, v0
	v_mov_b32_e32 v27, v0
	v_mov_b32_e32 v28, v0
	v_mov_b32_e32 v29, v0
	v_mov_b32_e32 v30, v0
	v_mov_b32_e32 v31, v0
	v_mov_b32_e32 v40, v0
	v_mov_b32_e32 v41, v0
	v_mov_b32_e32 v42, v0
	v_mov_b32_e32 v43, v0
	v_mov_b32_e32 v44, v0
	v_mov_b32_e32 v45, v0
	v_mov_b32_e32 v46, v0
	v_mov_b32_e32 v47, v0
	v_mov_b32_e32 v16, v0
	v_mov_b32_e32 v17, v0
	v_mov_b32_e32 v18, v0
	v_mov_b32_e32 v19, v0
	v_mov_b32_e32 v20, v0
	v_mov_b32_e32 v21, v0
	v_mov_b32_e32 v22, v0
	v_mov_b32_e32 v23, v0
	v_mov_b32_e32 v32, v0
	v_mov_b32_e32 v33, v0
	v_mov_b32_e32 v34, v0
	v_mov_b32_e32 v35, v0
	v_mov_b32_e32 v36, v0
	v_mov_b32_e32 v37, v0
	v_mov_b32_e32 v38, v0
	v_mov_b32_e32 v39, v0
	v_mov_b32_e32 v48, v0
	v_mov_b32_e32 v49, v0
	v_mov_b32_e32 v50, v0
	v_mov_b32_e32 v51, v0
	v_mov_b32_e32 v52, v0
	v_mov_b32_e32 v53, v0
	v_mov_b32_e32 v54, v0
	v_mov_b32_e32 v55, v0
	v_mov_b32_e32 v56, v0
	v_mov_b32_e32 v57, v0
	v_mov_b32_e32 v58, v0
	v_mov_b32_e32 v59, v0
	v_mov_b32_e32 v60, v0
	v_mov_b32_e32 v61, v0
	v_mov_b32_e32 v62, v0
	v_mov_b32_e32 v63, v0
	v_mov_b32_e32 v64, v0
	v_mov_b32_e32 v65, v0
	v_mov_b32_e32 v66, v0
	v_mov_b32_e32 v67, v0
	v_mov_b32_e32 v68, v0
	v_mov_b32_e32 v69, v0
	v_mov_b32_e32 v70, v0
	v_mov_b32_e32 v71, v0
	v_mov_b32_e32 v72, v0
	v_mov_b32_e32 v73, v0
	v_mov_b32_e32 v74, v0
	v_mov_b32_e32 v75, v0
	v_mov_b32_e32 v76, v0
	v_mov_b32_e32 v77, v0
	v_mov_b32_e32 v78, v0
	v_mov_b32_e32 v79, v0
	v_mov_b32_e32 v88, v0
	v_mov_b32_e32 v89, v0
	v_mov_b32_e32 v90, v0
	v_mov_b32_e32 v91, v0
	v_mov_b32_e32 v92, v0
	v_mov_b32_e32 v93, v0
	v_mov_b32_e32 v94, v0
	v_mov_b32_e32 v95, v0
	v_mov_b32_e32 v104, v0
	v_mov_b32_e32 v105, v0
	v_mov_b32_e32 v106, v0
	v_mov_b32_e32 v107, v0
	v_mov_b32_e32 v108, v0
	v_mov_b32_e32 v109, v0
	v_mov_b32_e32 v110, v0
	v_mov_b32_e32 v111, v0
	v_mov_b32_e32 v80, v0
	v_mov_b32_e32 v81, v0
	v_mov_b32_e32 v82, v0
	v_mov_b32_e32 v83, v0
	v_mov_b32_e32 v84, v0
	v_mov_b32_e32 v85, v0
	v_mov_b32_e32 v86, v0
	v_mov_b32_e32 v87, v0
	v_mov_b32_e32 v96, v0
	v_mov_b32_e32 v97, v0
	v_mov_b32_e32 v98, v0
	v_mov_b32_e32 v99, v0
	v_mov_b32_e32 v100, v0
	v_mov_b32_e32 v101, v0
	v_mov_b32_e32 v102, v0
	v_mov_b32_e32 v103, v0
	v_mov_b32_e32 v112, v0
	v_mov_b32_e32 v113, v0
	v_mov_b32_e32 v114, v0
	v_mov_b32_e32 v115, v0
	v_mov_b32_e32 v116, v0
	v_mov_b32_e32 v117, v0
	v_mov_b32_e32 v118, v0
	v_mov_b32_e32 v119, v0
	v_mov_b32_e32 v120, v0
	v_mov_b32_e32 v121, v0
	v_mov_b32_e32 v122, v0
	v_mov_b32_e32 v123, v0
	v_mov_b32_e32 v124, v0
	v_mov_b32_e32 v125, v0
	v_mov_b32_e32 v126, v0
	v_mov_b32_e32 v127, v0
	s_cmp_eq_u32 s100, 1
	s_cbranch_scc0 .Lgemm_nobar_724
	s_mov_b32 s100, 0
	s_barrier
.Lgemm_nobar_724:
.LBB0_729:
	ds_read_b128 v[150:153], v147
	ds_read_b128 v[154:157], v147 offset:1024
	ds_read_b128 v[158:161], v147 offset:2048
	ds_read_b128 v[162:165], v147 offset:3072
	ds_read_b128 v[166:169], v148
	ds_read_b128 v[170:173], v148 offset:1024
	ds_read_b128 v[174:177], v148 offset:2048
	ds_read_b128 v[178:181], v148 offset:3072
	s_add_u32 s36, s34, 0xfffc0080
	s_addc_u32 s37, s35, -1
	s_cmp_eq_u32 s59, 12
	s_cselect_b32 s39, s27, s37
	s_cselect_b32 s38, s55, s36
	s_cselect_b32 s37, s25, s58
	s_cselect_b32 s36, s56, s57
	v_lshl_add_u64 v[214:215], s[34:35], 0, v[138:139]
	s_add_i32 m0, s40, 0xc000
	ds_read_b128 v[182:185], v149
	ds_read_b128 v[186:189], v149 offset:1024
	ds_read_b128 v[190:193], v149 offset:2048
	ds_read_b128 v[194:197], v149 offset:3072
	ds_read_b128 v[198:201], v149 offset:4096
	ds_read_b128 v[202:205], v149 offset:5120
	ds_read_b128 v[206:209], v149 offset:6144
	ds_read_b128 v[210:213], v149 offset:7168
	global_load_lds_dwordx4 v[214:215], off
	v_lshl_add_u64 v[214:215], s[34:35], 0, v[136:137]
	s_add_i32 m0, s40, 0xe000
	s_nop 0
	global_load_lds_dwordx4 v[214:215], off
	s_waitcnt vmcnt(8)
	s_waitcnt lgkmcnt(0)
	s_barrier
	s_setprio 1
	s_waitcnt lgkmcnt(0)
	v_mfma_f32_16x16x32_bf16 v[124:127], v[150:153], v[182:185], v[124:127]
	v_mfma_f32_16x16x32_bf16 v[120:123], v[158:161], v[182:185], v[120:123]
	v_mfma_f32_16x16x32_bf16 v[116:119], v[150:153], v[190:193], v[116:119]
	v_mfma_f32_16x16x32_bf16 v[112:115], v[158:161], v[190:193], v[112:115]
	v_mfma_f32_16x16x32_bf16 v[100:103], v[150:153], v[198:201], v[100:103]
	v_mfma_f32_16x16x32_bf16 v[96:99], v[158:161], v[198:201], v[96:99]
	v_mfma_f32_16x16x32_bf16 v[84:87], v[150:153], v[206:209], v[84:87]
	v_mfma_f32_16x16x32_bf16 v[80:83], v[158:161], v[206:209], v[80:83]
	v_mfma_f32_16x16x32_bf16 v[124:127], v[154:157], v[186:189], v[124:127]
	v_mfma_f32_16x16x32_bf16 v[120:123], v[162:165], v[186:189], v[120:123]
	v_mfma_f32_16x16x32_bf16 v[116:119], v[154:157], v[194:197], v[116:119]
	v_mfma_f32_16x16x32_bf16 v[112:115], v[162:165], v[194:197], v[112:115]
	v_mfma_f32_16x16x32_bf16 v[100:103], v[154:157], v[202:205], v[100:103]
	v_mfma_f32_16x16x32_bf16 v[96:99], v[162:165], v[202:205], v[96:99]
	v_mfma_f32_16x16x32_bf16 v[84:87], v[154:157], v[210:213], v[84:87]
	v_mfma_f32_16x16x32_bf16 v[80:83], v[162:165], v[210:213], v[80:83]
	s_setprio 0
	s_setprio 1
	v_mfma_f32_16x16x32_bf16 v[108:111], v[166:169], v[182:185], v[108:111]
	v_mfma_f32_16x16x32_bf16 v[104:107], v[174:177], v[182:185], v[104:107]
	v_mfma_f32_16x16x32_bf16 v[92:95], v[166:169], v[190:193], v[92:95]
	v_mfma_f32_16x16x32_bf16 v[88:91], v[174:177], v[190:193], v[88:91]
	v_mfma_f32_16x16x32_bf16 v[76:79], v[166:169], v[198:201], v[76:79]
	v_mfma_f32_16x16x32_bf16 v[72:75], v[174:177], v[198:201], v[72:75]
	v_mfma_f32_16x16x32_bf16 v[68:71], v[166:169], v[206:209], v[68:71]
	v_mfma_f32_16x16x32_bf16 v[64:67], v[174:177], v[206:209], v[64:67]
	v_mfma_f32_16x16x32_bf16 v[108:111], v[170:173], v[186:189], v[108:111]
	v_mfma_f32_16x16x32_bf16 v[104:107], v[178:181], v[186:189], v[104:107]
	v_mfma_f32_16x16x32_bf16 v[92:95], v[170:173], v[194:197], v[92:95]
	v_mfma_f32_16x16x32_bf16 v[88:91], v[178:181], v[194:197], v[88:91]
	v_mfma_f32_16x16x32_bf16 v[76:79], v[170:173], v[202:205], v[76:79]
	v_mfma_f32_16x16x32_bf16 v[72:75], v[178:181], v[202:205], v[72:75]
	v_mfma_f32_16x16x32_bf16 v[68:71], v[170:173], v[210:213], v[68:71]
	v_mfma_f32_16x16x32_bf16 v[64:67], v[178:181], v[210:213], v[64:67]
	s_setprio 0
	s_barrier
	s_add_i32 s60, s47, s33
	v_lshl_add_u64 v[214:215], s[36:37], 0, v[132:133]
	s_mov_b32 m0, s60
	ds_read_b128 v[182:185], v149 offset:16384
	ds_read_b128 v[186:189], v149 offset:17408
	ds_read_b128 v[190:193], v149 offset:18432
	ds_read_b128 v[194:197], v149 offset:19456
	ds_read_b128 v[198:201], v149 offset:20480
	ds_read_b128 v[202:205], v149 offset:21504
	ds_read_b128 v[206:209], v149 offset:22528
	ds_read_b128 v[210:213], v149 offset:23552
	global_load_lds_dwordx4 v[214:215], off
	s_add_i32 m0, s60, 0x2000
	s_add_u32 s60, s36, 0x40000
	v_lshl_add_u64 v[216:217], s[36:37], 0, v[128:129]
	s_addc_u32 s61, s37, 0
	s_add_i32 s62, s48, s33
	global_load_lds_dwordx4 v[216:217], off
	v_lshl_add_u64 v[218:219], s[60:61], 0, v[132:133]
	s_mov_b32 m0, s62
	v_lshl_add_u64 v[220:221], s[38:39], 0, v[130:131]
	global_load_lds_dwordx4 v[218:219], off
	v_lshl_add_u64 v[218:219], s[60:61], 0, v[128:129]
	s_add_i32 m0, s62, 0x2000
	s_nop 0
	global_load_lds_dwordx4 v[218:219], off
	v_lshl_add_u64 v[218:219], s[38:39], 0, v[134:135]
	s_mov_b32 m0, s40
	s_nop 0
	global_load_lds_dwordx4 v[218:219], off
	s_mov_b32 m0, s41
	s_nop 0
	global_load_lds_dwordx4 v[220:221], off
	s_waitcnt vmcnt(8)
	s_waitcnt lgkmcnt(0)
	s_barrier
	s_setprio 1
	s_waitcnt lgkmcnt(0)
	v_mfma_f32_16x16x32_bf16 v[60:63], v[150:153], v[182:185], v[60:63]
	v_mfma_f32_16x16x32_bf16 v[56:59], v[158:161], v[182:185], v[56:59]
	v_mfma_f32_16x16x32_bf16 v[52:55], v[150:153], v[190:193], v[52:55]
	v_mfma_f32_16x16x32_bf16 v[48:51], v[158:161], v[190:193], v[48:51]
	v_mfma_f32_16x16x32_bf16 v[36:39], v[150:153], v[198:201], v[36:39]
	v_mfma_f32_16x16x32_bf16 v[32:35], v[158:161], v[198:201], v[32:35]
	v_mfma_f32_16x16x32_bf16 v[20:23], v[150:153], v[206:209], v[20:23]
	v_mfma_f32_16x16x32_bf16 v[16:19], v[158:161], v[206:209], v[16:19]
	v_mfma_f32_16x16x32_bf16 v[60:63], v[154:157], v[186:189], v[60:63]
	v_mfma_f32_16x16x32_bf16 v[56:59], v[162:165], v[186:189], v[56:59]
	v_mfma_f32_16x16x32_bf16 v[52:55], v[154:157], v[194:197], v[52:55]
	v_mfma_f32_16x16x32_bf16 v[48:51], v[162:165], v[194:197], v[48:51]
	v_mfma_f32_16x16x32_bf16 v[36:39], v[154:157], v[202:205], v[36:39]
	v_mfma_f32_16x16x32_bf16 v[32:35], v[162:165], v[202:205], v[32:35]
	v_mfma_f32_16x16x32_bf16 v[20:23], v[154:157], v[210:213], v[20:23]
	v_mfma_f32_16x16x32_bf16 v[16:19], v[162:165], v[210:213], v[16:19]
	s_setprio 0
	s_setprio 1
	v_mfma_f32_16x16x32_bf16 v[44:47], v[166:169], v[182:185], v[44:47]
	v_mfma_f32_16x16x32_bf16 v[40:43], v[174:177], v[182:185], v[40:43]
	v_mfma_f32_16x16x32_bf16 v[28:31], v[166:169], v[190:193], v[28:31]
	v_mfma_f32_16x16x32_bf16 v[24:27], v[174:177], v[190:193], v[24:27]
	v_mfma_f32_16x16x32_bf16 v[12:15], v[166:169], v[198:201], v[12:15]
	v_mfma_f32_16x16x32_bf16 v[8:11], v[174:177], v[198:201], v[8:11]
	v_mfma_f32_16x16x32_bf16 v[4:7], v[166:169], v[206:209], v[4:7]
	v_mfma_f32_16x16x32_bf16 v[0:3], v[174:177], v[206:209], v[0:3]
	v_mfma_f32_16x16x32_bf16 v[44:47], v[170:173], v[186:189], v[44:47]
	v_mfma_f32_16x16x32_bf16 v[40:43], v[178:181], v[186:189], v[40:43]
	v_mfma_f32_16x16x32_bf16 v[28:31], v[170:173], v[194:197], v[28:31]
	v_mfma_f32_16x16x32_bf16 v[24:27], v[178:181], v[194:197], v[24:27]
	v_mfma_f32_16x16x32_bf16 v[12:15], v[170:173], v[202:205], v[12:15]
	v_mfma_f32_16x16x32_bf16 v[8:11], v[178:181], v[202:205], v[8:11]
	v_mfma_f32_16x16x32_bf16 v[4:7], v[170:173], v[210:213], v[4:7]
	v_mfma_f32_16x16x32_bf16 v[0:3], v[178:181], v[210:213], v[0:3]
	s_setprio 0
	s_barrier
	s_add_i32 s60, 0, 0x18000
	s_add_i32 s61, 0, 0x1c000
	v_add_u32_e32 v162, s60, v145
	v_add_u32_e32 v178, s61, v145
	ds_read_b128 v[150:153], v162
	ds_read_b128 v[154:157], v162 offset:1024
	ds_read_b128 v[158:161], v162 offset:2048
	ds_read_b128 v[162:165], v162 offset:3072
	ds_read_b128 v[166:169], v178
	ds_read_b128 v[170:173], v178 offset:1024
	ds_read_b128 v[174:177], v178 offset:2048
	ds_read_b128 v[178:181], v178 offset:3072
	s_add_u32 s38, s38, 0x40000
	s_addc_u32 s39, s39, 0
	s_mov_b32 m0, s42
	v_lshl_add_u64 v[222:223], s[38:39], 0, v[134:135]
	ds_read_b128 v[182:185], v149 offset:32768
	ds_read_b128 v[186:189], v149 offset:33792
	ds_read_b128 v[190:193], v149 offset:34816
	ds_read_b128 v[194:197], v149 offset:35840
	ds_read_b128 v[198:201], v149 offset:36864
	ds_read_b128 v[202:205], v149 offset:37888
	ds_read_b128 v[206:209], v149 offset:38912
	ds_read_b128 v[210:213], v149 offset:39936
	global_load_lds_dwordx4 v[222:223], off
	v_lshl_add_u64 v[222:223], s[38:39], 0, v[130:131]
	s_mov_b32 m0, s43
	s_nop 0
	global_load_lds_dwordx4 v[222:223], off
	s_waitcnt vmcnt(8)
	s_waitcnt lgkmcnt(0)
	s_barrier
	s_setprio 1
	s_waitcnt lgkmcnt(0)
	v_mfma_f32_16x16x32_bf16 v[124:127], v[150:153], v[182:185], v[124:127]
	v_mfma_f32_16x16x32_bf16 v[120:123], v[158:161], v[182:185], v[120:123]
	v_mfma_f32_16x16x32_bf16 v[116:119], v[150:153], v[190:193], v[116:119]
	v_mfma_f32_16x16x32_bf16 v[112:115], v[158:161], v[190:193], v[112:115]
	v_mfma_f32_16x16x32_bf16 v[100:103], v[150:153], v[198:201], v[100:103]
	v_mfma_f32_16x16x32_bf16 v[96:99], v[158:161], v[198:201], v[96:99]
	v_mfma_f32_16x16x32_bf16 v[84:87], v[150:153], v[206:209], v[84:87]
	v_mfma_f32_16x16x32_bf16 v[80:83], v[158:161], v[206:209], v[80:83]
	v_mfma_f32_16x16x32_bf16 v[124:127], v[154:157], v[186:189], v[124:127]
	v_mfma_f32_16x16x32_bf16 v[120:123], v[162:165], v[186:189], v[120:123]
	v_mfma_f32_16x16x32_bf16 v[116:119], v[154:157], v[194:197], v[116:119]
	v_mfma_f32_16x16x32_bf16 v[112:115], v[162:165], v[194:197], v[112:115]
	v_mfma_f32_16x16x32_bf16 v[100:103], v[154:157], v[202:205], v[100:103]
	v_mfma_f32_16x16x32_bf16 v[96:99], v[162:165], v[202:205], v[96:99]
	v_mfma_f32_16x16x32_bf16 v[84:87], v[154:157], v[210:213], v[84:87]
	v_mfma_f32_16x16x32_bf16 v[80:83], v[162:165], v[210:213], v[80:83]
	s_setprio 0
	s_setprio 1
	v_mfma_f32_16x16x32_bf16 v[108:111], v[166:169], v[182:185], v[108:111]
	v_mfma_f32_16x16x32_bf16 v[104:107], v[174:177], v[182:185], v[104:107]
	v_mfma_f32_16x16x32_bf16 v[92:95], v[166:169], v[190:193], v[92:95]
	v_mfma_f32_16x16x32_bf16 v[88:91], v[174:177], v[190:193], v[88:91]
	v_mfma_f32_16x16x32_bf16 v[76:79], v[166:169], v[198:201], v[76:79]
	v_mfma_f32_16x16x32_bf16 v[72:75], v[174:177], v[198:201], v[72:75]
	v_mfma_f32_16x16x32_bf16 v[68:71], v[166:169], v[206:209], v[68:71]
	v_mfma_f32_16x16x32_bf16 v[64:67], v[174:177], v[206:209], v[64:67]
	v_mfma_f32_16x16x32_bf16 v[108:111], v[170:173], v[186:189], v[108:111]
	v_mfma_f32_16x16x32_bf16 v[104:107], v[178:181], v[186:189], v[104:107]
	v_mfma_f32_16x16x32_bf16 v[92:95], v[170:173], v[194:197], v[92:95]
	v_mfma_f32_16x16x32_bf16 v[88:91], v[178:181], v[194:197], v[88:91]
	v_mfma_f32_16x16x32_bf16 v[76:79], v[170:173], v[202:205], v[76:79]
	v_mfma_f32_16x16x32_bf16 v[72:75], v[178:181], v[202:205], v[72:75]
	v_mfma_f32_16x16x32_bf16 v[68:71], v[170:173], v[210:213], v[68:71]
	v_mfma_f32_16x16x32_bf16 v[64:67], v[178:181], v[210:213], v[64:67]
	s_setprio 0
	s_barrier
	s_add_i32 s38, s60, s33
	v_lshl_add_u64 v[214:215], v[214:215], 0, s[14:15]
	s_mov_b32 m0, s38
	ds_read_b128 v[182:185], v149 offset:49152
	ds_read_b128 v[186:189], v149 offset:50176
	ds_read_b128 v[190:193], v149 offset:51200
	ds_read_b128 v[194:197], v149 offset:52224
	ds_read_b128 v[198:201], v149 offset:53248
	ds_read_b128 v[202:205], v149 offset:54272
	ds_read_b128 v[206:209], v149 offset:55296
	ds_read_b128 v[210:213], v149 offset:56320
	global_load_lds_dwordx4 v[214:215], off
	s_add_i32 m0, s38, 0x2000
	s_add_u32 s36, s36, 0x40080
	v_lshl_add_u64 v[214:215], v[216:217], 0, s[14:15]
	s_addc_u32 s37, s37, 0
	s_add_i32 s38, s61, s33
	global_load_lds_dwordx4 v[214:215], off
	v_lshl_add_u64 v[214:215], s[36:37], 0, v[132:133]
	s_mov_b32 m0, s38
	s_nop 0
	global_load_lds_dwordx4 v[214:215], off
	v_lshl_add_u64 v[214:215], s[36:37], 0, v[128:129]
	s_add_i32 m0, s38, 0x2000
	s_nop 0
	global_load_lds_dwordx4 v[214:215], off
	v_lshl_add_u64 v[214:215], v[218:219], 0, s[14:15]
	s_mov_b32 m0, s45
	s_nop 0
	global_load_lds_dwordx4 v[214:215], off
	v_lshl_add_u64 v[214:215], v[220:221], 0, s[14:15]
	s_mov_b32 m0, s46
	s_nop 0
	global_load_lds_dwordx4 v[214:215], off
	s_waitcnt vmcnt(8)
	s_waitcnt lgkmcnt(0)
	s_barrier
	s_setprio 1
	s_waitcnt lgkmcnt(0)
	v_mfma_f32_16x16x32_bf16 v[60:63], v[150:153], v[182:185], v[60:63]
	v_mfma_f32_16x16x32_bf16 v[56:59], v[158:161], v[182:185], v[56:59]
	v_mfma_f32_16x16x32_bf16 v[52:55], v[150:153], v[190:193], v[52:55]
	v_mfma_f32_16x16x32_bf16 v[48:51], v[158:161], v[190:193], v[48:51]
	v_mfma_f32_16x16x32_bf16 v[36:39], v[150:153], v[198:201], v[36:39]
	v_mfma_f32_16x16x32_bf16 v[32:35], v[158:161], v[198:201], v[32:35]
	v_mfma_f32_16x16x32_bf16 v[20:23], v[150:153], v[206:209], v[20:23]
	v_mfma_f32_16x16x32_bf16 v[16:19], v[158:161], v[206:209], v[16:19]
	v_mfma_f32_16x16x32_bf16 v[60:63], v[154:157], v[186:189], v[60:63]
	v_mfma_f32_16x16x32_bf16 v[56:59], v[162:165], v[186:189], v[56:59]
	v_mfma_f32_16x16x32_bf16 v[52:55], v[154:157], v[194:197], v[52:55]
	v_mfma_f32_16x16x32_bf16 v[48:51], v[162:165], v[194:197], v[48:51]
	v_mfma_f32_16x16x32_bf16 v[36:39], v[154:157], v[202:205], v[36:39]
	v_mfma_f32_16x16x32_bf16 v[32:35], v[162:165], v[202:205], v[32:35]
	v_mfma_f32_16x16x32_bf16 v[20:23], v[154:157], v[210:213], v[20:23]
	v_mfma_f32_16x16x32_bf16 v[16:19], v[162:165], v[210:213], v[16:19]
	s_setprio 0
	s_setprio 1
	v_mfma_f32_16x16x32_bf16 v[44:47], v[166:169], v[182:185], v[44:47]
	v_mfma_f32_16x16x32_bf16 v[40:43], v[174:177], v[182:185], v[40:43]
	v_mfma_f32_16x16x32_bf16 v[28:31], v[166:169], v[190:193], v[28:31]
	v_mfma_f32_16x16x32_bf16 v[24:27], v[174:177], v[190:193], v[24:27]
	v_mfma_f32_16x16x32_bf16 v[12:15], v[166:169], v[198:201], v[12:15]
	v_mfma_f32_16x16x32_bf16 v[8:11], v[174:177], v[198:201], v[8:11]
	v_mfma_f32_16x16x32_bf16 v[4:7], v[166:169], v[206:209], v[4:7]
	v_mfma_f32_16x16x32_bf16 v[0:3], v[174:177], v[206:209], v[0:3]
	v_mfma_f32_16x16x32_bf16 v[44:47], v[170:173], v[186:189], v[44:47]
	v_mfma_f32_16x16x32_bf16 v[40:43], v[178:181], v[186:189], v[40:43]
	v_mfma_f32_16x16x32_bf16 v[28:31], v[170:173], v[194:197], v[28:31]
	v_mfma_f32_16x16x32_bf16 v[24:27], v[178:181], v[194:197], v[24:27]
	v_mfma_f32_16x16x32_bf16 v[12:15], v[170:173], v[202:205], v[12:15]
	v_mfma_f32_16x16x32_bf16 v[8:11], v[178:181], v[202:205], v[8:11]
	v_mfma_f32_16x16x32_bf16 v[4:7], v[170:173], v[210:213], v[4:7]
	v_mfma_f32_16x16x32_bf16 v[0:3], v[178:181], v[210:213], v[0:3]
	s_setprio 0
	s_barrier
	s_add_i32 s59, s59, 2
	s_add_u32 s57, s57, 0x100
	s_addc_u32 s58, s58, 0
	s_add_u32 s34, s34, 0x100
	s_addc_u32 s35, s35, 0
	s_cmp_gt_u32 s59, 13
	s_cbranch_scc0 .LBB0_729
	s_and_b64 vcc, exec, s[16:17]
	s_cbranch_vccz .LBB0_732
	s_barrier
.LBB0_732:
	v_lshl_or_b32 v150, s53, 8, v146
	v_lshl_add_u32 v152, s54, 8, v144
	s_mov_b64 s[34:35], s[10:11]
	v_ashrrev_i32_e32 v151, 31, v150
	v_ashrrev_i32_e32 v153, 31, v152
	v_lshlrev_b64 v[154:155], 11, v[152:153]
	v_lshl_add_u64 v[150:151], v[150:151], 1, s[34:35]
	v_lshl_add_u64 v[154:155], v[150:151], 0, v[154:155]
	v_cvt_pk_bf16_f32 v60, v60, v61
	v_cvt_pk_bf16_f32 v61, v62, v63
	v_cvt_pk_bf16_f32 v62, v56, v57
	v_add_co_u32_e32 v56, vcc, s49, v154
	v_cvt_pk_bf16_f32 v68, v68, v69
	v_cvt_pk_bf16_f32 v69, v70, v71
	v_cvt_pk_bf16_f32 v70, v64, v65
	v_lshl_add_u64 v[64:65], v[154:155], 0, s[4:5]
	v_addc_co_u32_e32 v57, vcc, 0, v155, vcc
	v_cvt_pk_bf16_f32 v44, v44, v45
	v_cvt_pk_bf16_f32 v45, v46, v47
	v_cvt_pk_bf16_f32 v46, v40, v41
	v_cvt_pk_bf16_f32 v47, v42, v43
	global_store_dwordx4 v[64:65], v[44:47], off offset:256
	v_cvt_pk_bf16_f32 v108, v108, v109
	v_cvt_pk_bf16_f32 v109, v110, v111
	v_add_co_u32_e32 v46, vcc, s50, v154
	v_cvt_pk_bf16_f32 v110, v104, v105
	v_or_b32_e32 v104, 16, v152
	v_lshl_add_u64 v[44:45], v[154:155], 0, s[18:19]
	v_addc_co_u32_e32 v47, vcc, 0, v155, vcc
	v_cvt_pk_bf16_f32 v28, v28, v29
	v_cvt_pk_bf16_f32 v29, v30, v31
	v_cvt_pk_bf16_f32 v30, v24, v25
	v_cvt_pk_bf16_f32 v31, v26, v27
	v_ashrrev_i32_e32 v105, 31, v104
	v_cvt_pk_bf16_f32 v92, v92, v93
	v_cvt_pk_bf16_f32 v93, v94, v95
	v_cvt_pk_bf16_f32 v94, v88, v89
	v_or_b32_e32 v88, 32, v152
	global_store_dwordx4 v[44:45], v[28:31], off offset:256
	v_cvt_pk_bf16_f32 v111, v106, v107
	v_lshlrev_b64 v[104:105], 11, v[104:105]
	v_add_co_u32_e32 v30, vcc, s51, v154
	v_ashrrev_i32_e32 v89, 31, v88
	v_cvt_pk_bf16_f32 v76, v76, v77
	v_cvt_pk_bf16_f32 v77, v78, v79
	v_cvt_pk_bf16_f32 v78, v72, v73
	v_or_b32_e32 v72, 48, v152
	v_lshl_add_u64 v[28:29], v[154:155], 0, s[20:21]
	v_addc_co_u32_e32 v31, vcc, 0, v155, vcc
	v_cvt_pk_bf16_f32 v12, v12, v13
	v_cvt_pk_bf16_f32 v13, v14, v15
	v_cvt_pk_bf16_f32 v14, v8, v9
	v_cvt_pk_bf16_f32 v15, v10, v11
	global_store_dwordx4 v[154:155], v[108:111], off offset:256
	v_cvt_pk_bf16_f32 v95, v90, v91
	v_lshlrev_b64 v[88:89], 11, v[88:89]
	v_lshl_add_u64 v[108:109], v[150:151], 0, v[104:105]
	v_ashrrev_i32_e32 v73, 31, v72
	global_store_dwordx4 v[28:29], v[12:15], off offset:256
	global_store_dwordx4 v[108:109], v[92:95], off offset:256
	v_cvt_pk_bf16_f32 v79, v74, v75
	v_add_co_u32_e32 v14, vcc, s52, v154
	v_lshl_add_u64 v[92:93], v[150:151], 0, v[88:89]
	v_lshlrev_b64 v[72:73], 11, v[72:73]
	v_addc_co_u32_e32 v15, vcc, 0, v155, vcc
	v_cvt_pk_bf16_f32 v124, v124, v125
	v_cvt_pk_bf16_f32 v125, v126, v127
	v_cvt_pk_bf16_f32 v126, v120, v121
	v_cvt_pk_bf16_f32 v127, v122, v123
	v_cvt_pk_bf16_f32 v104, v116, v117
	v_cvt_pk_bf16_f32 v105, v118, v119
	v_cvt_pk_bf16_f32 v106, v112, v113
	v_cvt_pk_bf16_f32 v107, v114, v115
	v_cvt_pk_bf16_f32 v88, v100, v101
	v_cvt_pk_bf16_f32 v89, v102, v103
	v_cvt_pk_bf16_f32 v90, v96, v97
	v_cvt_pk_bf16_f32 v91, v98, v99
	global_store_dwordx4 v[92:93], v[76:79], off offset:256
	v_cvt_pk_bf16_f32 v74, v80, v81
	v_cvt_pk_bf16_f32 v75, v82, v83
	v_lshl_add_u64 v[76:77], v[150:151], 0, v[72:73]
	v_cvt_pk_bf16_f32 v72, v84, v85
	v_cvt_pk_bf16_f32 v73, v86, v87
	v_cvt_pk_bf16_f32 v71, v66, v67
	v_cvt_pk_bf16_f32 v63, v58, v59
	v_cvt_pk_bf16_f32 v40, v52, v53
	v_cvt_pk_bf16_f32 v41, v54, v55
	v_cvt_pk_bf16_f32 v42, v48, v49
	v_cvt_pk_bf16_f32 v43, v50, v51
	v_cvt_pk_bf16_f32 v24, v36, v37
	v_cvt_pk_bf16_f32 v25, v38, v39
	v_cvt_pk_bf16_f32 v26, v32, v33
	v_cvt_pk_bf16_f32 v27, v34, v35
	v_lshl_add_u64 v[12:13], v[154:155], 0, s[22:23]
	v_cvt_pk_bf16_f32 v8, v20, v21
	v_cvt_pk_bf16_f32 v9, v22, v23
	v_cvt_pk_bf16_f32 v10, v16, v17
	v_cvt_pk_bf16_f32 v11, v18, v19
	v_cvt_pk_bf16_f32 v4, v4, v5
	v_cvt_pk_bf16_f32 v5, v6, v7
	v_cvt_pk_bf16_f32 v6, v0, v1
	v_cvt_pk_bf16_f32 v7, v2, v3
	s_andn2_b64 vcc, exec, s[6:7]
	s_mov_b64 s[6:7], -1
	global_store_dwordx4 v[154:155], v[124:127], off
	global_store_dwordx4 v[108:109], v[104:107], off
	global_store_dwordx4 v[92:93], v[88:91], off
	global_store_dwordx4 v[76:77], v[72:75], off
	global_store_dwordx4 v[76:77], v[68:71], off offset:256
	global_store_dwordx4 v[56:57], v[60:63], off
	global_store_dwordx4 v[46:47], v[40:43], off
	global_store_dwordx4 v[30:31], v[24:27], off
	global_store_dwordx4 v[14:15], v[8:11], off
	global_store_dwordx4 v[12:13], v[4:7], off offset:256
	s_cbranch_vccnz .LBB0_725
	s_andn2_b64 vcc, exec, s[12:13]
	s_cbranch_vccnz .LBB0_724
	s_mov_b32 s100, 1
	s_branch .LBB0_724

.LBB0_871:
	s_add_u32 s10, s6, 0x11800000
	s_addc_u32 s11, s7, 0
	s_lshl_b32 s6, s12, 5
	s_mov_b64 s[12:13], 0x80
	s_and_b32 s17, s6, 0x60
	s_add_i32 m0, s31, 0x18000
	v_lshl_add_u64 v[6:7], v[6:7], 0, s[12:13]
	s_lshl_b32 s16, s15, 13
	s_lshl_b32 s18, s17, 7
	s_waitcnt vmcnt(2)
	s_barrier
	global_load_lds_dwordx4 v[6:7], off
	v_lshl_add_u64 v[4:5], v[4:5], 0, s[12:13]
	s_add_i32 m0, s31, 0x1a000
	s_add_i32 s37, s31, 0x8000
	s_add_i32 s38, s31, 0xa000
	global_load_lds_dwordx4 v[4:5], off
	v_lshl_add_u64 v[0:1], v[0:1], 0, s[12:13]
	s_mov_b32 m0, s37
	s_add_u32 s6, s24, 0x40080
	global_load_lds_dwordx4 v[0:1], off
	v_lshl_add_u64 v[0:1], v[2:3], 0, s[12:13]
	s_mov_b32 m0, s38
	s_addc_u32 s7, s25, 0
	global_load_lds_dwordx4 v[0:1], off
	s_add_i32 m0, s31, 0x1c000
	v_lshl_add_u64 v[0:1], s[6:7], 0, v[132:133]
	global_load_lds_dwordx4 v[0:1], off
	v_lshl_add_u64 v[0:1], s[6:7], 0, v[128:129]
	s_add_i32 m0, s31, 0x1e000
	s_cmpk_lt_u32 s14, 0x100
	global_load_lds_dwordx4 v[0:1], off
	v_lshrrev_b32_e32 v1, 1, v8
	v_and_b32_e32 v1, 24, v1
	v_and_b32_e32 v0, 15, v8
	v_lshlrev_b32_e32 v2, 1, v1
	v_lshl_or_b32 v146, s15, 6, v0
	v_lshl_or_b32 v0, v0, 6, v2
	v_lshlrev_b32_e32 v2, 2, v8
	v_and_b32_e32 v2, 32, v2
	v_bitop3_b32 v3, v0, s16, v2 bitop3:0xde
	v_bitop3_b32 v147, s18, v0, v2 bitop3:0xf6
	v_lshlrev_b32_e32 v0, 14, v9
	v_and_b32_e32 v0, 0xffff8000, v0
	v_or_b32_e32 v148, s17, v1
	v_lshl_add_u32 v0, v10, 11, v0
	v_and_b32_e32 v1, 1, v9
	v_lshl_or_b32 v0, v1, 6, v0
	v_lshl_add_u32 v136, v11, 1, v0
	v_lshlrev_b32_e32 v0, 14, v13
	v_and_b32_e32 v0, 0xffff8000, v0
	s_waitcnt vmcnt(6)
	v_lshl_add_u32 v0, v12, 11, v0
	v_and_b32_e32 v1, 1, v13
	s_cselect_b64 s[14:15], -1, 0
	v_lshl_or_b32 v0, v1, 6, v0
	s_add_i32 s40, 0, 0x10000
	s_add_i32 s41, 0, 0x14000
	v_mov_b32_e32 v137, v133
	v_lshl_add_u32 v138, v14, 1, v0
	v_mov_b32_e32 v139, v133
	v_mov_b64_e32 v[140:141], 0xb00
	v_mov_b64_e32 v[142:143], 0xaff
	s_movk_i32 s39, 0x161
	v_add_u32_e32 v149, s40, v147
	v_add_u32_e32 v150, s41, v147
	v_add_u32_e32 v151, 0, v3
	s_movk_i32 s42, 0x1600
	s_mov_b32 s43, s86
	s_mov_b32 s44, s88
	s_barrier
	s_mov_b32 s100, 0
	s_branch .LBB0_874

.LBB0_876:
	s_ashr_i32 s19, s18, 31
	s_lshl_b64 s[20:21], s[18:19], 19
	s_add_u32 s20, s0, s20
	s_addc_u32 s21, s1, s21
	s_and_b64 s[22:23], s[6:7], exec
	s_cselect_b32 s19, s21, s27
	s_cselect_b32 s45, s20, s26
	s_ashr_i32 s17, s16, 31
	s_lshl_b64 s[22:23], s[16:17], 19
	s_add_u32 s22, s4, s22
	s_addc_u32 s23, s5, s23
	s_and_b64 s[28:29], s[6:7], exec
	s_cselect_b32 s17, s23, s25
	s_cselect_b32 s46, s22, s24
	s_add_u32 s47, s24, 0x100
	s_addc_u32 s48, s25, 0
	s_add_u32 s24, s26, 0x40080
	v_mov_b32_e32 v0, 0
	s_addc_u32 s25, s27, 0
	s_mov_b32 s49, -2
	v_mov_b32_e32 v1, v0
	v_mov_b32_e32 v2, v0
	v_mov_b32_e32 v3, v0
	v_mov_b32_e32 v4, v0
	v_mov_b32_e32 v5, v0
	v_mov_b32_e32 v6, v0
	v_mov_b32_e32 v7, v0
	v_mov_b32_e32 v16, v0
	v_mov_b32_e32 v17, v0
	v_mov_b32_e32 v18, v0
	v_mov_b32_e32 v19, v0
	v_mov_b32_e32 v20, v0
	v_mov_b32_e32 v21, v0
	v_mov_b32_e32 v22, v0
	v_mov_b32_e32 v23, v0
	v_mov_b32_e32 v32, v0
	v_mov_b32_e32 v33, v0
	v_mov_b32_e32 v34, v0
	v_mov_b32_e32 v35, v0
	v_mov_b32_e32 v36, v0
	v_mov_b32_e32 v37, v0
	v_mov_b32_e32 v38, v0
	v_mov_b32_e32 v39, v0
	v_mov_b32_e32 v48, v0
	v_mov_b32_e32 v49, v0
	v_mov_b32_e32 v50, v0
	v_mov_b32_e32 v51, v0
	v_mov_b32_e32 v52, v0
	v_mov_b32_e32 v53, v0
	v_mov_b32_e32 v54, v0
	v_mov_b32_e32 v55, v0
	v_mov_b32_e32 v8, v0
	v_mov_b32_e32 v9, v0
	v_mov_b32_e32 v10, v0
	v_mov_b32_e32 v11, v0
	v_mov_b32_e32 v12, v0
	v_mov_b32_e32 v13, v0
	v_mov_b32_e32 v14, v0
	v_mov_b32_e32 v15, v0
	v_mov_b32_e32 v24, v0
	v_mov_b32_e32 v25, v0
	v_mov_b32_e32 v26, v0
	v_mov_b32_e32 v27, v0
	v_mov_b32_e32 v28, v0
	v_mov_b32_e32 v29, v0
	v_mov_b32_e32 v30, v0
	v_mov_b32_e32 v31, v0
	v_mov_b32_e32 v40, v0
	v_mov_b32_e32 v41, v0
	v_mov_b32_e32 v42, v0
	v_mov_b32_e32 v43, v0
	v_mov_b32_e32 v44, v0
	v_mov_b32_e32 v45, v0
	v_mov_b32_e32 v46, v0
	v_mov_b32_e32 v47, v0
	v_mov_b32_e32 v56, v0
	v_mov_b32_e32 v57, v0
	v_mov_b32_e32 v58, v0
	v_mov_b32_e32 v59, v0
	v_mov_b32_e32 v60, v0
	v_mov_b32_e32 v61, v0
	v_mov_b32_e32 v62, v0
	v_mov_b32_e32 v63, v0
	v_mov_b32_e32 v64, v0
	v_mov_b32_e32 v65, v0
	v_mov_b32_e32 v66, v0
	v_mov_b32_e32 v67, v0
	v_mov_b32_e32 v68, v0
	v_mov_b32_e32 v69, v0
	v_mov_b32_e32 v70, v0
	v_mov_b32_e32 v71, v0
	v_mov_b32_e32 v80, v0
	v_mov_b32_e32 v81, v0
	v_mov_b32_e32 v82, v0
	v_mov_b32_e32 v83, v0
	v_mov_b32_e32 v84, v0
	v_mov_b32_e32 v85, v0
	v_mov_b32_e32 v86, v0
	v_mov_b32_e32 v87, v0
	v_mov_b32_e32 v96, v0
	v_mov_b32_e32 v97, v0
	v_mov_b32_e32 v98, v0
	v_mov_b32_e32 v99, v0
	v_mov_b32_e32 v100, v0
	v_mov_b32_e32 v101, v0
	v_mov_b32_e32 v102, v0
	v_mov_b32_e32 v103, v0
	v_mov_b32_e32 v112, v0
	v_mov_b32_e32 v113, v0
	v_mov_b32_e32 v114, v0
	v_mov_b32_e32 v115, v0
	v_mov_b32_e32 v116, v0
	v_mov_b32_e32 v117, v0
	v_mov_b32_e32 v118, v0
	v_mov_b32_e32 v119, v0
	v_mov_b32_e32 v72, v0
	v_mov_b32_e32 v73, v0
	v_mov_b32_e32 v74, v0
	v_mov_b32_e32 v75, v0
	v_mov_b32_e32 v76, v0
	v_mov_b32_e32 v77, v0
	v_mov_b32_e32 v78, v0
	v_mov_b32_e32 v79, v0
	v_mov_b32_e32 v88, v0
	v_mov_b32_e32 v89, v0
	v_mov_b32_e32 v90, v0
	v_mov_b32_e32 v91, v0
	v_mov_b32_e32 v92, v0
	v_mov_b32_e32 v93, v0
	v_mov_b32_e32 v94, v0
	v_mov_b32_e32 v95, v0
	v_mov_b32_e32 v104, v0
	v_mov_b32_e32 v105, v0
	v_mov_b32_e32 v106, v0
	v_mov_b32_e32 v107, v0
	v_mov_b32_e32 v108, v0
	v_mov_b32_e32 v109, v0
	v_mov_b32_e32 v110, v0
	v_mov_b32_e32 v111, v0
	v_mov_b32_e32 v120, v0
	v_mov_b32_e32 v121, v0
	v_mov_b32_e32 v122, v0
	v_mov_b32_e32 v123, v0
	v_mov_b32_e32 v124, v0
	v_mov_b32_e32 v125, v0
	v_mov_b32_e32 v126, v0
	v_mov_b32_e32 v127, v0
	s_cmp_eq_u32 s100, 1
	s_cbranch_scc0 .Lgemm_nobar_872
	s_mov_b32 s100, 0
	s_barrier
.Lgemm_nobar_872:
.LBB0_877:
	ds_read_b128 v[152:155], v149
	ds_read_b128 v[156:159], v149 offset:1024
	ds_read_b128 v[160:163], v149 offset:2048
	ds_read_b128 v[164:167], v149 offset:3072
	ds_read_b128 v[168:171], v150
	ds_read_b128 v[172:175], v150 offset:1024
	ds_read_b128 v[176:179], v150 offset:2048
	ds_read_b128 v[180:183], v150 offset:3072
	s_add_u32 s26, s24, 0xfffc0080
	s_addc_u32 s27, s25, -1
	s_cmp_eq_u32 s49, 12
	s_cselect_b32 s29, s19, s27
	s_cselect_b32 s28, s45, s26
	s_cselect_b32 s27, s17, s48
	s_cselect_b32 s26, s46, s47
	v_lshl_add_u64 v[144:145], s[24:25], 0, v[138:139]
	s_add_i32 m0, s31, 0xc000
	ds_read_b128 v[184:187], v151
	ds_read_b128 v[188:191], v151 offset:1024
	ds_read_b128 v[192:195], v151 offset:2048
	ds_read_b128 v[196:199], v151 offset:3072
	ds_read_b128 v[200:203], v151 offset:4096
	ds_read_b128 v[204:207], v151 offset:5120
	ds_read_b128 v[208:211], v151 offset:6144
	ds_read_b128 v[212:215], v151 offset:7168
	global_load_lds_dwordx4 v[144:145], off
	v_lshl_add_u64 v[144:145], s[24:25], 0, v[136:137]
	s_add_i32 m0, s31, 0xe000
	s_nop 0
	global_load_lds_dwordx4 v[144:145], off
	s_waitcnt vmcnt(8)
	s_waitcnt lgkmcnt(0)
	s_barrier
	s_setprio 1
	s_waitcnt lgkmcnt(0)
	v_mfma_f32_16x16x32_bf16 v[124:127], v[152:155], v[184:187], v[124:127]
	v_mfma_f32_16x16x32_bf16 v[120:123], v[160:163], v[184:187], v[120:123]
	v_mfma_f32_16x16x32_bf16 v[108:111], v[152:155], v[192:195], v[108:111]
	v_mfma_f32_16x16x32_bf16 v[104:107], v[160:163], v[192:195], v[104:107]
	v_mfma_f32_16x16x32_bf16 v[92:95], v[152:155], v[200:203], v[92:95]
	v_mfma_f32_16x16x32_bf16 v[88:91], v[160:163], v[200:203], v[88:91]
	v_mfma_f32_16x16x32_bf16 v[76:79], v[152:155], v[208:211], v[76:79]
	v_mfma_f32_16x16x32_bf16 v[72:75], v[160:163], v[208:211], v[72:75]
	v_mfma_f32_16x16x32_bf16 v[124:127], v[156:159], v[188:191], v[124:127]
	v_mfma_f32_16x16x32_bf16 v[120:123], v[164:167], v[188:191], v[120:123]
	v_mfma_f32_16x16x32_bf16 v[108:111], v[156:159], v[196:199], v[108:111]
	v_mfma_f32_16x16x32_bf16 v[104:107], v[164:167], v[196:199], v[104:107]
	v_mfma_f32_16x16x32_bf16 v[92:95], v[156:159], v[204:207], v[92:95]
	v_mfma_f32_16x16x32_bf16 v[88:91], v[164:167], v[204:207], v[88:91]
	v_mfma_f32_16x16x32_bf16 v[76:79], v[156:159], v[212:215], v[76:79]
	v_mfma_f32_16x16x32_bf16 v[72:75], v[164:167], v[212:215], v[72:75]
	s_setprio 0
	s_setprio 1
	v_mfma_f32_16x16x32_bf16 v[116:119], v[168:171], v[184:187], v[116:119]
	v_mfma_f32_16x16x32_bf16 v[112:115], v[176:179], v[184:187], v[112:115]
	v_mfma_f32_16x16x32_bf16 v[100:103], v[168:171], v[192:195], v[100:103]
	v_mfma_f32_16x16x32_bf16 v[96:99], v[176:179], v[192:195], v[96:99]
	v_mfma_f32_16x16x32_bf16 v[84:87], v[168:171], v[200:203], v[84:87]
	v_mfma_f32_16x16x32_bf16 v[80:83], v[176:179], v[200:203], v[80:83]
	v_mfma_f32_16x16x32_bf16 v[68:71], v[168:171], v[208:211], v[68:71]
	v_mfma_f32_16x16x32_bf16 v[64:67], v[176:179], v[208:211], v[64:67]
	v_mfma_f32_16x16x32_bf16 v[116:119], v[172:175], v[188:191], v[116:119]
	v_mfma_f32_16x16x32_bf16 v[112:115], v[180:183], v[188:191], v[112:115]
	v_mfma_f32_16x16x32_bf16 v[100:103], v[172:175], v[196:199], v[100:103]
	v_mfma_f32_16x16x32_bf16 v[96:99], v[180:183], v[196:199], v[96:99]
	v_mfma_f32_16x16x32_bf16 v[84:87], v[172:175], v[204:207], v[84:87]
	v_mfma_f32_16x16x32_bf16 v[80:83], v[180:183], v[204:207], v[80:83]
	v_mfma_f32_16x16x32_bf16 v[68:71], v[172:175], v[212:215], v[68:71]
	v_mfma_f32_16x16x32_bf16 v[64:67], v[180:183], v[212:215], v[64:67]
	s_setprio 0
	s_barrier
	s_add_i32 s50, s40, s30
	v_lshl_add_u64 v[144:145], s[26:27], 0, v[132:133]
	s_mov_b32 m0, s50
	ds_read_b128 v[184:187], v151 offset:16384
	ds_read_b128 v[188:191], v151 offset:17408
	ds_read_b128 v[192:195], v151 offset:18432
	ds_read_b128 v[196:199], v151 offset:19456
	ds_read_b128 v[200:203], v151 offset:20480
	ds_read_b128 v[204:207], v151 offset:21504
	ds_read_b128 v[208:211], v151 offset:22528
	ds_read_b128 v[212:215], v151 offset:23552
	global_load_lds_dwordx4 v[144:145], off
	s_add_i32 m0, s50, 0x2000
	s_add_u32 s50, s26, 0x40000
	v_lshl_add_u64 v[216:217], s[26:27], 0, v[128:129]
	s_addc_u32 s51, s27, 0
	s_add_i32 s52, s41, s30
	global_load_lds_dwordx4 v[216:217], off
	v_lshl_add_u64 v[218:219], s[50:51], 0, v[132:133]
	s_mov_b32 m0, s52
	v_lshl_add_u64 v[220:221], s[28:29], 0, v[130:131]
	global_load_lds_dwordx4 v[218:219], off
	v_lshl_add_u64 v[218:219], s[50:51], 0, v[128:129]
	s_add_i32 m0, s52, 0x2000
	s_nop 0
	global_load_lds_dwordx4 v[218:219], off
	v_lshl_add_u64 v[218:219], s[28:29], 0, v[134:135]
	s_mov_b32 m0, s31
	s_nop 0
	global_load_lds_dwordx4 v[218:219], off
	s_mov_b32 m0, s33
	s_nop 0
	global_load_lds_dwordx4 v[220:221], off
	s_waitcnt vmcnt(8)
	s_waitcnt lgkmcnt(0)
	s_barrier
	s_setprio 1
	s_waitcnt lgkmcnt(0)
	v_mfma_f32_16x16x32_bf16 v[60:63], v[152:155], v[184:187], v[60:63]
	v_mfma_f32_16x16x32_bf16 v[56:59], v[160:163], v[184:187], v[56:59]
	v_mfma_f32_16x16x32_bf16 v[44:47], v[152:155], v[192:195], v[44:47]
	v_mfma_f32_16x16x32_bf16 v[40:43], v[160:163], v[192:195], v[40:43]
	v_mfma_f32_16x16x32_bf16 v[28:31], v[152:155], v[200:203], v[28:31]
	v_mfma_f32_16x16x32_bf16 v[24:27], v[160:163], v[200:203], v[24:27]
	v_mfma_f32_16x16x32_bf16 v[12:15], v[152:155], v[208:211], v[12:15]
	v_mfma_f32_16x16x32_bf16 v[8:11], v[160:163], v[208:211], v[8:11]
	v_mfma_f32_16x16x32_bf16 v[60:63], v[156:159], v[188:191], v[60:63]
	v_mfma_f32_16x16x32_bf16 v[56:59], v[164:167], v[188:191], v[56:59]
	v_mfma_f32_16x16x32_bf16 v[44:47], v[156:159], v[196:199], v[44:47]
	v_mfma_f32_16x16x32_bf16 v[40:43], v[164:167], v[196:199], v[40:43]
	v_mfma_f32_16x16x32_bf16 v[28:31], v[156:159], v[204:207], v[28:31]
	v_mfma_f32_16x16x32_bf16 v[24:27], v[164:167], v[204:207], v[24:27]
	v_mfma_f32_16x16x32_bf16 v[12:15], v[156:159], v[212:215], v[12:15]
	v_mfma_f32_16x16x32_bf16 v[8:11], v[164:167], v[212:215], v[8:11]
	s_setprio 0
	s_setprio 1
	v_mfma_f32_16x16x32_bf16 v[52:55], v[168:171], v[184:187], v[52:55]
	v_mfma_f32_16x16x32_bf16 v[48:51], v[176:179], v[184:187], v[48:51]
	v_mfma_f32_16x16x32_bf16 v[36:39], v[168:171], v[192:195], v[36:39]
	v_mfma_f32_16x16x32_bf16 v[32:35], v[176:179], v[192:195], v[32:35]
	v_mfma_f32_16x16x32_bf16 v[20:23], v[168:171], v[200:203], v[20:23]
	v_mfma_f32_16x16x32_bf16 v[16:19], v[176:179], v[200:203], v[16:19]
	v_mfma_f32_16x16x32_bf16 v[4:7], v[168:171], v[208:211], v[4:7]
	v_mfma_f32_16x16x32_bf16 v[0:3], v[176:179], v[208:211], v[0:3]
	v_mfma_f32_16x16x32_bf16 v[52:55], v[172:175], v[188:191], v[52:55]
	v_mfma_f32_16x16x32_bf16 v[48:51], v[180:183], v[188:191], v[48:51]
	v_mfma_f32_16x16x32_bf16 v[36:39], v[172:175], v[196:199], v[36:39]
	v_mfma_f32_16x16x32_bf16 v[32:35], v[180:183], v[196:199], v[32:35]
	v_mfma_f32_16x16x32_bf16 v[20:23], v[172:175], v[204:207], v[20:23]
	v_mfma_f32_16x16x32_bf16 v[16:19], v[180:183], v[204:207], v[16:19]
	v_mfma_f32_16x16x32_bf16 v[4:7], v[172:175], v[212:215], v[4:7]
	v_mfma_f32_16x16x32_bf16 v[0:3], v[180:183], v[212:215], v[0:3]
	s_setprio 0
	s_barrier
	s_add_i32 s50, 0, 0x18000
	s_add_i32 s51, 0, 0x1c000
	v_add_u32_e32 v164, s50, v147
	v_add_u32_e32 v180, s51, v147
	ds_read_b128 v[152:155], v164
	ds_read_b128 v[156:159], v164 offset:1024
	ds_read_b128 v[160:163], v164 offset:2048
	ds_read_b128 v[164:167], v164 offset:3072
	ds_read_b128 v[168:171], v180
	ds_read_b128 v[172:175], v180 offset:1024
	ds_read_b128 v[176:179], v180 offset:2048
	ds_read_b128 v[180:183], v180 offset:3072
	s_add_u32 s28, s28, 0x40000
	s_addc_u32 s29, s29, 0
	s_mov_b32 m0, s34
	v_lshl_add_u64 v[222:223], s[28:29], 0, v[134:135]
	ds_read_b128 v[184:187], v151 offset:32768
	ds_read_b128 v[188:191], v151 offset:33792
	ds_read_b128 v[192:195], v151 offset:34816
	ds_read_b128 v[196:199], v151 offset:35840
	ds_read_b128 v[200:203], v151 offset:36864
	ds_read_b128 v[204:207], v151 offset:37888
	ds_read_b128 v[208:211], v151 offset:38912
	ds_read_b128 v[212:215], v151 offset:39936
	global_load_lds_dwordx4 v[222:223], off
	v_lshl_add_u64 v[222:223], s[28:29], 0, v[130:131]
	s_mov_b32 m0, s35
	s_nop 0
	global_load_lds_dwordx4 v[222:223], off
	s_waitcnt vmcnt(8)
	s_waitcnt lgkmcnt(0)
	s_barrier
	s_setprio 1
	s_waitcnt lgkmcnt(0)
	v_mfma_f32_16x16x32_bf16 v[124:127], v[152:155], v[184:187], v[124:127]
	v_mfma_f32_16x16x32_bf16 v[120:123], v[160:163], v[184:187], v[120:123]
	v_mfma_f32_16x16x32_bf16 v[108:111], v[152:155], v[192:195], v[108:111]
	v_mfma_f32_16x16x32_bf16 v[104:107], v[160:163], v[192:195], v[104:107]
	v_mfma_f32_16x16x32_bf16 v[92:95], v[152:155], v[200:203], v[92:95]
	v_mfma_f32_16x16x32_bf16 v[88:91], v[160:163], v[200:203], v[88:91]
	v_mfma_f32_16x16x32_bf16 v[76:79], v[152:155], v[208:211], v[76:79]
	v_mfma_f32_16x16x32_bf16 v[72:75], v[160:163], v[208:211], v[72:75]
	v_mfma_f32_16x16x32_bf16 v[124:127], v[156:159], v[188:191], v[124:127]
	v_mfma_f32_16x16x32_bf16 v[120:123], v[164:167], v[188:191], v[120:123]
	v_mfma_f32_16x16x32_bf16 v[108:111], v[156:159], v[196:199], v[108:111]
	v_mfma_f32_16x16x32_bf16 v[104:107], v[164:167], v[196:199], v[104:107]
	v_mfma_f32_16x16x32_bf16 v[92:95], v[156:159], v[204:207], v[92:95]
	v_mfma_f32_16x16x32_bf16 v[88:91], v[164:167], v[204:207], v[88:91]
	v_mfma_f32_16x16x32_bf16 v[76:79], v[156:159], v[212:215], v[76:79]
	v_mfma_f32_16x16x32_bf16 v[72:75], v[164:167], v[212:215], v[72:75]
	s_setprio 0
	s_setprio 1
	v_mfma_f32_16x16x32_bf16 v[116:119], v[168:171], v[184:187], v[116:119]
	v_mfma_f32_16x16x32_bf16 v[112:115], v[176:179], v[184:187], v[112:115]
	v_mfma_f32_16x16x32_bf16 v[100:103], v[168:171], v[192:195], v[100:103]
	v_mfma_f32_16x16x32_bf16 v[96:99], v[176:179], v[192:195], v[96:99]
	v_mfma_f32_16x16x32_bf16 v[84:87], v[168:171], v[200:203], v[84:87]
	v_mfma_f32_16x16x32_bf16 v[80:83], v[176:179], v[200:203], v[80:83]
	v_mfma_f32_16x16x32_bf16 v[68:71], v[168:171], v[208:211], v[68:71]
	v_mfma_f32_16x16x32_bf16 v[64:67], v[176:179], v[208:211], v[64:67]
	v_mfma_f32_16x16x32_bf16 v[116:119], v[172:175], v[188:191], v[116:119]
	v_mfma_f32_16x16x32_bf16 v[112:115], v[180:183], v[188:191], v[112:115]
	v_mfma_f32_16x16x32_bf16 v[100:103], v[172:175], v[196:199], v[100:103]
	v_mfma_f32_16x16x32_bf16 v[96:99], v[180:183], v[196:199], v[96:99]
	v_mfma_f32_16x16x32_bf16 v[84:87], v[172:175], v[204:207], v[84:87]
	v_mfma_f32_16x16x32_bf16 v[80:83], v[180:183], v[204:207], v[80:83]
	v_mfma_f32_16x16x32_bf16 v[68:71], v[172:175], v[212:215], v[68:71]
	v_mfma_f32_16x16x32_bf16 v[64:67], v[180:183], v[212:215], v[64:67]
	s_setprio 0
	s_barrier
	s_add_i32 s28, s50, s30
	v_lshl_add_u64 v[144:145], v[144:145], 0, s[12:13]
	s_mov_b32 m0, s28
	ds_read_b128 v[184:187], v151 offset:49152
	ds_read_b128 v[188:191], v151 offset:50176
	ds_read_b128 v[192:195], v151 offset:51200
	ds_read_b128 v[196:199], v151 offset:52224
	ds_read_b128 v[200:203], v151 offset:53248
	ds_read_b128 v[204:207], v151 offset:54272
	ds_read_b128 v[208:211], v151 offset:55296
	ds_read_b128 v[212:215], v151 offset:56320
	global_load_lds_dwordx4 v[144:145], off
	s_add_i32 m0, s28, 0x2000
	s_add_u32 s26, s26, 0x40080
	v_lshl_add_u64 v[144:145], v[216:217], 0, s[12:13]
	s_addc_u32 s27, s27, 0
	s_add_i32 s28, s51, s30
	global_load_lds_dwordx4 v[144:145], off
	v_lshl_add_u64 v[144:145], s[26:27], 0, v[132:133]
	s_mov_b32 m0, s28
	s_nop 0
	global_load_lds_dwordx4 v[144:145], off
	v_lshl_add_u64 v[144:145], s[26:27], 0, v[128:129]
	s_add_i32 m0, s28, 0x2000
	s_nop 0
	global_load_lds_dwordx4 v[144:145], off
	v_lshl_add_u64 v[144:145], v[218:219], 0, s[12:13]
	s_mov_b32 m0, s37
	s_nop 0
	global_load_lds_dwordx4 v[144:145], off
	v_lshl_add_u64 v[144:145], v[220:221], 0, s[12:13]
	s_mov_b32 m0, s38
	s_nop 0
	global_load_lds_dwordx4 v[144:145], off
	s_waitcnt vmcnt(8)
	s_waitcnt lgkmcnt(0)
	s_barrier
	s_setprio 1
	s_waitcnt lgkmcnt(0)
	v_mfma_f32_16x16x32_bf16 v[60:63], v[152:155], v[184:187], v[60:63]
	v_mfma_f32_16x16x32_bf16 v[56:59], v[160:163], v[184:187], v[56:59]
	v_mfma_f32_16x16x32_bf16 v[44:47], v[152:155], v[192:195], v[44:47]
	v_mfma_f32_16x16x32_bf16 v[40:43], v[160:163], v[192:195], v[40:43]
	v_mfma_f32_16x16x32_bf16 v[28:31], v[152:155], v[200:203], v[28:31]
	v_mfma_f32_16x16x32_bf16 v[24:27], v[160:163], v[200:203], v[24:27]
	v_mfma_f32_16x16x32_bf16 v[12:15], v[152:155], v[208:211], v[12:15]
	v_mfma_f32_16x16x32_bf16 v[8:11], v[160:163], v[208:211], v[8:11]
	v_mfma_f32_16x16x32_bf16 v[60:63], v[156:159], v[188:191], v[60:63]
	v_mfma_f32_16x16x32_bf16 v[56:59], v[164:167], v[188:191], v[56:59]
	v_mfma_f32_16x16x32_bf16 v[44:47], v[156:159], v[196:199], v[44:47]
	v_mfma_f32_16x16x32_bf16 v[40:43], v[164:167], v[196:199], v[40:43]
	v_mfma_f32_16x16x32_bf16 v[28:31], v[156:159], v[204:207], v[28:31]
	v_mfma_f32_16x16x32_bf16 v[24:27], v[164:167], v[204:207], v[24:27]
	v_mfma_f32_16x16x32_bf16 v[12:15], v[156:159], v[212:215], v[12:15]
	v_mfma_f32_16x16x32_bf16 v[8:11], v[164:167], v[212:215], v[8:11]
	s_setprio 0
	s_setprio 1
	v_mfma_f32_16x16x32_bf16 v[52:55], v[168:171], v[184:187], v[52:55]
	v_mfma_f32_16x16x32_bf16 v[48:51], v[176:179], v[184:187], v[48:51]
	v_mfma_f32_16x16x32_bf16 v[36:39], v[168:171], v[192:195], v[36:39]
	v_mfma_f32_16x16x32_bf16 v[32:35], v[176:179], v[192:195], v[32:35]
	v_mfma_f32_16x16x32_bf16 v[20:23], v[168:171], v[200:203], v[20:23]
	v_mfma_f32_16x16x32_bf16 v[16:19], v[176:179], v[200:203], v[16:19]
	v_mfma_f32_16x16x32_bf16 v[4:7], v[168:171], v[208:211], v[4:7]
	v_mfma_f32_16x16x32_bf16 v[0:3], v[176:179], v[208:211], v[0:3]
	v_mfma_f32_16x16x32_bf16 v[52:55], v[172:175], v[188:191], v[52:55]
	v_mfma_f32_16x16x32_bf16 v[48:51], v[180:183], v[188:191], v[48:51]
	v_mfma_f32_16x16x32_bf16 v[36:39], v[172:175], v[196:199], v[36:39]
	v_mfma_f32_16x16x32_bf16 v[32:35], v[180:183], v[196:199], v[32:35]
	v_mfma_f32_16x16x32_bf16 v[20:23], v[172:175], v[204:207], v[20:23]
	v_mfma_f32_16x16x32_bf16 v[16:19], v[180:183], v[204:207], v[16:19]
	v_mfma_f32_16x16x32_bf16 v[4:7], v[172:175], v[212:215], v[4:7]
	v_mfma_f32_16x16x32_bf16 v[0:3], v[180:183], v[212:215], v[0:3]
	s_setprio 0
	s_barrier
	s_add_i32 s49, s49, 2
	s_add_u32 s47, s47, 0x100
	s_addc_u32 s48, s48, 0
	s_add_u32 s24, s24, 0x100
	s_addc_u32 s25, s25, 0
	s_cmp_gt_u32 s49, 13
	s_cbranch_scc0 .LBB0_877
	s_and_b64 vcc, exec, s[14:15]
	s_cbranch_vccz .LBB0_880
	s_barrier
.LBB0_880:
	v_mul_f32_e32 v153, 0xbfb8aa3b, v124
	v_mul_f32_e32 v154, 0xbfb8aa3b, v120
	v_exp_f32_e32 v153, v153
	v_exp_f32_e32 v155, v154
	v_mul_f32_e32 v154, 0xbfb8aa3b, v125
	v_exp_f32_e32 v156, v154
	v_add_f32_e32 v153, 1.0, v153
	v_rcp_f32_e32 v154, v153
	v_add_f32_e32 v153, 1.0, v155
	v_add_f32_e32 v155, 1.0, v156
	v_rcp_f32_e32 v155, v155
	v_mul_f32_e32 v156, 0xbfb8aa3b, v121
	v_exp_f32_e32 v157, v156
	v_rcp_f32_e32 v156, v153
	v_pk_mul_f32 v[124:125], v[124:125], v[154:155]
	v_mul_f32_e32 v153, 0xbfb8aa3b, v127
	v_pk_mul_f32 v[116:117], v[124:125], v[116:117]
	v_add_f32_e32 v124, 1.0, v157
	v_mul_f32_e32 v125, 0xbfb8aa3b, v122
	v_rcp_f32_e32 v157, v124
	v_mul_f32_e32 v124, 0xbfb8aa3b, v126
	v_exp_f32_e32 v125, v125
	v_exp_f32_e32 v124, v124
	v_exp_f32_e32 v153, v153
	v_mul_f32_e32 v154, 0xbfb8aa3b, v123
	v_exp_f32_e32 v155, v154
	v_add_f32_e32 v125, 1.0, v125
	v_add_f32_e32 v124, 1.0, v124
	v_rcp_f32_e32 v154, v125
	v_add_f32_e32 v125, 1.0, v153
	v_rcp_f32_e32 v124, v124
	v_rcp_f32_e32 v125, v125
	v_add_f32_e32 v153, 1.0, v155
	v_rcp_f32_e32 v155, v153
	v_pk_mul_f32 v[120:121], v[120:121], v[156:157]
	v_lshl_or_b32 v144, s43, 7, v148
	v_pk_mul_f32 v[120:121], v[120:121], v[112:113]
	v_pk_mul_f32 v[112:113], v[126:127], v[124:125]
	s_mov_b64 s[24:25], s[10:11]
	v_ashrrev_i32_e32 v145, 31, v144
	v_pk_mul_f32 v[118:119], v[112:113], v[118:119]
	v_pk_mul_f32 v[112:113], v[122:123], v[154:155]
	v_lshl_add_u32 v152, s44, 8, v146
	v_lshl_add_u64 v[144:145], v[144:145], 1, s[24:25]
	v_pk_mul_f32 v[122:123], v[112:113], v[114:115]
	v_mad_i64_i32 v[124:125], s[24:25], v152, s42, v[144:145]
	v_cvt_pk_bf16_f32 v112, v116, v117
	v_cvt_pk_bf16_f32 v113, v118, v119
	v_cvt_pk_bf16_f32 v114, v120, v121
	v_cvt_pk_bf16_f32 v115, v122, v123
	global_store_dwordx4 v[124:125], v[112:115], off
	v_or_b32_e32 v116, 16, v152
	s_andn2_b64 vcc, exec, s[6:7]
	v_mul_f32_e32 v112, 0xbfb8aa3b, v108
	v_mul_f32_e32 v113, 0xbfb8aa3b, v104
	v_mul_f32_e32 v114, 0xbfb8aa3b, v109
	v_exp_f32_e32 v112, v112
	v_exp_f32_e32 v113, v113
	v_exp_f32_e32 v114, v114
	s_mov_b64 s[6:7], -1
	v_add_f32_e32 v112, 1.0, v112
	v_add_f32_e32 v115, 1.0, v113
	v_add_f32_e32 v113, 1.0, v114
	v_rcp_f32_e32 v112, v112
	v_rcp_f32_e32 v113, v113
	v_mul_f32_e32 v114, 0xbfb8aa3b, v105
	v_exp_f32_e32 v117, v114
	v_rcp_f32_e32 v114, v115
	v_pk_mul_f32 v[108:109], v[108:109], v[112:113]
	v_mul_f32_e32 v112, 0xbfb8aa3b, v111
	v_pk_mul_f32 v[100:101], v[108:109], v[100:101]
	v_add_f32_e32 v108, 1.0, v117
	v_rcp_f32_e32 v115, v108
	v_mul_f32_e32 v109, 0xbfb8aa3b, v106
	v_mul_f32_e32 v108, 0xbfb8aa3b, v110
	v_exp_f32_e32 v109, v109
	v_exp_f32_e32 v108, v108
	v_exp_f32_e32 v113, v112
	v_mul_f32_e32 v112, 0xbfb8aa3b, v107
	v_pk_mul_f32 v[104:105], v[104:105], v[114:115]
	v_exp_f32_e32 v114, v112
	v_add_f32_e32 v109, 1.0, v109
	v_add_f32_e32 v108, 1.0, v108
	v_rcp_f32_e32 v112, v109
	v_add_f32_e32 v109, 1.0, v113
	v_rcp_f32_e32 v108, v108
	v_rcp_f32_e32 v109, v109
	v_add_f32_e32 v113, 1.0, v114
	v_rcp_f32_e32 v113, v113
	v_pk_mul_f32 v[104:105], v[104:105], v[96:97]
	v_pk_mul_f32 v[96:97], v[110:111], v[108:109]
	v_mad_i64_i32 v[108:109], s[24:25], v116, s42, v[144:145]
	v_pk_mul_f32 v[102:103], v[96:97], v[102:103]
	v_pk_mul_f32 v[96:97], v[106:107], v[112:113]
	s_nop 0
	v_pk_mul_f32 v[106:107], v[96:97], v[98:99]
	v_cvt_pk_bf16_f32 v96, v100, v101
	v_cvt_pk_bf16_f32 v97, v102, v103
	v_cvt_pk_bf16_f32 v98, v104, v105
	v_cvt_pk_bf16_f32 v99, v106, v107
	global_store_dwordx4 v[108:109], v[96:99], off
	v_or_b32_e32 v100, 32, v152
	s_nop 0
	v_mul_f32_e32 v96, 0xbfb8aa3b, v92
	v_mul_f32_e32 v97, 0xbfb8aa3b, v88
	v_mul_f32_e32 v98, 0xbfb8aa3b, v93
	v_exp_f32_e32 v96, v96
	v_exp_f32_e32 v97, v97
	v_exp_f32_e32 v98, v98
	v_add_f32_e32 v96, 1.0, v96
	v_add_f32_e32 v99, 1.0, v97
	v_add_f32_e32 v97, 1.0, v98
	v_rcp_f32_e32 v96, v96
	v_rcp_f32_e32 v97, v97
	v_mul_f32_e32 v98, 0xbfb8aa3b, v89
	v_exp_f32_e32 v101, v98
	v_rcp_f32_e32 v98, v99
	v_pk_mul_f32 v[92:93], v[92:93], v[96:97]
	v_mul_f32_e32 v96, 0xbfb8aa3b, v95
	v_pk_mul_f32 v[84:85], v[92:93], v[84:85]
	v_add_f32_e32 v92, 1.0, v101
	v_rcp_f32_e32 v99, v92
	v_mul_f32_e32 v93, 0xbfb8aa3b, v90
	v_mul_f32_e32 v92, 0xbfb8aa3b, v94
	v_exp_f32_e32 v93, v93
	v_exp_f32_e32 v92, v92
	v_exp_f32_e32 v97, v96
	v_mul_f32_e32 v96, 0xbfb8aa3b, v91
	v_pk_mul_f32 v[88:89], v[88:89], v[98:99]
	v_exp_f32_e32 v98, v96
	v_add_f32_e32 v93, 1.0, v93
	v_add_f32_e32 v92, 1.0, v92
	v_rcp_f32_e32 v96, v93
	v_add_f32_e32 v93, 1.0, v97
	v_rcp_f32_e32 v92, v92
	v_rcp_f32_e32 v93, v93
	v_add_f32_e32 v97, 1.0, v98
	v_rcp_f32_e32 v97, v97
	v_pk_mul_f32 v[88:89], v[88:89], v[80:81]
	v_pk_mul_f32 v[80:81], v[94:95], v[92:93]
	v_mad_i64_i32 v[92:93], s[24:25], v100, s42, v[144:145]
	v_pk_mul_f32 v[86:87], v[80:81], v[86:87]
	v_pk_mul_f32 v[80:81], v[90:91], v[96:97]
	s_nop 0
	v_pk_mul_f32 v[90:91], v[80:81], v[82:83]
	v_cvt_pk_bf16_f32 v80, v84, v85
	v_cvt_pk_bf16_f32 v81, v86, v87
	v_cvt_pk_bf16_f32 v82, v88, v89
	v_cvt_pk_bf16_f32 v83, v90, v91
	global_store_dwordx4 v[92:93], v[80:83], off
	v_or_b32_e32 v84, 48, v152
	s_nop 0
	v_mul_f32_e32 v80, 0xbfb8aa3b, v76
	v_mul_f32_e32 v81, 0xbfb8aa3b, v72
	v_mul_f32_e32 v82, 0xbfb8aa3b, v77
	v_exp_f32_e32 v80, v80
	v_exp_f32_e32 v81, v81
	v_exp_f32_e32 v82, v82
	v_add_f32_e32 v80, 1.0, v80
	v_add_f32_e32 v83, 1.0, v81
	v_add_f32_e32 v81, 1.0, v82
	v_rcp_f32_e32 v80, v80
	v_rcp_f32_e32 v81, v81
	v_mul_f32_e32 v82, 0xbfb8aa3b, v73
	v_exp_f32_e32 v85, v82
	v_rcp_f32_e32 v82, v83
	v_pk_mul_f32 v[76:77], v[76:77], v[80:81]
	v_mul_f32_e32 v80, 0xbfb8aa3b, v79
	v_pk_mul_f32 v[68:69], v[76:77], v[68:69]
	v_add_f32_e32 v76, 1.0, v85
	v_rcp_f32_e32 v83, v76
	v_mul_f32_e32 v77, 0xbfb8aa3b, v74
	v_mul_f32_e32 v76, 0xbfb8aa3b, v78
	v_exp_f32_e32 v77, v77
	v_exp_f32_e32 v76, v76
	v_exp_f32_e32 v81, v80
	v_mul_f32_e32 v80, 0xbfb8aa3b, v75
	v_pk_mul_f32 v[72:73], v[72:73], v[82:83]
	v_exp_f32_e32 v82, v80
	v_add_f32_e32 v77, 1.0, v77
	v_add_f32_e32 v76, 1.0, v76
	v_rcp_f32_e32 v80, v77
	v_add_f32_e32 v77, 1.0, v81
	v_rcp_f32_e32 v76, v76
	v_rcp_f32_e32 v77, v77
	v_add_f32_e32 v81, 1.0, v82
	v_rcp_f32_e32 v81, v81
	v_pk_mul_f32 v[72:73], v[72:73], v[64:65]
	v_pk_mul_f32 v[64:65], v[78:79], v[76:77]
	v_mad_i64_i32 v[76:77], s[24:25], v84, s42, v[144:145]
	v_pk_mul_f32 v[70:71], v[64:65], v[70:71]
	v_pk_mul_f32 v[64:65], v[74:75], v[80:81]
	s_nop 0
	v_pk_mul_f32 v[74:75], v[64:65], v[66:67]
	v_cvt_pk_bf16_f32 v64, v68, v69
	v_cvt_pk_bf16_f32 v65, v70, v71
	v_cvt_pk_bf16_f32 v66, v72, v73
	v_cvt_pk_bf16_f32 v67, v74, v75
	global_store_dwordx4 v[76:77], v[64:67], off
	v_add_u32_e32 v68, 0x80, v152
	s_nop 0
	v_mul_f32_e32 v64, 0xbfb8aa3b, v60
	v_mul_f32_e32 v65, 0xbfb8aa3b, v56
	v_mul_f32_e32 v66, 0xbfb8aa3b, v61
	v_exp_f32_e32 v64, v64
	v_exp_f32_e32 v65, v65
	v_exp_f32_e32 v66, v66
	v_add_f32_e32 v64, 1.0, v64
	v_add_f32_e32 v67, 1.0, v65
	v_add_f32_e32 v65, 1.0, v66
	v_rcp_f32_e32 v64, v64
	v_rcp_f32_e32 v65, v65
	v_mul_f32_e32 v66, 0xbfb8aa3b, v57
	v_exp_f32_e32 v69, v66
	v_rcp_f32_e32 v66, v67
	v_pk_mul_f32 v[60:61], v[60:61], v[64:65]
	v_mul_f32_e32 v64, 0xbfb8aa3b, v63
	v_pk_mul_f32 v[52:53], v[60:61], v[52:53]
	v_add_f32_e32 v60, 1.0, v69
	v_rcp_f32_e32 v67, v60
	v_mul_f32_e32 v61, 0xbfb8aa3b, v58
	v_mul_f32_e32 v60, 0xbfb8aa3b, v62
	v_exp_f32_e32 v61, v61
	v_exp_f32_e32 v60, v60
	v_exp_f32_e32 v65, v64
	v_mul_f32_e32 v64, 0xbfb8aa3b, v59
	v_pk_mul_f32 v[56:57], v[56:57], v[66:67]
	v_exp_f32_e32 v66, v64
	v_add_f32_e32 v61, 1.0, v61
	v_add_f32_e32 v60, 1.0, v60
	v_rcp_f32_e32 v64, v61
	v_add_f32_e32 v61, 1.0, v65
	v_rcp_f32_e32 v60, v60
	v_rcp_f32_e32 v61, v61
	v_add_f32_e32 v65, 1.0, v66
	v_rcp_f32_e32 v65, v65
	v_pk_mul_f32 v[56:57], v[56:57], v[48:49]
	v_pk_mul_f32 v[48:49], v[62:63], v[60:61]
	v_mad_i64_i32 v[60:61], s[24:25], v68, s42, v[144:145]
	v_pk_mul_f32 v[54:55], v[48:49], v[54:55]
	v_pk_mul_f32 v[48:49], v[58:59], v[64:65]
	s_nop 0
	v_pk_mul_f32 v[58:59], v[48:49], v[50:51]
	v_cvt_pk_bf16_f32 v48, v52, v53
	v_cvt_pk_bf16_f32 v49, v54, v55
	v_cvt_pk_bf16_f32 v50, v56, v57
	v_cvt_pk_bf16_f32 v51, v58, v59
	global_store_dwordx4 v[60:61], v[48:51], off
	v_add_u32_e32 v52, 0x90, v152
	s_nop 0
	v_mul_f32_e32 v48, 0xbfb8aa3b, v44
	v_mul_f32_e32 v49, 0xbfb8aa3b, v40
	v_mul_f32_e32 v50, 0xbfb8aa3b, v45
	v_exp_f32_e32 v48, v48
	v_exp_f32_e32 v49, v49
	v_exp_f32_e32 v50, v50
	v_add_f32_e32 v48, 1.0, v48
	v_add_f32_e32 v51, 1.0, v49
	v_add_f32_e32 v49, 1.0, v50
	v_rcp_f32_e32 v48, v48
	v_rcp_f32_e32 v49, v49
	v_mul_f32_e32 v50, 0xbfb8aa3b, v41
	v_exp_f32_e32 v53, v50
	v_rcp_f32_e32 v50, v51
	v_pk_mul_f32 v[44:45], v[44:45], v[48:49]
	v_mul_f32_e32 v48, 0xbfb8aa3b, v47
	v_pk_mul_f32 v[36:37], v[44:45], v[36:37]
	v_add_f32_e32 v44, 1.0, v53
	v_rcp_f32_e32 v51, v44
	v_mul_f32_e32 v45, 0xbfb8aa3b, v42
	v_mul_f32_e32 v44, 0xbfb8aa3b, v46
	v_exp_f32_e32 v45, v45
	v_exp_f32_e32 v44, v44
	v_exp_f32_e32 v49, v48
	v_mul_f32_e32 v48, 0xbfb8aa3b, v43
	v_pk_mul_f32 v[40:41], v[40:41], v[50:51]
	v_exp_f32_e32 v50, v48
	v_add_f32_e32 v45, 1.0, v45
	v_add_f32_e32 v44, 1.0, v44
	v_rcp_f32_e32 v48, v45
	v_add_f32_e32 v45, 1.0, v49
	v_rcp_f32_e32 v44, v44
	v_rcp_f32_e32 v45, v45
	v_add_f32_e32 v49, 1.0, v50
	v_rcp_f32_e32 v49, v49
	v_pk_mul_f32 v[40:41], v[40:41], v[32:33]
	v_pk_mul_f32 v[32:33], v[46:47], v[44:45]
	v_mad_i64_i32 v[44:45], s[24:25], v52, s42, v[144:145]
	v_pk_mul_f32 v[38:39], v[32:33], v[38:39]
	v_pk_mul_f32 v[32:33], v[42:43], v[48:49]
	s_nop 0
	v_pk_mul_f32 v[42:43], v[32:33], v[34:35]
	v_cvt_pk_bf16_f32 v32, v36, v37
	v_cvt_pk_bf16_f32 v33, v38, v39
	v_cvt_pk_bf16_f32 v34, v40, v41
	v_cvt_pk_bf16_f32 v35, v42, v43
	global_store_dwordx4 v[44:45], v[32:35], off
	v_add_u32_e32 v36, 0xa0, v152
	s_nop 0
	v_mul_f32_e32 v32, 0xbfb8aa3b, v28
	v_mul_f32_e32 v33, 0xbfb8aa3b, v24
	v_mul_f32_e32 v34, 0xbfb8aa3b, v29
	v_exp_f32_e32 v32, v32
	v_exp_f32_e32 v33, v33
	v_exp_f32_e32 v34, v34
	v_add_f32_e32 v32, 1.0, v32
	v_add_f32_e32 v35, 1.0, v33
	v_add_f32_e32 v33, 1.0, v34
	v_rcp_f32_e32 v32, v32
	v_rcp_f32_e32 v33, v33
	v_mul_f32_e32 v34, 0xbfb8aa3b, v25
	v_exp_f32_e32 v37, v34
	v_rcp_f32_e32 v34, v35
	v_pk_mul_f32 v[28:29], v[28:29], v[32:33]
	v_mul_f32_e32 v32, 0xbfb8aa3b, v31
	v_pk_mul_f32 v[20:21], v[28:29], v[20:21]
	v_add_f32_e32 v28, 1.0, v37
	v_rcp_f32_e32 v35, v28
	v_mul_f32_e32 v29, 0xbfb8aa3b, v26
	v_mul_f32_e32 v28, 0xbfb8aa3b, v30
	v_exp_f32_e32 v29, v29
	v_exp_f32_e32 v28, v28
	v_exp_f32_e32 v33, v32
	v_mul_f32_e32 v32, 0xbfb8aa3b, v27
	v_pk_mul_f32 v[24:25], v[24:25], v[34:35]
	v_exp_f32_e32 v34, v32
	v_add_f32_e32 v29, 1.0, v29
	v_add_f32_e32 v28, 1.0, v28
	v_rcp_f32_e32 v32, v29
	v_add_f32_e32 v29, 1.0, v33
	v_rcp_f32_e32 v28, v28
	v_rcp_f32_e32 v29, v29
	v_add_f32_e32 v33, 1.0, v34
	v_rcp_f32_e32 v33, v33
	v_pk_mul_f32 v[24:25], v[24:25], v[16:17]
	v_pk_mul_f32 v[16:17], v[30:31], v[28:29]
	v_mad_i64_i32 v[28:29], s[24:25], v36, s42, v[144:145]
	v_pk_mul_f32 v[22:23], v[16:17], v[22:23]
	v_pk_mul_f32 v[16:17], v[26:27], v[32:33]
	s_nop 0
	v_pk_mul_f32 v[26:27], v[16:17], v[18:19]
	v_cvt_pk_bf16_f32 v16, v20, v21
	v_cvt_pk_bf16_f32 v17, v22, v23
	v_cvt_pk_bf16_f32 v18, v24, v25
	v_cvt_pk_bf16_f32 v19, v26, v27
	global_store_dwordx4 v[28:29], v[16:19], off
	v_add_u32_e32 v20, 0xb0, v152
	s_nop 0
	v_mul_f32_e32 v16, 0xbfb8aa3b, v12
	v_mul_f32_e32 v17, 0xbfb8aa3b, v8
	v_mul_f32_e32 v18, 0xbfb8aa3b, v13
	v_exp_f32_e32 v16, v16
	v_exp_f32_e32 v17, v17
	v_exp_f32_e32 v18, v18
	v_add_f32_e32 v16, 1.0, v16
	v_add_f32_e32 v19, 1.0, v17
	v_add_f32_e32 v17, 1.0, v18
	v_rcp_f32_e32 v16, v16
	v_rcp_f32_e32 v17, v17
	v_mul_f32_e32 v18, 0xbfb8aa3b, v9
	v_exp_f32_e32 v21, v18
	v_rcp_f32_e32 v18, v19
	v_pk_mul_f32 v[12:13], v[12:13], v[16:17]
	v_mul_f32_e32 v16, 0xbfb8aa3b, v15
	v_pk_mul_f32 v[4:5], v[12:13], v[4:5]
	v_add_f32_e32 v12, 1.0, v21
	v_rcp_f32_e32 v19, v12
	v_mul_f32_e32 v13, 0xbfb8aa3b, v10
	v_mul_f32_e32 v12, 0xbfb8aa3b, v14
	v_exp_f32_e32 v13, v13
	v_exp_f32_e32 v12, v12
	v_exp_f32_e32 v17, v16
	v_mul_f32_e32 v16, 0xbfb8aa3b, v11
	v_pk_mul_f32 v[8:9], v[8:9], v[18:19]
	v_exp_f32_e32 v18, v16
	v_add_f32_e32 v13, 1.0, v13
	v_add_f32_e32 v12, 1.0, v12
	v_rcp_f32_e32 v16, v13
	v_add_f32_e32 v13, 1.0, v17
	v_rcp_f32_e32 v12, v12
	v_rcp_f32_e32 v13, v13
	v_add_f32_e32 v17, 1.0, v18
	v_rcp_f32_e32 v17, v17
	v_pk_mul_f32 v[8:9], v[8:9], v[0:1]
	v_pk_mul_f32 v[0:1], v[14:15], v[12:13]
	v_mad_i64_i32 v[12:13], s[24:25], v20, s42, v[144:145]
	v_pk_mul_f32 v[6:7], v[0:1], v[6:7]
	v_pk_mul_f32 v[0:1], v[10:11], v[16:17]
	s_nop 0
	v_pk_mul_f32 v[10:11], v[0:1], v[2:3]
	v_cvt_pk_bf16_f32 v0, v4, v5
	v_cvt_pk_bf16_f32 v1, v6, v7
	v_cvt_pk_bf16_f32 v2, v8, v9
	v_cvt_pk_bf16_f32 v3, v10, v11
	global_store_dwordx4 v[12:13], v[0:3], off
	s_cbranch_vccnz .LBB0_873
	s_andn2_b64 vcc, exec, s[8:9]
	s_cbranch_vccnz .LBB0_872
	s_mov_b32 s100, 1
	s_branch .LBB0_872

.LBB0_939:
	s_add_u32 s14, s8, 0xd800000
	s_addc_u32 s15, s9, 0
	s_lshl_b32 s8, s16, 5
	s_mov_b64 s[16:17], 0x80
	s_and_b32 s21, s8, 0x60
	s_add_i32 m0, s40, 0x18000
	v_lshl_add_u64 v[6:7], v[6:7], 0, s[16:17]
	s_lshl_b32 s18, s11, 13
	s_lshl_b32 s19, s21, 7
	s_waitcnt vmcnt(2)
	s_barrier
	global_load_lds_dwordx4 v[6:7], off
	v_lshl_add_u64 v[4:5], v[4:5], 0, s[16:17]
	s_add_i32 m0, s40, 0x1a000
	s_add_i32 s45, s40, 0x8000
	s_add_i32 s46, s40, 0xa000
	global_load_lds_dwordx4 v[4:5], off
	v_lshl_add_u64 v[0:1], v[0:1], 0, s[16:17]
	s_mov_b32 m0, s45
	s_add_u32 s8, s34, 0xb0080
	global_load_lds_dwordx4 v[0:1], off
	v_lshl_add_u64 v[0:1], v[2:3], 0, s[16:17]
	s_mov_b32 m0, s46
	s_addc_u32 s9, s35, 0
	global_load_lds_dwordx4 v[0:1], off
	s_add_i32 m0, s40, 0x1c000
	v_lshl_add_u64 v[0:1], s[8:9], 0, v[132:133]
	global_load_lds_dwordx4 v[0:1], off
	v_lshl_add_u64 v[0:1], s[8:9], 0, v[128:129]
	s_add_i32 m0, s40, 0x1e000
	s_cmpk_lt_u32 s10, 0x100
	global_load_lds_dwordx4 v[0:1], off
	v_lshrrev_b32_e32 v1, 1, v8
	v_and_b32_e32 v1, 24, v1
	v_and_b32_e32 v0, 15, v8
	v_lshlrev_b32_e32 v2, 1, v1
	v_lshl_or_b32 v144, s11, 6, v0
	v_lshl_or_b32 v0, v0, 6, v2
	v_lshlrev_b32_e32 v2, 2, v8
	v_and_b32_e32 v2, 32, v2
	v_bitop3_b32 v3, v0, s18, v2 bitop3:0xde
	v_bitop3_b32 v145, s19, v0, v2 bitop3:0xf6
	v_or_b32_e32 v146, s21, v1
	v_lshrrev_b32_e32 v1, 1, v9
	v_mul_lo_u32 v0, v10, s20
	s_mov_b32 s21, 0xb000
	v_mad_u64_u32 v[0:1], s[10:11], v1, s21, v[0:1]
	v_or_b32_e32 v0, v0, v11
	s_mov_b64 s[8:9], 0xb0080
	v_add_lshl_u32 v0, v0, v12, 1
	v_mov_b32_e32 v1, v133
	v_lshl_add_u64 v[136:137], v[0:1], 0, s[8:9]
	v_lshrrev_b32_e32 v1, 1, v14
	v_mul_lo_u32 v0, v13, s20
	v_mad_u64_u32 v[0:1], s[10:11], v1, s21, v[0:1]
	s_waitcnt vmcnt(6)
	v_or_b32_e32 v0, v0, v15
	s_cselect_b64 s[18:19], -1, 0
	v_add_lshl_u32 v0, v0, v16, 1
	v_mov_b32_e32 v1, v133
	s_add_i32 s47, 0, 0x10000
	s_add_i32 s48, 0, 0x14000
	v_lshl_add_u64 v[138:139], v[0:1], 0, s[8:9]
	v_mov_b64_e32 v[140:141], 0x200
	v_mov_b64_e32 v[142:143], 0x1ff
	v_add_u32_e32 v147, s47, v145
	v_add_u32_e32 v148, s48, v145
	v_add_u32_e32 v149, 0, v3
	s_mov_b64 s[20:21], 0x40000
	s_mov_b32 s49, 0x40000
	s_mov_b64 s[22:23], 0x48000
	s_mov_b32 s50, 0x48000
	s_mov_b64 s[24:25], 0x50000
	s_mov_b32 s51, 0x50000
	s_mov_b64 s[26:27], 0x58000
	s_mov_b32 s52, 0x58000
	v_readlane_b32 s55, v254, 11
	s_mov_b32 s56, s92
	s_barrier
	s_mov_b32 s100, 0
	s_branch .LBB0_942

.LBB0_948:
	s_add_u32 s57, s34, 0x100
	v_mov_b32_e32 v0, 0
	s_addc_u32 s58, s35, 0
	s_mov_b32 s59, -2
	v_mov_b32_e32 v1, v0
	v_mov_b32_e32 v2, v0
	v_mov_b32_e32 v3, v0
	v_mov_b32_e32 v4, v0
	v_mov_b32_e32 v5, v0
	v_mov_b32_e32 v6, v0
	v_mov_b32_e32 v7, v0
	v_mov_b32_e32 v8, v0
	v_mov_b32_e32 v9, v0
	v_mov_b32_e32 v10, v0
	v_mov_b32_e32 v11, v0
	v_mov_b32_e32 v12, v0
	v_mov_b32_e32 v13, v0
	v_mov_b32_e32 v14, v0
	v_mov_b32_e32 v15, v0
	v_mov_b32_e32 v24, v0
	v_mov_b32_e32 v25, v0
	v_mov_b32_e32 v26, v0
	v_mov_b32_e32 v27, v0
	v_mov_b32_e32 v28, v0
	v_mov_b32_e32 v29, v0
	v_mov_b32_e32 v30, v0
	v_mov_b32_e32 v31, v0
	v_mov_b32_e32 v40, v0
	v_mov_b32_e32 v41, v0
	v_mov_b32_e32 v42, v0
	v_mov_b32_e32 v43, v0
	v_mov_b32_e32 v44, v0
	v_mov_b32_e32 v45, v0
	v_mov_b32_e32 v46, v0
	v_mov_b32_e32 v47, v0
	v_mov_b32_e32 v16, v0
	v_mov_b32_e32 v17, v0
	v_mov_b32_e32 v18, v0
	v_mov_b32_e32 v19, v0
	v_mov_b32_e32 v20, v0
	v_mov_b32_e32 v21, v0
	v_mov_b32_e32 v22, v0
	v_mov_b32_e32 v23, v0
	v_mov_b32_e32 v32, v0
	v_mov_b32_e32 v33, v0
	v_mov_b32_e32 v34, v0
	v_mov_b32_e32 v35, v0
	v_mov_b32_e32 v36, v0
	v_mov_b32_e32 v37, v0
	v_mov_b32_e32 v38, v0
	v_mov_b32_e32 v39, v0
	v_mov_b32_e32 v48, v0
	v_mov_b32_e32 v49, v0
	v_mov_b32_e32 v50, v0
	v_mov_b32_e32 v51, v0
	v_mov_b32_e32 v52, v0
	v_mov_b32_e32 v53, v0
	v_mov_b32_e32 v54, v0
	v_mov_b32_e32 v55, v0
	v_mov_b32_e32 v56, v0
	v_mov_b32_e32 v57, v0
	v_mov_b32_e32 v58, v0
	v_mov_b32_e32 v59, v0
	v_mov_b32_e32 v60, v0
	v_mov_b32_e32 v61, v0
	v_mov_b32_e32 v62, v0
	v_mov_b32_e32 v63, v0
	v_mov_b32_e32 v64, v0
	v_mov_b32_e32 v65, v0
	v_mov_b32_e32 v66, v0
	v_mov_b32_e32 v67, v0
	v_mov_b32_e32 v68, v0
	v_mov_b32_e32 v69, v0
	v_mov_b32_e32 v70, v0
	v_mov_b32_e32 v71, v0
	v_mov_b32_e32 v72, v0
	v_mov_b32_e32 v73, v0
	v_mov_b32_e32 v74, v0
	v_mov_b32_e32 v75, v0
	v_mov_b32_e32 v76, v0
	v_mov_b32_e32 v77, v0
	v_mov_b32_e32 v78, v0
	v_mov_b32_e32 v79, v0
	v_mov_b32_e32 v88, v0
	v_mov_b32_e32 v89, v0
	v_mov_b32_e32 v90, v0
	v_mov_b32_e32 v91, v0
	v_mov_b32_e32 v92, v0
	v_mov_b32_e32 v93, v0
	v_mov_b32_e32 v94, v0
	v_mov_b32_e32 v95, v0
	v_mov_b32_e32 v104, v0
	v_mov_b32_e32 v105, v0
	v_mov_b32_e32 v106, v0
	v_mov_b32_e32 v107, v0
	v_mov_b32_e32 v108, v0
	v_mov_b32_e32 v109, v0
	v_mov_b32_e32 v110, v0
	v_mov_b32_e32 v111, v0
	v_mov_b32_e32 v80, v0
	v_mov_b32_e32 v81, v0
	v_mov_b32_e32 v82, v0
	v_mov_b32_e32 v83, v0
	v_mov_b32_e32 v84, v0
	v_mov_b32_e32 v85, v0
	v_mov_b32_e32 v86, v0
	v_mov_b32_e32 v87, v0
	v_mov_b32_e32 v96, v0
	v_mov_b32_e32 v97, v0
	v_mov_b32_e32 v98, v0
	v_mov_b32_e32 v99, v0
	v_mov_b32_e32 v100, v0
	v_mov_b32_e32 v101, v0
	v_mov_b32_e32 v102, v0
	v_mov_b32_e32 v103, v0
	v_mov_b32_e32 v112, v0
	v_mov_b32_e32 v113, v0
	v_mov_b32_e32 v114, v0
	v_mov_b32_e32 v115, v0
	v_mov_b32_e32 v116, v0
	v_mov_b32_e32 v117, v0
	v_mov_b32_e32 v118, v0
	v_mov_b32_e32 v119, v0
	v_mov_b32_e32 v120, v0
	v_mov_b32_e32 v121, v0
	v_mov_b32_e32 v122, v0
	v_mov_b32_e32 v123, v0
	v_mov_b32_e32 v124, v0
	v_mov_b32_e32 v125, v0
	v_mov_b32_e32 v126, v0
	v_mov_b32_e32 v127, v0
	s_cmp_eq_u32 s100, 1
	s_cbranch_scc0 .Lgemm_nobar_940
	s_mov_b32 s100, 0
	s_barrier
.Lgemm_nobar_940:
.LBB0_949:
	ds_read_b128 v[150:153], v147
	ds_read_b128 v[154:157], v147 offset:1024
	ds_read_b128 v[158:161], v147 offset:2048
	ds_read_b128 v[162:165], v147 offset:3072
	ds_read_b128 v[166:169], v148
	ds_read_b128 v[170:173], v148 offset:1024
	ds_read_b128 v[174:177], v148 offset:2048
	ds_read_b128 v[178:181], v148 offset:3072
	s_add_u32 s34, s30, 0x100
	s_addc_u32 s35, s31, 0
	s_cmp_eq_u32 s59, 40
	s_cselect_b32 s39, s11, s35
	s_cselect_b32 s38, s10, s34
	s_cselect_b32 s37, s29, s58
	s_cselect_b32 s36, s28, s57
	v_lshl_add_u64 v[214:215], s[30:31], 0, v[138:139]
	s_add_i32 m0, s40, 0xc000
	ds_read_b128 v[182:185], v149
	ds_read_b128 v[186:189], v149 offset:1024
	ds_read_b128 v[190:193], v149 offset:2048
	ds_read_b128 v[194:197], v149 offset:3072
	ds_read_b128 v[198:201], v149 offset:4096
	ds_read_b128 v[202:205], v149 offset:5120
	ds_read_b128 v[206:209], v149 offset:6144
	ds_read_b128 v[210:213], v149 offset:7168
	global_load_lds_dwordx4 v[214:215], off
	v_lshl_add_u64 v[214:215], s[30:31], 0, v[136:137]
	s_add_i32 m0, s40, 0xe000
	s_nop 0
	global_load_lds_dwordx4 v[214:215], off
	s_waitcnt vmcnt(8)
	s_waitcnt lgkmcnt(0)
	s_barrier
	s_setprio 1
	s_waitcnt lgkmcnt(0)
	v_mfma_f32_16x16x32_bf16 v[124:127], v[150:153], v[182:185], v[124:127]
	v_mfma_f32_16x16x32_bf16 v[120:123], v[158:161], v[182:185], v[120:123]
	v_mfma_f32_16x16x32_bf16 v[116:119], v[150:153], v[190:193], v[116:119]
	v_mfma_f32_16x16x32_bf16 v[112:115], v[158:161], v[190:193], v[112:115]
	v_mfma_f32_16x16x32_bf16 v[100:103], v[150:153], v[198:201], v[100:103]
	v_mfma_f32_16x16x32_bf16 v[96:99], v[158:161], v[198:201], v[96:99]
	v_mfma_f32_16x16x32_bf16 v[84:87], v[150:153], v[206:209], v[84:87]
	v_mfma_f32_16x16x32_bf16 v[80:83], v[158:161], v[206:209], v[80:83]
	v_mfma_f32_16x16x32_bf16 v[124:127], v[154:157], v[186:189], v[124:127]
	v_mfma_f32_16x16x32_bf16 v[120:123], v[162:165], v[186:189], v[120:123]
	v_mfma_f32_16x16x32_bf16 v[116:119], v[154:157], v[194:197], v[116:119]
	v_mfma_f32_16x16x32_bf16 v[112:115], v[162:165], v[194:197], v[112:115]
	v_mfma_f32_16x16x32_bf16 v[100:103], v[154:157], v[202:205], v[100:103]
	v_mfma_f32_16x16x32_bf16 v[96:99], v[162:165], v[202:205], v[96:99]
	v_mfma_f32_16x16x32_bf16 v[84:87], v[154:157], v[210:213], v[84:87]
	v_mfma_f32_16x16x32_bf16 v[80:83], v[162:165], v[210:213], v[80:83]
	s_setprio 0
	s_setprio 1
	v_mfma_f32_16x16x32_bf16 v[108:111], v[166:169], v[182:185], v[108:111]
	v_mfma_f32_16x16x32_bf16 v[104:107], v[174:177], v[182:185], v[104:107]
	v_mfma_f32_16x16x32_bf16 v[92:95], v[166:169], v[190:193], v[92:95]
	v_mfma_f32_16x16x32_bf16 v[88:91], v[174:177], v[190:193], v[88:91]
	v_mfma_f32_16x16x32_bf16 v[76:79], v[166:169], v[198:201], v[76:79]
	v_mfma_f32_16x16x32_bf16 v[72:75], v[174:177], v[198:201], v[72:75]
	v_mfma_f32_16x16x32_bf16 v[68:71], v[166:169], v[206:209], v[68:71]
	v_mfma_f32_16x16x32_bf16 v[64:67], v[174:177], v[206:209], v[64:67]
	v_mfma_f32_16x16x32_bf16 v[108:111], v[170:173], v[186:189], v[108:111]
	v_mfma_f32_16x16x32_bf16 v[104:107], v[178:181], v[186:189], v[104:107]
	v_mfma_f32_16x16x32_bf16 v[92:95], v[170:173], v[194:197], v[92:95]
	v_mfma_f32_16x16x32_bf16 v[88:91], v[178:181], v[194:197], v[88:91]
	v_mfma_f32_16x16x32_bf16 v[76:79], v[170:173], v[202:205], v[76:79]
	v_mfma_f32_16x16x32_bf16 v[72:75], v[178:181], v[202:205], v[72:75]
	v_mfma_f32_16x16x32_bf16 v[68:71], v[170:173], v[210:213], v[68:71]
	v_mfma_f32_16x16x32_bf16 v[64:67], v[178:181], v[210:213], v[64:67]
	s_setprio 0
	s_barrier
	s_add_i32 s30, s47, s33
	v_lshl_add_u64 v[214:215], s[36:37], 0, v[132:133]
	s_mov_b32 m0, s30
	ds_read_b128 v[182:185], v149 offset:16384
	ds_read_b128 v[186:189], v149 offset:17408
	ds_read_b128 v[190:193], v149 offset:18432
	ds_read_b128 v[194:197], v149 offset:19456
	ds_read_b128 v[198:201], v149 offset:20480
	ds_read_b128 v[202:205], v149 offset:21504
	ds_read_b128 v[206:209], v149 offset:22528
	ds_read_b128 v[210:213], v149 offset:23552
	global_load_lds_dwordx4 v[214:215], off
	s_add_i32 m0, s30, 0x2000
	s_add_u32 s30, s36, 0xb0000
	v_lshl_add_u64 v[216:217], s[36:37], 0, v[128:129]
	s_addc_u32 s31, s37, 0
	s_add_i32 s60, s48, s33
	global_load_lds_dwordx4 v[216:217], off
	v_lshl_add_u64 v[218:219], s[30:31], 0, v[132:133]
	s_mov_b32 m0, s60
	v_lshl_add_u64 v[220:221], s[38:39], 0, v[130:131]
	global_load_lds_dwordx4 v[218:219], off
	v_lshl_add_u64 v[218:219], s[30:31], 0, v[128:129]
	s_add_i32 m0, s60, 0x2000
	s_nop 0
	global_load_lds_dwordx4 v[218:219], off
	v_lshl_add_u64 v[218:219], s[38:39], 0, v[134:135]
	s_mov_b32 m0, s40
	s_nop 0
	global_load_lds_dwordx4 v[218:219], off
	s_mov_b32 m0, s41
	s_nop 0
	global_load_lds_dwordx4 v[220:221], off
	s_waitcnt vmcnt(8)
	s_waitcnt lgkmcnt(0)
	s_barrier
	s_setprio 1
	s_waitcnt lgkmcnt(0)
	v_mfma_f32_16x16x32_bf16 v[60:63], v[150:153], v[182:185], v[60:63]
	v_mfma_f32_16x16x32_bf16 v[56:59], v[158:161], v[182:185], v[56:59]
	v_mfma_f32_16x16x32_bf16 v[52:55], v[150:153], v[190:193], v[52:55]
	v_mfma_f32_16x16x32_bf16 v[48:51], v[158:161], v[190:193], v[48:51]
	v_mfma_f32_16x16x32_bf16 v[36:39], v[150:153], v[198:201], v[36:39]
	v_mfma_f32_16x16x32_bf16 v[32:35], v[158:161], v[198:201], v[32:35]
	v_mfma_f32_16x16x32_bf16 v[20:23], v[150:153], v[206:209], v[20:23]
	v_mfma_f32_16x16x32_bf16 v[16:19], v[158:161], v[206:209], v[16:19]
	v_mfma_f32_16x16x32_bf16 v[60:63], v[154:157], v[186:189], v[60:63]
	v_mfma_f32_16x16x32_bf16 v[56:59], v[162:165], v[186:189], v[56:59]
	v_mfma_f32_16x16x32_bf16 v[52:55], v[154:157], v[194:197], v[52:55]
	v_mfma_f32_16x16x32_bf16 v[48:51], v[162:165], v[194:197], v[48:51]
	v_mfma_f32_16x16x32_bf16 v[36:39], v[154:157], v[202:205], v[36:39]
	v_mfma_f32_16x16x32_bf16 v[32:35], v[162:165], v[202:205], v[32:35]
	v_mfma_f32_16x16x32_bf16 v[20:23], v[154:157], v[210:213], v[20:23]
	v_mfma_f32_16x16x32_bf16 v[16:19], v[162:165], v[210:213], v[16:19]
	s_setprio 0
	s_setprio 1
	v_mfma_f32_16x16x32_bf16 v[44:47], v[166:169], v[182:185], v[44:47]
	v_mfma_f32_16x16x32_bf16 v[40:43], v[174:177], v[182:185], v[40:43]
	v_mfma_f32_16x16x32_bf16 v[28:31], v[166:169], v[190:193], v[28:31]
	v_mfma_f32_16x16x32_bf16 v[24:27], v[174:177], v[190:193], v[24:27]
	v_mfma_f32_16x16x32_bf16 v[12:15], v[166:169], v[198:201], v[12:15]
	v_mfma_f32_16x16x32_bf16 v[8:11], v[174:177], v[198:201], v[8:11]
	v_mfma_f32_16x16x32_bf16 v[4:7], v[166:169], v[206:209], v[4:7]
	v_mfma_f32_16x16x32_bf16 v[0:3], v[174:177], v[206:209], v[0:3]
	v_mfma_f32_16x16x32_bf16 v[44:47], v[170:173], v[186:189], v[44:47]
	v_mfma_f32_16x16x32_bf16 v[40:43], v[178:181], v[186:189], v[40:43]
	v_mfma_f32_16x16x32_bf16 v[28:31], v[170:173], v[194:197], v[28:31]
	v_mfma_f32_16x16x32_bf16 v[24:27], v[178:181], v[194:197], v[24:27]
	v_mfma_f32_16x16x32_bf16 v[12:15], v[170:173], v[202:205], v[12:15]
	v_mfma_f32_16x16x32_bf16 v[8:11], v[178:181], v[202:205], v[8:11]
	v_mfma_f32_16x16x32_bf16 v[4:7], v[170:173], v[210:213], v[4:7]
	v_mfma_f32_16x16x32_bf16 v[0:3], v[178:181], v[210:213], v[0:3]
	s_setprio 0
	s_barrier
	s_add_i32 s60, 0, 0x18000
	s_add_i32 s61, 0, 0x1c000
	v_add_u32_e32 v162, s60, v145
	v_add_u32_e32 v178, s61, v145
	ds_read_b128 v[150:153], v162
	ds_read_b128 v[154:157], v162 offset:1024
	ds_read_b128 v[158:161], v162 offset:2048
	ds_read_b128 v[162:165], v162 offset:3072
	ds_read_b128 v[166:169], v178
	ds_read_b128 v[170:173], v178 offset:1024
	ds_read_b128 v[174:177], v178 offset:2048
	ds_read_b128 v[178:181], v178 offset:3072
	s_add_u32 s30, s38, 0xb0000
	s_addc_u32 s31, s39, 0
	s_mov_b32 m0, s42
	v_lshl_add_u64 v[222:223], s[30:31], 0, v[134:135]
	ds_read_b128 v[182:185], v149 offset:32768
	ds_read_b128 v[186:189], v149 offset:33792
	ds_read_b128 v[190:193], v149 offset:34816
	ds_read_b128 v[194:197], v149 offset:35840
	ds_read_b128 v[198:201], v149 offset:36864
	ds_read_b128 v[202:205], v149 offset:37888
	ds_read_b128 v[206:209], v149 offset:38912
	ds_read_b128 v[210:213], v149 offset:39936
	global_load_lds_dwordx4 v[222:223], off
	v_lshl_add_u64 v[222:223], s[30:31], 0, v[130:131]
	s_mov_b32 m0, s43
	s_nop 0
	global_load_lds_dwordx4 v[222:223], off
	s_waitcnt vmcnt(8)
	s_waitcnt lgkmcnt(0)
	s_barrier
	s_setprio 1
	s_waitcnt lgkmcnt(0)
	v_mfma_f32_16x16x32_bf16 v[124:127], v[150:153], v[182:185], v[124:127]
	v_mfma_f32_16x16x32_bf16 v[120:123], v[158:161], v[182:185], v[120:123]
	v_mfma_f32_16x16x32_bf16 v[116:119], v[150:153], v[190:193], v[116:119]
	v_mfma_f32_16x16x32_bf16 v[112:115], v[158:161], v[190:193], v[112:115]
	v_mfma_f32_16x16x32_bf16 v[100:103], v[150:153], v[198:201], v[100:103]
	v_mfma_f32_16x16x32_bf16 v[96:99], v[158:161], v[198:201], v[96:99]
	v_mfma_f32_16x16x32_bf16 v[84:87], v[150:153], v[206:209], v[84:87]
	v_mfma_f32_16x16x32_bf16 v[80:83], v[158:161], v[206:209], v[80:83]
	v_mfma_f32_16x16x32_bf16 v[124:127], v[154:157], v[186:189], v[124:127]
	v_mfma_f32_16x16x32_bf16 v[120:123], v[162:165], v[186:189], v[120:123]
	v_mfma_f32_16x16x32_bf16 v[116:119], v[154:157], v[194:197], v[116:119]
	v_mfma_f32_16x16x32_bf16 v[112:115], v[162:165], v[194:197], v[112:115]
	v_mfma_f32_16x16x32_bf16 v[100:103], v[154:157], v[202:205], v[100:103]
	v_mfma_f32_16x16x32_bf16 v[96:99], v[162:165], v[202:205], v[96:99]
	v_mfma_f32_16x16x32_bf16 v[84:87], v[154:157], v[210:213], v[84:87]
	v_mfma_f32_16x16x32_bf16 v[80:83], v[162:165], v[210:213], v[80:83]
	s_setprio 0
	s_setprio 1
	v_mfma_f32_16x16x32_bf16 v[108:111], v[166:169], v[182:185], v[108:111]
	v_mfma_f32_16x16x32_bf16 v[104:107], v[174:177], v[182:185], v[104:107]
	v_mfma_f32_16x16x32_bf16 v[92:95], v[166:169], v[190:193], v[92:95]
	v_mfma_f32_16x16x32_bf16 v[88:91], v[174:177], v[190:193], v[88:91]
	v_mfma_f32_16x16x32_bf16 v[76:79], v[166:169], v[198:201], v[76:79]
	v_mfma_f32_16x16x32_bf16 v[72:75], v[174:177], v[198:201], v[72:75]
	v_mfma_f32_16x16x32_bf16 v[68:71], v[166:169], v[206:209], v[68:71]
	v_mfma_f32_16x16x32_bf16 v[64:67], v[174:177], v[206:209], v[64:67]
	v_mfma_f32_16x16x32_bf16 v[108:111], v[170:173], v[186:189], v[108:111]
	v_mfma_f32_16x16x32_bf16 v[104:107], v[178:181], v[186:189], v[104:107]
	v_mfma_f32_16x16x32_bf16 v[92:95], v[170:173], v[194:197], v[92:95]
	v_mfma_f32_16x16x32_bf16 v[88:91], v[178:181], v[194:197], v[88:91]
	v_mfma_f32_16x16x32_bf16 v[76:79], v[170:173], v[202:205], v[76:79]
	v_mfma_f32_16x16x32_bf16 v[72:75], v[178:181], v[202:205], v[72:75]
	v_mfma_f32_16x16x32_bf16 v[68:71], v[170:173], v[210:213], v[68:71]
	v_mfma_f32_16x16x32_bf16 v[64:67], v[178:181], v[210:213], v[64:67]
	s_setprio 0
	s_barrier
	s_add_i32 s30, s60, s33
	v_lshl_add_u64 v[214:215], v[214:215], 0, s[16:17]
	s_mov_b32 m0, s30
	ds_read_b128 v[182:185], v149 offset:49152
	ds_read_b128 v[186:189], v149 offset:50176
	ds_read_b128 v[190:193], v149 offset:51200
	ds_read_b128 v[194:197], v149 offset:52224
	ds_read_b128 v[198:201], v149 offset:53248
	ds_read_b128 v[202:205], v149 offset:54272
	ds_read_b128 v[206:209], v149 offset:55296
	ds_read_b128 v[210:213], v149 offset:56320
	global_load_lds_dwordx4 v[214:215], off
	s_add_i32 m0, s30, 0x2000
	s_add_u32 s30, s36, 0xb0080
	v_lshl_add_u64 v[214:215], v[216:217], 0, s[16:17]
	s_addc_u32 s31, s37, 0
	s_add_i32 s36, s61, s33
	global_load_lds_dwordx4 v[214:215], off
	v_lshl_add_u64 v[214:215], s[30:31], 0, v[132:133]
	s_mov_b32 m0, s36
	s_nop 0
	global_load_lds_dwordx4 v[214:215], off
	v_lshl_add_u64 v[214:215], s[30:31], 0, v[128:129]
	s_add_i32 m0, s36, 0x2000
	s_nop 0
	global_load_lds_dwordx4 v[214:215], off
	v_lshl_add_u64 v[214:215], v[218:219], 0, s[16:17]
	s_mov_b32 m0, s45
	s_nop 0
	global_load_lds_dwordx4 v[214:215], off
	v_lshl_add_u64 v[214:215], v[220:221], 0, s[16:17]
	s_mov_b32 m0, s46
	s_nop 0
	global_load_lds_dwordx4 v[214:215], off
	s_waitcnt vmcnt(8)
	s_waitcnt lgkmcnt(0)
	s_barrier
	s_setprio 1
	s_waitcnt lgkmcnt(0)
	v_mfma_f32_16x16x32_bf16 v[60:63], v[150:153], v[182:185], v[60:63]
	v_mfma_f32_16x16x32_bf16 v[56:59], v[158:161], v[182:185], v[56:59]
	v_mfma_f32_16x16x32_bf16 v[52:55], v[150:153], v[190:193], v[52:55]
	v_mfma_f32_16x16x32_bf16 v[48:51], v[158:161], v[190:193], v[48:51]
	v_mfma_f32_16x16x32_bf16 v[36:39], v[150:153], v[198:201], v[36:39]
	v_mfma_f32_16x16x32_bf16 v[32:35], v[158:161], v[198:201], v[32:35]
	v_mfma_f32_16x16x32_bf16 v[20:23], v[150:153], v[206:209], v[20:23]
	v_mfma_f32_16x16x32_bf16 v[16:19], v[158:161], v[206:209], v[16:19]
	v_mfma_f32_16x16x32_bf16 v[60:63], v[154:157], v[186:189], v[60:63]
	v_mfma_f32_16x16x32_bf16 v[56:59], v[162:165], v[186:189], v[56:59]
	v_mfma_f32_16x16x32_bf16 v[52:55], v[154:157], v[194:197], v[52:55]
	v_mfma_f32_16x16x32_bf16 v[48:51], v[162:165], v[194:197], v[48:51]
	v_mfma_f32_16x16x32_bf16 v[36:39], v[154:157], v[202:205], v[36:39]
	v_mfma_f32_16x16x32_bf16 v[32:35], v[162:165], v[202:205], v[32:35]
	v_mfma_f32_16x16x32_bf16 v[20:23], v[154:157], v[210:213], v[20:23]
	v_mfma_f32_16x16x32_bf16 v[16:19], v[162:165], v[210:213], v[16:19]
	s_setprio 0
	s_setprio 1
	v_mfma_f32_16x16x32_bf16 v[44:47], v[166:169], v[182:185], v[44:47]
	v_mfma_f32_16x16x32_bf16 v[40:43], v[174:177], v[182:185], v[40:43]
	v_mfma_f32_16x16x32_bf16 v[28:31], v[166:169], v[190:193], v[28:31]
	v_mfma_f32_16x16x32_bf16 v[24:27], v[174:177], v[190:193], v[24:27]
	v_mfma_f32_16x16x32_bf16 v[12:15], v[166:169], v[198:201], v[12:15]
	v_mfma_f32_16x16x32_bf16 v[8:11], v[174:177], v[198:201], v[8:11]
	v_mfma_f32_16x16x32_bf16 v[4:7], v[166:169], v[206:209], v[4:7]
	v_mfma_f32_16x16x32_bf16 v[0:3], v[174:177], v[206:209], v[0:3]
	v_mfma_f32_16x16x32_bf16 v[44:47], v[170:173], v[186:189], v[44:47]
	v_mfma_f32_16x16x32_bf16 v[40:43], v[178:181], v[186:189], v[40:43]
	v_mfma_f32_16x16x32_bf16 v[28:31], v[170:173], v[194:197], v[28:31]
	v_mfma_f32_16x16x32_bf16 v[24:27], v[178:181], v[194:197], v[24:27]
	v_mfma_f32_16x16x32_bf16 v[12:15], v[170:173], v[202:205], v[12:15]
	v_mfma_f32_16x16x32_bf16 v[8:11], v[178:181], v[202:205], v[8:11]
	v_mfma_f32_16x16x32_bf16 v[4:7], v[170:173], v[210:213], v[4:7]
	v_mfma_f32_16x16x32_bf16 v[0:3], v[178:181], v[210:213], v[0:3]
	s_setprio 0
	s_barrier
	s_add_i32 s59, s59, 2
	s_add_u32 s57, s57, 0x100
	s_addc_u32 s58, s58, 0
	s_cmp_gt_u32 s59, 41
	s_mov_b64 s[30:31], s[34:35]
	s_cbranch_scc0 .LBB0_949
	s_and_b64 vcc, exec, s[18:19]
	s_cbranch_vccz .LBB0_952
	s_barrier
.LBB0_952:
	v_lshl_or_b32 v150, s55, 8, v146
	v_lshl_add_u32 v152, s56, 8, v144
	s_mov_b64 s[30:31], s[14:15]
	v_ashrrev_i32_e32 v151, 31, v150
	v_ashrrev_i32_e32 v153, 31, v152
	v_lshlrev_b64 v[154:155], 11, v[152:153]
	v_lshl_add_u64 v[150:151], v[150:151], 1, s[30:31]
	v_lshl_add_u64 v[154:155], v[150:151], 0, v[154:155]
	v_cvt_pk_bf16_f32 v60, v60, v61
	v_cvt_pk_bf16_f32 v61, v62, v63
	v_cvt_pk_bf16_f32 v62, v56, v57
	v_add_co_u32_e32 v56, vcc, s49, v154
	v_cvt_pk_bf16_f32 v68, v68, v69
	v_cvt_pk_bf16_f32 v69, v70, v71
	v_cvt_pk_bf16_f32 v70, v64, v65
	v_lshl_add_u64 v[64:65], v[154:155], 0, s[20:21]
	v_addc_co_u32_e32 v57, vcc, 0, v155, vcc
	v_cvt_pk_bf16_f32 v44, v44, v45
	v_cvt_pk_bf16_f32 v45, v46, v47
	v_cvt_pk_bf16_f32 v46, v40, v41
	v_cvt_pk_bf16_f32 v47, v42, v43
	global_store_dwordx4 v[64:65], v[44:47], off offset:256
	v_cvt_pk_bf16_f32 v108, v108, v109
	v_cvt_pk_bf16_f32 v109, v110, v111
	v_add_co_u32_e32 v46, vcc, s50, v154
	v_cvt_pk_bf16_f32 v110, v104, v105
	v_or_b32_e32 v104, 16, v152
	v_lshl_add_u64 v[44:45], v[154:155], 0, s[22:23]
	v_addc_co_u32_e32 v47, vcc, 0, v155, vcc
	v_cvt_pk_bf16_f32 v28, v28, v29
	v_cvt_pk_bf16_f32 v29, v30, v31
	v_cvt_pk_bf16_f32 v30, v24, v25
	v_cvt_pk_bf16_f32 v31, v26, v27
	v_ashrrev_i32_e32 v105, 31, v104
	v_cvt_pk_bf16_f32 v92, v92, v93
	v_cvt_pk_bf16_f32 v93, v94, v95
	v_cvt_pk_bf16_f32 v94, v88, v89
	v_or_b32_e32 v88, 32, v152
	global_store_dwordx4 v[44:45], v[28:31], off offset:256
	v_cvt_pk_bf16_f32 v111, v106, v107
	v_lshlrev_b64 v[104:105], 11, v[104:105]
	v_add_co_u32_e32 v30, vcc, s51, v154
	v_ashrrev_i32_e32 v89, 31, v88
	v_cvt_pk_bf16_f32 v76, v76, v77
	v_cvt_pk_bf16_f32 v77, v78, v79
	v_cvt_pk_bf16_f32 v78, v72, v73
	v_or_b32_e32 v72, 48, v152
	v_lshl_add_u64 v[28:29], v[154:155], 0, s[24:25]
	v_addc_co_u32_e32 v31, vcc, 0, v155, vcc
	v_cvt_pk_bf16_f32 v12, v12, v13
	v_cvt_pk_bf16_f32 v13, v14, v15
	v_cvt_pk_bf16_f32 v14, v8, v9
	v_cvt_pk_bf16_f32 v15, v10, v11
	global_store_dwordx4 v[154:155], v[108:111], off offset:256
	v_cvt_pk_bf16_f32 v95, v90, v91
	v_lshlrev_b64 v[88:89], 11, v[88:89]
	v_lshl_add_u64 v[108:109], v[150:151], 0, v[104:105]
	v_ashrrev_i32_e32 v73, 31, v72
	global_store_dwordx4 v[28:29], v[12:15], off offset:256
	global_store_dwordx4 v[108:109], v[92:95], off offset:256
	v_cvt_pk_bf16_f32 v79, v74, v75
	v_add_co_u32_e32 v14, vcc, s52, v154
	v_lshl_add_u64 v[92:93], v[150:151], 0, v[88:89]
	v_lshlrev_b64 v[72:73], 11, v[72:73]
	v_addc_co_u32_e32 v15, vcc, 0, v155, vcc
	v_cvt_pk_bf16_f32 v124, v124, v125
	v_cvt_pk_bf16_f32 v125, v126, v127
	v_cvt_pk_bf16_f32 v126, v120, v121
	v_cvt_pk_bf16_f32 v127, v122, v123
	v_cvt_pk_bf16_f32 v104, v116, v117
	v_cvt_pk_bf16_f32 v105, v118, v119
	v_cvt_pk_bf16_f32 v106, v112, v113
	v_cvt_pk_bf16_f32 v107, v114, v115
	v_cvt_pk_bf16_f32 v88, v100, v101
	v_cvt_pk_bf16_f32 v89, v102, v103
	v_cvt_pk_bf16_f32 v90, v96, v97
	v_cvt_pk_bf16_f32 v91, v98, v99
	global_store_dwordx4 v[92:93], v[76:79], off offset:256
	v_cvt_pk_bf16_f32 v74, v80, v81
	v_cvt_pk_bf16_f32 v75, v82, v83
	v_lshl_add_u64 v[76:77], v[150:151], 0, v[72:73]
	v_cvt_pk_bf16_f32 v72, v84, v85
	v_cvt_pk_bf16_f32 v73, v86, v87
	v_cvt_pk_bf16_f32 v71, v66, v67
	v_cvt_pk_bf16_f32 v63, v58, v59
	v_cvt_pk_bf16_f32 v40, v52, v53
	v_cvt_pk_bf16_f32 v41, v54, v55
	v_cvt_pk_bf16_f32 v42, v48, v49
	v_cvt_pk_bf16_f32 v43, v50, v51
	v_cvt_pk_bf16_f32 v24, v36, v37
	v_cvt_pk_bf16_f32 v25, v38, v39
	v_cvt_pk_bf16_f32 v26, v32, v33
	v_cvt_pk_bf16_f32 v27, v34, v35
	v_lshl_add_u64 v[12:13], v[154:155], 0, s[26:27]
	v_cvt_pk_bf16_f32 v8, v20, v21
	v_cvt_pk_bf16_f32 v9, v22, v23
	v_cvt_pk_bf16_f32 v10, v16, v17
	v_cvt_pk_bf16_f32 v11, v18, v19
	v_cvt_pk_bf16_f32 v4, v4, v5
	v_cvt_pk_bf16_f32 v5, v6, v7
	v_cvt_pk_bf16_f32 v6, v0, v1
	v_cvt_pk_bf16_f32 v7, v2, v3
	s_and_b64 vcc, exec, s[8:9]
	s_mov_b64 s[8:9], -1
	global_store_dwordx4 v[154:155], v[124:127], off
	global_store_dwordx4 v[108:109], v[104:107], off
	global_store_dwordx4 v[92:93], v[88:91], off
	global_store_dwordx4 v[76:77], v[72:75], off
	global_store_dwordx4 v[76:77], v[68:71], off offset:256
	global_store_dwordx4 v[56:57], v[60:63], off
	global_store_dwordx4 v[46:47], v[40:43], off
	global_store_dwordx4 v[30:31], v[24:27], off
	global_store_dwordx4 v[14:15], v[8:11], off
	global_store_dwordx4 v[12:13], v[4:7], off offset:256
	s_cbranch_vccnz .LBB0_941
	s_andn2_b64 vcc, exec, s[12:13]
	s_cbranch_vccnz .LBB0_940
	s_mov_b32 s100, 1
	s_branch .LBB0_940

.LBB0_1101:
	s_lshl_b32 s18, s18, 5
	s_and_b32 s24, s18, 0x60
	s_mov_b64 s[18:19], 0x80
	s_add_i32 m0, s39, 0x18000
	v_lshl_add_u64 v[6:7], v[6:7], 0, s[18:19]
	s_lshl_b32 s21, s9, 13
	s_lshl_b32 s25, s24, 7
	s_waitcnt vmcnt(2)
	s_barrier
	global_load_lds_dwordx4 v[6:7], off
	v_lshl_add_u64 v[2:3], v[2:3], 0, s[18:19]
	s_add_i32 m0, s39, 0x1a000
	s_add_i32 s50, s39, 0x8000
	s_add_i32 s51, s39, 0xa000
	global_load_lds_dwordx4 v[2:3], off
	v_lshl_add_u64 v[0:1], v[0:1], 0, s[18:19]
	s_mov_b32 m0, s50
	s_add_u32 s22, s40, 0x40080
	global_load_lds_dwordx4 v[0:1], off
	v_lshl_add_u64 v[0:1], v[4:5], 0, s[18:19]
	s_mov_b32 m0, s51
	s_addc_u32 s23, s41, 0
	global_load_lds_dwordx4 v[0:1], off
	s_add_i32 m0, s39, 0x1c000
	v_lshl_add_u64 v[0:1], s[22:23], 0, v[130:131]
	global_load_lds_dwordx4 v[0:1], off
	v_lshl_add_u64 v[0:1], s[22:23], 0, v[134:135]
	s_add_i32 m0, s39, 0x1e000
	s_cmpk_lt_u32 s20, 0x100
	global_load_lds_dwordx4 v[0:1], off
	v_lshrrev_b32_e32 v1, 1, v8
	v_and_b32_e32 v1, 24, v1
	v_and_b32_e32 v0, 15, v8
	v_lshlrev_b32_e32 v2, 1, v1
	v_lshl_or_b32 v150, s9, 6, v0
	v_lshl_or_b32 v0, v0, 6, v2
	v_lshlrev_b32_e32 v2, 2, v8
	v_and_b32_e32 v2, 32, v2
	v_bitop3_b32 v3, v0, s21, v2 bitop3:0xde
	v_bitop3_b32 v151, s25, v0, v2 bitop3:0xf6
	v_lshlrev_b32_e32 v0, 14, v12
	v_and_b32_e32 v0, 0xffff8000, v0
	v_or_b32_e32 v152, s24, v1
	v_lshl_add_u32 v0, v13, 11, v0
	v_and_b32_e32 v1, 1, v12
	v_lshl_or_b32 v0, v1, 6, v0
	v_lshl_add_u32 v136, v14, 1, v0
	v_lshlrev_b32_e32 v0, 14, v9
	v_and_b32_e32 v0, 0xffff8000, v0
	s_waitcnt vmcnt(6)
	v_lshl_add_u32 v0, v10, 11, v0
	v_and_b32_e32 v1, 1, v9
	s_cselect_b64 s[20:21], -1, 0
	v_lshl_or_b32 v0, v1, 6, v0
	s_add_i32 s52, 0, 0x10000
	s_add_i32 s53, 0, 0x14000
	s_sext_i32_i8 s58, s8
	v_mov_b32_e32 v137, v131
	v_lshl_add_u32 v138, v11, 1, v0
	v_mov_b32_e32 v139, v131
	v_mov_b64_e32 v[140:141], 0x200
	v_mov_b64_e32 v[142:143], 0x1ff
	v_add_u32_e32 v153, s52, v151
	v_add_u32_e32 v154, s53, v151
	v_add_u32_e32 v155, 0, v3
	s_mov_b32 s54, 0x40000
	s_mov_b64 s[22:23], 0x48000
	s_mov_b32 s55, 0x48000
	s_mov_b64 s[24:25], 0x50000
	s_mov_b32 s56, 0x50000
	s_mov_b64 s[26:27], 0x58000
	s_mov_b32 s57, 0x58000
	s_barrier
	s_mov_b32 s100, 0
	s_branch .LBB0_1104

.LBB0_1110:
	s_ashr_i32 s31, s30, 31
	s_lshl_b64 s[34:35], s[30:31], 19
	s_add_u32 s34, s10, s34
	s_addc_u32 s35, s11, s35
	s_and_b64 s[36:37], s[8:9], exec
	s_cselect_b32 s31, s35, s43
	s_cselect_b32 s59, s34, s42
	s_ashr_i32 s29, s28, 31
	s_lshl_b64 s[36:37], s[28:29], 19
	s_add_u32 s36, s12, s36
	s_addc_u32 s37, s13, s37
	s_and_b64 s[44:45], s[8:9], exec
	s_cselect_b32 s29, s37, s41
	s_cselect_b32 s60, s36, s40
	s_add_u32 s61, s40, 0x100
	s_addc_u32 s62, s41, 0
	s_add_u32 s40, s42, 0x40080
	v_mov_b32_e32 v0, 0
	s_addc_u32 s41, s43, 0
	s_mov_b32 s63, -2
	v_mov_b32_e32 v1, v0
	v_mov_b32_e32 v2, v0
	v_mov_b32_e32 v3, v0
	v_mov_b32_e32 v4, v0
	v_mov_b32_e32 v5, v0
	v_mov_b32_e32 v6, v0
	v_mov_b32_e32 v7, v0
	v_mov_b32_e32 v16, v0
	v_mov_b32_e32 v17, v0
	v_mov_b32_e32 v18, v0
	v_mov_b32_e32 v19, v0
	v_mov_b32_e32 v20, v0
	v_mov_b32_e32 v21, v0
	v_mov_b32_e32 v22, v0
	v_mov_b32_e32 v23, v0
	v_mov_b32_e32 v32, v0
	v_mov_b32_e32 v33, v0
	v_mov_b32_e32 v34, v0
	v_mov_b32_e32 v35, v0
	v_mov_b32_e32 v36, v0
	v_mov_b32_e32 v37, v0
	v_mov_b32_e32 v38, v0
	v_mov_b32_e32 v39, v0
	v_mov_b32_e32 v48, v0
	v_mov_b32_e32 v49, v0
	v_mov_b32_e32 v50, v0
	v_mov_b32_e32 v51, v0
	v_mov_b32_e32 v52, v0
	v_mov_b32_e32 v53, v0
	v_mov_b32_e32 v54, v0
	v_mov_b32_e32 v55, v0
	v_mov_b32_e32 v8, v0
	v_mov_b32_e32 v9, v0
	v_mov_b32_e32 v10, v0
	v_mov_b32_e32 v11, v0
	v_mov_b32_e32 v12, v0
	v_mov_b32_e32 v13, v0
	v_mov_b32_e32 v14, v0
	v_mov_b32_e32 v15, v0
	v_mov_b32_e32 v24, v0
	v_mov_b32_e32 v25, v0
	v_mov_b32_e32 v26, v0
	v_mov_b32_e32 v27, v0
	v_mov_b32_e32 v28, v0
	v_mov_b32_e32 v29, v0
	v_mov_b32_e32 v30, v0
	v_mov_b32_e32 v31, v0
	v_mov_b32_e32 v40, v0
	v_mov_b32_e32 v41, v0
	v_mov_b32_e32 v42, v0
	v_mov_b32_e32 v43, v0
	v_mov_b32_e32 v44, v0
	v_mov_b32_e32 v45, v0
	v_mov_b32_e32 v46, v0
	v_mov_b32_e32 v47, v0
	v_mov_b32_e32 v56, v0
	v_mov_b32_e32 v57, v0
	v_mov_b32_e32 v58, v0
	v_mov_b32_e32 v59, v0
	v_mov_b32_e32 v60, v0
	v_mov_b32_e32 v61, v0
	v_mov_b32_e32 v62, v0
	v_mov_b32_e32 v63, v0
	v_mov_b32_e32 v64, v0
	v_mov_b32_e32 v65, v0
	v_mov_b32_e32 v66, v0
	v_mov_b32_e32 v67, v0
	v_mov_b32_e32 v68, v0
	v_mov_b32_e32 v69, v0
	v_mov_b32_e32 v70, v0
	v_mov_b32_e32 v71, v0
	v_mov_b32_e32 v80, v0
	v_mov_b32_e32 v81, v0
	v_mov_b32_e32 v82, v0
	v_mov_b32_e32 v83, v0
	v_mov_b32_e32 v84, v0
	v_mov_b32_e32 v85, v0
	v_mov_b32_e32 v86, v0
	v_mov_b32_e32 v87, v0
	v_mov_b32_e32 v96, v0
	v_mov_b32_e32 v97, v0
	v_mov_b32_e32 v98, v0
	v_mov_b32_e32 v99, v0
	v_mov_b32_e32 v100, v0
	v_mov_b32_e32 v101, v0
	v_mov_b32_e32 v102, v0
	v_mov_b32_e32 v103, v0
	v_mov_b32_e32 v112, v0
	v_mov_b32_e32 v113, v0
	v_mov_b32_e32 v114, v0
	v_mov_b32_e32 v115, v0
	v_mov_b32_e32 v116, v0
	v_mov_b32_e32 v117, v0
	v_mov_b32_e32 v118, v0
	v_mov_b32_e32 v119, v0
	v_mov_b32_e32 v72, v0
	v_mov_b32_e32 v73, v0
	v_mov_b32_e32 v74, v0
	v_mov_b32_e32 v75, v0
	v_mov_b32_e32 v76, v0
	v_mov_b32_e32 v77, v0
	v_mov_b32_e32 v78, v0
	v_mov_b32_e32 v79, v0
	v_mov_b32_e32 v88, v0
	v_mov_b32_e32 v89, v0
	v_mov_b32_e32 v90, v0
	v_mov_b32_e32 v91, v0
	v_mov_b32_e32 v92, v0
	v_mov_b32_e32 v93, v0
	v_mov_b32_e32 v94, v0
	v_mov_b32_e32 v95, v0
	v_mov_b32_e32 v104, v0
	v_mov_b32_e32 v105, v0
	v_mov_b32_e32 v106, v0
	v_mov_b32_e32 v107, v0
	v_mov_b32_e32 v108, v0
	v_mov_b32_e32 v109, v0
	v_mov_b32_e32 v110, v0
	v_mov_b32_e32 v111, v0
	v_mov_b32_e32 v120, v0
	v_mov_b32_e32 v121, v0
	v_mov_b32_e32 v122, v0
	v_mov_b32_e32 v123, v0
	v_mov_b32_e32 v124, v0
	v_mov_b32_e32 v125, v0
	v_mov_b32_e32 v126, v0
	v_mov_b32_e32 v127, v0
	s_cmp_eq_u32 s100, 1
	s_cbranch_scc0 .Lgemm_nobar_1102
	s_mov_b32 s100, 0
	s_barrier
.Lgemm_nobar_1102:
.LBB0_1111:
	ds_read_b128 v[144:147], v153
	ds_read_b128 v[156:159], v153 offset:1024
	ds_read_b128 v[160:163], v153 offset:2048
	ds_read_b128 v[164:167], v153 offset:3072
	ds_read_b128 v[168:171], v154
	ds_read_b128 v[172:175], v154 offset:1024
	ds_read_b128 v[176:179], v154 offset:2048
	ds_read_b128 v[180:183], v154 offset:3072
	s_add_u32 s42, s40, 0xfffc0080
	s_addc_u32 s43, s41, -1
	s_cmp_eq_u32 s63, 12
	s_cselect_b32 s45, s31, s43
	s_cselect_b32 s44, s59, s42
	s_cselect_b32 s43, s29, s62
	s_cselect_b32 s42, s60, s61
	v_lshl_add_u64 v[148:149], s[40:41], 0, v[138:139]
	s_add_i32 m0, s39, 0xc000
	ds_read_b128 v[184:187], v155
	ds_read_b128 v[188:191], v155 offset:1024
	ds_read_b128 v[192:195], v155 offset:2048
	ds_read_b128 v[196:199], v155 offset:3072
	ds_read_b128 v[200:203], v155 offset:4096
	ds_read_b128 v[204:207], v155 offset:5120
	ds_read_b128 v[208:211], v155 offset:6144
	ds_read_b128 v[212:215], v155 offset:7168
	global_load_lds_dwordx4 v[148:149], off
	v_lshl_add_u64 v[148:149], s[40:41], 0, v[136:137]
	s_add_i32 m0, s39, 0xe000
	s_nop 0
	global_load_lds_dwordx4 v[148:149], off
	s_waitcnt vmcnt(8)
	s_waitcnt lgkmcnt(0)
	s_barrier
	s_setprio 1
	s_waitcnt lgkmcnt(0)
	v_mfma_f32_16x16x32_bf16 v[124:127], v[144:147], v[184:187], v[124:127]
	v_mfma_f32_16x16x32_bf16 v[120:123], v[160:163], v[184:187], v[120:123]
	v_mfma_f32_16x16x32_bf16 v[108:111], v[144:147], v[192:195], v[108:111]
	v_mfma_f32_16x16x32_bf16 v[104:107], v[160:163], v[192:195], v[104:107]
	v_mfma_f32_16x16x32_bf16 v[92:95], v[144:147], v[200:203], v[92:95]
	v_mfma_f32_16x16x32_bf16 v[88:91], v[160:163], v[200:203], v[88:91]
	v_mfma_f32_16x16x32_bf16 v[76:79], v[144:147], v[208:211], v[76:79]
	v_mfma_f32_16x16x32_bf16 v[72:75], v[160:163], v[208:211], v[72:75]
	v_mfma_f32_16x16x32_bf16 v[124:127], v[156:159], v[188:191], v[124:127]
	v_mfma_f32_16x16x32_bf16 v[120:123], v[164:167], v[188:191], v[120:123]
	v_mfma_f32_16x16x32_bf16 v[108:111], v[156:159], v[196:199], v[108:111]
	v_mfma_f32_16x16x32_bf16 v[104:107], v[164:167], v[196:199], v[104:107]
	v_mfma_f32_16x16x32_bf16 v[92:95], v[156:159], v[204:207], v[92:95]
	v_mfma_f32_16x16x32_bf16 v[88:91], v[164:167], v[204:207], v[88:91]
	v_mfma_f32_16x16x32_bf16 v[76:79], v[156:159], v[212:215], v[76:79]
	v_mfma_f32_16x16x32_bf16 v[72:75], v[164:167], v[212:215], v[72:75]
	s_setprio 0
	s_setprio 1
	v_mfma_f32_16x16x32_bf16 v[116:119], v[168:171], v[184:187], v[116:119]
	v_mfma_f32_16x16x32_bf16 v[112:115], v[176:179], v[184:187], v[112:115]
	v_mfma_f32_16x16x32_bf16 v[100:103], v[168:171], v[192:195], v[100:103]
	v_mfma_f32_16x16x32_bf16 v[96:99], v[176:179], v[192:195], v[96:99]
	v_mfma_f32_16x16x32_bf16 v[84:87], v[168:171], v[200:203], v[84:87]
	v_mfma_f32_16x16x32_bf16 v[80:83], v[176:179], v[200:203], v[80:83]
	v_mfma_f32_16x16x32_bf16 v[68:71], v[168:171], v[208:211], v[68:71]
	v_mfma_f32_16x16x32_bf16 v[64:67], v[176:179], v[208:211], v[64:67]
	v_mfma_f32_16x16x32_bf16 v[116:119], v[172:175], v[188:191], v[116:119]
	v_mfma_f32_16x16x32_bf16 v[112:115], v[180:183], v[188:191], v[112:115]
	v_mfma_f32_16x16x32_bf16 v[100:103], v[172:175], v[196:199], v[100:103]
	v_mfma_f32_16x16x32_bf16 v[96:99], v[180:183], v[196:199], v[96:99]
	v_mfma_f32_16x16x32_bf16 v[84:87], v[172:175], v[204:207], v[84:87]
	v_mfma_f32_16x16x32_bf16 v[80:83], v[180:183], v[204:207], v[80:83]
	v_mfma_f32_16x16x32_bf16 v[68:71], v[172:175], v[212:215], v[68:71]
	v_mfma_f32_16x16x32_bf16 v[64:67], v[180:183], v[212:215], v[64:67]
	s_setprio 0
	s_barrier
	s_add_i32 s64, s52, s33
	v_lshl_add_u64 v[148:149], s[42:43], 0, v[130:131]
	s_mov_b32 m0, s64
	ds_read_b128 v[184:187], v155 offset:16384
	ds_read_b128 v[188:191], v155 offset:17408
	ds_read_b128 v[192:195], v155 offset:18432
	ds_read_b128 v[196:199], v155 offset:19456
	ds_read_b128 v[200:203], v155 offset:20480
	ds_read_b128 v[204:207], v155 offset:21504
	ds_read_b128 v[208:211], v155 offset:22528
	ds_read_b128 v[212:215], v155 offset:23552
	global_load_lds_dwordx4 v[148:149], off
	s_add_i32 m0, s64, 0x2000
	s_add_u32 s64, s42, 0x40000
	v_lshl_add_u64 v[216:217], s[42:43], 0, v[134:135]
	s_addc_u32 s65, s43, 0
	s_add_i32 s66, s53, s33
	global_load_lds_dwordx4 v[216:217], off
	v_lshl_add_u64 v[218:219], s[64:65], 0, v[130:131]
	s_mov_b32 m0, s66
	v_lshl_add_u64 v[220:221], s[44:45], 0, v[132:133]
	global_load_lds_dwordx4 v[218:219], off
	v_lshl_add_u64 v[218:219], s[64:65], 0, v[134:135]
	s_add_i32 m0, s66, 0x2000
	s_nop 0
	global_load_lds_dwordx4 v[218:219], off
	v_lshl_add_u64 v[218:219], s[44:45], 0, v[128:129]
	s_mov_b32 m0, s39
	s_nop 0
	global_load_lds_dwordx4 v[218:219], off
	s_mov_b32 m0, s46
	s_nop 0
	global_load_lds_dwordx4 v[220:221], off
	s_waitcnt vmcnt(8)
	s_waitcnt lgkmcnt(0)
	s_barrier
	s_setprio 1
	s_waitcnt lgkmcnt(0)
	v_mfma_f32_16x16x32_bf16 v[60:63], v[144:147], v[184:187], v[60:63]
	v_mfma_f32_16x16x32_bf16 v[56:59], v[160:163], v[184:187], v[56:59]
	v_mfma_f32_16x16x32_bf16 v[44:47], v[144:147], v[192:195], v[44:47]
	v_mfma_f32_16x16x32_bf16 v[40:43], v[160:163], v[192:195], v[40:43]
	v_mfma_f32_16x16x32_bf16 v[28:31], v[144:147], v[200:203], v[28:31]
	v_mfma_f32_16x16x32_bf16 v[24:27], v[160:163], v[200:203], v[24:27]
	v_mfma_f32_16x16x32_bf16 v[12:15], v[144:147], v[208:211], v[12:15]
	v_mfma_f32_16x16x32_bf16 v[8:11], v[160:163], v[208:211], v[8:11]
	v_mfma_f32_16x16x32_bf16 v[60:63], v[156:159], v[188:191], v[60:63]
	v_mfma_f32_16x16x32_bf16 v[56:59], v[164:167], v[188:191], v[56:59]
	v_mfma_f32_16x16x32_bf16 v[44:47], v[156:159], v[196:199], v[44:47]
	v_mfma_f32_16x16x32_bf16 v[40:43], v[164:167], v[196:199], v[40:43]
	v_mfma_f32_16x16x32_bf16 v[28:31], v[156:159], v[204:207], v[28:31]
	v_mfma_f32_16x16x32_bf16 v[24:27], v[164:167], v[204:207], v[24:27]
	v_mfma_f32_16x16x32_bf16 v[12:15], v[156:159], v[212:215], v[12:15]
	v_mfma_f32_16x16x32_bf16 v[8:11], v[164:167], v[212:215], v[8:11]
	s_setprio 0
	s_setprio 1
	v_mfma_f32_16x16x32_bf16 v[52:55], v[168:171], v[184:187], v[52:55]
	v_mfma_f32_16x16x32_bf16 v[48:51], v[176:179], v[184:187], v[48:51]
	v_mfma_f32_16x16x32_bf16 v[36:39], v[168:171], v[192:195], v[36:39]
	v_mfma_f32_16x16x32_bf16 v[32:35], v[176:179], v[192:195], v[32:35]
	v_mfma_f32_16x16x32_bf16 v[20:23], v[168:171], v[200:203], v[20:23]
	v_mfma_f32_16x16x32_bf16 v[16:19], v[176:179], v[200:203], v[16:19]
	v_mfma_f32_16x16x32_bf16 v[4:7], v[168:171], v[208:211], v[4:7]
	v_mfma_f32_16x16x32_bf16 v[0:3], v[176:179], v[208:211], v[0:3]
	v_mfma_f32_16x16x32_bf16 v[52:55], v[172:175], v[188:191], v[52:55]
	v_mfma_f32_16x16x32_bf16 v[48:51], v[180:183], v[188:191], v[48:51]
	v_mfma_f32_16x16x32_bf16 v[36:39], v[172:175], v[196:199], v[36:39]
	v_mfma_f32_16x16x32_bf16 v[32:35], v[180:183], v[196:199], v[32:35]
	v_mfma_f32_16x16x32_bf16 v[20:23], v[172:175], v[204:207], v[20:23]
	v_mfma_f32_16x16x32_bf16 v[16:19], v[180:183], v[204:207], v[16:19]
	v_mfma_f32_16x16x32_bf16 v[4:7], v[172:175], v[212:215], v[4:7]
	v_mfma_f32_16x16x32_bf16 v[0:3], v[180:183], v[212:215], v[0:3]
	s_setprio 0
	s_barrier
	s_add_i32 s64, 0, 0x18000
	s_add_i32 s65, 0, 0x1c000
	v_add_u32_e32 v164, s64, v151
	v_add_u32_e32 v180, s65, v151
	ds_read_b128 v[144:147], v164
	ds_read_b128 v[156:159], v164 offset:1024
	ds_read_b128 v[160:163], v164 offset:2048
	ds_read_b128 v[164:167], v164 offset:3072
	ds_read_b128 v[168:171], v180
	ds_read_b128 v[172:175], v180 offset:1024
	ds_read_b128 v[176:179], v180 offset:2048
	ds_read_b128 v[180:183], v180 offset:3072
	s_add_u32 s44, s44, 0x40000
	s_addc_u32 s45, s45, 0
	s_mov_b32 m0, s47
	v_lshl_add_u64 v[222:223], s[44:45], 0, v[128:129]
	ds_read_b128 v[184:187], v155 offset:32768
	ds_read_b128 v[188:191], v155 offset:33792
	ds_read_b128 v[192:195], v155 offset:34816
	ds_read_b128 v[196:199], v155 offset:35840
	ds_read_b128 v[200:203], v155 offset:36864
	ds_read_b128 v[204:207], v155 offset:37888
	ds_read_b128 v[208:211], v155 offset:38912
	ds_read_b128 v[212:215], v155 offset:39936
	global_load_lds_dwordx4 v[222:223], off
	v_lshl_add_u64 v[222:223], s[44:45], 0, v[132:133]
	s_mov_b32 m0, s48
	s_nop 0
	global_load_lds_dwordx4 v[222:223], off
	s_waitcnt vmcnt(8)
	s_waitcnt lgkmcnt(0)
	s_barrier
	s_setprio 1
	s_waitcnt lgkmcnt(0)
	v_mfma_f32_16x16x32_bf16 v[124:127], v[144:147], v[184:187], v[124:127]
	v_mfma_f32_16x16x32_bf16 v[120:123], v[160:163], v[184:187], v[120:123]
	v_mfma_f32_16x16x32_bf16 v[108:111], v[144:147], v[192:195], v[108:111]
	v_mfma_f32_16x16x32_bf16 v[104:107], v[160:163], v[192:195], v[104:107]
	v_mfma_f32_16x16x32_bf16 v[92:95], v[144:147], v[200:203], v[92:95]
	v_mfma_f32_16x16x32_bf16 v[88:91], v[160:163], v[200:203], v[88:91]
	v_mfma_f32_16x16x32_bf16 v[76:79], v[144:147], v[208:211], v[76:79]
	v_mfma_f32_16x16x32_bf16 v[72:75], v[160:163], v[208:211], v[72:75]
	v_mfma_f32_16x16x32_bf16 v[124:127], v[156:159], v[188:191], v[124:127]
	v_mfma_f32_16x16x32_bf16 v[120:123], v[164:167], v[188:191], v[120:123]
	v_mfma_f32_16x16x32_bf16 v[108:111], v[156:159], v[196:199], v[108:111]
	v_mfma_f32_16x16x32_bf16 v[104:107], v[164:167], v[196:199], v[104:107]
	v_mfma_f32_16x16x32_bf16 v[92:95], v[156:159], v[204:207], v[92:95]
	v_mfma_f32_16x16x32_bf16 v[88:91], v[164:167], v[204:207], v[88:91]
	v_mfma_f32_16x16x32_bf16 v[76:79], v[156:159], v[212:215], v[76:79]
	v_mfma_f32_16x16x32_bf16 v[72:75], v[164:167], v[212:215], v[72:75]
	s_setprio 0
	s_setprio 1
	v_mfma_f32_16x16x32_bf16 v[116:119], v[168:171], v[184:187], v[116:119]
	v_mfma_f32_16x16x32_bf16 v[112:115], v[176:179], v[184:187], v[112:115]
	v_mfma_f32_16x16x32_bf16 v[100:103], v[168:171], v[192:195], v[100:103]
	v_mfma_f32_16x16x32_bf16 v[96:99], v[176:179], v[192:195], v[96:99]
	v_mfma_f32_16x16x32_bf16 v[84:87], v[168:171], v[200:203], v[84:87]
	v_mfma_f32_16x16x32_bf16 v[80:83], v[176:179], v[200:203], v[80:83]
	v_mfma_f32_16x16x32_bf16 v[68:71], v[168:171], v[208:211], v[68:71]
	v_mfma_f32_16x16x32_bf16 v[64:67], v[176:179], v[208:211], v[64:67]
	v_mfma_f32_16x16x32_bf16 v[116:119], v[172:175], v[188:191], v[116:119]
	v_mfma_f32_16x16x32_bf16 v[112:115], v[180:183], v[188:191], v[112:115]
	v_mfma_f32_16x16x32_bf16 v[100:103], v[172:175], v[196:199], v[100:103]
	v_mfma_f32_16x16x32_bf16 v[96:99], v[180:183], v[196:199], v[96:99]
	v_mfma_f32_16x16x32_bf16 v[84:87], v[172:175], v[204:207], v[84:87]
	v_mfma_f32_16x16x32_bf16 v[80:83], v[180:183], v[204:207], v[80:83]
	v_mfma_f32_16x16x32_bf16 v[68:71], v[172:175], v[212:215], v[68:71]
	v_mfma_f32_16x16x32_bf16 v[64:67], v[180:183], v[212:215], v[64:67]
	s_setprio 0
	s_barrier
	s_add_i32 s44, s64, s33
	v_lshl_add_u64 v[148:149], v[148:149], 0, s[18:19]
	s_mov_b32 m0, s44
	ds_read_b128 v[184:187], v155 offset:49152
	ds_read_b128 v[188:191], v155 offset:50176
	ds_read_b128 v[192:195], v155 offset:51200
	ds_read_b128 v[196:199], v155 offset:52224
	ds_read_b128 v[200:203], v155 offset:53248
	ds_read_b128 v[204:207], v155 offset:54272
	ds_read_b128 v[208:211], v155 offset:55296
	ds_read_b128 v[212:215], v155 offset:56320
	global_load_lds_dwordx4 v[148:149], off
	s_add_i32 m0, s44, 0x2000
	s_add_u32 s42, s42, 0x40080
	v_lshl_add_u64 v[148:149], v[216:217], 0, s[18:19]
	s_addc_u32 s43, s43, 0
	s_add_i32 s44, s65, s33
	global_load_lds_dwordx4 v[148:149], off
	v_lshl_add_u64 v[148:149], s[42:43], 0, v[130:131]
	s_mov_b32 m0, s44
	s_nop 0
	global_load_lds_dwordx4 v[148:149], off
	v_lshl_add_u64 v[148:149], s[42:43], 0, v[134:135]
	s_add_i32 m0, s44, 0x2000
	s_nop 0
	global_load_lds_dwordx4 v[148:149], off
	v_lshl_add_u64 v[148:149], v[218:219], 0, s[18:19]
	s_mov_b32 m0, s50
	s_nop 0
	global_load_lds_dwordx4 v[148:149], off
	v_lshl_add_u64 v[148:149], v[220:221], 0, s[18:19]
	s_mov_b32 m0, s51
	s_nop 0
	global_load_lds_dwordx4 v[148:149], off
	s_waitcnt vmcnt(8)
	s_waitcnt lgkmcnt(0)
	s_barrier
	s_setprio 1
	s_waitcnt lgkmcnt(0)
	v_mfma_f32_16x16x32_bf16 v[60:63], v[144:147], v[184:187], v[60:63]
	v_mfma_f32_16x16x32_bf16 v[56:59], v[160:163], v[184:187], v[56:59]
	v_mfma_f32_16x16x32_bf16 v[44:47], v[144:147], v[192:195], v[44:47]
	v_mfma_f32_16x16x32_bf16 v[40:43], v[160:163], v[192:195], v[40:43]
	v_mfma_f32_16x16x32_bf16 v[28:31], v[144:147], v[200:203], v[28:31]
	v_mfma_f32_16x16x32_bf16 v[24:27], v[160:163], v[200:203], v[24:27]
	v_mfma_f32_16x16x32_bf16 v[12:15], v[144:147], v[208:211], v[12:15]
	v_mfma_f32_16x16x32_bf16 v[8:11], v[160:163], v[208:211], v[8:11]
	v_mfma_f32_16x16x32_bf16 v[60:63], v[156:159], v[188:191], v[60:63]
	v_mfma_f32_16x16x32_bf16 v[56:59], v[164:167], v[188:191], v[56:59]
	v_mfma_f32_16x16x32_bf16 v[44:47], v[156:159], v[196:199], v[44:47]
	v_mfma_f32_16x16x32_bf16 v[40:43], v[164:167], v[196:199], v[40:43]
	v_mfma_f32_16x16x32_bf16 v[28:31], v[156:159], v[204:207], v[28:31]
	v_mfma_f32_16x16x32_bf16 v[24:27], v[164:167], v[204:207], v[24:27]
	v_mfma_f32_16x16x32_bf16 v[12:15], v[156:159], v[212:215], v[12:15]
	v_mfma_f32_16x16x32_bf16 v[8:11], v[164:167], v[212:215], v[8:11]
	s_setprio 0
	s_setprio 1
	v_mfma_f32_16x16x32_bf16 v[52:55], v[168:171], v[184:187], v[52:55]
	v_mfma_f32_16x16x32_bf16 v[48:51], v[176:179], v[184:187], v[48:51]
	v_mfma_f32_16x16x32_bf16 v[36:39], v[168:171], v[192:195], v[36:39]
	v_mfma_f32_16x16x32_bf16 v[32:35], v[176:179], v[192:195], v[32:35]
	v_mfma_f32_16x16x32_bf16 v[20:23], v[168:171], v[200:203], v[20:23]
	v_mfma_f32_16x16x32_bf16 v[16:19], v[176:179], v[200:203], v[16:19]
	v_mfma_f32_16x16x32_bf16 v[4:7], v[168:171], v[208:211], v[4:7]
	v_mfma_f32_16x16x32_bf16 v[0:3], v[176:179], v[208:211], v[0:3]
	v_mfma_f32_16x16x32_bf16 v[52:55], v[172:175], v[188:191], v[52:55]
	v_mfma_f32_16x16x32_bf16 v[48:51], v[180:183], v[188:191], v[48:51]
	v_mfma_f32_16x16x32_bf16 v[36:39], v[172:175], v[196:199], v[36:39]
	v_mfma_f32_16x16x32_bf16 v[32:35], v[180:183], v[196:199], v[32:35]
	v_mfma_f32_16x16x32_bf16 v[20:23], v[172:175], v[204:207], v[20:23]
	v_mfma_f32_16x16x32_bf16 v[16:19], v[180:183], v[204:207], v[16:19]
	v_mfma_f32_16x16x32_bf16 v[4:7], v[172:175], v[212:215], v[4:7]
	v_mfma_f32_16x16x32_bf16 v[0:3], v[180:183], v[212:215], v[0:3]
	s_setprio 0
	s_barrier
	s_add_i32 s63, s63, 2
	s_add_u32 s61, s61, 0x100
	s_addc_u32 s62, s62, 0
	s_add_u32 s40, s40, 0x100
	s_addc_u32 s41, s41, 0
	s_cmp_gt_u32 s63, 13
	s_cbranch_scc0 .LBB0_1111
	s_and_b64 vcc, exec, s[20:21]
	s_cbranch_vccz .LBB0_1114
	s_barrier
.LBB0_1114:
	v_mul_f32_e32 v120, 0xbfb8aa3b, v120
	v_exp_f32_e32 v120, v120
	v_mul_f32_e32 v125, 0xbfb8aa3b, v125
	v_exp_f32_e32 v125, v125
	v_lshl_add_u32 v148, s38, 8, v150
	v_lshl_or_b32 v144, s58, 8, v152
	s_mov_b64 s[40:41], s[0:1]
	v_ashrrev_i32_e32 v145, 31, v144
	v_ashrrev_i32_e32 v149, 31, v148
	v_add_f32_e32 v120, 1.0, v120
	v_mul_f32_e32 v121, 0xbfb8aa3b, v121
	v_exp_f32_e32 v121, v121
	v_lshl_add_u64 v[146:147], v[144:145], 1, s[40:41]
	v_lshlrev_b64 v[144:145], 11, v[148:149]
	v_rcp_f32_e32 v149, v120
	v_add_f32_e32 v120, 1.0, v125
	v_mul_f32_e32 v125, 0xbfb8aa3b, v126
	v_exp_f32_e32 v125, v125
	v_add_f32_e32 v121, 1.0, v121
	v_mul_f32_e32 v122, 0xbfb8aa3b, v122
	v_mul_f32_e32 v124, 0xbfb8aa3b, v124
	v_exp_f32_e32 v122, v122
	v_rcp_f32_e32 v126, v121
	v_add_f32_e32 v121, 1.0, v125
	v_mul_f32_e32 v125, 0xbfb8aa3b, v127
	v_mul_f32_e32 v123, 0xbfb8aa3b, v123
	v_exp_f32_e32 v124, v124
	v_exp_f32_e32 v125, v125
	v_exp_f32_e32 v123, v123
	v_add_f32_e32 v122, 1.0, v122
	v_add_f32_e32 v124, 1.0, v124
	v_rcp_f32_e32 v127, v122
	v_add_f32_e32 v122, 1.0, v125
	v_add_f32_e32 v123, 1.0, v123
	v_mul_f32_e32 v112, 0xbfb8aa3b, v112
	v_rcp_f32_e32 v124, v124
	v_rcp_f32_e32 v120, v120
	v_rcp_f32_e32 v121, v121
	v_rcp_f32_e32 v122, v122
	v_rcp_f32_e32 v123, v123
	v_exp_f32_e32 v112, v112
	v_mul_f32_e32 v117, 0xbfb8aa3b, v117
	v_exp_f32_e32 v117, v117
	v_lshl_add_u64 v[144:145], v[146:147], 0, v[144:145]
	v_cvt_pk_bf16_f32 v120, v124, v120
	v_cvt_pk_bf16_f32 v121, v121, v122
	v_cvt_pk_bf16_f32 v122, v149, v126
	v_cvt_pk_bf16_f32 v123, v127, v123
	v_add_f32_e32 v112, 1.0, v112
	v_mul_f32_e32 v113, 0xbfb8aa3b, v113
	global_store_dwordx4 v[144:145], v[120:123], off
	v_exp_f32_e32 v113, v113
	v_mul_f32_e32 v114, 0xbfb8aa3b, v114
	v_rcp_f32_e32 v120, v112
	v_add_f32_e32 v112, 1.0, v117
	v_mul_f32_e32 v117, 0xbfb8aa3b, v118
	v_exp_f32_e32 v117, v117
	v_add_f32_e32 v113, 1.0, v113
	v_mul_f32_e32 v116, 0xbfb8aa3b, v116
	v_exp_f32_e32 v114, v114
	v_rcp_f32_e32 v118, v113
	v_add_f32_e32 v113, 1.0, v117
	v_mul_f32_e32 v117, 0xbfb8aa3b, v119
	v_mul_f32_e32 v115, 0xbfb8aa3b, v115
	v_exp_f32_e32 v116, v116
	v_exp_f32_e32 v117, v117
	v_exp_f32_e32 v115, v115
	v_add_f32_e32 v114, 1.0, v114
	v_add_f32_e32 v116, 1.0, v116
	v_rcp_f32_e32 v119, v114
	v_add_f32_e32 v114, 1.0, v117
	v_add_f32_e32 v115, 1.0, v115
	v_mul_f32_e32 v104, 0xbfb8aa3b, v104
	v_rcp_f32_e32 v116, v116
	v_rcp_f32_e32 v112, v112
	v_rcp_f32_e32 v113, v113
	v_rcp_f32_e32 v114, v114
	v_rcp_f32_e32 v115, v115
	v_exp_f32_e32 v104, v104
	v_mul_f32_e32 v109, 0xbfb8aa3b, v109
	v_exp_f32_e32 v109, v109
	v_cvt_pk_bf16_f32 v112, v116, v112
	v_cvt_pk_bf16_f32 v113, v113, v114
	v_cvt_pk_bf16_f32 v114, v120, v118
	v_cvt_pk_bf16_f32 v115, v119, v115
	v_add_f32_e32 v104, 1.0, v104
	v_mul_f32_e32 v105, 0xbfb8aa3b, v105
	global_store_dwordx4 v[144:145], v[112:115], off offset:256
	v_exp_f32_e32 v105, v105
	v_mul_f32_e32 v106, 0xbfb8aa3b, v106
	v_rcp_f32_e32 v114, v104
	v_add_f32_e32 v104, 1.0, v109
	v_mul_f32_e32 v109, 0xbfb8aa3b, v110
	v_exp_f32_e32 v109, v109
	v_add_f32_e32 v105, 1.0, v105
	v_mul_f32_e32 v108, 0xbfb8aa3b, v108
	v_exp_f32_e32 v106, v106
	v_rcp_f32_e32 v110, v105
	v_add_f32_e32 v105, 1.0, v109
	v_mul_f32_e32 v109, 0xbfb8aa3b, v111
	v_mul_f32_e32 v107, 0xbfb8aa3b, v107
	v_exp_f32_e32 v108, v108
	v_exp_f32_e32 v109, v109
	v_exp_f32_e32 v107, v107
	v_add_f32_e32 v106, 1.0, v106
	v_add_f32_e32 v108, 1.0, v108
	v_rcp_f32_e32 v111, v106
	v_add_f32_e32 v106, 1.0, v109
	v_add_f32_e32 v107, 1.0, v107
	v_mul_f32_e32 v96, 0xbfb8aa3b, v96
	v_rcp_f32_e32 v108, v108
	v_rcp_f32_e32 v104, v104
	v_rcp_f32_e32 v105, v105
	v_rcp_f32_e32 v106, v106
	v_rcp_f32_e32 v107, v107
	v_exp_f32_e32 v96, v96
	v_mul_f32_e32 v101, 0xbfb8aa3b, v101
	v_or_b32_e32 v112, 16, v148
	v_exp_f32_e32 v101, v101
	v_ashrrev_i32_e32 v113, 31, v112
	v_lshlrev_b64 v[112:113], 11, v[112:113]
	v_lshl_add_u64 v[112:113], v[146:147], 0, v[112:113]
	v_cvt_pk_bf16_f32 v104, v108, v104
	v_cvt_pk_bf16_f32 v105, v105, v106
	v_cvt_pk_bf16_f32 v106, v114, v110
	v_cvt_pk_bf16_f32 v107, v111, v107
	v_add_f32_e32 v96, 1.0, v96
	v_mul_f32_e32 v97, 0xbfb8aa3b, v97
	global_store_dwordx4 v[112:113], v[104:107], off
	v_exp_f32_e32 v97, v97
	v_mul_f32_e32 v98, 0xbfb8aa3b, v98
	v_rcp_f32_e32 v104, v96
	v_add_f32_e32 v96, 1.0, v101
	v_mul_f32_e32 v101, 0xbfb8aa3b, v102
	v_exp_f32_e32 v101, v101
	v_add_f32_e32 v97, 1.0, v97
	v_mul_f32_e32 v100, 0xbfb8aa3b, v100
	v_exp_f32_e32 v98, v98
	v_rcp_f32_e32 v102, v97
	v_add_f32_e32 v97, 1.0, v101
	v_mul_f32_e32 v101, 0xbfb8aa3b, v103
	v_mul_f32_e32 v99, 0xbfb8aa3b, v99
	v_exp_f32_e32 v100, v100
	v_exp_f32_e32 v101, v101
	v_exp_f32_e32 v99, v99
	v_add_f32_e32 v98, 1.0, v98
	v_add_f32_e32 v100, 1.0, v100
	v_rcp_f32_e32 v103, v98
	v_add_f32_e32 v98, 1.0, v101
	v_add_f32_e32 v99, 1.0, v99
	v_mul_f32_e32 v88, 0xbfb8aa3b, v88
	v_rcp_f32_e32 v100, v100
	v_rcp_f32_e32 v96, v96
	v_rcp_f32_e32 v97, v97
	v_rcp_f32_e32 v98, v98
	v_rcp_f32_e32 v99, v99
	v_exp_f32_e32 v88, v88
	v_mul_f32_e32 v93, 0xbfb8aa3b, v93
	v_exp_f32_e32 v93, v93
	v_cvt_pk_bf16_f32 v96, v100, v96
	v_cvt_pk_bf16_f32 v97, v97, v98
	v_cvt_pk_bf16_f32 v98, v104, v102
	v_cvt_pk_bf16_f32 v99, v103, v99
	v_add_f32_e32 v88, 1.0, v88
	v_mul_f32_e32 v89, 0xbfb8aa3b, v89
	global_store_dwordx4 v[112:113], v[96:99], off offset:256
	v_exp_f32_e32 v89, v89
	v_mul_f32_e32 v90, 0xbfb8aa3b, v90
	v_rcp_f32_e32 v98, v88
	v_add_f32_e32 v88, 1.0, v93
	v_mul_f32_e32 v93, 0xbfb8aa3b, v94
	v_exp_f32_e32 v93, v93
	v_add_f32_e32 v89, 1.0, v89
	v_mul_f32_e32 v92, 0xbfb8aa3b, v92
	v_exp_f32_e32 v90, v90
	v_rcp_f32_e32 v94, v89
	v_add_f32_e32 v89, 1.0, v93
	v_mul_f32_e32 v93, 0xbfb8aa3b, v95
	v_mul_f32_e32 v91, 0xbfb8aa3b, v91
	v_exp_f32_e32 v92, v92
	v_exp_f32_e32 v93, v93
	v_exp_f32_e32 v91, v91
	v_add_f32_e32 v90, 1.0, v90
	v_add_f32_e32 v92, 1.0, v92
	v_rcp_f32_e32 v95, v90
	v_add_f32_e32 v90, 1.0, v93
	v_add_f32_e32 v91, 1.0, v91
	v_mul_f32_e32 v80, 0xbfb8aa3b, v80
	v_rcp_f32_e32 v92, v92
	v_rcp_f32_e32 v88, v88
	v_rcp_f32_e32 v89, v89
	v_rcp_f32_e32 v90, v90
	v_rcp_f32_e32 v91, v91
	v_exp_f32_e32 v80, v80
	v_mul_f32_e32 v85, 0xbfb8aa3b, v85
	v_or_b32_e32 v96, 32, v148
	v_exp_f32_e32 v85, v85
	v_ashrrev_i32_e32 v97, 31, v96
	v_lshlrev_b64 v[96:97], 11, v[96:97]
	v_lshl_add_u64 v[96:97], v[146:147], 0, v[96:97]
	v_cvt_pk_bf16_f32 v88, v92, v88
	v_cvt_pk_bf16_f32 v89, v89, v90
	v_cvt_pk_bf16_f32 v90, v98, v94
	v_cvt_pk_bf16_f32 v91, v95, v91
	v_add_f32_e32 v80, 1.0, v80
	v_mul_f32_e32 v81, 0xbfb8aa3b, v81
	global_store_dwordx4 v[96:97], v[88:91], off
	v_exp_f32_e32 v81, v81
	v_mul_f32_e32 v82, 0xbfb8aa3b, v82
	v_rcp_f32_e32 v88, v80
	v_add_f32_e32 v80, 1.0, v85
	v_mul_f32_e32 v85, 0xbfb8aa3b, v86
	v_exp_f32_e32 v85, v85
	v_add_f32_e32 v81, 1.0, v81
	v_mul_f32_e32 v84, 0xbfb8aa3b, v84
	v_exp_f32_e32 v82, v82
	v_rcp_f32_e32 v86, v81
	v_add_f32_e32 v81, 1.0, v85
	v_mul_f32_e32 v85, 0xbfb8aa3b, v87
	v_mul_f32_e32 v83, 0xbfb8aa3b, v83
	v_exp_f32_e32 v84, v84
	v_exp_f32_e32 v85, v85
	v_exp_f32_e32 v83, v83
	v_add_f32_e32 v82, 1.0, v82
	v_add_f32_e32 v84, 1.0, v84
	v_rcp_f32_e32 v87, v82
	v_add_f32_e32 v82, 1.0, v85
	v_add_f32_e32 v83, 1.0, v83
	v_mul_f32_e32 v72, 0xbfb8aa3b, v72
	v_rcp_f32_e32 v84, v84
	v_rcp_f32_e32 v80, v80
	v_rcp_f32_e32 v81, v81
	v_rcp_f32_e32 v82, v82
	v_rcp_f32_e32 v83, v83
	v_exp_f32_e32 v72, v72
	v_mul_f32_e32 v77, 0xbfb8aa3b, v77
	v_exp_f32_e32 v77, v77
	v_cvt_pk_bf16_f32 v80, v84, v80
	v_cvt_pk_bf16_f32 v81, v81, v82
	v_cvt_pk_bf16_f32 v82, v88, v86
	v_cvt_pk_bf16_f32 v83, v87, v83
	v_add_f32_e32 v72, 1.0, v72
	v_mul_f32_e32 v73, 0xbfb8aa3b, v73
	global_store_dwordx4 v[96:97], v[80:83], off offset:256
	v_exp_f32_e32 v73, v73
	v_mul_f32_e32 v74, 0xbfb8aa3b, v74
	v_rcp_f32_e32 v82, v72
	v_add_f32_e32 v72, 1.0, v77
	v_mul_f32_e32 v77, 0xbfb8aa3b, v78
	v_exp_f32_e32 v77, v77
	v_add_f32_e32 v73, 1.0, v73
	v_mul_f32_e32 v76, 0xbfb8aa3b, v76
	v_exp_f32_e32 v74, v74
	v_rcp_f32_e32 v78, v73
	v_add_f32_e32 v73, 1.0, v77
	v_mul_f32_e32 v77, 0xbfb8aa3b, v79
	v_mul_f32_e32 v75, 0xbfb8aa3b, v75
	v_exp_f32_e32 v76, v76
	v_exp_f32_e32 v77, v77
	v_exp_f32_e32 v75, v75
	v_add_f32_e32 v74, 1.0, v74
	v_add_f32_e32 v76, 1.0, v76
	v_rcp_f32_e32 v79, v74
	v_add_f32_e32 v74, 1.0, v77
	v_add_f32_e32 v75, 1.0, v75
	v_mul_f32_e32 v64, 0xbfb8aa3b, v64
	v_rcp_f32_e32 v76, v76
	v_rcp_f32_e32 v72, v72
	v_rcp_f32_e32 v73, v73
	v_rcp_f32_e32 v74, v74
	v_rcp_f32_e32 v75, v75
	v_exp_f32_e32 v64, v64
	v_mul_f32_e32 v69, 0xbfb8aa3b, v69
	v_or_b32_e32 v80, 48, v148
	v_exp_f32_e32 v69, v69
	v_ashrrev_i32_e32 v81, 31, v80
	v_lshlrev_b64 v[80:81], 11, v[80:81]
	v_lshl_add_u64 v[80:81], v[146:147], 0, v[80:81]
	v_cvt_pk_bf16_f32 v72, v76, v72
	v_cvt_pk_bf16_f32 v73, v73, v74
	v_cvt_pk_bf16_f32 v74, v82, v78
	v_cvt_pk_bf16_f32 v75, v79, v75
	v_add_f32_e32 v64, 1.0, v64
	v_mul_f32_e32 v65, 0xbfb8aa3b, v65
	global_store_dwordx4 v[80:81], v[72:75], off
	v_exp_f32_e32 v65, v65
	v_mul_f32_e32 v66, 0xbfb8aa3b, v66
	v_rcp_f32_e32 v72, v64
	v_add_f32_e32 v64, 1.0, v69
	v_mul_f32_e32 v69, 0xbfb8aa3b, v70
	v_exp_f32_e32 v69, v69
	v_add_f32_e32 v65, 1.0, v65
	v_mul_f32_e32 v68, 0xbfb8aa3b, v68
	v_exp_f32_e32 v66, v66
	v_rcp_f32_e32 v70, v65
	v_add_f32_e32 v65, 1.0, v69
	v_mul_f32_e32 v69, 0xbfb8aa3b, v71
	v_mul_f32_e32 v67, 0xbfb8aa3b, v67
	v_exp_f32_e32 v68, v68
	v_exp_f32_e32 v69, v69
	v_exp_f32_e32 v67, v67
	v_add_f32_e32 v66, 1.0, v66
	v_add_f32_e32 v68, 1.0, v68
	v_rcp_f32_e32 v71, v66
	v_add_f32_e32 v66, 1.0, v69
	v_add_f32_e32 v67, 1.0, v67
	v_mul_f32_e32 v56, 0xbfb8aa3b, v56
	v_rcp_f32_e32 v68, v68
	v_rcp_f32_e32 v64, v64
	v_rcp_f32_e32 v65, v65
	v_rcp_f32_e32 v66, v66
	v_rcp_f32_e32 v67, v67
	v_exp_f32_e32 v56, v56
	v_mul_f32_e32 v61, 0xbfb8aa3b, v61
	v_exp_f32_e32 v61, v61
	v_cvt_pk_bf16_f32 v64, v68, v64
	v_cvt_pk_bf16_f32 v65, v65, v66
	v_cvt_pk_bf16_f32 v66, v72, v70
	v_cvt_pk_bf16_f32 v67, v71, v67
	v_add_f32_e32 v56, 1.0, v56
	v_mul_f32_e32 v57, 0xbfb8aa3b, v57
	global_store_dwordx4 v[80:81], v[64:67], off offset:256
	v_exp_f32_e32 v57, v57
	v_mul_f32_e32 v60, 0xbfb8aa3b, v60
	v_rcp_f32_e32 v66, v56
	v_add_f32_e32 v56, 1.0, v61
	v_mul_f32_e32 v61, 0xbfb8aa3b, v62
	v_exp_f32_e32 v61, v61
	v_add_f32_e32 v57, 1.0, v57
	v_mul_f32_e32 v58, 0xbfb8aa3b, v58
	v_exp_f32_e32 v60, v60
	v_exp_f32_e32 v58, v58
	v_rcp_f32_e32 v62, v57
	v_add_f32_e32 v57, 1.0, v61
	v_mul_f32_e32 v61, 0xbfb8aa3b, v63
	v_mul_f32_e32 v59, 0xbfb8aa3b, v59
	v_exp_f32_e32 v61, v61
	v_exp_f32_e32 v59, v59
	v_add_f32_e32 v60, 1.0, v60
	v_add_f32_e32 v58, 1.0, v58
	v_rcp_f32_e32 v60, v60
	v_rcp_f32_e32 v56, v56
	v_rcp_f32_e32 v63, v58
	v_add_f32_e32 v58, 1.0, v61
	v_add_f32_e32 v59, 1.0, v59
	v_mul_f32_e32 v48, 0xbfb8aa3b, v48
	v_rcp_f32_e32 v57, v57
	v_rcp_f32_e32 v58, v58
	v_rcp_f32_e32 v59, v59
	v_exp_f32_e32 v48, v48
	v_mul_f32_e32 v53, 0xbfb8aa3b, v53
	v_exp_f32_e32 v53, v53
	v_cvt_pk_bf16_f32 v56, v60, v56
	v_add_co_u32_e32 v60, vcc, s54, v144
	v_cvt_pk_bf16_f32 v57, v57, v58
	v_cvt_pk_bf16_f32 v58, v66, v62
	v_cvt_pk_bf16_f32 v59, v63, v59
	v_addc_co_u32_e32 v61, vcc, 0, v145, vcc
	v_add_f32_e32 v48, 1.0, v48
	v_mul_f32_e32 v49, 0xbfb8aa3b, v49
	global_store_dwordx4 v[60:61], v[56:59], off
	v_exp_f32_e32 v49, v49
	v_mul_f32_e32 v50, 0xbfb8aa3b, v50
	v_rcp_f32_e32 v56, v48
	v_add_f32_e32 v48, 1.0, v53
	v_mul_f32_e32 v53, 0xbfb8aa3b, v54
	v_exp_f32_e32 v53, v53
	v_add_f32_e32 v49, 1.0, v49
	v_mul_f32_e32 v52, 0xbfb8aa3b, v52
	v_exp_f32_e32 v50, v50
	v_rcp_f32_e32 v54, v49
	v_add_f32_e32 v49, 1.0, v53
	v_mul_f32_e32 v53, 0xbfb8aa3b, v55
	v_mul_f32_e32 v51, 0xbfb8aa3b, v51
	v_exp_f32_e32 v52, v52
	v_exp_f32_e32 v53, v53
	v_exp_f32_e32 v51, v51
	v_add_f32_e32 v50, 1.0, v50
	v_add_f32_e32 v52, 1.0, v52
	v_rcp_f32_e32 v55, v50
	v_add_f32_e32 v50, 1.0, v53
	v_add_f32_e32 v51, 1.0, v51
	v_mul_f32_e32 v40, 0xbfb8aa3b, v40
	v_rcp_f32_e32 v52, v52
	v_rcp_f32_e32 v48, v48
	v_rcp_f32_e32 v49, v49
	v_rcp_f32_e32 v50, v50
	v_rcp_f32_e32 v51, v51
	v_exp_f32_e32 v40, v40
	v_mul_f32_e32 v45, 0xbfb8aa3b, v45
	v_exp_f32_e32 v45, v45
	v_lshl_add_u64 v[64:65], v[144:145], 0, s[14:15]
	v_cvt_pk_bf16_f32 v48, v52, v48
	v_cvt_pk_bf16_f32 v49, v49, v50
	v_cvt_pk_bf16_f32 v50, v56, v54
	v_cvt_pk_bf16_f32 v51, v55, v51
	v_add_f32_e32 v40, 1.0, v40
	v_mul_f32_e32 v41, 0xbfb8aa3b, v41
	global_store_dwordx4 v[64:65], v[48:51], off offset:256
	v_exp_f32_e32 v41, v41
	v_mul_f32_e32 v44, 0xbfb8aa3b, v44
	v_rcp_f32_e32 v50, v40
	v_add_f32_e32 v40, 1.0, v45
	v_mul_f32_e32 v45, 0xbfb8aa3b, v46
	v_exp_f32_e32 v45, v45
	v_add_f32_e32 v41, 1.0, v41
	v_mul_f32_e32 v42, 0xbfb8aa3b, v42
	v_exp_f32_e32 v44, v44
	v_exp_f32_e32 v42, v42
	v_rcp_f32_e32 v46, v41
	v_add_f32_e32 v41, 1.0, v45
	v_mul_f32_e32 v45, 0xbfb8aa3b, v47
	v_mul_f32_e32 v43, 0xbfb8aa3b, v43
	v_exp_f32_e32 v45, v45
	v_exp_f32_e32 v43, v43
	v_add_f32_e32 v44, 1.0, v44
	v_add_f32_e32 v42, 1.0, v42
	v_rcp_f32_e32 v44, v44
	v_rcp_f32_e32 v40, v40
	v_rcp_f32_e32 v47, v42
	v_add_f32_e32 v42, 1.0, v45
	v_add_f32_e32 v43, 1.0, v43
	v_mul_f32_e32 v32, 0xbfb8aa3b, v32
	v_rcp_f32_e32 v41, v41
	v_rcp_f32_e32 v42, v42
	v_rcp_f32_e32 v43, v43
	v_exp_f32_e32 v32, v32
	v_mul_f32_e32 v37, 0xbfb8aa3b, v37
	v_exp_f32_e32 v37, v37
	v_cvt_pk_bf16_f32 v40, v44, v40
	v_add_co_u32_e32 v44, vcc, s55, v144
	v_cvt_pk_bf16_f32 v41, v41, v42
	v_cvt_pk_bf16_f32 v42, v50, v46
	v_cvt_pk_bf16_f32 v43, v47, v43
	v_addc_co_u32_e32 v45, vcc, 0, v145, vcc
	v_add_f32_e32 v32, 1.0, v32
	v_mul_f32_e32 v33, 0xbfb8aa3b, v33
	global_store_dwordx4 v[44:45], v[40:43], off
	v_exp_f32_e32 v33, v33
	v_mul_f32_e32 v34, 0xbfb8aa3b, v34
	v_rcp_f32_e32 v40, v32
	v_add_f32_e32 v32, 1.0, v37
	v_mul_f32_e32 v37, 0xbfb8aa3b, v38
	v_exp_f32_e32 v37, v37
	v_add_f32_e32 v33, 1.0, v33
	v_mul_f32_e32 v36, 0xbfb8aa3b, v36
	v_exp_f32_e32 v34, v34
	v_rcp_f32_e32 v38, v33
	v_add_f32_e32 v33, 1.0, v37
	v_mul_f32_e32 v37, 0xbfb8aa3b, v39
	v_mul_f32_e32 v35, 0xbfb8aa3b, v35
	v_exp_f32_e32 v36, v36
	v_exp_f32_e32 v37, v37
	v_exp_f32_e32 v35, v35
	v_add_f32_e32 v34, 1.0, v34
	v_add_f32_e32 v36, 1.0, v36
	v_rcp_f32_e32 v39, v34
	v_add_f32_e32 v34, 1.0, v37
	v_add_f32_e32 v35, 1.0, v35
	v_mul_f32_e32 v24, 0xbfb8aa3b, v24
	v_rcp_f32_e32 v36, v36
	v_rcp_f32_e32 v32, v32
	v_rcp_f32_e32 v33, v33
	v_rcp_f32_e32 v34, v34
	v_rcp_f32_e32 v35, v35
	v_exp_f32_e32 v24, v24
	v_mul_f32_e32 v29, 0xbfb8aa3b, v29
	v_exp_f32_e32 v29, v29
	v_lshl_add_u64 v[48:49], v[144:145], 0, s[22:23]
	v_cvt_pk_bf16_f32 v32, v36, v32
	v_cvt_pk_bf16_f32 v33, v33, v34
	v_cvt_pk_bf16_f32 v34, v40, v38
	v_cvt_pk_bf16_f32 v35, v39, v35
	v_add_f32_e32 v24, 1.0, v24
	v_mul_f32_e32 v25, 0xbfb8aa3b, v25
	global_store_dwordx4 v[48:49], v[32:35], off offset:256
	v_exp_f32_e32 v25, v25
	v_mul_f32_e32 v28, 0xbfb8aa3b, v28
	v_rcp_f32_e32 v34, v24
	v_add_f32_e32 v24, 1.0, v29
	v_mul_f32_e32 v29, 0xbfb8aa3b, v30
	v_exp_f32_e32 v29, v29
	v_add_f32_e32 v25, 1.0, v25
	v_mul_f32_e32 v26, 0xbfb8aa3b, v26
	v_exp_f32_e32 v28, v28
	v_exp_f32_e32 v26, v26
	v_rcp_f32_e32 v30, v25
	v_add_f32_e32 v25, 1.0, v29
	v_mul_f32_e32 v29, 0xbfb8aa3b, v31
	v_mul_f32_e32 v27, 0xbfb8aa3b, v27
	v_exp_f32_e32 v29, v29
	v_exp_f32_e32 v27, v27
	v_add_f32_e32 v28, 1.0, v28
	v_add_f32_e32 v26, 1.0, v26
	v_rcp_f32_e32 v28, v28
	v_rcp_f32_e32 v24, v24
	v_rcp_f32_e32 v31, v26
	v_add_f32_e32 v26, 1.0, v29
	v_add_f32_e32 v27, 1.0, v27
	v_mul_f32_e32 v16, 0xbfb8aa3b, v16
	v_rcp_f32_e32 v25, v25
	v_rcp_f32_e32 v26, v26
	v_rcp_f32_e32 v27, v27
	v_exp_f32_e32 v16, v16
	v_mul_f32_e32 v21, 0xbfb8aa3b, v21
	v_exp_f32_e32 v21, v21
	v_cvt_pk_bf16_f32 v24, v28, v24
	v_add_co_u32_e32 v28, vcc, s56, v144
	v_cvt_pk_bf16_f32 v25, v25, v26
	v_cvt_pk_bf16_f32 v26, v34, v30
	v_cvt_pk_bf16_f32 v27, v31, v27
	v_addc_co_u32_e32 v29, vcc, 0, v145, vcc
	v_add_f32_e32 v16, 1.0, v16
	v_mul_f32_e32 v17, 0xbfb8aa3b, v17
	global_store_dwordx4 v[28:29], v[24:27], off
	v_exp_f32_e32 v17, v17
	v_mul_f32_e32 v18, 0xbfb8aa3b, v18
	v_rcp_f32_e32 v24, v16
	v_add_f32_e32 v16, 1.0, v21
	v_mul_f32_e32 v21, 0xbfb8aa3b, v22
	v_exp_f32_e32 v21, v21
	v_add_f32_e32 v17, 1.0, v17
	v_mul_f32_e32 v20, 0xbfb8aa3b, v20
	v_exp_f32_e32 v18, v18
	v_rcp_f32_e32 v22, v17
	v_add_f32_e32 v17, 1.0, v21
	v_mul_f32_e32 v21, 0xbfb8aa3b, v23
	v_mul_f32_e32 v19, 0xbfb8aa3b, v19
	v_exp_f32_e32 v20, v20
	v_exp_f32_e32 v21, v21
	v_exp_f32_e32 v19, v19
	v_add_f32_e32 v18, 1.0, v18
	v_add_f32_e32 v20, 1.0, v20
	v_rcp_f32_e32 v23, v18
	v_add_f32_e32 v18, 1.0, v21
	v_add_f32_e32 v19, 1.0, v19
	v_mul_f32_e32 v8, 0xbfb8aa3b, v8
	v_rcp_f32_e32 v20, v20
	v_rcp_f32_e32 v16, v16
	v_rcp_f32_e32 v17, v17
	v_rcp_f32_e32 v18, v18
	v_rcp_f32_e32 v19, v19
	v_exp_f32_e32 v8, v8
	v_mul_f32_e32 v13, 0xbfb8aa3b, v13
	v_exp_f32_e32 v13, v13
	v_lshl_add_u64 v[32:33], v[144:145], 0, s[24:25]
	v_cvt_pk_bf16_f32 v16, v20, v16
	v_cvt_pk_bf16_f32 v17, v17, v18
	v_cvt_pk_bf16_f32 v18, v24, v22
	v_cvt_pk_bf16_f32 v19, v23, v19
	v_add_f32_e32 v8, 1.0, v8
	v_mul_f32_e32 v9, 0xbfb8aa3b, v9
	global_store_dwordx4 v[32:33], v[16:19], off offset:256
	v_exp_f32_e32 v9, v9
	v_mul_f32_e32 v12, 0xbfb8aa3b, v12
	v_rcp_f32_e32 v18, v8
	v_add_f32_e32 v8, 1.0, v13
	v_mul_f32_e32 v13, 0xbfb8aa3b, v14
	v_exp_f32_e32 v13, v13
	v_add_f32_e32 v9, 1.0, v9
	v_mul_f32_e32 v10, 0xbfb8aa3b, v10
	v_exp_f32_e32 v12, v12
	v_exp_f32_e32 v10, v10
	v_rcp_f32_e32 v14, v9
	v_add_f32_e32 v9, 1.0, v13
	v_mul_f32_e32 v13, 0xbfb8aa3b, v15
	v_mul_f32_e32 v11, 0xbfb8aa3b, v11
	v_exp_f32_e32 v13, v13
	v_exp_f32_e32 v11, v11
	v_add_f32_e32 v12, 1.0, v12
	v_add_f32_e32 v10, 1.0, v10
	v_rcp_f32_e32 v12, v12
	v_rcp_f32_e32 v8, v8
	v_rcp_f32_e32 v15, v10
	v_add_f32_e32 v10, 1.0, v13
	v_add_f32_e32 v11, 1.0, v11
	v_mul_f32_e32 v0, 0xbfb8aa3b, v0
	v_rcp_f32_e32 v9, v9
	v_rcp_f32_e32 v10, v10
	v_rcp_f32_e32 v11, v11
	v_exp_f32_e32 v0, v0
	v_mul_f32_e32 v5, 0xbfb8aa3b, v5
	v_exp_f32_e32 v5, v5
	v_cvt_pk_bf16_f32 v8, v12, v8
	v_add_co_u32_e32 v12, vcc, s57, v144
	v_cvt_pk_bf16_f32 v9, v9, v10
	v_cvt_pk_bf16_f32 v10, v18, v14
	v_cvt_pk_bf16_f32 v11, v15, v11
	v_addc_co_u32_e32 v13, vcc, 0, v145, vcc
	v_add_f32_e32 v0, 1.0, v0
	v_mul_f32_e32 v1, 0xbfb8aa3b, v1
	global_store_dwordx4 v[12:13], v[8:11], off
	v_exp_f32_e32 v1, v1
	v_mul_f32_e32 v2, 0xbfb8aa3b, v2
	v_rcp_f32_e32 v8, v0
	v_add_f32_e32 v0, 1.0, v5
	v_mul_f32_e32 v5, 0xbfb8aa3b, v6
	v_exp_f32_e32 v5, v5
	v_add_f32_e32 v1, 1.0, v1
	v_mul_f32_e32 v4, 0xbfb8aa3b, v4
	v_exp_f32_e32 v2, v2
	v_rcp_f32_e32 v6, v1
	v_add_f32_e32 v1, 1.0, v5
	v_mul_f32_e32 v5, 0xbfb8aa3b, v7
	v_mul_f32_e32 v3, 0xbfb8aa3b, v3
	v_exp_f32_e32 v4, v4
	v_exp_f32_e32 v5, v5
	v_exp_f32_e32 v3, v3
	v_add_f32_e32 v2, 1.0, v2
	v_add_f32_e32 v4, 1.0, v4
	v_rcp_f32_e32 v7, v2
	v_add_f32_e32 v2, 1.0, v5
	v_add_f32_e32 v3, 1.0, v3
	v_rcp_f32_e32 v4, v4
	v_rcp_f32_e32 v0, v0
	v_rcp_f32_e32 v1, v1
	v_rcp_f32_e32 v2, v2
	v_rcp_f32_e32 v3, v3
	v_lshl_add_u64 v[16:17], v[144:145], 0, s[26:27]
	v_cvt_pk_bf16_f32 v0, v4, v0
	v_cvt_pk_bf16_f32 v1, v1, v2
	v_cvt_pk_bf16_f32 v2, v8, v6
	v_cvt_pk_bf16_f32 v3, v7, v3
	s_andn2_b64 vcc, exec, s[8:9]
	s_mov_b64 s[8:9], -1
	global_store_dwordx4 v[16:17], v[0:3], off offset:256
	s_cbranch_vccnz .LBB0_1103
	s_andn2_b64 vcc, exec, s[16:17]
	s_cbranch_vccnz .LBB0_1102
	s_mov_b32 s100, 1
	s_branch .LBB0_1102

.LBB0_1275:
	s_add_u32 s12, s8, 0x11800000
	s_addc_u32 s13, s9, 0
	s_lshl_b32 s8, s14, 5
	s_mov_b64 s[14:15], 0x80
	s_and_b32 s19, s8, 0x60
	s_add_i32 m0, s34, 0x18000
	v_lshl_add_u64 v[6:7], v[6:7], 0, s[14:15]
	s_lshl_b32 s18, s17, 13
	s_lshl_b32 s20, s19, 7
	s_waitcnt vmcnt(2)
	s_barrier
	global_load_lds_dwordx4 v[6:7], off
	v_lshl_add_u64 v[4:5], v[4:5], 0, s[14:15]
	s_add_i32 m0, s34, 0x1a000
	s_add_i32 s39, s34, 0x8000
	s_add_i32 s40, s34, 0xa000
	global_load_lds_dwordx4 v[4:5], off
	v_lshl_add_u64 v[0:1], v[0:1], 0, s[14:15]
	s_mov_b32 m0, s39
	s_add_u32 s8, s26, 0x40080
	global_load_lds_dwordx4 v[0:1], off
	v_lshl_add_u64 v[0:1], v[2:3], 0, s[14:15]
	s_mov_b32 m0, s40
	s_addc_u32 s9, s27, 0
	global_load_lds_dwordx4 v[0:1], off
	s_add_i32 m0, s34, 0x1c000
	v_lshl_add_u64 v[0:1], s[8:9], 0, v[132:133]
	global_load_lds_dwordx4 v[0:1], off
	v_lshl_add_u64 v[0:1], s[8:9], 0, v[128:129]
	s_add_i32 m0, s34, 0x1e000
	s_cmpk_lt_u32 s16, 0x100
	global_load_lds_dwordx4 v[0:1], off
	v_lshrrev_b32_e32 v1, 1, v8
	v_and_b32_e32 v1, 24, v1
	v_and_b32_e32 v0, 15, v8
	v_lshlrev_b32_e32 v2, 1, v1
	v_lshl_or_b32 v146, s17, 6, v0
	v_lshl_or_b32 v0, v0, 6, v2
	v_lshlrev_b32_e32 v2, 2, v8
	v_and_b32_e32 v2, 32, v2
	v_bitop3_b32 v3, v0, s18, v2 bitop3:0xde
	v_bitop3_b32 v147, s20, v0, v2 bitop3:0xf6
	v_lshlrev_b32_e32 v0, 14, v9
	v_and_b32_e32 v0, 0xffff8000, v0
	v_or_b32_e32 v148, s19, v1
	v_lshl_add_u32 v0, v10, 11, v0
	v_and_b32_e32 v1, 1, v9
	v_lshl_or_b32 v0, v1, 6, v0
	v_lshl_add_u32 v136, v11, 1, v0
	v_lshlrev_b32_e32 v0, 14, v13
	v_and_b32_e32 v0, 0xffff8000, v0
	s_waitcnt vmcnt(6)
	v_lshl_add_u32 v0, v12, 11, v0
	v_and_b32_e32 v1, 1, v13
	s_cselect_b64 s[16:17], -1, 0
	v_lshl_or_b32 v0, v1, 6, v0
	s_add_i32 s42, 0, 0x10000
	s_add_i32 s43, 0, 0x14000
	v_mov_b32_e32 v137, v133
	v_lshl_add_u32 v138, v14, 1, v0
	v_mov_b32_e32 v139, v133
	v_mov_b64_e32 v[140:141], 0xb00
	v_mov_b64_e32 v[142:143], 0xaff
	s_movk_i32 s41, 0x161
	v_add_u32_e32 v149, s42, v147
	v_add_u32_e32 v150, s43, v147
	v_add_u32_e32 v151, 0, v3
	s_movk_i32 s44, 0x1600
	s_mov_b32 s45, s86
	s_mov_b32 s46, s88
	s_barrier
	s_mov_b32 s100, 0
	s_branch .LBB0_1278

.LBB0_1280:
	s_ashr_i32 s21, s20, 31
	s_lshl_b64 s[22:23], s[20:21], 19
	s_add_u32 s22, s0, s22
	s_addc_u32 s23, s1, s23
	s_and_b64 s[24:25], s[8:9], exec
	s_cselect_b32 s21, s23, s29
	s_cselect_b32 s47, s22, s28
	s_ashr_i32 s19, s18, 31
	s_lshl_b64 s[24:25], s[18:19], 19
	s_add_u32 s24, s4, s24
	s_addc_u32 s25, s5, s25
	s_and_b64 s[30:31], s[8:9], exec
	s_cselect_b32 s19, s25, s27
	s_cselect_b32 s48, s24, s26
	s_add_u32 s49, s26, 0x100
	s_addc_u32 s50, s27, 0
	s_add_u32 s26, s28, 0x40080
	v_mov_b32_e32 v0, 0
	s_addc_u32 s27, s29, 0
	s_mov_b32 s51, -2
	v_mov_b32_e32 v1, v0
	v_mov_b32_e32 v2, v0
	v_mov_b32_e32 v3, v0
	v_mov_b32_e32 v4, v0
	v_mov_b32_e32 v5, v0
	v_mov_b32_e32 v6, v0
	v_mov_b32_e32 v7, v0
	v_mov_b32_e32 v16, v0
	v_mov_b32_e32 v17, v0
	v_mov_b32_e32 v18, v0
	v_mov_b32_e32 v19, v0
	v_mov_b32_e32 v20, v0
	v_mov_b32_e32 v21, v0
	v_mov_b32_e32 v22, v0
	v_mov_b32_e32 v23, v0
	v_mov_b32_e32 v32, v0
	v_mov_b32_e32 v33, v0
	v_mov_b32_e32 v34, v0
	v_mov_b32_e32 v35, v0
	v_mov_b32_e32 v36, v0
	v_mov_b32_e32 v37, v0
	v_mov_b32_e32 v38, v0
	v_mov_b32_e32 v39, v0
	v_mov_b32_e32 v48, v0
	v_mov_b32_e32 v49, v0
	v_mov_b32_e32 v50, v0
	v_mov_b32_e32 v51, v0
	v_mov_b32_e32 v52, v0
	v_mov_b32_e32 v53, v0
	v_mov_b32_e32 v54, v0
	v_mov_b32_e32 v55, v0
	v_mov_b32_e32 v8, v0
	v_mov_b32_e32 v9, v0
	v_mov_b32_e32 v10, v0
	v_mov_b32_e32 v11, v0
	v_mov_b32_e32 v12, v0
	v_mov_b32_e32 v13, v0
	v_mov_b32_e32 v14, v0
	v_mov_b32_e32 v15, v0
	v_mov_b32_e32 v24, v0
	v_mov_b32_e32 v25, v0
	v_mov_b32_e32 v26, v0
	v_mov_b32_e32 v27, v0
	v_mov_b32_e32 v28, v0
	v_mov_b32_e32 v29, v0
	v_mov_b32_e32 v30, v0
	v_mov_b32_e32 v31, v0
	v_mov_b32_e32 v40, v0
	v_mov_b32_e32 v41, v0
	v_mov_b32_e32 v42, v0
	v_mov_b32_e32 v43, v0
	v_mov_b32_e32 v44, v0
	v_mov_b32_e32 v45, v0
	v_mov_b32_e32 v46, v0
	v_mov_b32_e32 v47, v0
	v_mov_b32_e32 v56, v0
	v_mov_b32_e32 v57, v0
	v_mov_b32_e32 v58, v0
	v_mov_b32_e32 v59, v0
	v_mov_b32_e32 v60, v0
	v_mov_b32_e32 v61, v0
	v_mov_b32_e32 v62, v0
	v_mov_b32_e32 v63, v0
	v_mov_b32_e32 v64, v0
	v_mov_b32_e32 v65, v0
	v_mov_b32_e32 v66, v0
	v_mov_b32_e32 v67, v0
	v_mov_b32_e32 v68, v0
	v_mov_b32_e32 v69, v0
	v_mov_b32_e32 v70, v0
	v_mov_b32_e32 v71, v0
	v_mov_b32_e32 v80, v0
	v_mov_b32_e32 v81, v0
	v_mov_b32_e32 v82, v0
	v_mov_b32_e32 v83, v0
	v_mov_b32_e32 v84, v0
	v_mov_b32_e32 v85, v0
	v_mov_b32_e32 v86, v0
	v_mov_b32_e32 v87, v0
	v_mov_b32_e32 v96, v0
	v_mov_b32_e32 v97, v0
	v_mov_b32_e32 v98, v0
	v_mov_b32_e32 v99, v0
	v_mov_b32_e32 v100, v0
	v_mov_b32_e32 v101, v0
	v_mov_b32_e32 v102, v0
	v_mov_b32_e32 v103, v0
	v_mov_b32_e32 v112, v0
	v_mov_b32_e32 v113, v0
	v_mov_b32_e32 v114, v0
	v_mov_b32_e32 v115, v0
	v_mov_b32_e32 v116, v0
	v_mov_b32_e32 v117, v0
	v_mov_b32_e32 v118, v0
	v_mov_b32_e32 v119, v0
	v_mov_b32_e32 v72, v0
	v_mov_b32_e32 v73, v0
	v_mov_b32_e32 v74, v0
	v_mov_b32_e32 v75, v0
	v_mov_b32_e32 v76, v0
	v_mov_b32_e32 v77, v0
	v_mov_b32_e32 v78, v0
	v_mov_b32_e32 v79, v0
	v_mov_b32_e32 v88, v0
	v_mov_b32_e32 v89, v0
	v_mov_b32_e32 v90, v0
	v_mov_b32_e32 v91, v0
	v_mov_b32_e32 v92, v0
	v_mov_b32_e32 v93, v0
	v_mov_b32_e32 v94, v0
	v_mov_b32_e32 v95, v0
	v_mov_b32_e32 v104, v0
	v_mov_b32_e32 v105, v0
	v_mov_b32_e32 v106, v0
	v_mov_b32_e32 v107, v0
	v_mov_b32_e32 v108, v0
	v_mov_b32_e32 v109, v0
	v_mov_b32_e32 v110, v0
	v_mov_b32_e32 v111, v0
	v_mov_b32_e32 v120, v0
	v_mov_b32_e32 v121, v0
	v_mov_b32_e32 v122, v0
	v_mov_b32_e32 v123, v0
	v_mov_b32_e32 v124, v0
	v_mov_b32_e32 v125, v0
	v_mov_b32_e32 v126, v0
	v_mov_b32_e32 v127, v0
	s_cmp_eq_u32 s100, 1
	s_cbranch_scc0 .Lgemm_nobar_1276
	s_mov_b32 s100, 0
	s_barrier
.Lgemm_nobar_1276:
.LBB0_1281:
	ds_read_b128 v[152:155], v149
	ds_read_b128 v[156:159], v149 offset:1024
	ds_read_b128 v[160:163], v149 offset:2048
	ds_read_b128 v[164:167], v149 offset:3072
	ds_read_b128 v[168:171], v150
	ds_read_b128 v[172:175], v150 offset:1024
	ds_read_b128 v[176:179], v150 offset:2048
	ds_read_b128 v[180:183], v150 offset:3072
	s_add_u32 s28, s26, 0xfffc0080
	s_addc_u32 s29, s27, -1
	s_cmp_eq_u32 s51, 12
	s_cselect_b32 s31, s21, s29
	s_cselect_b32 s30, s47, s28
	s_cselect_b32 s29, s19, s50
	s_cselect_b32 s28, s48, s49
	v_lshl_add_u64 v[144:145], s[26:27], 0, v[138:139]
	s_add_i32 m0, s34, 0xc000
	ds_read_b128 v[184:187], v151
	ds_read_b128 v[188:191], v151 offset:1024
	ds_read_b128 v[192:195], v151 offset:2048
	ds_read_b128 v[196:199], v151 offset:3072
	ds_read_b128 v[200:203], v151 offset:4096
	ds_read_b128 v[204:207], v151 offset:5120
	ds_read_b128 v[208:211], v151 offset:6144
	ds_read_b128 v[212:215], v151 offset:7168
	global_load_lds_dwordx4 v[144:145], off
	v_lshl_add_u64 v[144:145], s[26:27], 0, v[136:137]
	s_add_i32 m0, s34, 0xe000
	s_nop 0
	global_load_lds_dwordx4 v[144:145], off
	s_waitcnt vmcnt(8)
	s_waitcnt lgkmcnt(0)
	s_barrier
	s_setprio 1
	s_waitcnt lgkmcnt(0)
	v_mfma_f32_16x16x32_bf16 v[124:127], v[152:155], v[184:187], v[124:127]
	v_mfma_f32_16x16x32_bf16 v[120:123], v[160:163], v[184:187], v[120:123]
	v_mfma_f32_16x16x32_bf16 v[108:111], v[152:155], v[192:195], v[108:111]
	v_mfma_f32_16x16x32_bf16 v[104:107], v[160:163], v[192:195], v[104:107]
	v_mfma_f32_16x16x32_bf16 v[92:95], v[152:155], v[200:203], v[92:95]
	v_mfma_f32_16x16x32_bf16 v[88:91], v[160:163], v[200:203], v[88:91]
	v_mfma_f32_16x16x32_bf16 v[76:79], v[152:155], v[208:211], v[76:79]
	v_mfma_f32_16x16x32_bf16 v[72:75], v[160:163], v[208:211], v[72:75]
	v_mfma_f32_16x16x32_bf16 v[124:127], v[156:159], v[188:191], v[124:127]
	v_mfma_f32_16x16x32_bf16 v[120:123], v[164:167], v[188:191], v[120:123]
	v_mfma_f32_16x16x32_bf16 v[108:111], v[156:159], v[196:199], v[108:111]
	v_mfma_f32_16x16x32_bf16 v[104:107], v[164:167], v[196:199], v[104:107]
	v_mfma_f32_16x16x32_bf16 v[92:95], v[156:159], v[204:207], v[92:95]
	v_mfma_f32_16x16x32_bf16 v[88:91], v[164:167], v[204:207], v[88:91]
	v_mfma_f32_16x16x32_bf16 v[76:79], v[156:159], v[212:215], v[76:79]
	v_mfma_f32_16x16x32_bf16 v[72:75], v[164:167], v[212:215], v[72:75]
	s_setprio 0
	s_setprio 1
	v_mfma_f32_16x16x32_bf16 v[116:119], v[168:171], v[184:187], v[116:119]
	v_mfma_f32_16x16x32_bf16 v[112:115], v[176:179], v[184:187], v[112:115]
	v_mfma_f32_16x16x32_bf16 v[100:103], v[168:171], v[192:195], v[100:103]
	v_mfma_f32_16x16x32_bf16 v[96:99], v[176:179], v[192:195], v[96:99]
	v_mfma_f32_16x16x32_bf16 v[84:87], v[168:171], v[200:203], v[84:87]
	v_mfma_f32_16x16x32_bf16 v[80:83], v[176:179], v[200:203], v[80:83]
	v_mfma_f32_16x16x32_bf16 v[68:71], v[168:171], v[208:211], v[68:71]
	v_mfma_f32_16x16x32_bf16 v[64:67], v[176:179], v[208:211], v[64:67]
	v_mfma_f32_16x16x32_bf16 v[116:119], v[172:175], v[188:191], v[116:119]
	v_mfma_f32_16x16x32_bf16 v[112:115], v[180:183], v[188:191], v[112:115]
	v_mfma_f32_16x16x32_bf16 v[100:103], v[172:175], v[196:199], v[100:103]
	v_mfma_f32_16x16x32_bf16 v[96:99], v[180:183], v[196:199], v[96:99]
	v_mfma_f32_16x16x32_bf16 v[84:87], v[172:175], v[204:207], v[84:87]
	v_mfma_f32_16x16x32_bf16 v[80:83], v[180:183], v[204:207], v[80:83]
	v_mfma_f32_16x16x32_bf16 v[68:71], v[172:175], v[212:215], v[68:71]
	v_mfma_f32_16x16x32_bf16 v[64:67], v[180:183], v[212:215], v[64:67]
	s_setprio 0
	s_barrier
	s_add_i32 s52, s42, s33
	v_lshl_add_u64 v[144:145], s[28:29], 0, v[132:133]
	s_mov_b32 m0, s52
	ds_read_b128 v[184:187], v151 offset:16384
	ds_read_b128 v[188:191], v151 offset:17408
	ds_read_b128 v[192:195], v151 offset:18432
	ds_read_b128 v[196:199], v151 offset:19456
	ds_read_b128 v[200:203], v151 offset:20480
	ds_read_b128 v[204:207], v151 offset:21504
	ds_read_b128 v[208:211], v151 offset:22528
	ds_read_b128 v[212:215], v151 offset:23552
	global_load_lds_dwordx4 v[144:145], off
	s_add_i32 m0, s52, 0x2000
	s_add_u32 s52, s28, 0x40000
	v_lshl_add_u64 v[216:217], s[28:29], 0, v[128:129]
	s_addc_u32 s53, s29, 0
	s_add_i32 s54, s43, s33
	global_load_lds_dwordx4 v[216:217], off
	v_lshl_add_u64 v[218:219], s[52:53], 0, v[132:133]
	s_mov_b32 m0, s54
	v_lshl_add_u64 v[220:221], s[30:31], 0, v[130:131]
	global_load_lds_dwordx4 v[218:219], off
	v_lshl_add_u64 v[218:219], s[52:53], 0, v[128:129]
	s_add_i32 m0, s54, 0x2000
	s_nop 0
	global_load_lds_dwordx4 v[218:219], off
	v_lshl_add_u64 v[218:219], s[30:31], 0, v[134:135]
	s_mov_b32 m0, s34
	s_nop 0
	global_load_lds_dwordx4 v[218:219], off
	s_mov_b32 m0, s35
	s_nop 0
	global_load_lds_dwordx4 v[220:221], off
	s_waitcnt vmcnt(8)
	s_waitcnt lgkmcnt(0)
	s_barrier
	s_setprio 1
	s_waitcnt lgkmcnt(0)
	v_mfma_f32_16x16x32_bf16 v[60:63], v[152:155], v[184:187], v[60:63]
	v_mfma_f32_16x16x32_bf16 v[56:59], v[160:163], v[184:187], v[56:59]
	v_mfma_f32_16x16x32_bf16 v[44:47], v[152:155], v[192:195], v[44:47]
	v_mfma_f32_16x16x32_bf16 v[40:43], v[160:163], v[192:195], v[40:43]
	v_mfma_f32_16x16x32_bf16 v[28:31], v[152:155], v[200:203], v[28:31]
	v_mfma_f32_16x16x32_bf16 v[24:27], v[160:163], v[200:203], v[24:27]
	v_mfma_f32_16x16x32_bf16 v[12:15], v[152:155], v[208:211], v[12:15]
	v_mfma_f32_16x16x32_bf16 v[8:11], v[160:163], v[208:211], v[8:11]
	v_mfma_f32_16x16x32_bf16 v[60:63], v[156:159], v[188:191], v[60:63]
	v_mfma_f32_16x16x32_bf16 v[56:59], v[164:167], v[188:191], v[56:59]
	v_mfma_f32_16x16x32_bf16 v[44:47], v[156:159], v[196:199], v[44:47]
	v_mfma_f32_16x16x32_bf16 v[40:43], v[164:167], v[196:199], v[40:43]
	v_mfma_f32_16x16x32_bf16 v[28:31], v[156:159], v[204:207], v[28:31]
	v_mfma_f32_16x16x32_bf16 v[24:27], v[164:167], v[204:207], v[24:27]
	v_mfma_f32_16x16x32_bf16 v[12:15], v[156:159], v[212:215], v[12:15]
	v_mfma_f32_16x16x32_bf16 v[8:11], v[164:167], v[212:215], v[8:11]
	s_setprio 0
	s_setprio 1
	v_mfma_f32_16x16x32_bf16 v[52:55], v[168:171], v[184:187], v[52:55]
	v_mfma_f32_16x16x32_bf16 v[48:51], v[176:179], v[184:187], v[48:51]
	v_mfma_f32_16x16x32_bf16 v[36:39], v[168:171], v[192:195], v[36:39]
	v_mfma_f32_16x16x32_bf16 v[32:35], v[176:179], v[192:195], v[32:35]
	v_mfma_f32_16x16x32_bf16 v[20:23], v[168:171], v[200:203], v[20:23]
	v_mfma_f32_16x16x32_bf16 v[16:19], v[176:179], v[200:203], v[16:19]
	v_mfma_f32_16x16x32_bf16 v[4:7], v[168:171], v[208:211], v[4:7]
	v_mfma_f32_16x16x32_bf16 v[0:3], v[176:179], v[208:211], v[0:3]
	v_mfma_f32_16x16x32_bf16 v[52:55], v[172:175], v[188:191], v[52:55]
	v_mfma_f32_16x16x32_bf16 v[48:51], v[180:183], v[188:191], v[48:51]
	v_mfma_f32_16x16x32_bf16 v[36:39], v[172:175], v[196:199], v[36:39]
	v_mfma_f32_16x16x32_bf16 v[32:35], v[180:183], v[196:199], v[32:35]
	v_mfma_f32_16x16x32_bf16 v[20:23], v[172:175], v[204:207], v[20:23]
	v_mfma_f32_16x16x32_bf16 v[16:19], v[180:183], v[204:207], v[16:19]
	v_mfma_f32_16x16x32_bf16 v[4:7], v[172:175], v[212:215], v[4:7]
	v_mfma_f32_16x16x32_bf16 v[0:3], v[180:183], v[212:215], v[0:3]
	s_setprio 0
	s_barrier
	s_add_i32 s52, 0, 0x18000
	s_add_i32 s53, 0, 0x1c000
	v_add_u32_e32 v164, s52, v147
	v_add_u32_e32 v180, s53, v147
	ds_read_b128 v[152:155], v164
	ds_read_b128 v[156:159], v164 offset:1024
	ds_read_b128 v[160:163], v164 offset:2048
	ds_read_b128 v[164:167], v164 offset:3072
	ds_read_b128 v[168:171], v180
	ds_read_b128 v[172:175], v180 offset:1024
	ds_read_b128 v[176:179], v180 offset:2048
	ds_read_b128 v[180:183], v180 offset:3072
	s_add_u32 s30, s30, 0x40000
	s_addc_u32 s31, s31, 0
	s_mov_b32 m0, s36
	v_lshl_add_u64 v[222:223], s[30:31], 0, v[134:135]
	ds_read_b128 v[184:187], v151 offset:32768
	ds_read_b128 v[188:191], v151 offset:33792
	ds_read_b128 v[192:195], v151 offset:34816
	ds_read_b128 v[196:199], v151 offset:35840
	ds_read_b128 v[200:203], v151 offset:36864
	ds_read_b128 v[204:207], v151 offset:37888
	ds_read_b128 v[208:211], v151 offset:38912
	ds_read_b128 v[212:215], v151 offset:39936
	global_load_lds_dwordx4 v[222:223], off
	v_lshl_add_u64 v[222:223], s[30:31], 0, v[130:131]
	s_mov_b32 m0, s37
	s_nop 0
	global_load_lds_dwordx4 v[222:223], off
	s_waitcnt vmcnt(8)
	s_waitcnt lgkmcnt(0)
	s_barrier
	s_setprio 1
	s_waitcnt lgkmcnt(0)
	v_mfma_f32_16x16x32_bf16 v[124:127], v[152:155], v[184:187], v[124:127]
	v_mfma_f32_16x16x32_bf16 v[120:123], v[160:163], v[184:187], v[120:123]
	v_mfma_f32_16x16x32_bf16 v[108:111], v[152:155], v[192:195], v[108:111]
	v_mfma_f32_16x16x32_bf16 v[104:107], v[160:163], v[192:195], v[104:107]
	v_mfma_f32_16x16x32_bf16 v[92:95], v[152:155], v[200:203], v[92:95]
	v_mfma_f32_16x16x32_bf16 v[88:91], v[160:163], v[200:203], v[88:91]
	v_mfma_f32_16x16x32_bf16 v[76:79], v[152:155], v[208:211], v[76:79]
	v_mfma_f32_16x16x32_bf16 v[72:75], v[160:163], v[208:211], v[72:75]
	v_mfma_f32_16x16x32_bf16 v[124:127], v[156:159], v[188:191], v[124:127]
	v_mfma_f32_16x16x32_bf16 v[120:123], v[164:167], v[188:191], v[120:123]
	v_mfma_f32_16x16x32_bf16 v[108:111], v[156:159], v[196:199], v[108:111]
	v_mfma_f32_16x16x32_bf16 v[104:107], v[164:167], v[196:199], v[104:107]
	v_mfma_f32_16x16x32_bf16 v[92:95], v[156:159], v[204:207], v[92:95]
	v_mfma_f32_16x16x32_bf16 v[88:91], v[164:167], v[204:207], v[88:91]
	v_mfma_f32_16x16x32_bf16 v[76:79], v[156:159], v[212:215], v[76:79]
	v_mfma_f32_16x16x32_bf16 v[72:75], v[164:167], v[212:215], v[72:75]
	s_setprio 0
	s_setprio 1
	v_mfma_f32_16x16x32_bf16 v[116:119], v[168:171], v[184:187], v[116:119]
	v_mfma_f32_16x16x32_bf16 v[112:115], v[176:179], v[184:187], v[112:115]
	v_mfma_f32_16x16x32_bf16 v[100:103], v[168:171], v[192:195], v[100:103]
	v_mfma_f32_16x16x32_bf16 v[96:99], v[176:179], v[192:195], v[96:99]
	v_mfma_f32_16x16x32_bf16 v[84:87], v[168:171], v[200:203], v[84:87]
	v_mfma_f32_16x16x32_bf16 v[80:83], v[176:179], v[200:203], v[80:83]
	v_mfma_f32_16x16x32_bf16 v[68:71], v[168:171], v[208:211], v[68:71]
	v_mfma_f32_16x16x32_bf16 v[64:67], v[176:179], v[208:211], v[64:67]
	v_mfma_f32_16x16x32_bf16 v[116:119], v[172:175], v[188:191], v[116:119]
	v_mfma_f32_16x16x32_bf16 v[112:115], v[180:183], v[188:191], v[112:115]
	v_mfma_f32_16x16x32_bf16 v[100:103], v[172:175], v[196:199], v[100:103]
	v_mfma_f32_16x16x32_bf16 v[96:99], v[180:183], v[196:199], v[96:99]
	v_mfma_f32_16x16x32_bf16 v[84:87], v[172:175], v[204:207], v[84:87]
	v_mfma_f32_16x16x32_bf16 v[80:83], v[180:183], v[204:207], v[80:83]
	v_mfma_f32_16x16x32_bf16 v[68:71], v[172:175], v[212:215], v[68:71]
	v_mfma_f32_16x16x32_bf16 v[64:67], v[180:183], v[212:215], v[64:67]
	s_setprio 0
	s_barrier
	s_add_i32 s30, s52, s33
	v_lshl_add_u64 v[144:145], v[144:145], 0, s[14:15]
	s_mov_b32 m0, s30
	ds_read_b128 v[184:187], v151 offset:49152
	ds_read_b128 v[188:191], v151 offset:50176
	ds_read_b128 v[192:195], v151 offset:51200
	ds_read_b128 v[196:199], v151 offset:52224
	ds_read_b128 v[200:203], v151 offset:53248
	ds_read_b128 v[204:207], v151 offset:54272
	ds_read_b128 v[208:211], v151 offset:55296
	ds_read_b128 v[212:215], v151 offset:56320
	global_load_lds_dwordx4 v[144:145], off
	s_add_i32 m0, s30, 0x2000
	s_add_u32 s28, s28, 0x40080
	v_lshl_add_u64 v[144:145], v[216:217], 0, s[14:15]
	s_addc_u32 s29, s29, 0
	s_add_i32 s30, s53, s33
	global_load_lds_dwordx4 v[144:145], off
	v_lshl_add_u64 v[144:145], s[28:29], 0, v[132:133]
	s_mov_b32 m0, s30
	s_nop 0
	global_load_lds_dwordx4 v[144:145], off
	v_lshl_add_u64 v[144:145], s[28:29], 0, v[128:129]
	s_add_i32 m0, s30, 0x2000
	s_nop 0
	global_load_lds_dwordx4 v[144:145], off
	v_lshl_add_u64 v[144:145], v[218:219], 0, s[14:15]
	s_mov_b32 m0, s39
	s_nop 0
	global_load_lds_dwordx4 v[144:145], off
	v_lshl_add_u64 v[144:145], v[220:221], 0, s[14:15]
	s_mov_b32 m0, s40
	s_nop 0
	global_load_lds_dwordx4 v[144:145], off
	s_waitcnt vmcnt(8)
	s_waitcnt lgkmcnt(0)
	s_barrier
	s_setprio 1
	s_waitcnt lgkmcnt(0)
	v_mfma_f32_16x16x32_bf16 v[60:63], v[152:155], v[184:187], v[60:63]
	v_mfma_f32_16x16x32_bf16 v[56:59], v[160:163], v[184:187], v[56:59]
	v_mfma_f32_16x16x32_bf16 v[44:47], v[152:155], v[192:195], v[44:47]
	v_mfma_f32_16x16x32_bf16 v[40:43], v[160:163], v[192:195], v[40:43]
	v_mfma_f32_16x16x32_bf16 v[28:31], v[152:155], v[200:203], v[28:31]
	v_mfma_f32_16x16x32_bf16 v[24:27], v[160:163], v[200:203], v[24:27]
	v_mfma_f32_16x16x32_bf16 v[12:15], v[152:155], v[208:211], v[12:15]
	v_mfma_f32_16x16x32_bf16 v[8:11], v[160:163], v[208:211], v[8:11]
	v_mfma_f32_16x16x32_bf16 v[60:63], v[156:159], v[188:191], v[60:63]
	v_mfma_f32_16x16x32_bf16 v[56:59], v[164:167], v[188:191], v[56:59]
	v_mfma_f32_16x16x32_bf16 v[44:47], v[156:159], v[196:199], v[44:47]
	v_mfma_f32_16x16x32_bf16 v[40:43], v[164:167], v[196:199], v[40:43]
	v_mfma_f32_16x16x32_bf16 v[28:31], v[156:159], v[204:207], v[28:31]
	v_mfma_f32_16x16x32_bf16 v[24:27], v[164:167], v[204:207], v[24:27]
	v_mfma_f32_16x16x32_bf16 v[12:15], v[156:159], v[212:215], v[12:15]
	v_mfma_f32_16x16x32_bf16 v[8:11], v[164:167], v[212:215], v[8:11]
	s_setprio 0
	s_setprio 1
	v_mfma_f32_16x16x32_bf16 v[52:55], v[168:171], v[184:187], v[52:55]
	v_mfma_f32_16x16x32_bf16 v[48:51], v[176:179], v[184:187], v[48:51]
	v_mfma_f32_16x16x32_bf16 v[36:39], v[168:171], v[192:195], v[36:39]
	v_mfma_f32_16x16x32_bf16 v[32:35], v[176:179], v[192:195], v[32:35]
	v_mfma_f32_16x16x32_bf16 v[20:23], v[168:171], v[200:203], v[20:23]
	v_mfma_f32_16x16x32_bf16 v[16:19], v[176:179], v[200:203], v[16:19]
	v_mfma_f32_16x16x32_bf16 v[4:7], v[168:171], v[208:211], v[4:7]
	v_mfma_f32_16x16x32_bf16 v[0:3], v[176:179], v[208:211], v[0:3]
	v_mfma_f32_16x16x32_bf16 v[52:55], v[172:175], v[188:191], v[52:55]
	v_mfma_f32_16x16x32_bf16 v[48:51], v[180:183], v[188:191], v[48:51]
	v_mfma_f32_16x16x32_bf16 v[36:39], v[172:175], v[196:199], v[36:39]
	v_mfma_f32_16x16x32_bf16 v[32:35], v[180:183], v[196:199], v[32:35]
	v_mfma_f32_16x16x32_bf16 v[20:23], v[172:175], v[204:207], v[20:23]
	v_mfma_f32_16x16x32_bf16 v[16:19], v[180:183], v[204:207], v[16:19]
	v_mfma_f32_16x16x32_bf16 v[4:7], v[172:175], v[212:215], v[4:7]
	v_mfma_f32_16x16x32_bf16 v[0:3], v[180:183], v[212:215], v[0:3]
	s_setprio 0
	s_barrier
	s_add_i32 s51, s51, 2
	s_add_u32 s49, s49, 0x100
	s_addc_u32 s50, s50, 0
	s_add_u32 s26, s26, 0x100
	s_addc_u32 s27, s27, 0
	s_cmp_gt_u32 s51, 13
	s_cbranch_scc0 .LBB0_1281
	s_and_b64 vcc, exec, s[16:17]
	s_cbranch_vccz .LBB0_1284
	s_barrier
.LBB0_1284:
	v_mul_f32_e32 v153, 0xbfb8aa3b, v124
	v_mul_f32_e32 v154, 0xbfb8aa3b, v120
	v_exp_f32_e32 v153, v153
	v_exp_f32_e32 v155, v154
	v_mul_f32_e32 v154, 0xbfb8aa3b, v125
	v_exp_f32_e32 v156, v154
	v_add_f32_e32 v153, 1.0, v153
	v_rcp_f32_e32 v154, v153
	v_add_f32_e32 v153, 1.0, v155
	v_add_f32_e32 v155, 1.0, v156
	v_rcp_f32_e32 v155, v155
	v_mul_f32_e32 v156, 0xbfb8aa3b, v121
	v_exp_f32_e32 v157, v156
	v_rcp_f32_e32 v156, v153
	v_pk_mul_f32 v[124:125], v[124:125], v[154:155]
	v_mul_f32_e32 v153, 0xbfb8aa3b, v127
	v_pk_mul_f32 v[116:117], v[124:125], v[116:117]
	v_add_f32_e32 v124, 1.0, v157
	v_mul_f32_e32 v125, 0xbfb8aa3b, v122
	v_rcp_f32_e32 v157, v124
	v_mul_f32_e32 v124, 0xbfb8aa3b, v126
	v_exp_f32_e32 v125, v125
	v_exp_f32_e32 v124, v124
	v_exp_f32_e32 v153, v153
	v_mul_f32_e32 v154, 0xbfb8aa3b, v123
	v_exp_f32_e32 v155, v154
	v_add_f32_e32 v125, 1.0, v125
	v_add_f32_e32 v124, 1.0, v124
	v_rcp_f32_e32 v154, v125
	v_add_f32_e32 v125, 1.0, v153
	v_rcp_f32_e32 v124, v124
	v_rcp_f32_e32 v125, v125
	v_add_f32_e32 v153, 1.0, v155
	v_rcp_f32_e32 v155, v153
	v_pk_mul_f32 v[120:121], v[120:121], v[156:157]
	v_lshl_or_b32 v144, s45, 7, v148
	v_pk_mul_f32 v[120:121], v[120:121], v[112:113]
	v_pk_mul_f32 v[112:113], v[126:127], v[124:125]
	s_mov_b64 s[26:27], s[12:13]
	v_ashrrev_i32_e32 v145, 31, v144
	v_pk_mul_f32 v[118:119], v[112:113], v[118:119]
	v_pk_mul_f32 v[112:113], v[122:123], v[154:155]
	v_lshl_add_u32 v152, s46, 8, v146
	v_lshl_add_u64 v[144:145], v[144:145], 1, s[26:27]
	v_pk_mul_f32 v[122:123], v[112:113], v[114:115]
	v_mad_i64_i32 v[124:125], s[26:27], v152, s44, v[144:145]
	v_cvt_pk_bf16_f32 v112, v116, v117
	v_cvt_pk_bf16_f32 v113, v118, v119
	v_cvt_pk_bf16_f32 v114, v120, v121
	v_cvt_pk_bf16_f32 v115, v122, v123
	global_store_dwordx4 v[124:125], v[112:115], off
	v_or_b32_e32 v116, 16, v152
	s_andn2_b64 vcc, exec, s[8:9]
	v_mul_f32_e32 v112, 0xbfb8aa3b, v108
	v_mul_f32_e32 v113, 0xbfb8aa3b, v104
	v_mul_f32_e32 v114, 0xbfb8aa3b, v109
	v_exp_f32_e32 v112, v112
	v_exp_f32_e32 v113, v113
	v_exp_f32_e32 v114, v114
	s_mov_b64 s[8:9], -1
	v_add_f32_e32 v112, 1.0, v112
	v_add_f32_e32 v115, 1.0, v113
	v_add_f32_e32 v113, 1.0, v114
	v_rcp_f32_e32 v112, v112
	v_rcp_f32_e32 v113, v113
	v_mul_f32_e32 v114, 0xbfb8aa3b, v105
	v_exp_f32_e32 v117, v114
	v_rcp_f32_e32 v114, v115
	v_pk_mul_f32 v[108:109], v[108:109], v[112:113]
	v_mul_f32_e32 v112, 0xbfb8aa3b, v111
	v_pk_mul_f32 v[100:101], v[108:109], v[100:101]
	v_add_f32_e32 v108, 1.0, v117
	v_rcp_f32_e32 v115, v108
	v_mul_f32_e32 v109, 0xbfb8aa3b, v106
	v_mul_f32_e32 v108, 0xbfb8aa3b, v110
	v_exp_f32_e32 v109, v109
	v_exp_f32_e32 v108, v108
	v_exp_f32_e32 v113, v112
	v_mul_f32_e32 v112, 0xbfb8aa3b, v107
	v_pk_mul_f32 v[104:105], v[104:105], v[114:115]
	v_exp_f32_e32 v114, v112
	v_add_f32_e32 v109, 1.0, v109
	v_add_f32_e32 v108, 1.0, v108
	v_rcp_f32_e32 v112, v109
	v_add_f32_e32 v109, 1.0, v113
	v_rcp_f32_e32 v108, v108
	v_rcp_f32_e32 v109, v109
	v_add_f32_e32 v113, 1.0, v114
	v_rcp_f32_e32 v113, v113
	v_pk_mul_f32 v[104:105], v[104:105], v[96:97]
	v_pk_mul_f32 v[96:97], v[110:111], v[108:109]
	v_mad_i64_i32 v[108:109], s[26:27], v116, s44, v[144:145]
	v_pk_mul_f32 v[102:103], v[96:97], v[102:103]
	v_pk_mul_f32 v[96:97], v[106:107], v[112:113]
	s_nop 0
	v_pk_mul_f32 v[106:107], v[96:97], v[98:99]
	v_cvt_pk_bf16_f32 v96, v100, v101
	v_cvt_pk_bf16_f32 v97, v102, v103
	v_cvt_pk_bf16_f32 v98, v104, v105
	v_cvt_pk_bf16_f32 v99, v106, v107
	global_store_dwordx4 v[108:109], v[96:99], off
	v_or_b32_e32 v100, 32, v152
	s_nop 0
	v_mul_f32_e32 v96, 0xbfb8aa3b, v92
	v_mul_f32_e32 v97, 0xbfb8aa3b, v88
	v_mul_f32_e32 v98, 0xbfb8aa3b, v93
	v_exp_f32_e32 v96, v96
	v_exp_f32_e32 v97, v97
	v_exp_f32_e32 v98, v98
	v_add_f32_e32 v96, 1.0, v96
	v_add_f32_e32 v99, 1.0, v97
	v_add_f32_e32 v97, 1.0, v98
	v_rcp_f32_e32 v96, v96
	v_rcp_f32_e32 v97, v97
	v_mul_f32_e32 v98, 0xbfb8aa3b, v89
	v_exp_f32_e32 v101, v98
	v_rcp_f32_e32 v98, v99
	v_pk_mul_f32 v[92:93], v[92:93], v[96:97]
	v_mul_f32_e32 v96, 0xbfb8aa3b, v95
	v_pk_mul_f32 v[84:85], v[92:93], v[84:85]
	v_add_f32_e32 v92, 1.0, v101
	v_rcp_f32_e32 v99, v92
	v_mul_f32_e32 v93, 0xbfb8aa3b, v90
	v_mul_f32_e32 v92, 0xbfb8aa3b, v94
	v_exp_f32_e32 v93, v93
	v_exp_f32_e32 v92, v92
	v_exp_f32_e32 v97, v96
	v_mul_f32_e32 v96, 0xbfb8aa3b, v91
	v_pk_mul_f32 v[88:89], v[88:89], v[98:99]
	v_exp_f32_e32 v98, v96
	v_add_f32_e32 v93, 1.0, v93
	v_add_f32_e32 v92, 1.0, v92
	v_rcp_f32_e32 v96, v93
	v_add_f32_e32 v93, 1.0, v97
	v_rcp_f32_e32 v92, v92
	v_rcp_f32_e32 v93, v93
	v_add_f32_e32 v97, 1.0, v98
	v_rcp_f32_e32 v97, v97
	v_pk_mul_f32 v[88:89], v[88:89], v[80:81]
	v_pk_mul_f32 v[80:81], v[94:95], v[92:93]
	v_mad_i64_i32 v[92:93], s[26:27], v100, s44, v[144:145]
	v_pk_mul_f32 v[86:87], v[80:81], v[86:87]
	v_pk_mul_f32 v[80:81], v[90:91], v[96:97]
	s_nop 0
	v_pk_mul_f32 v[90:91], v[80:81], v[82:83]
	v_cvt_pk_bf16_f32 v80, v84, v85
	v_cvt_pk_bf16_f32 v81, v86, v87
	v_cvt_pk_bf16_f32 v82, v88, v89
	v_cvt_pk_bf16_f32 v83, v90, v91
	global_store_dwordx4 v[92:93], v[80:83], off
	v_or_b32_e32 v84, 48, v152
	s_nop 0
	v_mul_f32_e32 v80, 0xbfb8aa3b, v76
	v_mul_f32_e32 v81, 0xbfb8aa3b, v72
	v_mul_f32_e32 v82, 0xbfb8aa3b, v77
	v_exp_f32_e32 v80, v80
	v_exp_f32_e32 v81, v81
	v_exp_f32_e32 v82, v82
	v_add_f32_e32 v80, 1.0, v80
	v_add_f32_e32 v83, 1.0, v81
	v_add_f32_e32 v81, 1.0, v82
	v_rcp_f32_e32 v80, v80
	v_rcp_f32_e32 v81, v81
	v_mul_f32_e32 v82, 0xbfb8aa3b, v73
	v_exp_f32_e32 v85, v82
	v_rcp_f32_e32 v82, v83
	v_pk_mul_f32 v[76:77], v[76:77], v[80:81]
	v_mul_f32_e32 v80, 0xbfb8aa3b, v79
	v_pk_mul_f32 v[68:69], v[76:77], v[68:69]
	v_add_f32_e32 v76, 1.0, v85
	v_rcp_f32_e32 v83, v76
	v_mul_f32_e32 v77, 0xbfb8aa3b, v74
	v_mul_f32_e32 v76, 0xbfb8aa3b, v78
	v_exp_f32_e32 v77, v77
	v_exp_f32_e32 v76, v76
	v_exp_f32_e32 v81, v80
	v_mul_f32_e32 v80, 0xbfb8aa3b, v75
	v_pk_mul_f32 v[72:73], v[72:73], v[82:83]
	v_exp_f32_e32 v82, v80
	v_add_f32_e32 v77, 1.0, v77
	v_add_f32_e32 v76, 1.0, v76
	v_rcp_f32_e32 v80, v77
	v_add_f32_e32 v77, 1.0, v81
	v_rcp_f32_e32 v76, v76
	v_rcp_f32_e32 v77, v77
	v_add_f32_e32 v81, 1.0, v82
	v_rcp_f32_e32 v81, v81
	v_pk_mul_f32 v[72:73], v[72:73], v[64:65]
	v_pk_mul_f32 v[64:65], v[78:79], v[76:77]
	v_mad_i64_i32 v[76:77], s[26:27], v84, s44, v[144:145]
	v_pk_mul_f32 v[70:71], v[64:65], v[70:71]
	v_pk_mul_f32 v[64:65], v[74:75], v[80:81]
	s_nop 0
	v_pk_mul_f32 v[74:75], v[64:65], v[66:67]
	v_cvt_pk_bf16_f32 v64, v68, v69
	v_cvt_pk_bf16_f32 v65, v70, v71
	v_cvt_pk_bf16_f32 v66, v72, v73
	v_cvt_pk_bf16_f32 v67, v74, v75
	global_store_dwordx4 v[76:77], v[64:67], off
	v_add_u32_e32 v68, 0x80, v152
	s_nop 0
	v_mul_f32_e32 v64, 0xbfb8aa3b, v60
	v_mul_f32_e32 v65, 0xbfb8aa3b, v56
	v_mul_f32_e32 v66, 0xbfb8aa3b, v61
	v_exp_f32_e32 v64, v64
	v_exp_f32_e32 v65, v65
	v_exp_f32_e32 v66, v66
	v_add_f32_e32 v64, 1.0, v64
	v_add_f32_e32 v67, 1.0, v65
	v_add_f32_e32 v65, 1.0, v66
	v_rcp_f32_e32 v64, v64
	v_rcp_f32_e32 v65, v65
	v_mul_f32_e32 v66, 0xbfb8aa3b, v57
	v_exp_f32_e32 v69, v66
	v_rcp_f32_e32 v66, v67
	v_pk_mul_f32 v[60:61], v[60:61], v[64:65]
	v_mul_f32_e32 v64, 0xbfb8aa3b, v63
	v_pk_mul_f32 v[52:53], v[60:61], v[52:53]
	v_add_f32_e32 v60, 1.0, v69
	v_rcp_f32_e32 v67, v60
	v_mul_f32_e32 v61, 0xbfb8aa3b, v58
	v_mul_f32_e32 v60, 0xbfb8aa3b, v62
	v_exp_f32_e32 v61, v61
	v_exp_f32_e32 v60, v60
	v_exp_f32_e32 v65, v64
	v_mul_f32_e32 v64, 0xbfb8aa3b, v59
	v_pk_mul_f32 v[56:57], v[56:57], v[66:67]
	v_exp_f32_e32 v66, v64
	v_add_f32_e32 v61, 1.0, v61
	v_add_f32_e32 v60, 1.0, v60
	v_rcp_f32_e32 v64, v61
	v_add_f32_e32 v61, 1.0, v65
	v_rcp_f32_e32 v60, v60
	v_rcp_f32_e32 v61, v61
	v_add_f32_e32 v65, 1.0, v66
	v_rcp_f32_e32 v65, v65
	v_pk_mul_f32 v[56:57], v[56:57], v[48:49]
	v_pk_mul_f32 v[48:49], v[62:63], v[60:61]
	v_mad_i64_i32 v[60:61], s[26:27], v68, s44, v[144:145]
	v_pk_mul_f32 v[54:55], v[48:49], v[54:55]
	v_pk_mul_f32 v[48:49], v[58:59], v[64:65]
	s_nop 0
	v_pk_mul_f32 v[58:59], v[48:49], v[50:51]
	v_cvt_pk_bf16_f32 v48, v52, v53
	v_cvt_pk_bf16_f32 v49, v54, v55
	v_cvt_pk_bf16_f32 v50, v56, v57
	v_cvt_pk_bf16_f32 v51, v58, v59
	global_store_dwordx4 v[60:61], v[48:51], off
	v_add_u32_e32 v52, 0x90, v152
	s_nop 0
	v_mul_f32_e32 v48, 0xbfb8aa3b, v44
	v_mul_f32_e32 v49, 0xbfb8aa3b, v40
	v_mul_f32_e32 v50, 0xbfb8aa3b, v45
	v_exp_f32_e32 v48, v48
	v_exp_f32_e32 v49, v49
	v_exp_f32_e32 v50, v50
	v_add_f32_e32 v48, 1.0, v48
	v_add_f32_e32 v51, 1.0, v49
	v_add_f32_e32 v49, 1.0, v50
	v_rcp_f32_e32 v48, v48
	v_rcp_f32_e32 v49, v49
	v_mul_f32_e32 v50, 0xbfb8aa3b, v41
	v_exp_f32_e32 v53, v50
	v_rcp_f32_e32 v50, v51
	v_pk_mul_f32 v[44:45], v[44:45], v[48:49]
	v_mul_f32_e32 v48, 0xbfb8aa3b, v47
	v_pk_mul_f32 v[36:37], v[44:45], v[36:37]
	v_add_f32_e32 v44, 1.0, v53
	v_rcp_f32_e32 v51, v44
	v_mul_f32_e32 v45, 0xbfb8aa3b, v42
	v_mul_f32_e32 v44, 0xbfb8aa3b, v46
	v_exp_f32_e32 v45, v45
	v_exp_f32_e32 v44, v44
	v_exp_f32_e32 v49, v48
	v_mul_f32_e32 v48, 0xbfb8aa3b, v43
	v_pk_mul_f32 v[40:41], v[40:41], v[50:51]
	v_exp_f32_e32 v50, v48
	v_add_f32_e32 v45, 1.0, v45
	v_add_f32_e32 v44, 1.0, v44
	v_rcp_f32_e32 v48, v45
	v_add_f32_e32 v45, 1.0, v49
	v_rcp_f32_e32 v44, v44
	v_rcp_f32_e32 v45, v45
	v_add_f32_e32 v49, 1.0, v50
	v_rcp_f32_e32 v49, v49
	v_pk_mul_f32 v[40:41], v[40:41], v[32:33]
	v_pk_mul_f32 v[32:33], v[46:47], v[44:45]
	v_mad_i64_i32 v[44:45], s[26:27], v52, s44, v[144:145]
	v_pk_mul_f32 v[38:39], v[32:33], v[38:39]
	v_pk_mul_f32 v[32:33], v[42:43], v[48:49]
	s_nop 0
	v_pk_mul_f32 v[42:43], v[32:33], v[34:35]
	v_cvt_pk_bf16_f32 v32, v36, v37
	v_cvt_pk_bf16_f32 v33, v38, v39
	v_cvt_pk_bf16_f32 v34, v40, v41
	v_cvt_pk_bf16_f32 v35, v42, v43
	global_store_dwordx4 v[44:45], v[32:35], off
	v_add_u32_e32 v36, 0xa0, v152
	s_nop 0
	v_mul_f32_e32 v32, 0xbfb8aa3b, v28
	v_mul_f32_e32 v33, 0xbfb8aa3b, v24
	v_mul_f32_e32 v34, 0xbfb8aa3b, v29
	v_exp_f32_e32 v32, v32
	v_exp_f32_e32 v33, v33
	v_exp_f32_e32 v34, v34
	v_add_f32_e32 v32, 1.0, v32
	v_add_f32_e32 v35, 1.0, v33
	v_add_f32_e32 v33, 1.0, v34
	v_rcp_f32_e32 v32, v32
	v_rcp_f32_e32 v33, v33
	v_mul_f32_e32 v34, 0xbfb8aa3b, v25
	v_exp_f32_e32 v37, v34
	v_rcp_f32_e32 v34, v35
	v_pk_mul_f32 v[28:29], v[28:29], v[32:33]
	v_mul_f32_e32 v32, 0xbfb8aa3b, v31
	v_pk_mul_f32 v[20:21], v[28:29], v[20:21]
	v_add_f32_e32 v28, 1.0, v37
	v_rcp_f32_e32 v35, v28
	v_mul_f32_e32 v29, 0xbfb8aa3b, v26
	v_mul_f32_e32 v28, 0xbfb8aa3b, v30
	v_exp_f32_e32 v29, v29
	v_exp_f32_e32 v28, v28
	v_exp_f32_e32 v33, v32
	v_mul_f32_e32 v32, 0xbfb8aa3b, v27
	v_pk_mul_f32 v[24:25], v[24:25], v[34:35]
	v_exp_f32_e32 v34, v32
	v_add_f32_e32 v29, 1.0, v29
	v_add_f32_e32 v28, 1.0, v28
	v_rcp_f32_e32 v32, v29
	v_add_f32_e32 v29, 1.0, v33
	v_rcp_f32_e32 v28, v28
	v_rcp_f32_e32 v29, v29
	v_add_f32_e32 v33, 1.0, v34
	v_rcp_f32_e32 v33, v33
	v_pk_mul_f32 v[24:25], v[24:25], v[16:17]
	v_pk_mul_f32 v[16:17], v[30:31], v[28:29]
	v_mad_i64_i32 v[28:29], s[26:27], v36, s44, v[144:145]
	v_pk_mul_f32 v[22:23], v[16:17], v[22:23]
	v_pk_mul_f32 v[16:17], v[26:27], v[32:33]
	s_nop 0
	v_pk_mul_f32 v[26:27], v[16:17], v[18:19]
	v_cvt_pk_bf16_f32 v16, v20, v21
	v_cvt_pk_bf16_f32 v17, v22, v23
	v_cvt_pk_bf16_f32 v18, v24, v25
	v_cvt_pk_bf16_f32 v19, v26, v27
	global_store_dwordx4 v[28:29], v[16:19], off
	v_add_u32_e32 v20, 0xb0, v152
	s_nop 0
	v_mul_f32_e32 v16, 0xbfb8aa3b, v12
	v_mul_f32_e32 v17, 0xbfb8aa3b, v8
	v_mul_f32_e32 v18, 0xbfb8aa3b, v13
	v_exp_f32_e32 v16, v16
	v_exp_f32_e32 v17, v17
	v_exp_f32_e32 v18, v18
	v_add_f32_e32 v16, 1.0, v16
	v_add_f32_e32 v19, 1.0, v17
	v_add_f32_e32 v17, 1.0, v18
	v_rcp_f32_e32 v16, v16
	v_rcp_f32_e32 v17, v17
	v_mul_f32_e32 v18, 0xbfb8aa3b, v9
	v_exp_f32_e32 v21, v18
	v_rcp_f32_e32 v18, v19
	v_pk_mul_f32 v[12:13], v[12:13], v[16:17]
	v_mul_f32_e32 v16, 0xbfb8aa3b, v15
	v_pk_mul_f32 v[4:5], v[12:13], v[4:5]
	v_add_f32_e32 v12, 1.0, v21
	v_rcp_f32_e32 v19, v12
	v_mul_f32_e32 v13, 0xbfb8aa3b, v10
	v_mul_f32_e32 v12, 0xbfb8aa3b, v14
	v_exp_f32_e32 v13, v13
	v_exp_f32_e32 v12, v12
	v_exp_f32_e32 v17, v16
	v_mul_f32_e32 v16, 0xbfb8aa3b, v11
	v_pk_mul_f32 v[8:9], v[8:9], v[18:19]
	v_exp_f32_e32 v18, v16
	v_add_f32_e32 v13, 1.0, v13
	v_add_f32_e32 v12, 1.0, v12
	v_rcp_f32_e32 v16, v13
	v_add_f32_e32 v13, 1.0, v17
	v_rcp_f32_e32 v12, v12
	v_rcp_f32_e32 v13, v13
	v_add_f32_e32 v17, 1.0, v18
	v_rcp_f32_e32 v17, v17
	v_pk_mul_f32 v[8:9], v[8:9], v[0:1]
	v_pk_mul_f32 v[0:1], v[14:15], v[12:13]
	v_mad_i64_i32 v[12:13], s[26:27], v20, s44, v[144:145]
	v_pk_mul_f32 v[6:7], v[0:1], v[6:7]
	v_pk_mul_f32 v[0:1], v[10:11], v[16:17]
	s_nop 0
	v_pk_mul_f32 v[10:11], v[0:1], v[2:3]
	v_cvt_pk_bf16_f32 v0, v4, v5
	v_cvt_pk_bf16_f32 v1, v6, v7
	v_cvt_pk_bf16_f32 v2, v8, v9
	v_cvt_pk_bf16_f32 v3, v10, v11
	global_store_dwordx4 v[12:13], v[0:3], off
	s_cbranch_vccnz .LBB0_1277
	s_andn2_b64 vcc, exec, s[10:11]
	s_cbranch_vccnz .LBB0_1276
	s_mov_b32 s100, 1
	s_branch .LBB0_1276

.LBB0_1507:
	s_add_u32 s16, s0, 0xd800000
	s_addc_u32 s17, s1, 0
	s_lshl_b32 s18, s18, 5
	s_and_b32 s23, s18, 0x60
	s_mov_b64 s[18:19], 0x80
	s_add_i32 m0, s44, 0x18000
	v_lshl_add_u64 v[6:7], v[6:7], 0, s[18:19]
	s_lshl_b32 s22, s9, 13
	s_lshl_b32 s24, s23, 7
	s_waitcnt vmcnt(2)
	s_barrier
	global_load_lds_dwordx4 v[6:7], off
	v_lshl_add_u64 v[2:3], v[2:3], 0, s[18:19]
	s_add_i32 m0, s44, 0x1a000
	s_add_i32 s49, s44, 0x8000
	s_add_i32 s50, s44, 0xa000
	global_load_lds_dwordx4 v[2:3], off
	v_lshl_add_u64 v[0:1], v[0:1], 0, s[18:19]
	s_mov_b32 m0, s49
	s_add_u32 s20, s38, 0x40080
	global_load_lds_dwordx4 v[0:1], off
	v_lshl_add_u64 v[0:1], v[4:5], 0, s[18:19]
	s_mov_b32 m0, s50
	s_addc_u32 s21, s39, 0
	global_load_lds_dwordx4 v[0:1], off
	s_add_i32 m0, s44, 0x1c000
	v_lshl_add_u64 v[0:1], s[20:21], 0, v[132:133]
	global_load_lds_dwordx4 v[0:1], off
	v_lshl_add_u64 v[0:1], s[20:21], 0, v[128:129]
	s_add_i32 m0, s44, 0x1e000
	s_cmpk_lt_u32 s8, 0x100
	global_load_lds_dwordx4 v[0:1], off
	v_lshrrev_b32_e32 v1, 1, v8
	v_and_b32_e32 v1, 24, v1
	v_and_b32_e32 v0, 15, v8
	v_lshlrev_b32_e32 v2, 1, v1
	v_lshl_or_b32 v145, s9, 6, v0
	v_lshl_or_b32 v0, v0, 6, v2
	v_lshlrev_b32_e32 v2, 2, v8
	v_and_b32_e32 v2, 32, v2
	v_bitop3_b32 v3, v0, s22, v2 bitop3:0xde
	v_bitop3_b32 v148, s24, v0, v2 bitop3:0xf6
	v_lshlrev_b32_e32 v0, 14, v9
	v_and_b32_e32 v0, 0xffff8000, v0
	v_or_b32_e32 v149, s23, v1
	v_lshl_add_u32 v0, v10, 11, v0
	v_and_b32_e32 v1, 1, v9
	v_lshl_or_b32 v0, v1, 6, v0
	v_lshl_add_u32 v136, v11, 1, v0
	v_lshlrev_b32_e32 v0, 14, v13
	v_and_b32_e32 v0, 0xffff8000, v0
	s_waitcnt vmcnt(6)
	v_lshl_add_u32 v0, v12, 11, v0
	v_and_b32_e32 v1, 1, v13
	s_cselect_b64 s[20:21], -1, 0
	v_lshl_or_b32 v0, v1, 6, v0
	s_add_i32 s51, 0, 0x10000
	s_add_i32 s52, 0, 0x14000
	v_mov_b32_e32 v137, v133
	v_lshl_add_u32 v138, v14, 1, v0
	v_mov_b32_e32 v139, v133
	v_mov_b64_e32 v[140:141], 0x200
	v_mov_b64_e32 v[142:143], 0x1ff
	v_add_u32_e32 v150, s51, v148
	v_add_u32_e32 v151, s52, v148
	v_add_u32_e32 v152, 0, v3
	s_mov_b32 s53, 0x40000
	s_mov_b64 s[22:23], 0x48000
	s_mov_b32 s54, 0x48000
	s_mov_b64 s[24:25], 0x50000
	s_mov_b32 s55, 0x50000
	s_mov_b64 s[26:27], 0x58000
	s_mov_b32 s56, 0x58000
	v_mov_b32_e32 v153, 0x3e38aa3b
	v_readlane_b32 s57, v254, 11
	s_mov_b32 s58, s92
	s_barrier
	s_mov_b32 s100, 0
	s_branch .LBB0_1510

.LBB0_1512:
	s_ashr_i32 s31, s30, 31
	s_lshl_b64 s[34:35], s[30:31], 19
	s_add_u32 s34, s4, s34
	s_addc_u32 s35, s5, s35
	s_and_b64 s[36:37], s[8:9], exec
	s_cselect_b32 s31, s35, s41
	s_cselect_b32 s59, s34, s40
	s_ashr_i32 s29, s28, 31
	s_lshl_b64 s[36:37], s[28:29], 19
	s_add_u32 s36, s10, s36
	s_addc_u32 s37, s11, s37
	s_and_b64 s[42:43], s[8:9], exec
	s_cselect_b32 s29, s37, s39
	s_cselect_b32 s60, s36, s38
	s_add_u32 s61, s38, 0x100
	s_addc_u32 s62, s39, 0
	s_add_u32 s38, s40, 0x40080
	v_mov_b32_e32 v0, 0
	s_addc_u32 s39, s41, 0
	s_mov_b32 s63, -2
	v_mov_b32_e32 v1, v0
	v_mov_b32_e32 v2, v0
	v_mov_b32_e32 v3, v0
	v_mov_b32_e32 v4, v0
	v_mov_b32_e32 v5, v0
	v_mov_b32_e32 v6, v0
	v_mov_b32_e32 v7, v0
	v_mov_b32_e32 v8, v0
	v_mov_b32_e32 v9, v0
	v_mov_b32_e32 v10, v0
	v_mov_b32_e32 v11, v0
	v_mov_b32_e32 v16, v0
	v_mov_b32_e32 v17, v0
	v_mov_b32_e32 v18, v0
	v_mov_b32_e32 v19, v0
	v_mov_b32_e32 v24, v0
	v_mov_b32_e32 v25, v0
	v_mov_b32_e32 v26, v0
	v_mov_b32_e32 v27, v0
	v_mov_b32_e32 v32, v0
	v_mov_b32_e32 v33, v0
	v_mov_b32_e32 v34, v0
	v_mov_b32_e32 v35, v0
	v_mov_b32_e32 v40, v0
	v_mov_b32_e32 v41, v0
	v_mov_b32_e32 v42, v0
	v_mov_b32_e32 v43, v0
	v_mov_b32_e32 v48, v0
	v_mov_b32_e32 v49, v0
	v_mov_b32_e32 v50, v0
	v_mov_b32_e32 v51, v0
	v_mov_b32_e32 v12, v0
	v_mov_b32_e32 v13, v0
	v_mov_b32_e32 v14, v0
	v_mov_b32_e32 v15, v0
	v_mov_b32_e32 v20, v0
	v_mov_b32_e32 v21, v0
	v_mov_b32_e32 v22, v0
	v_mov_b32_e32 v23, v0
	v_mov_b32_e32 v28, v0
	v_mov_b32_e32 v29, v0
	v_mov_b32_e32 v30, v0
	v_mov_b32_e32 v31, v0
	v_mov_b32_e32 v36, v0
	v_mov_b32_e32 v37, v0
	v_mov_b32_e32 v38, v0
	v_mov_b32_e32 v39, v0
	v_mov_b32_e32 v44, v0
	v_mov_b32_e32 v45, v0
	v_mov_b32_e32 v46, v0
	v_mov_b32_e32 v47, v0
	v_mov_b32_e32 v52, v0
	v_mov_b32_e32 v53, v0
	v_mov_b32_e32 v54, v0
	v_mov_b32_e32 v55, v0
	v_mov_b32_e32 v56, v0
	v_mov_b32_e32 v57, v0
	v_mov_b32_e32 v58, v0
	v_mov_b32_e32 v59, v0
	v_mov_b32_e32 v60, v0
	v_mov_b32_e32 v61, v0
	v_mov_b32_e32 v62, v0
	v_mov_b32_e32 v63, v0
	v_mov_b32_e32 v64, v0
	v_mov_b32_e32 v65, v0
	v_mov_b32_e32 v66, v0
	v_mov_b32_e32 v67, v0
	v_mov_b32_e32 v68, v0
	v_mov_b32_e32 v69, v0
	v_mov_b32_e32 v70, v0
	v_mov_b32_e32 v71, v0
	v_mov_b32_e32 v72, v0
	v_mov_b32_e32 v73, v0
	v_mov_b32_e32 v74, v0
	v_mov_b32_e32 v75, v0
	v_mov_b32_e32 v80, v0
	v_mov_b32_e32 v81, v0
	v_mov_b32_e32 v82, v0
	v_mov_b32_e32 v83, v0
	v_mov_b32_e32 v88, v0
	v_mov_b32_e32 v89, v0
	v_mov_b32_e32 v90, v0
	v_mov_b32_e32 v91, v0
	v_mov_b32_e32 v96, v0
	v_mov_b32_e32 v97, v0
	v_mov_b32_e32 v98, v0
	v_mov_b32_e32 v99, v0
	v_mov_b32_e32 v104, v0
	v_mov_b32_e32 v105, v0
	v_mov_b32_e32 v106, v0
	v_mov_b32_e32 v107, v0
	v_mov_b32_e32 v112, v0
	v_mov_b32_e32 v113, v0
	v_mov_b32_e32 v114, v0
	v_mov_b32_e32 v115, v0
	v_mov_b32_e32 v76, v0
	v_mov_b32_e32 v77, v0
	v_mov_b32_e32 v78, v0
	v_mov_b32_e32 v79, v0
	v_mov_b32_e32 v84, v0
	v_mov_b32_e32 v85, v0
	v_mov_b32_e32 v86, v0
	v_mov_b32_e32 v87, v0
	v_mov_b32_e32 v92, v0
	v_mov_b32_e32 v93, v0
	v_mov_b32_e32 v94, v0
	v_mov_b32_e32 v95, v0
	v_mov_b32_e32 v100, v0
	v_mov_b32_e32 v101, v0
	v_mov_b32_e32 v102, v0
	v_mov_b32_e32 v103, v0
	v_mov_b32_e32 v108, v0
	v_mov_b32_e32 v109, v0
	v_mov_b32_e32 v110, v0
	v_mov_b32_e32 v111, v0
	v_mov_b32_e32 v116, v0
	v_mov_b32_e32 v117, v0
	v_mov_b32_e32 v118, v0
	v_mov_b32_e32 v119, v0
	v_mov_b32_e32 v120, v0
	v_mov_b32_e32 v121, v0
	v_mov_b32_e32 v122, v0
	v_mov_b32_e32 v123, v0
	v_mov_b32_e32 v124, v0
	v_mov_b32_e32 v125, v0
	v_mov_b32_e32 v126, v0
	v_mov_b32_e32 v127, v0
	s_cmp_eq_u32 s100, 1
	s_cbranch_scc0 .Lgemm_nobar_1508
	s_mov_b32 s100, 0
	s_barrier
.Lgemm_nobar_1508:
.LBB0_1513:
	ds_read_b128 v[154:157], v150
	ds_read_b128 v[158:161], v150 offset:1024
	ds_read_b128 v[162:165], v150 offset:2048
	ds_read_b128 v[166:169], v150 offset:3072
	ds_read_b128 v[170:173], v151
	ds_read_b128 v[174:177], v151 offset:1024
	ds_read_b128 v[178:181], v151 offset:2048
	ds_read_b128 v[182:185], v151 offset:3072
	s_add_u32 s40, s38, 0xfffc0080
	s_addc_u32 s41, s39, -1
	s_cmp_eq_u32 s63, 12
	s_cselect_b32 s43, s31, s41
	s_cselect_b32 s42, s59, s40
	s_cselect_b32 s41, s29, s62
	s_cselect_b32 s40, s60, s61
	v_lshl_add_u64 v[146:147], s[38:39], 0, v[138:139]
	s_add_i32 m0, s44, 0xc000
	ds_read_b128 v[186:189], v152
	ds_read_b128 v[190:193], v152 offset:1024
	ds_read_b128 v[194:197], v152 offset:2048
	ds_read_b128 v[198:201], v152 offset:3072
	ds_read_b128 v[202:205], v152 offset:4096
	ds_read_b128 v[206:209], v152 offset:5120
	ds_read_b128 v[210:213], v152 offset:6144
	ds_read_b128 v[214:217], v152 offset:7168
	global_load_lds_dwordx4 v[146:147], off
	v_lshl_add_u64 v[146:147], s[38:39], 0, v[136:137]
	s_add_i32 m0, s44, 0xe000
	s_nop 0
	global_load_lds_dwordx4 v[146:147], off
	s_waitcnt vmcnt(8)
	s_waitcnt lgkmcnt(0)
	s_barrier
	s_setprio 1
	s_waitcnt lgkmcnt(0)
	v_mfma_f32_16x16x32_bf16 v[124:127], v[154:157], v[186:189], v[124:127]
	v_mfma_f32_16x16x32_bf16 v[120:123], v[162:165], v[186:189], v[120:123]
	v_mfma_f32_16x16x32_bf16 v[116:119], v[154:157], v[194:197], v[116:119]
	v_mfma_f32_16x16x32_bf16 v[108:111], v[162:165], v[194:197], v[108:111]
	v_mfma_f32_16x16x32_bf16 v[100:103], v[154:157], v[202:205], v[100:103]
	v_mfma_f32_16x16x32_bf16 v[92:95], v[162:165], v[202:205], v[92:95]
	v_mfma_f32_16x16x32_bf16 v[84:87], v[154:157], v[210:213], v[84:87]
	v_mfma_f32_16x16x32_bf16 v[76:79], v[162:165], v[210:213], v[76:79]
	v_mfma_f32_16x16x32_bf16 v[124:127], v[158:161], v[190:193], v[124:127]
	v_mfma_f32_16x16x32_bf16 v[120:123], v[166:169], v[190:193], v[120:123]
	v_mfma_f32_16x16x32_bf16 v[116:119], v[158:161], v[198:201], v[116:119]
	v_mfma_f32_16x16x32_bf16 v[108:111], v[166:169], v[198:201], v[108:111]
	v_mfma_f32_16x16x32_bf16 v[100:103], v[158:161], v[206:209], v[100:103]
	v_mfma_f32_16x16x32_bf16 v[92:95], v[166:169], v[206:209], v[92:95]
	v_mfma_f32_16x16x32_bf16 v[84:87], v[158:161], v[214:217], v[84:87]
	v_mfma_f32_16x16x32_bf16 v[76:79], v[166:169], v[214:217], v[76:79]
	s_setprio 0
	s_setprio 1
	v_mfma_f32_16x16x32_bf16 v[112:115], v[170:173], v[186:189], v[112:115]
	v_mfma_f32_16x16x32_bf16 v[104:107], v[178:181], v[186:189], v[104:107]
	v_mfma_f32_16x16x32_bf16 v[96:99], v[170:173], v[194:197], v[96:99]
	v_mfma_f32_16x16x32_bf16 v[88:91], v[178:181], v[194:197], v[88:91]
	v_mfma_f32_16x16x32_bf16 v[80:83], v[170:173], v[202:205], v[80:83]
	v_mfma_f32_16x16x32_bf16 v[72:75], v[178:181], v[202:205], v[72:75]
	v_mfma_f32_16x16x32_bf16 v[68:71], v[170:173], v[210:213], v[68:71]
	v_mfma_f32_16x16x32_bf16 v[64:67], v[178:181], v[210:213], v[64:67]
	v_mfma_f32_16x16x32_bf16 v[112:115], v[174:177], v[190:193], v[112:115]
	v_mfma_f32_16x16x32_bf16 v[104:107], v[182:185], v[190:193], v[104:107]
	v_mfma_f32_16x16x32_bf16 v[96:99], v[174:177], v[198:201], v[96:99]
	v_mfma_f32_16x16x32_bf16 v[88:91], v[182:185], v[198:201], v[88:91]
	v_mfma_f32_16x16x32_bf16 v[80:83], v[174:177], v[206:209], v[80:83]
	v_mfma_f32_16x16x32_bf16 v[72:75], v[182:185], v[206:209], v[72:75]
	v_mfma_f32_16x16x32_bf16 v[68:71], v[174:177], v[214:217], v[68:71]
	v_mfma_f32_16x16x32_bf16 v[64:67], v[182:185], v[214:217], v[64:67]
	s_setprio 0
	s_barrier
	s_add_i32 s64, s51, s33
	v_lshl_add_u64 v[146:147], s[40:41], 0, v[132:133]
	s_mov_b32 m0, s64
	ds_read_b128 v[186:189], v152 offset:16384
	ds_read_b128 v[190:193], v152 offset:17408
	ds_read_b128 v[194:197], v152 offset:18432
	ds_read_b128 v[198:201], v152 offset:19456
	ds_read_b128 v[202:205], v152 offset:20480
	ds_read_b128 v[206:209], v152 offset:21504
	ds_read_b128 v[210:213], v152 offset:22528
	ds_read_b128 v[214:217], v152 offset:23552
	global_load_lds_dwordx4 v[146:147], off
	s_add_i32 m0, s64, 0x2000
	s_add_u32 s64, s40, 0x40000
	v_lshl_add_u64 v[218:219], s[40:41], 0, v[128:129]
	s_addc_u32 s65, s41, 0
	s_add_i32 s66, s52, s33
	global_load_lds_dwordx4 v[218:219], off
	v_lshl_add_u64 v[220:221], s[64:65], 0, v[132:133]
	s_mov_b32 m0, s66
	v_lshl_add_u64 v[222:223], s[42:43], 0, v[130:131]
	global_load_lds_dwordx4 v[220:221], off
	v_lshl_add_u64 v[220:221], s[64:65], 0, v[128:129]
	s_add_i32 m0, s66, 0x2000
	s_nop 0
	global_load_lds_dwordx4 v[220:221], off
	v_lshl_add_u64 v[220:221], s[42:43], 0, v[134:135]
	s_mov_b32 m0, s44
	s_nop 0
	global_load_lds_dwordx4 v[220:221], off
	s_mov_b32 m0, s45
	s_nop 0
	global_load_lds_dwordx4 v[222:223], off
	s_waitcnt vmcnt(8)
	s_waitcnt lgkmcnt(0)
	s_barrier
	s_setprio 1
	s_waitcnt lgkmcnt(0)
	v_mfma_f32_16x16x32_bf16 v[60:63], v[154:157], v[186:189], v[60:63]
	v_mfma_f32_16x16x32_bf16 v[56:59], v[162:165], v[186:189], v[56:59]
	v_mfma_f32_16x16x32_bf16 v[52:55], v[154:157], v[194:197], v[52:55]
	v_mfma_f32_16x16x32_bf16 v[44:47], v[162:165], v[194:197], v[44:47]
	v_mfma_f32_16x16x32_bf16 v[36:39], v[154:157], v[202:205], v[36:39]
	v_mfma_f32_16x16x32_bf16 v[28:31], v[162:165], v[202:205], v[28:31]
	v_mfma_f32_16x16x32_bf16 v[20:23], v[154:157], v[210:213], v[20:23]
	v_mfma_f32_16x16x32_bf16 v[12:15], v[162:165], v[210:213], v[12:15]
	v_mfma_f32_16x16x32_bf16 v[60:63], v[158:161], v[190:193], v[60:63]
	v_mfma_f32_16x16x32_bf16 v[56:59], v[166:169], v[190:193], v[56:59]
	v_mfma_f32_16x16x32_bf16 v[52:55], v[158:161], v[198:201], v[52:55]
	v_mfma_f32_16x16x32_bf16 v[44:47], v[166:169], v[198:201], v[44:47]
	v_mfma_f32_16x16x32_bf16 v[36:39], v[158:161], v[206:209], v[36:39]
	v_mfma_f32_16x16x32_bf16 v[28:31], v[166:169], v[206:209], v[28:31]
	v_mfma_f32_16x16x32_bf16 v[20:23], v[158:161], v[214:217], v[20:23]
	v_mfma_f32_16x16x32_bf16 v[12:15], v[166:169], v[214:217], v[12:15]
	s_setprio 0
	s_setprio 1
	v_mfma_f32_16x16x32_bf16 v[48:51], v[170:173], v[186:189], v[48:51]
	v_mfma_f32_16x16x32_bf16 v[40:43], v[178:181], v[186:189], v[40:43]
	v_mfma_f32_16x16x32_bf16 v[32:35], v[170:173], v[194:197], v[32:35]
	v_mfma_f32_16x16x32_bf16 v[24:27], v[178:181], v[194:197], v[24:27]
	v_mfma_f32_16x16x32_bf16 v[16:19], v[170:173], v[202:205], v[16:19]
	v_mfma_f32_16x16x32_bf16 v[8:11], v[178:181], v[202:205], v[8:11]
	v_mfma_f32_16x16x32_bf16 v[4:7], v[170:173], v[210:213], v[4:7]
	v_mfma_f32_16x16x32_bf16 v[0:3], v[178:181], v[210:213], v[0:3]
	v_mfma_f32_16x16x32_bf16 v[48:51], v[174:177], v[190:193], v[48:51]
	v_mfma_f32_16x16x32_bf16 v[40:43], v[182:185], v[190:193], v[40:43]
	v_mfma_f32_16x16x32_bf16 v[32:35], v[174:177], v[198:201], v[32:35]
	v_mfma_f32_16x16x32_bf16 v[24:27], v[182:185], v[198:201], v[24:27]
	v_mfma_f32_16x16x32_bf16 v[16:19], v[174:177], v[206:209], v[16:19]
	v_mfma_f32_16x16x32_bf16 v[8:11], v[182:185], v[206:209], v[8:11]
	v_mfma_f32_16x16x32_bf16 v[4:7], v[174:177], v[214:217], v[4:7]
	v_mfma_f32_16x16x32_bf16 v[0:3], v[182:185], v[214:217], v[0:3]
	s_setprio 0
	s_barrier
	s_add_i32 s64, 0, 0x18000
	v_add_u32_e32 v144, s64, v148
	s_add_i32 s65, 0, 0x1c000
	ds_read_b128 v[154:157], v144
	ds_read_b128 v[158:161], v144 offset:1024
	ds_read_b128 v[162:165], v144 offset:2048
	ds_read_b128 v[166:169], v144 offset:3072
	v_add_u32_e32 v144, s65, v148
	ds_read_b128 v[170:173], v144
	ds_read_b128 v[174:177], v144 offset:1024
	ds_read_b128 v[178:181], v144 offset:2048
	ds_read_b128 v[182:185], v144 offset:3072
	s_add_u32 s42, s42, 0x40000
	s_addc_u32 s43, s43, 0
	s_mov_b32 m0, s46
	v_lshl_add_u64 v[224:225], s[42:43], 0, v[134:135]
	ds_read_b128 v[186:189], v152 offset:32768
	ds_read_b128 v[190:193], v152 offset:33792
	ds_read_b128 v[194:197], v152 offset:34816
	ds_read_b128 v[198:201], v152 offset:35840
	ds_read_b128 v[202:205], v152 offset:36864
	ds_read_b128 v[206:209], v152 offset:37888
	ds_read_b128 v[210:213], v152 offset:38912
	ds_read_b128 v[214:217], v152 offset:39936
	global_load_lds_dwordx4 v[224:225], off
	v_lshl_add_u64 v[224:225], s[42:43], 0, v[130:131]
	s_mov_b32 m0, s47
	s_nop 0
	global_load_lds_dwordx4 v[224:225], off
	s_waitcnt vmcnt(8)
	s_waitcnt lgkmcnt(0)
	s_barrier
	s_setprio 1
	s_waitcnt lgkmcnt(0)
	v_mfma_f32_16x16x32_bf16 v[124:127], v[154:157], v[186:189], v[124:127]
	v_mfma_f32_16x16x32_bf16 v[120:123], v[162:165], v[186:189], v[120:123]
	v_mfma_f32_16x16x32_bf16 v[116:119], v[154:157], v[194:197], v[116:119]
	v_mfma_f32_16x16x32_bf16 v[108:111], v[162:165], v[194:197], v[108:111]
	v_mfma_f32_16x16x32_bf16 v[100:103], v[154:157], v[202:205], v[100:103]
	v_mfma_f32_16x16x32_bf16 v[92:95], v[162:165], v[202:205], v[92:95]
	v_mfma_f32_16x16x32_bf16 v[84:87], v[154:157], v[210:213], v[84:87]
	v_mfma_f32_16x16x32_bf16 v[76:79], v[162:165], v[210:213], v[76:79]
	v_mfma_f32_16x16x32_bf16 v[124:127], v[158:161], v[190:193], v[124:127]
	v_mfma_f32_16x16x32_bf16 v[120:123], v[166:169], v[190:193], v[120:123]
	v_mfma_f32_16x16x32_bf16 v[116:119], v[158:161], v[198:201], v[116:119]
	v_mfma_f32_16x16x32_bf16 v[108:111], v[166:169], v[198:201], v[108:111]
	v_mfma_f32_16x16x32_bf16 v[100:103], v[158:161], v[206:209], v[100:103]
	v_mfma_f32_16x16x32_bf16 v[92:95], v[166:169], v[206:209], v[92:95]
	v_mfma_f32_16x16x32_bf16 v[84:87], v[158:161], v[214:217], v[84:87]
	v_mfma_f32_16x16x32_bf16 v[76:79], v[166:169], v[214:217], v[76:79]
	s_setprio 0
	s_setprio 1
	v_mfma_f32_16x16x32_bf16 v[112:115], v[170:173], v[186:189], v[112:115]
	v_mfma_f32_16x16x32_bf16 v[104:107], v[178:181], v[186:189], v[104:107]
	v_mfma_f32_16x16x32_bf16 v[96:99], v[170:173], v[194:197], v[96:99]
	v_mfma_f32_16x16x32_bf16 v[88:91], v[178:181], v[194:197], v[88:91]
	v_mfma_f32_16x16x32_bf16 v[80:83], v[170:173], v[202:205], v[80:83]
	v_mfma_f32_16x16x32_bf16 v[72:75], v[178:181], v[202:205], v[72:75]
	v_mfma_f32_16x16x32_bf16 v[68:71], v[170:173], v[210:213], v[68:71]
	v_mfma_f32_16x16x32_bf16 v[64:67], v[178:181], v[210:213], v[64:67]
	v_mfma_f32_16x16x32_bf16 v[112:115], v[174:177], v[190:193], v[112:115]
	v_mfma_f32_16x16x32_bf16 v[104:107], v[182:185], v[190:193], v[104:107]
	v_mfma_f32_16x16x32_bf16 v[96:99], v[174:177], v[198:201], v[96:99]
	v_mfma_f32_16x16x32_bf16 v[88:91], v[182:185], v[198:201], v[88:91]
	v_mfma_f32_16x16x32_bf16 v[80:83], v[174:177], v[206:209], v[80:83]
	v_mfma_f32_16x16x32_bf16 v[72:75], v[182:185], v[206:209], v[72:75]
	v_mfma_f32_16x16x32_bf16 v[68:71], v[174:177], v[214:217], v[68:71]
	v_mfma_f32_16x16x32_bf16 v[64:67], v[182:185], v[214:217], v[64:67]
	s_setprio 0
	s_barrier
	s_add_i32 s42, s64, s33
	v_lshl_add_u64 v[146:147], v[146:147], 0, s[18:19]
	s_mov_b32 m0, s42
	ds_read_b128 v[186:189], v152 offset:49152
	ds_read_b128 v[190:193], v152 offset:50176
	ds_read_b128 v[194:197], v152 offset:51200
	ds_read_b128 v[198:201], v152 offset:52224
	ds_read_b128 v[202:205], v152 offset:53248
	ds_read_b128 v[206:209], v152 offset:54272
	ds_read_b128 v[210:213], v152 offset:55296
	ds_read_b128 v[214:217], v152 offset:56320
	global_load_lds_dwordx4 v[146:147], off
	s_add_i32 m0, s42, 0x2000
	s_add_u32 s40, s40, 0x40080
	v_lshl_add_u64 v[146:147], v[218:219], 0, s[18:19]
	s_addc_u32 s41, s41, 0
	s_add_i32 s42, s65, s33
	global_load_lds_dwordx4 v[146:147], off
	v_lshl_add_u64 v[146:147], s[40:41], 0, v[132:133]
	s_mov_b32 m0, s42
	s_nop 0
	global_load_lds_dwordx4 v[146:147], off
	v_lshl_add_u64 v[146:147], s[40:41], 0, v[128:129]
	s_add_i32 m0, s42, 0x2000
	s_nop 0
	global_load_lds_dwordx4 v[146:147], off
	v_lshl_add_u64 v[146:147], v[220:221], 0, s[18:19]
	s_mov_b32 m0, s49
	s_nop 0
	global_load_lds_dwordx4 v[146:147], off
	v_lshl_add_u64 v[146:147], v[222:223], 0, s[18:19]
	s_mov_b32 m0, s50
	s_nop 0
	global_load_lds_dwordx4 v[146:147], off
	s_waitcnt vmcnt(8)
	s_waitcnt lgkmcnt(0)
	s_barrier
	s_setprio 1
	s_waitcnt lgkmcnt(0)
	v_mfma_f32_16x16x32_bf16 v[60:63], v[154:157], v[186:189], v[60:63]
	v_mfma_f32_16x16x32_bf16 v[56:59], v[162:165], v[186:189], v[56:59]
	v_mfma_f32_16x16x32_bf16 v[52:55], v[154:157], v[194:197], v[52:55]
	v_mfma_f32_16x16x32_bf16 v[44:47], v[162:165], v[194:197], v[44:47]
	v_mfma_f32_16x16x32_bf16 v[36:39], v[154:157], v[202:205], v[36:39]
	v_mfma_f32_16x16x32_bf16 v[28:31], v[162:165], v[202:205], v[28:31]
	v_mfma_f32_16x16x32_bf16 v[20:23], v[154:157], v[210:213], v[20:23]
	v_mfma_f32_16x16x32_bf16 v[12:15], v[162:165], v[210:213], v[12:15]
	v_mfma_f32_16x16x32_bf16 v[60:63], v[158:161], v[190:193], v[60:63]
	v_mfma_f32_16x16x32_bf16 v[56:59], v[166:169], v[190:193], v[56:59]
	v_mfma_f32_16x16x32_bf16 v[52:55], v[158:161], v[198:201], v[52:55]
	v_mfma_f32_16x16x32_bf16 v[44:47], v[166:169], v[198:201], v[44:47]
	v_mfma_f32_16x16x32_bf16 v[36:39], v[158:161], v[206:209], v[36:39]
	v_mfma_f32_16x16x32_bf16 v[28:31], v[166:169], v[206:209], v[28:31]
	v_mfma_f32_16x16x32_bf16 v[20:23], v[158:161], v[214:217], v[20:23]
	v_mfma_f32_16x16x32_bf16 v[12:15], v[166:169], v[214:217], v[12:15]
	s_setprio 0
	s_setprio 1
	v_mfma_f32_16x16x32_bf16 v[48:51], v[170:173], v[186:189], v[48:51]
	v_mfma_f32_16x16x32_bf16 v[40:43], v[178:181], v[186:189], v[40:43]
	v_mfma_f32_16x16x32_bf16 v[32:35], v[170:173], v[194:197], v[32:35]
	v_mfma_f32_16x16x32_bf16 v[24:27], v[178:181], v[194:197], v[24:27]
	v_mfma_f32_16x16x32_bf16 v[16:19], v[170:173], v[202:205], v[16:19]
	v_mfma_f32_16x16x32_bf16 v[8:11], v[178:181], v[202:205], v[8:11]
	v_mfma_f32_16x16x32_bf16 v[4:7], v[170:173], v[210:213], v[4:7]
	v_mfma_f32_16x16x32_bf16 v[0:3], v[178:181], v[210:213], v[0:3]
	v_mfma_f32_16x16x32_bf16 v[48:51], v[174:177], v[190:193], v[48:51]
	v_mfma_f32_16x16x32_bf16 v[40:43], v[182:185], v[190:193], v[40:43]
	v_mfma_f32_16x16x32_bf16 v[32:35], v[174:177], v[198:201], v[32:35]
	v_mfma_f32_16x16x32_bf16 v[24:27], v[182:185], v[198:201], v[24:27]
	v_mfma_f32_16x16x32_bf16 v[16:19], v[174:177], v[206:209], v[16:19]
	v_mfma_f32_16x16x32_bf16 v[8:11], v[182:185], v[206:209], v[8:11]
	v_mfma_f32_16x16x32_bf16 v[4:7], v[174:177], v[214:217], v[4:7]
	v_mfma_f32_16x16x32_bf16 v[0:3], v[182:185], v[214:217], v[0:3]
	s_setprio 0
	s_barrier
	s_add_i32 s63, s63, 2
	s_add_u32 s61, s61, 0x100
	s_addc_u32 s62, s62, 0
	s_add_u32 s38, s38, 0x100
	s_addc_u32 s39, s39, 0
	s_cmp_gt_u32 s63, 13
	s_cbranch_scc0 .LBB0_1513
	s_and_b64 vcc, exec, s[20:21]
	s_cbranch_vccz .LBB0_1516
	s_barrier
.LBB0_1516:
	s_cmp_lt_u32 s57, 4
	s_cselect_b64 vcc, -1, 0
	v_lshl_or_b32 v146, s57, 8, v149
	v_lshl_add_u32 v154, s58, 8, v145
	s_mov_b64 s[38:39], s[16:17]
	v_cndmask_b32_e32 v144, 1.0, v153, vcc
	v_ashrrev_i32_e32 v147, 31, v146
	v_ashrrev_i32_e32 v155, 31, v154
	v_pk_mul_f32 v[126:127], v[144:145], v[126:127] op_sel_hi:[0,1]
	v_lshl_add_u64 v[156:157], v[146:147], 1, s[38:39]
	v_lshlrev_b64 v[146:147], 11, v[154:155]
	v_pk_mul_f32 v[124:125], v[144:145], v[124:125] op_sel_hi:[0,1]
	v_pk_mul_f32 v[158:159], v[144:145], v[122:123] op_sel_hi:[0,1]
	v_pk_mul_f32 v[122:123], v[144:145], v[120:121] op_sel_hi:[0,1]
	v_lshl_add_u64 v[146:147], v[156:157], 0, v[146:147]
	v_cvt_pk_bf16_f32 v120, v124, v125
	v_cvt_pk_bf16_f32 v121, v126, v127
	v_cvt_pk_bf16_f32 v122, v122, v123
	v_cvt_pk_bf16_f32 v123, v158, v159
	global_store_dwordx4 v[146:147], v[120:123], off
	v_pk_mul_f32 v[114:115], v[144:145], v[114:115] op_sel_hi:[0,1]
	v_pk_mul_f32 v[112:113], v[144:145], v[112:113] op_sel_hi:[0,1]
	v_pk_mul_f32 v[120:121], v[144:145], v[106:107] op_sel_hi:[0,1]
	v_pk_mul_f32 v[106:107], v[144:145], v[104:105] op_sel_hi:[0,1]
	v_cvt_pk_bf16_f32 v104, v112, v113
	v_cvt_pk_bf16_f32 v105, v114, v115
	v_cvt_pk_bf16_f32 v106, v106, v107
	v_cvt_pk_bf16_f32 v107, v120, v121
	global_store_dwordx4 v[146:147], v[104:107], off offset:256
	v_pk_mul_f32 v[110:111], v[144:145], v[110:111] op_sel_hi:[0,1]
	v_pk_mul_f32 v[108:109], v[144:145], v[108:109] op_sel_hi:[0,1]
	v_or_b32_e32 v104, 16, v154
	v_ashrrev_i32_e32 v105, 31, v104
	v_lshlrev_b64 v[104:105], 11, v[104:105]
	v_lshl_add_u64 v[112:113], v[156:157], 0, v[104:105]
	v_pk_mul_f32 v[106:107], v[144:145], v[118:119] op_sel_hi:[0,1]
	v_pk_mul_f32 v[104:105], v[144:145], v[116:117] op_sel_hi:[0,1]
	v_cvt_pk_bf16_f32 v104, v104, v105
	v_cvt_pk_bf16_f32 v105, v106, v107
	v_cvt_pk_bf16_f32 v106, v108, v109
	v_cvt_pk_bf16_f32 v107, v110, v111
	global_store_dwordx4 v[112:113], v[104:107], off
	v_pk_mul_f32 v[98:99], v[144:145], v[98:99] op_sel_hi:[0,1]
	v_pk_mul_f32 v[96:97], v[144:145], v[96:97] op_sel_hi:[0,1]
	v_pk_mul_f32 v[104:105], v[144:145], v[90:91] op_sel_hi:[0,1]
	v_pk_mul_f32 v[90:91], v[144:145], v[88:89] op_sel_hi:[0,1]
	v_cvt_pk_bf16_f32 v88, v96, v97
	v_cvt_pk_bf16_f32 v89, v98, v99
	v_cvt_pk_bf16_f32 v90, v90, v91
	v_cvt_pk_bf16_f32 v91, v104, v105
	global_store_dwordx4 v[112:113], v[88:91], off offset:256
	v_pk_mul_f32 v[94:95], v[144:145], v[94:95] op_sel_hi:[0,1]
	v_pk_mul_f32 v[92:93], v[144:145], v[92:93] op_sel_hi:[0,1]
	v_or_b32_e32 v88, 32, v154
	v_ashrrev_i32_e32 v89, 31, v88
	v_lshlrev_b64 v[88:89], 11, v[88:89]
	v_lshl_add_u64 v[96:97], v[156:157], 0, v[88:89]
	v_pk_mul_f32 v[90:91], v[144:145], v[102:103] op_sel_hi:[0,1]
	v_pk_mul_f32 v[88:89], v[144:145], v[100:101] op_sel_hi:[0,1]
	v_cvt_pk_bf16_f32 v88, v88, v89
	v_cvt_pk_bf16_f32 v89, v90, v91
	v_cvt_pk_bf16_f32 v90, v92, v93
	v_cvt_pk_bf16_f32 v91, v94, v95
	global_store_dwordx4 v[96:97], v[88:91], off
	v_pk_mul_f32 v[82:83], v[144:145], v[82:83] op_sel_hi:[0,1]
	v_pk_mul_f32 v[80:81], v[144:145], v[80:81] op_sel_hi:[0,1]
	v_pk_mul_f32 v[88:89], v[144:145], v[74:75] op_sel_hi:[0,1]
	v_pk_mul_f32 v[74:75], v[144:145], v[72:73] op_sel_hi:[0,1]
	v_cvt_pk_bf16_f32 v72, v80, v81
	v_cvt_pk_bf16_f32 v73, v82, v83
	v_cvt_pk_bf16_f32 v74, v74, v75
	v_cvt_pk_bf16_f32 v75, v88, v89
	global_store_dwordx4 v[96:97], v[72:75], off offset:256
	v_pk_mul_f32 v[78:79], v[144:145], v[78:79] op_sel_hi:[0,1]
	v_pk_mul_f32 v[76:77], v[144:145], v[76:77] op_sel_hi:[0,1]
	v_or_b32_e32 v72, 48, v154
	v_ashrrev_i32_e32 v73, 31, v72
	v_lshlrev_b64 v[72:73], 11, v[72:73]
	v_lshl_add_u64 v[80:81], v[156:157], 0, v[72:73]
	v_pk_mul_f32 v[74:75], v[144:145], v[86:87] op_sel_hi:[0,1]
	v_pk_mul_f32 v[72:73], v[144:145], v[84:85] op_sel_hi:[0,1]
	v_cvt_pk_bf16_f32 v72, v72, v73
	v_cvt_pk_bf16_f32 v73, v74, v75
	v_cvt_pk_bf16_f32 v74, v76, v77
	v_cvt_pk_bf16_f32 v75, v78, v79
	global_store_dwordx4 v[80:81], v[72:75], off
	v_pk_mul_f32 v[70:71], v[144:145], v[70:71] op_sel_hi:[0,1]
	v_pk_mul_f32 v[68:69], v[144:145], v[68:69] op_sel_hi:[0,1]
	v_pk_mul_f32 v[72:73], v[144:145], v[66:67] op_sel_hi:[0,1]
	v_pk_mul_f32 v[66:67], v[144:145], v[64:65] op_sel_hi:[0,1]
	v_cvt_pk_bf16_f32 v64, v68, v69
	v_cvt_pk_bf16_f32 v65, v70, v71
	v_cvt_pk_bf16_f32 v66, v66, v67
	v_cvt_pk_bf16_f32 v67, v72, v73
	v_pk_mul_f32 v[60:61], v[144:145], v[60:61] op_sel_hi:[0,1]
	global_store_dwordx4 v[80:81], v[64:67], off offset:256
	v_pk_mul_f32 v[62:63], v[144:145], v[62:63] op_sel_hi:[0,1]
	v_pk_mul_f32 v[50:51], v[144:145], v[50:51] op_sel_hi:[0,1]
	v_pk_mul_f32 v[66:67], v[144:145], v[58:59] op_sel_hi:[0,1]
	v_pk_mul_f32 v[58:59], v[144:145], v[56:57] op_sel_hi:[0,1]
	v_cvt_pk_bf16_f32 v56, v60, v61
	v_add_co_u32_e32 v60, vcc, s53, v146
	v_cvt_pk_bf16_f32 v57, v62, v63
	v_cvt_pk_bf16_f32 v58, v58, v59
	v_cvt_pk_bf16_f32 v59, v66, v67
	v_addc_co_u32_e32 v61, vcc, 0, v147, vcc
	global_store_dwordx4 v[60:61], v[56:59], off
	v_pk_mul_f32 v[48:49], v[144:145], v[48:49] op_sel_hi:[0,1]
	v_lshl_add_u64 v[64:65], v[146:147], 0, s[12:13]
	v_pk_mul_f32 v[56:57], v[144:145], v[42:43] op_sel_hi:[0,1]
	v_pk_mul_f32 v[42:43], v[144:145], v[40:41] op_sel_hi:[0,1]
	v_cvt_pk_bf16_f32 v40, v48, v49
	v_cvt_pk_bf16_f32 v41, v50, v51
	v_cvt_pk_bf16_f32 v42, v42, v43
	v_cvt_pk_bf16_f32 v43, v56, v57
	global_store_dwordx4 v[64:65], v[40:43], off offset:256
	v_pk_mul_f32 v[44:45], v[144:145], v[44:45] op_sel_hi:[0,1]
	v_pk_mul_f32 v[46:47], v[144:145], v[46:47] op_sel_hi:[0,1]
	v_pk_mul_f32 v[42:43], v[144:145], v[54:55] op_sel_hi:[0,1]
	v_pk_mul_f32 v[40:41], v[144:145], v[52:53] op_sel_hi:[0,1]
	v_cvt_pk_bf16_f32 v40, v40, v41
	v_cvt_pk_bf16_f32 v41, v42, v43
	v_cvt_pk_bf16_f32 v42, v44, v45
	v_add_co_u32_e32 v44, vcc, s54, v146
	v_cvt_pk_bf16_f32 v43, v46, v47
	s_nop 0
	v_addc_co_u32_e32 v45, vcc, 0, v147, vcc
	global_store_dwordx4 v[44:45], v[40:43], off
	v_pk_mul_f32 v[34:35], v[144:145], v[34:35] op_sel_hi:[0,1]
	v_pk_mul_f32 v[32:33], v[144:145], v[32:33] op_sel_hi:[0,1]
	v_pk_mul_f32 v[40:41], v[144:145], v[26:27] op_sel_hi:[0,1]
	v_pk_mul_f32 v[26:27], v[144:145], v[24:25] op_sel_hi:[0,1]
	v_lshl_add_u64 v[48:49], v[146:147], 0, s[22:23]
	v_cvt_pk_bf16_f32 v24, v32, v33
	v_cvt_pk_bf16_f32 v25, v34, v35
	v_cvt_pk_bf16_f32 v26, v26, v27
	v_cvt_pk_bf16_f32 v27, v40, v41
	global_store_dwordx4 v[48:49], v[24:27], off offset:256
	v_pk_mul_f32 v[28:29], v[144:145], v[28:29] op_sel_hi:[0,1]
	v_pk_mul_f32 v[30:31], v[144:145], v[30:31] op_sel_hi:[0,1]
	v_pk_mul_f32 v[26:27], v[144:145], v[38:39] op_sel_hi:[0,1]
	v_pk_mul_f32 v[24:25], v[144:145], v[36:37] op_sel_hi:[0,1]
	v_cvt_pk_bf16_f32 v24, v24, v25
	v_cvt_pk_bf16_f32 v25, v26, v27
	v_cvt_pk_bf16_f32 v26, v28, v29
	v_add_co_u32_e32 v28, vcc, s55, v146
	v_cvt_pk_bf16_f32 v27, v30, v31
	s_nop 0
	v_addc_co_u32_e32 v29, vcc, 0, v147, vcc
	global_store_dwordx4 v[28:29], v[24:27], off
	v_pk_mul_f32 v[18:19], v[144:145], v[18:19] op_sel_hi:[0,1]
	v_pk_mul_f32 v[16:17], v[144:145], v[16:17] op_sel_hi:[0,1]
	v_pk_mul_f32 v[24:25], v[144:145], v[10:11] op_sel_hi:[0,1]
	v_pk_mul_f32 v[10:11], v[144:145], v[8:9] op_sel_hi:[0,1]
	v_lshl_add_u64 v[32:33], v[146:147], 0, s[24:25]
	v_cvt_pk_bf16_f32 v8, v16, v17
	v_cvt_pk_bf16_f32 v9, v18, v19
	v_cvt_pk_bf16_f32 v10, v10, v11
	v_cvt_pk_bf16_f32 v11, v24, v25
	global_store_dwordx4 v[32:33], v[8:11], off offset:256
	v_pk_mul_f32 v[12:13], v[144:145], v[12:13] op_sel_hi:[0,1]
	v_pk_mul_f32 v[14:15], v[144:145], v[14:15] op_sel_hi:[0,1]
	v_pk_mul_f32 v[10:11], v[144:145], v[22:23] op_sel_hi:[0,1]
	v_pk_mul_f32 v[8:9], v[144:145], v[20:21] op_sel_hi:[0,1]
	v_cvt_pk_bf16_f32 v8, v8, v9
	v_cvt_pk_bf16_f32 v9, v10, v11
	v_cvt_pk_bf16_f32 v10, v12, v13
	v_add_co_u32_e32 v12, vcc, s56, v146
	v_cvt_pk_bf16_f32 v11, v14, v15
	s_nop 0
	v_addc_co_u32_e32 v13, vcc, 0, v147, vcc
	global_store_dwordx4 v[12:13], v[8:11], off
	v_pk_mul_f32 v[6:7], v[144:145], v[6:7] op_sel_hi:[0,1]
	v_pk_mul_f32 v[4:5], v[144:145], v[4:5] op_sel_hi:[0,1]
	v_pk_mul_f32 v[8:9], v[144:145], v[2:3] op_sel_hi:[0,1]
	v_pk_mul_f32 v[2:3], v[144:145], v[0:1] op_sel_hi:[0,1]
	v_lshl_add_u64 v[16:17], v[146:147], 0, s[26:27]
	v_cvt_pk_bf16_f32 v0, v4, v5
	v_cvt_pk_bf16_f32 v1, v6, v7
	v_cvt_pk_bf16_f32 v2, v2, v3
	v_cvt_pk_bf16_f32 v3, v8, v9
	s_andn2_b64 vcc, exec, s[8:9]
	s_mov_b64 s[8:9], -1
	global_store_dwordx4 v[16:17], v[0:3], off offset:256
	s_cbranch_vccnz .LBB0_1509
	s_andn2_b64 vcc, exec, s[14:15]
	s_cbranch_vccnz .LBB0_1508
	s_mov_b32 s100, 1
	s_branch .LBB0_1508

.LBB0_1523:
	s_add_u32 s0, s0, 0x11800000
	s_addc_u32 s1, s1, 0
	s_lshl_b32 s16, s16, 5
	s_and_b32 s22, s16, 0x60
	s_mov_b64 s[16:17], 0x80
	s_add_i32 m0, s27, 0x18000
	v_lshl_add_u64 v[6:7], v[6:7], 0, s[16:17]
	s_lshl_b32 s19, s18, 13
	s_lshl_b32 s23, s22, 7
	s_waitcnt vmcnt(2)
	s_barrier
	global_load_lds_dwordx4 v[6:7], off
	v_lshl_add_u64 v[2:3], v[2:3], 0, s[16:17]
	s_add_i32 m0, s27, 0x1a000
	s_add_i32 s49, s27, 0x8000
	s_add_i32 s50, s27, 0xa000
	global_load_lds_dwordx4 v[2:3], off
	v_lshl_add_u64 v[0:1], v[0:1], 0, s[16:17]
	s_mov_b32 m0, s49
	s_add_u32 s20, s38, 0x40080
	global_load_lds_dwordx4 v[0:1], off
	v_lshl_add_u64 v[0:1], v[4:5], 0, s[16:17]
	s_mov_b32 m0, s50
	s_addc_u32 s21, s39, 0
	global_load_lds_dwordx4 v[0:1], off
	s_add_i32 m0, s27, 0x1c000
	v_lshl_add_u64 v[0:1], s[20:21], 0, v[132:133]
	global_load_lds_dwordx4 v[0:1], off
	v_lshl_add_u64 v[0:1], s[20:21], 0, v[128:129]
	s_add_i32 m0, s27, 0x1e000
	s_cmpk_lt_u32 s9, 0x100
	global_load_lds_dwordx4 v[0:1], off
	v_lshrrev_b32_e32 v1, 1, v8
	v_and_b32_e32 v1, 24, v1
	v_and_b32_e32 v0, 15, v8
	v_lshlrev_b32_e32 v2, 1, v1
	v_lshl_or_b32 v144, s18, 6, v0
	v_lshl_or_b32 v0, v0, 6, v2
	v_lshlrev_b32_e32 v2, 2, v8
	v_and_b32_e32 v2, 32, v2
	v_bitop3_b32 v3, v0, s19, v2 bitop3:0xde
	v_bitop3_b32 v145, s23, v0, v2 bitop3:0xf6
	v_lshlrev_b32_e32 v0, 14, v9
	v_and_b32_e32 v0, 0xffff8000, v0
	v_or_b32_e32 v146, s22, v1
	v_lshl_add_u32 v0, v10, 11, v0
	v_and_b32_e32 v1, 1, v9
	v_lshl_or_b32 v0, v1, 6, v0
	v_lshl_add_u32 v136, v11, 1, v0
	v_lshlrev_b32_e32 v0, 14, v13
	v_and_b32_e32 v0, 0xffff8000, v0
	s_waitcnt vmcnt(6)
	v_lshl_add_u32 v0, v12, 11, v0
	v_and_b32_e32 v1, 1, v13
	s_cselect_b64 s[18:19], -1, 0
	v_lshl_or_b32 v0, v1, 6, v0
	s_add_i32 s51, 0, 0x10000
	s_add_i32 s52, 0, 0x14000
	s_sext_i32_i8 s57, s8
	v_mov_b32_e32 v137, v133
	v_lshl_add_u32 v138, v14, 1, v0
	v_mov_b32_e32 v139, v133
	v_mov_b64_e32 v[140:141], 0x400
	v_mov_b64_e32 v[142:143], 0x3ff
	v_add_u32_e32 v147, s51, v145
	v_add_u32_e32 v148, s52, v145
	v_add_u32_e32 v149, 0, v3
	s_mov_b32 s53, 0x40000
	s_mov_b64 s[20:21], 0x48000
	s_mov_b32 s54, 0x48000
	s_mov_b64 s[22:23], 0x50000
	s_mov_b32 s55, 0x50000
	s_mov_b64 s[24:25], 0x58000
	s_mov_b32 s56, 0x58000
	s_barrier
	s_mov_b32 s100, 0
	s_branch .LBB0_1526

.LBB0_1528:
	s_ashr_i32 s31, s30, 31
	s_lshl_b64 s[34:35], s[30:31], 19
	s_add_u32 s34, s4, s34
	s_addc_u32 s35, s5, s35
	s_and_b64 s[36:37], s[8:9], exec
	s_cselect_b32 s31, s35, s41
	s_cselect_b32 s58, s34, s40
	s_ashr_i32 s29, s28, 31
	s_lshl_b64 s[36:37], s[28:29], 19
	s_add_u32 s36, s10, s36
	s_addc_u32 s37, s11, s37
	s_and_b64 s[42:43], s[8:9], exec
	s_cselect_b32 s29, s37, s39
	s_cselect_b32 s59, s36, s38
	s_add_u32 s60, s38, 0x100
	s_addc_u32 s61, s39, 0
	s_add_u32 s38, s40, 0x40080
	v_mov_b32_e32 v0, 0
	s_addc_u32 s39, s41, 0
	s_mov_b32 s62, -2
	v_mov_b32_e32 v1, v0
	v_mov_b32_e32 v2, v0
	v_mov_b32_e32 v3, v0
	v_mov_b32_e32 v4, v0
	v_mov_b32_e32 v5, v0
	v_mov_b32_e32 v6, v0
	v_mov_b32_e32 v7, v0
	v_mov_b32_e32 v8, v0
	v_mov_b32_e32 v9, v0
	v_mov_b32_e32 v10, v0
	v_mov_b32_e32 v11, v0
	v_mov_b32_e32 v12, v0
	v_mov_b32_e32 v13, v0
	v_mov_b32_e32 v14, v0
	v_mov_b32_e32 v15, v0
	v_mov_b32_e32 v24, v0
	v_mov_b32_e32 v25, v0
	v_mov_b32_e32 v26, v0
	v_mov_b32_e32 v27, v0
	v_mov_b32_e32 v28, v0
	v_mov_b32_e32 v29, v0
	v_mov_b32_e32 v30, v0
	v_mov_b32_e32 v31, v0
	v_mov_b32_e32 v40, v0
	v_mov_b32_e32 v41, v0
	v_mov_b32_e32 v42, v0
	v_mov_b32_e32 v43, v0
	v_mov_b32_e32 v44, v0
	v_mov_b32_e32 v45, v0
	v_mov_b32_e32 v46, v0
	v_mov_b32_e32 v47, v0
	v_mov_b32_e32 v16, v0
	v_mov_b32_e32 v17, v0
	v_mov_b32_e32 v18, v0
	v_mov_b32_e32 v19, v0
	v_mov_b32_e32 v20, v0
	v_mov_b32_e32 v21, v0
	v_mov_b32_e32 v22, v0
	v_mov_b32_e32 v23, v0
	v_mov_b32_e32 v32, v0
	v_mov_b32_e32 v33, v0
	v_mov_b32_e32 v34, v0
	v_mov_b32_e32 v35, v0
	v_mov_b32_e32 v36, v0
	v_mov_b32_e32 v37, v0
	v_mov_b32_e32 v38, v0
	v_mov_b32_e32 v39, v0
	v_mov_b32_e32 v48, v0
	v_mov_b32_e32 v49, v0
	v_mov_b32_e32 v50, v0
	v_mov_b32_e32 v51, v0
	v_mov_b32_e32 v52, v0
	v_mov_b32_e32 v53, v0
	v_mov_b32_e32 v54, v0
	v_mov_b32_e32 v55, v0
	v_mov_b32_e32 v56, v0
	v_mov_b32_e32 v57, v0
	v_mov_b32_e32 v58, v0
	v_mov_b32_e32 v59, v0
	v_mov_b32_e32 v60, v0
	v_mov_b32_e32 v61, v0
	v_mov_b32_e32 v62, v0
	v_mov_b32_e32 v63, v0
	v_mov_b32_e32 v64, v0
	v_mov_b32_e32 v65, v0
	v_mov_b32_e32 v66, v0
	v_mov_b32_e32 v67, v0
	v_mov_b32_e32 v68, v0
	v_mov_b32_e32 v69, v0
	v_mov_b32_e32 v70, v0
	v_mov_b32_e32 v71, v0
	v_mov_b32_e32 v72, v0
	v_mov_b32_e32 v73, v0
	v_mov_b32_e32 v74, v0
	v_mov_b32_e32 v75, v0
	v_mov_b32_e32 v76, v0
	v_mov_b32_e32 v77, v0
	v_mov_b32_e32 v78, v0
	v_mov_b32_e32 v79, v0
	v_mov_b32_e32 v88, v0
	v_mov_b32_e32 v89, v0
	v_mov_b32_e32 v90, v0
	v_mov_b32_e32 v91, v0
	v_mov_b32_e32 v92, v0
	v_mov_b32_e32 v93, v0
	v_mov_b32_e32 v94, v0
	v_mov_b32_e32 v95, v0
	v_mov_b32_e32 v104, v0
	v_mov_b32_e32 v105, v0
	v_mov_b32_e32 v106, v0
	v_mov_b32_e32 v107, v0
	v_mov_b32_e32 v108, v0
	v_mov_b32_e32 v109, v0
	v_mov_b32_e32 v110, v0
	v_mov_b32_e32 v111, v0
	v_mov_b32_e32 v80, v0
	v_mov_b32_e32 v81, v0
	v_mov_b32_e32 v82, v0
	v_mov_b32_e32 v83, v0
	v_mov_b32_e32 v84, v0
	v_mov_b32_e32 v85, v0
	v_mov_b32_e32 v86, v0
	v_mov_b32_e32 v87, v0
	v_mov_b32_e32 v96, v0
	v_mov_b32_e32 v97, v0
	v_mov_b32_e32 v98, v0
	v_mov_b32_e32 v99, v0
	v_mov_b32_e32 v100, v0
	v_mov_b32_e32 v101, v0
	v_mov_b32_e32 v102, v0
	v_mov_b32_e32 v103, v0
	v_mov_b32_e32 v112, v0
	v_mov_b32_e32 v113, v0
	v_mov_b32_e32 v114, v0
	v_mov_b32_e32 v115, v0
	v_mov_b32_e32 v116, v0
	v_mov_b32_e32 v117, v0
	v_mov_b32_e32 v118, v0
	v_mov_b32_e32 v119, v0
	v_mov_b32_e32 v120, v0
	v_mov_b32_e32 v121, v0
	v_mov_b32_e32 v122, v0
	v_mov_b32_e32 v123, v0
	v_mov_b32_e32 v124, v0
	v_mov_b32_e32 v125, v0
	v_mov_b32_e32 v126, v0
	v_mov_b32_e32 v127, v0
	s_cmp_eq_u32 s100, 1
	s_cbranch_scc0 .Lgemm_nobar_1524
	s_mov_b32 s100, 0
	s_barrier
.Lgemm_nobar_1524:
.LBB0_1529:
	ds_read_b128 v[150:153], v147
	ds_read_b128 v[154:157], v147 offset:1024
	ds_read_b128 v[158:161], v147 offset:2048
	ds_read_b128 v[162:165], v147 offset:3072
	ds_read_b128 v[166:169], v148
	ds_read_b128 v[170:173], v148 offset:1024
	ds_read_b128 v[174:177], v148 offset:2048
	ds_read_b128 v[178:181], v148 offset:3072
	s_add_u32 s40, s38, 0xfffc0080
	s_addc_u32 s41, s39, -1
	s_cmp_eq_u32 s62, 12
	s_cselect_b32 s43, s31, s41
	s_cselect_b32 s42, s58, s40
	s_cselect_b32 s41, s29, s61
	s_cselect_b32 s40, s59, s60
	v_lshl_add_u64 v[214:215], s[38:39], 0, v[138:139]
	s_add_i32 m0, s27, 0xc000
	ds_read_b128 v[182:185], v149
	ds_read_b128 v[186:189], v149 offset:1024
	ds_read_b128 v[190:193], v149 offset:2048
	ds_read_b128 v[194:197], v149 offset:3072
	ds_read_b128 v[198:201], v149 offset:4096
	ds_read_b128 v[202:205], v149 offset:5120
	ds_read_b128 v[206:209], v149 offset:6144
	ds_read_b128 v[210:213], v149 offset:7168
	global_load_lds_dwordx4 v[214:215], off
	v_lshl_add_u64 v[214:215], s[38:39], 0, v[136:137]
	s_add_i32 m0, s27, 0xe000
	s_nop 0
	global_load_lds_dwordx4 v[214:215], off
	s_waitcnt vmcnt(8)
	s_waitcnt lgkmcnt(0)
	s_barrier
	s_setprio 1
	s_waitcnt lgkmcnt(0)
	v_mfma_f32_16x16x32_bf16 v[124:127], v[150:153], v[182:185], v[124:127]
	v_mfma_f32_16x16x32_bf16 v[120:123], v[158:161], v[182:185], v[120:123]
	v_mfma_f32_16x16x32_bf16 v[116:119], v[150:153], v[190:193], v[116:119]
	v_mfma_f32_16x16x32_bf16 v[112:115], v[158:161], v[190:193], v[112:115]
	v_mfma_f32_16x16x32_bf16 v[100:103], v[150:153], v[198:201], v[100:103]
	v_mfma_f32_16x16x32_bf16 v[96:99], v[158:161], v[198:201], v[96:99]
	v_mfma_f32_16x16x32_bf16 v[84:87], v[150:153], v[206:209], v[84:87]
	v_mfma_f32_16x16x32_bf16 v[80:83], v[158:161], v[206:209], v[80:83]
	v_mfma_f32_16x16x32_bf16 v[124:127], v[154:157], v[186:189], v[124:127]
	v_mfma_f32_16x16x32_bf16 v[120:123], v[162:165], v[186:189], v[120:123]
	v_mfma_f32_16x16x32_bf16 v[116:119], v[154:157], v[194:197], v[116:119]
	v_mfma_f32_16x16x32_bf16 v[112:115], v[162:165], v[194:197], v[112:115]
	v_mfma_f32_16x16x32_bf16 v[100:103], v[154:157], v[202:205], v[100:103]
	v_mfma_f32_16x16x32_bf16 v[96:99], v[162:165], v[202:205], v[96:99]
	v_mfma_f32_16x16x32_bf16 v[84:87], v[154:157], v[210:213], v[84:87]
	v_mfma_f32_16x16x32_bf16 v[80:83], v[162:165], v[210:213], v[80:83]
	s_setprio 0
	s_setprio 1
	v_mfma_f32_16x16x32_bf16 v[108:111], v[166:169], v[182:185], v[108:111]
	v_mfma_f32_16x16x32_bf16 v[104:107], v[174:177], v[182:185], v[104:107]
	v_mfma_f32_16x16x32_bf16 v[92:95], v[166:169], v[190:193], v[92:95]
	v_mfma_f32_16x16x32_bf16 v[88:91], v[174:177], v[190:193], v[88:91]
	v_mfma_f32_16x16x32_bf16 v[76:79], v[166:169], v[198:201], v[76:79]
	v_mfma_f32_16x16x32_bf16 v[72:75], v[174:177], v[198:201], v[72:75]
	v_mfma_f32_16x16x32_bf16 v[68:71], v[166:169], v[206:209], v[68:71]
	v_mfma_f32_16x16x32_bf16 v[64:67], v[174:177], v[206:209], v[64:67]
	v_mfma_f32_16x16x32_bf16 v[108:111], v[170:173], v[186:189], v[108:111]
	v_mfma_f32_16x16x32_bf16 v[104:107], v[178:181], v[186:189], v[104:107]
	v_mfma_f32_16x16x32_bf16 v[92:95], v[170:173], v[194:197], v[92:95]
	v_mfma_f32_16x16x32_bf16 v[88:91], v[178:181], v[194:197], v[88:91]
	v_mfma_f32_16x16x32_bf16 v[76:79], v[170:173], v[202:205], v[76:79]
	v_mfma_f32_16x16x32_bf16 v[72:75], v[178:181], v[202:205], v[72:75]
	v_mfma_f32_16x16x32_bf16 v[68:71], v[170:173], v[210:213], v[68:71]
	v_mfma_f32_16x16x32_bf16 v[64:67], v[178:181], v[210:213], v[64:67]
	s_setprio 0
	s_barrier
	s_add_i32 s63, s51, s33
	v_lshl_add_u64 v[214:215], s[40:41], 0, v[132:133]
	s_mov_b32 m0, s63
	ds_read_b128 v[182:185], v149 offset:16384
	ds_read_b128 v[186:189], v149 offset:17408
	ds_read_b128 v[190:193], v149 offset:18432
	ds_read_b128 v[194:197], v149 offset:19456
	ds_read_b128 v[198:201], v149 offset:20480
	ds_read_b128 v[202:205], v149 offset:21504
	ds_read_b128 v[206:209], v149 offset:22528
	ds_read_b128 v[210:213], v149 offset:23552
	global_load_lds_dwordx4 v[214:215], off
	s_add_i32 m0, s63, 0x2000
	s_add_u32 s64, s40, 0x40000
	v_lshl_add_u64 v[216:217], s[40:41], 0, v[128:129]
	s_addc_u32 s65, s41, 0
	s_add_i32 s63, s52, s33
	global_load_lds_dwordx4 v[216:217], off
	v_lshl_add_u64 v[218:219], s[64:65], 0, v[132:133]
	s_mov_b32 m0, s63
	v_lshl_add_u64 v[220:221], s[42:43], 0, v[130:131]
	global_load_lds_dwordx4 v[218:219], off
	v_lshl_add_u64 v[218:219], s[64:65], 0, v[128:129]
	s_add_i32 m0, s63, 0x2000
	s_nop 0
	global_load_lds_dwordx4 v[218:219], off
	v_lshl_add_u64 v[218:219], s[42:43], 0, v[134:135]
	s_mov_b32 m0, s27
	s_nop 0
	global_load_lds_dwordx4 v[218:219], off
	s_mov_b32 m0, s45
	s_nop 0
	global_load_lds_dwordx4 v[220:221], off
	s_waitcnt vmcnt(8)
	s_waitcnt lgkmcnt(0)
	s_barrier
	s_setprio 1
	s_waitcnt lgkmcnt(0)
	v_mfma_f32_16x16x32_bf16 v[60:63], v[150:153], v[182:185], v[60:63]
	v_mfma_f32_16x16x32_bf16 v[56:59], v[158:161], v[182:185], v[56:59]
	v_mfma_f32_16x16x32_bf16 v[52:55], v[150:153], v[190:193], v[52:55]
	v_mfma_f32_16x16x32_bf16 v[48:51], v[158:161], v[190:193], v[48:51]
	v_mfma_f32_16x16x32_bf16 v[36:39], v[150:153], v[198:201], v[36:39]
	v_mfma_f32_16x16x32_bf16 v[32:35], v[158:161], v[198:201], v[32:35]
	v_mfma_f32_16x16x32_bf16 v[20:23], v[150:153], v[206:209], v[20:23]
	v_mfma_f32_16x16x32_bf16 v[16:19], v[158:161], v[206:209], v[16:19]
	v_mfma_f32_16x16x32_bf16 v[60:63], v[154:157], v[186:189], v[60:63]
	v_mfma_f32_16x16x32_bf16 v[56:59], v[162:165], v[186:189], v[56:59]
	v_mfma_f32_16x16x32_bf16 v[52:55], v[154:157], v[194:197], v[52:55]
	v_mfma_f32_16x16x32_bf16 v[48:51], v[162:165], v[194:197], v[48:51]
	v_mfma_f32_16x16x32_bf16 v[36:39], v[154:157], v[202:205], v[36:39]
	v_mfma_f32_16x16x32_bf16 v[32:35], v[162:165], v[202:205], v[32:35]
	v_mfma_f32_16x16x32_bf16 v[20:23], v[154:157], v[210:213], v[20:23]
	v_mfma_f32_16x16x32_bf16 v[16:19], v[162:165], v[210:213], v[16:19]
	s_setprio 0
	s_setprio 1
	v_mfma_f32_16x16x32_bf16 v[44:47], v[166:169], v[182:185], v[44:47]
	v_mfma_f32_16x16x32_bf16 v[40:43], v[174:177], v[182:185], v[40:43]
	v_mfma_f32_16x16x32_bf16 v[28:31], v[166:169], v[190:193], v[28:31]
	v_mfma_f32_16x16x32_bf16 v[24:27], v[174:177], v[190:193], v[24:27]
	v_mfma_f32_16x16x32_bf16 v[12:15], v[166:169], v[198:201], v[12:15]
	v_mfma_f32_16x16x32_bf16 v[8:11], v[174:177], v[198:201], v[8:11]
	v_mfma_f32_16x16x32_bf16 v[4:7], v[166:169], v[206:209], v[4:7]
	v_mfma_f32_16x16x32_bf16 v[0:3], v[174:177], v[206:209], v[0:3]
	v_mfma_f32_16x16x32_bf16 v[44:47], v[170:173], v[186:189], v[44:47]
	v_mfma_f32_16x16x32_bf16 v[40:43], v[178:181], v[186:189], v[40:43]
	v_mfma_f32_16x16x32_bf16 v[28:31], v[170:173], v[194:197], v[28:31]
	v_mfma_f32_16x16x32_bf16 v[24:27], v[178:181], v[194:197], v[24:27]
	v_mfma_f32_16x16x32_bf16 v[12:15], v[170:173], v[202:205], v[12:15]
	v_mfma_f32_16x16x32_bf16 v[8:11], v[178:181], v[202:205], v[8:11]
	v_mfma_f32_16x16x32_bf16 v[4:7], v[170:173], v[210:213], v[4:7]
	v_mfma_f32_16x16x32_bf16 v[0:3], v[178:181], v[210:213], v[0:3]
	s_setprio 0
	s_barrier
	s_add_i32 s63, 0, 0x18000
	s_add_i32 s64, 0, 0x1c000
	v_add_u32_e32 v162, s63, v145
	v_add_u32_e32 v178, s64, v145
	ds_read_b128 v[150:153], v162
	ds_read_b128 v[154:157], v162 offset:1024
	ds_read_b128 v[158:161], v162 offset:2048
	ds_read_b128 v[162:165], v162 offset:3072
	ds_read_b128 v[166:169], v178
	ds_read_b128 v[170:173], v178 offset:1024
	ds_read_b128 v[174:177], v178 offset:2048
	ds_read_b128 v[178:181], v178 offset:3072
	s_add_u32 s42, s42, 0x40000
	s_addc_u32 s43, s43, 0
	s_mov_b32 m0, s46
	v_lshl_add_u64 v[222:223], s[42:43], 0, v[134:135]
	ds_read_b128 v[182:185], v149 offset:32768
	ds_read_b128 v[186:189], v149 offset:33792
	ds_read_b128 v[190:193], v149 offset:34816
	ds_read_b128 v[194:197], v149 offset:35840
	ds_read_b128 v[198:201], v149 offset:36864
	ds_read_b128 v[202:205], v149 offset:37888
	ds_read_b128 v[206:209], v149 offset:38912
	ds_read_b128 v[210:213], v149 offset:39936
	global_load_lds_dwordx4 v[222:223], off
	v_lshl_add_u64 v[222:223], s[42:43], 0, v[130:131]
	s_mov_b32 m0, s47
	s_nop 0
	global_load_lds_dwordx4 v[222:223], off
	s_waitcnt vmcnt(8)
	s_waitcnt lgkmcnt(0)
	s_barrier
	s_setprio 1
	s_waitcnt lgkmcnt(0)
	v_mfma_f32_16x16x32_bf16 v[124:127], v[150:153], v[182:185], v[124:127]
	v_mfma_f32_16x16x32_bf16 v[120:123], v[158:161], v[182:185], v[120:123]
	v_mfma_f32_16x16x32_bf16 v[116:119], v[150:153], v[190:193], v[116:119]
	v_mfma_f32_16x16x32_bf16 v[112:115], v[158:161], v[190:193], v[112:115]
	v_mfma_f32_16x16x32_bf16 v[100:103], v[150:153], v[198:201], v[100:103]
	v_mfma_f32_16x16x32_bf16 v[96:99], v[158:161], v[198:201], v[96:99]
	v_mfma_f32_16x16x32_bf16 v[84:87], v[150:153], v[206:209], v[84:87]
	v_mfma_f32_16x16x32_bf16 v[80:83], v[158:161], v[206:209], v[80:83]
	v_mfma_f32_16x16x32_bf16 v[124:127], v[154:157], v[186:189], v[124:127]
	v_mfma_f32_16x16x32_bf16 v[120:123], v[162:165], v[186:189], v[120:123]
	v_mfma_f32_16x16x32_bf16 v[116:119], v[154:157], v[194:197], v[116:119]
	v_mfma_f32_16x16x32_bf16 v[112:115], v[162:165], v[194:197], v[112:115]
	v_mfma_f32_16x16x32_bf16 v[100:103], v[154:157], v[202:205], v[100:103]
	v_mfma_f32_16x16x32_bf16 v[96:99], v[162:165], v[202:205], v[96:99]
	v_mfma_f32_16x16x32_bf16 v[84:87], v[154:157], v[210:213], v[84:87]
	v_mfma_f32_16x16x32_bf16 v[80:83], v[162:165], v[210:213], v[80:83]
	s_setprio 0
	s_setprio 1
	v_mfma_f32_16x16x32_bf16 v[108:111], v[166:169], v[182:185], v[108:111]
	v_mfma_f32_16x16x32_bf16 v[104:107], v[174:177], v[182:185], v[104:107]
	v_mfma_f32_16x16x32_bf16 v[92:95], v[166:169], v[190:193], v[92:95]
	v_mfma_f32_16x16x32_bf16 v[88:91], v[174:177], v[190:193], v[88:91]
	v_mfma_f32_16x16x32_bf16 v[76:79], v[166:169], v[198:201], v[76:79]
	v_mfma_f32_16x16x32_bf16 v[72:75], v[174:177], v[198:201], v[72:75]
	v_mfma_f32_16x16x32_bf16 v[68:71], v[166:169], v[206:209], v[68:71]
	v_mfma_f32_16x16x32_bf16 v[64:67], v[174:177], v[206:209], v[64:67]
	v_mfma_f32_16x16x32_bf16 v[108:111], v[170:173], v[186:189], v[108:111]
	v_mfma_f32_16x16x32_bf16 v[104:107], v[178:181], v[186:189], v[104:107]
	v_mfma_f32_16x16x32_bf16 v[92:95], v[170:173], v[194:197], v[92:95]
	v_mfma_f32_16x16x32_bf16 v[88:91], v[178:181], v[194:197], v[88:91]
	v_mfma_f32_16x16x32_bf16 v[76:79], v[170:173], v[202:205], v[76:79]
	v_mfma_f32_16x16x32_bf16 v[72:75], v[178:181], v[202:205], v[72:75]
	v_mfma_f32_16x16x32_bf16 v[68:71], v[170:173], v[210:213], v[68:71]
	v_mfma_f32_16x16x32_bf16 v[64:67], v[178:181], v[210:213], v[64:67]
	s_setprio 0
	s_barrier
	s_add_i32 s42, s63, s33
	v_lshl_add_u64 v[214:215], v[214:215], 0, s[16:17]
	s_mov_b32 m0, s42
	ds_read_b128 v[182:185], v149 offset:49152
	ds_read_b128 v[186:189], v149 offset:50176
	ds_read_b128 v[190:193], v149 offset:51200
	ds_read_b128 v[194:197], v149 offset:52224
	ds_read_b128 v[198:201], v149 offset:53248
	ds_read_b128 v[202:205], v149 offset:54272
	ds_read_b128 v[206:209], v149 offset:55296
	ds_read_b128 v[210:213], v149 offset:56320
	global_load_lds_dwordx4 v[214:215], off
	s_add_i32 m0, s42, 0x2000
	s_add_u32 s40, s40, 0x40080
	v_lshl_add_u64 v[214:215], v[216:217], 0, s[16:17]
	s_addc_u32 s41, s41, 0
	s_add_i32 s42, s64, s33
	global_load_lds_dwordx4 v[214:215], off
	v_lshl_add_u64 v[214:215], s[40:41], 0, v[132:133]
	s_mov_b32 m0, s42
	s_nop 0
	global_load_lds_dwordx4 v[214:215], off
	v_lshl_add_u64 v[214:215], s[40:41], 0, v[128:129]
	s_add_i32 m0, s42, 0x2000
	s_nop 0
	global_load_lds_dwordx4 v[214:215], off
	v_lshl_add_u64 v[214:215], v[218:219], 0, s[16:17]
	s_mov_b32 m0, s49
	s_nop 0
	global_load_lds_dwordx4 v[214:215], off
	v_lshl_add_u64 v[214:215], v[220:221], 0, s[16:17]
	s_mov_b32 m0, s50
	s_nop 0
	global_load_lds_dwordx4 v[214:215], off
	s_waitcnt vmcnt(8)
	s_waitcnt lgkmcnt(0)
	s_barrier
	s_setprio 1
	s_waitcnt lgkmcnt(0)
	v_mfma_f32_16x16x32_bf16 v[60:63], v[150:153], v[182:185], v[60:63]
	v_mfma_f32_16x16x32_bf16 v[56:59], v[158:161], v[182:185], v[56:59]
	v_mfma_f32_16x16x32_bf16 v[52:55], v[150:153], v[190:193], v[52:55]
	v_mfma_f32_16x16x32_bf16 v[48:51], v[158:161], v[190:193], v[48:51]
	v_mfma_f32_16x16x32_bf16 v[36:39], v[150:153], v[198:201], v[36:39]
	v_mfma_f32_16x16x32_bf16 v[32:35], v[158:161], v[198:201], v[32:35]
	v_mfma_f32_16x16x32_bf16 v[20:23], v[150:153], v[206:209], v[20:23]
	v_mfma_f32_16x16x32_bf16 v[16:19], v[158:161], v[206:209], v[16:19]
	v_mfma_f32_16x16x32_bf16 v[60:63], v[154:157], v[186:189], v[60:63]
	v_mfma_f32_16x16x32_bf16 v[56:59], v[162:165], v[186:189], v[56:59]
	v_mfma_f32_16x16x32_bf16 v[52:55], v[154:157], v[194:197], v[52:55]
	v_mfma_f32_16x16x32_bf16 v[48:51], v[162:165], v[194:197], v[48:51]
	v_mfma_f32_16x16x32_bf16 v[36:39], v[154:157], v[202:205], v[36:39]
	v_mfma_f32_16x16x32_bf16 v[32:35], v[162:165], v[202:205], v[32:35]
	v_mfma_f32_16x16x32_bf16 v[20:23], v[154:157], v[210:213], v[20:23]
	v_mfma_f32_16x16x32_bf16 v[16:19], v[162:165], v[210:213], v[16:19]
	s_setprio 0
	s_setprio 1
	v_mfma_f32_16x16x32_bf16 v[44:47], v[166:169], v[182:185], v[44:47]
	v_mfma_f32_16x16x32_bf16 v[40:43], v[174:177], v[182:185], v[40:43]
	v_mfma_f32_16x16x32_bf16 v[28:31], v[166:169], v[190:193], v[28:31]
	v_mfma_f32_16x16x32_bf16 v[24:27], v[174:177], v[190:193], v[24:27]
	v_mfma_f32_16x16x32_bf16 v[12:15], v[166:169], v[198:201], v[12:15]
	v_mfma_f32_16x16x32_bf16 v[8:11], v[174:177], v[198:201], v[8:11]
	v_mfma_f32_16x16x32_bf16 v[4:7], v[166:169], v[206:209], v[4:7]
	v_mfma_f32_16x16x32_bf16 v[0:3], v[174:177], v[206:209], v[0:3]
	v_mfma_f32_16x16x32_bf16 v[44:47], v[170:173], v[186:189], v[44:47]
	v_mfma_f32_16x16x32_bf16 v[40:43], v[178:181], v[186:189], v[40:43]
	v_mfma_f32_16x16x32_bf16 v[28:31], v[170:173], v[194:197], v[28:31]
	v_mfma_f32_16x16x32_bf16 v[24:27], v[178:181], v[194:197], v[24:27]
	v_mfma_f32_16x16x32_bf16 v[12:15], v[170:173], v[202:205], v[12:15]
	v_mfma_f32_16x16x32_bf16 v[8:11], v[178:181], v[202:205], v[8:11]
	v_mfma_f32_16x16x32_bf16 v[4:7], v[170:173], v[210:213], v[4:7]
	v_mfma_f32_16x16x32_bf16 v[0:3], v[178:181], v[210:213], v[0:3]
	s_setprio 0
	s_barrier
	s_add_i32 s62, s62, 2
	s_add_u32 s60, s60, 0x100
	s_addc_u32 s61, s61, 0
	s_add_u32 s38, s38, 0x100
	s_addc_u32 s39, s39, 0
	s_cmp_gt_u32 s62, 13
	s_cbranch_scc0 .LBB0_1529
	s_and_b64 vcc, exec, s[18:19]
	s_cbranch_vccz .LBB0_1532
	s_barrier
.LBB0_1532:
	s_ashr_i32 s31, s57, 31
	s_lshr_b32 s31, s31, 30
	s_add_i32 s31, s57, s31
	s_ashr_i32 s40, s31, 2
	s_mov_b64 s[38:39], s[0:1]
	s_ashr_i32 s41, s40, 31
	s_lshl_b32 s29, s57, 8
	s_lshl_b64 s[42:43], s[40:41], 26
	s_add_u32 s38, s38, s42
	s_addc_u32 s39, s39, s43
	s_lshl_b32 s31, s40, 10
	s_sub_i32 s29, s29, s31
	v_or_b32_e32 v150, s29, v146
	v_lshl_add_u32 v152, s26, 8, v144
	v_ashrrev_i32_e32 v151, 31, v150
	v_ashrrev_i32_e32 v153, 31, v152
	v_lshl_add_u64 v[150:151], v[150:151], 1, s[38:39]
	v_lshlrev_b64 v[154:155], 11, v[152:153]
	v_lshl_add_u64 v[154:155], v[150:151], 0, v[154:155]
	v_cvt_pk_bf16_f32 v60, v60, v61
	v_cvt_pk_bf16_f32 v61, v62, v63
	v_cvt_pk_bf16_f32 v62, v56, v57
	v_add_co_u32_e32 v56, vcc, s53, v154
	v_cvt_pk_bf16_f32 v68, v68, v69
	v_cvt_pk_bf16_f32 v69, v70, v71
	v_cvt_pk_bf16_f32 v70, v64, v65
	v_lshl_add_u64 v[64:65], v[154:155], 0, s[12:13]
	v_addc_co_u32_e32 v57, vcc, 0, v155, vcc
	v_cvt_pk_bf16_f32 v44, v44, v45
	v_cvt_pk_bf16_f32 v45, v46, v47
	v_cvt_pk_bf16_f32 v46, v40, v41
	v_cvt_pk_bf16_f32 v47, v42, v43
	global_store_dwordx4 v[64:65], v[44:47], off offset:256
	v_cvt_pk_bf16_f32 v108, v108, v109
	v_cvt_pk_bf16_f32 v109, v110, v111
	v_add_co_u32_e32 v46, vcc, s54, v154
	v_cvt_pk_bf16_f32 v110, v104, v105
	v_or_b32_e32 v104, 16, v152
	v_lshl_add_u64 v[44:45], v[154:155], 0, s[20:21]
	v_addc_co_u32_e32 v47, vcc, 0, v155, vcc
	v_cvt_pk_bf16_f32 v28, v28, v29
	v_cvt_pk_bf16_f32 v29, v30, v31
	v_cvt_pk_bf16_f32 v30, v24, v25
	v_cvt_pk_bf16_f32 v31, v26, v27
	v_ashrrev_i32_e32 v105, 31, v104
	v_cvt_pk_bf16_f32 v92, v92, v93
	v_cvt_pk_bf16_f32 v93, v94, v95
	v_cvt_pk_bf16_f32 v94, v88, v89
	v_or_b32_e32 v88, 32, v152
	global_store_dwordx4 v[44:45], v[28:31], off offset:256
	v_cvt_pk_bf16_f32 v111, v106, v107
	v_lshlrev_b64 v[104:105], 11, v[104:105]
	v_add_co_u32_e32 v30, vcc, s55, v154
	v_ashrrev_i32_e32 v89, 31, v88
	v_cvt_pk_bf16_f32 v76, v76, v77
	v_cvt_pk_bf16_f32 v77, v78, v79
	v_cvt_pk_bf16_f32 v78, v72, v73
	v_or_b32_e32 v72, 48, v152
	v_lshl_add_u64 v[28:29], v[154:155], 0, s[22:23]
	v_addc_co_u32_e32 v31, vcc, 0, v155, vcc
	v_cvt_pk_bf16_f32 v12, v12, v13
	v_cvt_pk_bf16_f32 v13, v14, v15
	v_cvt_pk_bf16_f32 v14, v8, v9
	v_cvt_pk_bf16_f32 v15, v10, v11
	global_store_dwordx4 v[154:155], v[108:111], off offset:256
	v_cvt_pk_bf16_f32 v95, v90, v91
	v_lshlrev_b64 v[88:89], 11, v[88:89]
	v_lshl_add_u64 v[108:109], v[150:151], 0, v[104:105]
	v_ashrrev_i32_e32 v73, 31, v72
	global_store_dwordx4 v[28:29], v[12:15], off offset:256
	global_store_dwordx4 v[108:109], v[92:95], off offset:256
	v_cvt_pk_bf16_f32 v79, v74, v75
	v_add_co_u32_e32 v14, vcc, s56, v154
	v_lshl_add_u64 v[92:93], v[150:151], 0, v[88:89]
	v_lshlrev_b64 v[72:73], 11, v[72:73]
	v_addc_co_u32_e32 v15, vcc, 0, v155, vcc
	v_cvt_pk_bf16_f32 v124, v124, v125
	v_cvt_pk_bf16_f32 v125, v126, v127
	v_cvt_pk_bf16_f32 v126, v120, v121
	v_cvt_pk_bf16_f32 v127, v122, v123
	v_cvt_pk_bf16_f32 v104, v116, v117
	v_cvt_pk_bf16_f32 v105, v118, v119
	v_cvt_pk_bf16_f32 v106, v112, v113
	v_cvt_pk_bf16_f32 v107, v114, v115
	v_cvt_pk_bf16_f32 v88, v100, v101
	v_cvt_pk_bf16_f32 v89, v102, v103
	v_cvt_pk_bf16_f32 v90, v96, v97
	v_cvt_pk_bf16_f32 v91, v98, v99
	global_store_dwordx4 v[92:93], v[76:79], off offset:256
	v_cvt_pk_bf16_f32 v74, v80, v81
	v_cvt_pk_bf16_f32 v75, v82, v83
	v_lshl_add_u64 v[76:77], v[150:151], 0, v[72:73]
	v_cvt_pk_bf16_f32 v72, v84, v85
	v_cvt_pk_bf16_f32 v73, v86, v87
	v_cvt_pk_bf16_f32 v71, v66, v67
	v_cvt_pk_bf16_f32 v63, v58, v59
	v_cvt_pk_bf16_f32 v40, v52, v53
	v_cvt_pk_bf16_f32 v41, v54, v55
	v_cvt_pk_bf16_f32 v42, v48, v49
	v_cvt_pk_bf16_f32 v43, v50, v51
	v_cvt_pk_bf16_f32 v24, v36, v37
	v_cvt_pk_bf16_f32 v25, v38, v39
	v_cvt_pk_bf16_f32 v26, v32, v33
	v_cvt_pk_bf16_f32 v27, v34, v35
	v_lshl_add_u64 v[12:13], v[154:155], 0, s[24:25]
	v_cvt_pk_bf16_f32 v8, v20, v21
	v_cvt_pk_bf16_f32 v9, v22, v23
	v_cvt_pk_bf16_f32 v10, v16, v17
	v_cvt_pk_bf16_f32 v11, v18, v19
	v_cvt_pk_bf16_f32 v4, v4, v5
	v_cvt_pk_bf16_f32 v5, v6, v7
	v_cvt_pk_bf16_f32 v6, v0, v1
	v_cvt_pk_bf16_f32 v7, v2, v3
	s_andn2_b64 vcc, exec, s[8:9]
	s_mov_b64 s[8:9], -1
	global_store_dwordx4 v[154:155], v[124:127], off
	global_store_dwordx4 v[108:109], v[104:107], off
	global_store_dwordx4 v[92:93], v[88:91], off
	global_store_dwordx4 v[76:77], v[72:75], off
	global_store_dwordx4 v[76:77], v[68:71], off offset:256
	global_store_dwordx4 v[56:57], v[60:63], off
	global_store_dwordx4 v[46:47], v[40:43], off
	global_store_dwordx4 v[30:31], v[24:27], off
	global_store_dwordx4 v[14:15], v[8:11], off
	global_store_dwordx4 v[12:13], v[4:7], off offset:256
	s_cbranch_vccnz .LBB0_1525
	s_andn2_b64 vcc, exec, s[14:15]
	s_cbranch_vccnz .LBB0_1524
	s_mov_b32 s100, 1
	s_branch .LBB0_1524

.LBB0_1795:
	s_add_u32 s14, s8, 0xd800000
	s_addc_u32 s15, s9, 0
	s_lshl_b32 s8, s16, 5
	s_mov_b64 s[16:17], 0x80
	s_and_b32 s21, s8, 0x60
	s_add_i32 m0, s42, 0x18000
	v_lshl_add_u64 v[6:7], v[6:7], 0, s[16:17]
	s_lshl_b32 s20, s19, 13
	s_lshl_b32 s22, s21, 7
	s_waitcnt vmcnt(2)
	s_barrier
	global_load_lds_dwordx4 v[6:7], off
	v_lshl_add_u64 v[2:3], v[2:3], 0, s[16:17]
	s_add_i32 m0, s42, 0x1a000
	s_add_i32 s47, s42, 0x8000
	s_add_i32 s48, s42, 0xa000
	global_load_lds_dwordx4 v[2:3], off
	v_lshl_add_u64 v[0:1], v[0:1], 0, s[16:17]
	s_mov_b32 m0, s47
	s_add_u32 s8, s36, 0x40080
	global_load_lds_dwordx4 v[0:1], off
	v_lshl_add_u64 v[0:1], v[4:5], 0, s[16:17]
	s_mov_b32 m0, s48
	s_addc_u32 s9, s37, 0
	global_load_lds_dwordx4 v[0:1], off
	s_add_i32 m0, s42, 0x1c000
	v_lshl_add_u64 v[0:1], s[8:9], 0, v[132:133]
	global_load_lds_dwordx4 v[0:1], off
	v_lshl_add_u64 v[0:1], s[8:9], 0, v[128:129]
	s_add_i32 m0, s42, 0x1e000
	s_cmpk_lt_u32 s18, 0x100
	global_load_lds_dwordx4 v[0:1], off
	v_lshrrev_b32_e32 v1, 1, v8
	v_and_b32_e32 v1, 24, v1
	v_and_b32_e32 v0, 15, v8
	v_lshlrev_b32_e32 v2, 1, v1
	v_lshl_or_b32 v144, s19, 6, v0
	v_lshl_or_b32 v0, v0, 6, v2
	v_lshlrev_b32_e32 v2, 2, v8
	v_and_b32_e32 v2, 32, v2
	v_bitop3_b32 v3, v0, s20, v2 bitop3:0xde
	v_bitop3_b32 v145, s22, v0, v2 bitop3:0xf6
	v_lshlrev_b32_e32 v0, 14, v9
	v_and_b32_e32 v0, 0xffff8000, v0
	v_or_b32_e32 v146, s21, v1
	v_lshl_add_u32 v0, v10, 11, v0
	v_and_b32_e32 v1, 1, v9
	v_lshl_or_b32 v0, v1, 6, v0
	v_lshl_add_u32 v136, v11, 1, v0
	v_lshlrev_b32_e32 v0, 14, v13
	v_and_b32_e32 v0, 0xffff8000, v0
	s_waitcnt vmcnt(6)
	v_lshl_add_u32 v0, v12, 11, v0
	v_and_b32_e32 v1, 1, v13
	s_cselect_b64 s[18:19], -1, 0
	v_lshl_or_b32 v0, v1, 6, v0
	s_add_i32 s49, 0, 0x10000
	s_add_i32 s50, 0, 0x14000
	v_mov_b32_e32 v137, v133
	v_lshl_add_u32 v138, v14, 1, v0
	v_mov_b32_e32 v139, v133
	v_mov_b64_e32 v[140:141], 0x200
	v_mov_b64_e32 v[142:143], 0x1ff
	v_add_u32_e32 v147, s49, v145
	v_add_u32_e32 v148, s50, v145
	v_add_u32_e32 v149, 0, v3
	s_mov_b32 s51, 0x40000
	s_mov_b64 s[20:21], 0x48000
	s_mov_b32 s52, 0x48000
	s_mov_b64 s[22:23], 0x50000
	s_mov_b32 s53, 0x50000
	s_mov_b64 s[24:25], 0x58000
	s_mov_b32 s54, 0x58000
	v_readlane_b32 s55, v254, 11
	s_mov_b32 s56, s92
	s_barrier
	s_mov_b32 s100, 0
	s_branch .LBB0_1798

.LBB0_1800:
	s_ashr_i32 s29, s28, 31
	s_lshl_b64 s[30:31], s[28:29], 19
	s_add_u32 s30, s0, s30
	s_addc_u32 s31, s1, s31
	s_and_b64 s[34:35], s[8:9], exec
	s_cselect_b32 s29, s31, s39
	s_cselect_b32 s57, s30, s38
	s_ashr_i32 s27, s26, 31
	s_lshl_b64 s[34:35], s[26:27], 19
	s_add_u32 s34, s4, s34
	s_addc_u32 s35, s5, s35
	s_and_b64 s[40:41], s[8:9], exec
	s_cselect_b32 s27, s35, s37
	s_cselect_b32 s58, s34, s36
	s_add_u32 s59, s36, 0x100
	s_addc_u32 s60, s37, 0
	s_add_u32 s36, s38, 0x40080
	v_mov_b32_e32 v0, 0
	s_addc_u32 s37, s39, 0
	s_mov_b32 s61, -2
	v_mov_b32_e32 v1, v0
	v_mov_b32_e32 v2, v0
	v_mov_b32_e32 v3, v0
	v_mov_b32_e32 v4, v0
	v_mov_b32_e32 v5, v0
	v_mov_b32_e32 v6, v0
	v_mov_b32_e32 v7, v0
	v_mov_b32_e32 v8, v0
	v_mov_b32_e32 v9, v0
	v_mov_b32_e32 v10, v0
	v_mov_b32_e32 v11, v0
	v_mov_b32_e32 v12, v0
	v_mov_b32_e32 v13, v0
	v_mov_b32_e32 v14, v0
	v_mov_b32_e32 v15, v0
	v_mov_b32_e32 v24, v0
	v_mov_b32_e32 v25, v0
	v_mov_b32_e32 v26, v0
	v_mov_b32_e32 v27, v0
	v_mov_b32_e32 v28, v0
	v_mov_b32_e32 v29, v0
	v_mov_b32_e32 v30, v0
	v_mov_b32_e32 v31, v0
	v_mov_b32_e32 v40, v0
	v_mov_b32_e32 v41, v0
	v_mov_b32_e32 v42, v0
	v_mov_b32_e32 v43, v0
	v_mov_b32_e32 v44, v0
	v_mov_b32_e32 v45, v0
	v_mov_b32_e32 v46, v0
	v_mov_b32_e32 v47, v0
	v_mov_b32_e32 v16, v0
	v_mov_b32_e32 v17, v0
	v_mov_b32_e32 v18, v0
	v_mov_b32_e32 v19, v0
	v_mov_b32_e32 v20, v0
	v_mov_b32_e32 v21, v0
	v_mov_b32_e32 v22, v0
	v_mov_b32_e32 v23, v0
	v_mov_b32_e32 v32, v0
	v_mov_b32_e32 v33, v0
	v_mov_b32_e32 v34, v0
	v_mov_b32_e32 v35, v0
	v_mov_b32_e32 v36, v0
	v_mov_b32_e32 v37, v0
	v_mov_b32_e32 v38, v0
	v_mov_b32_e32 v39, v0
	v_mov_b32_e32 v48, v0
	v_mov_b32_e32 v49, v0
	v_mov_b32_e32 v50, v0
	v_mov_b32_e32 v51, v0
	v_mov_b32_e32 v52, v0
	v_mov_b32_e32 v53, v0
	v_mov_b32_e32 v54, v0
	v_mov_b32_e32 v55, v0
	v_mov_b32_e32 v56, v0
	v_mov_b32_e32 v57, v0
	v_mov_b32_e32 v58, v0
	v_mov_b32_e32 v59, v0
	v_mov_b32_e32 v60, v0
	v_mov_b32_e32 v61, v0
	v_mov_b32_e32 v62, v0
	v_mov_b32_e32 v63, v0
	v_mov_b32_e32 v64, v0
	v_mov_b32_e32 v65, v0
	v_mov_b32_e32 v66, v0
	v_mov_b32_e32 v67, v0
	v_mov_b32_e32 v68, v0
	v_mov_b32_e32 v69, v0
	v_mov_b32_e32 v70, v0
	v_mov_b32_e32 v71, v0
	v_mov_b32_e32 v72, v0
	v_mov_b32_e32 v73, v0
	v_mov_b32_e32 v74, v0
	v_mov_b32_e32 v75, v0
	v_mov_b32_e32 v76, v0
	v_mov_b32_e32 v77, v0
	v_mov_b32_e32 v78, v0
	v_mov_b32_e32 v79, v0
	v_mov_b32_e32 v88, v0
	v_mov_b32_e32 v89, v0
	v_mov_b32_e32 v90, v0
	v_mov_b32_e32 v91, v0
	v_mov_b32_e32 v92, v0
	v_mov_b32_e32 v93, v0
	v_mov_b32_e32 v94, v0
	v_mov_b32_e32 v95, v0
	v_mov_b32_e32 v104, v0
	v_mov_b32_e32 v105, v0
	v_mov_b32_e32 v106, v0
	v_mov_b32_e32 v107, v0
	v_mov_b32_e32 v108, v0
	v_mov_b32_e32 v109, v0
	v_mov_b32_e32 v110, v0
	v_mov_b32_e32 v111, v0
	v_mov_b32_e32 v80, v0
	v_mov_b32_e32 v81, v0
	v_mov_b32_e32 v82, v0
	v_mov_b32_e32 v83, v0
	v_mov_b32_e32 v84, v0
	v_mov_b32_e32 v85, v0
	v_mov_b32_e32 v86, v0
	v_mov_b32_e32 v87, v0
	v_mov_b32_e32 v96, v0
	v_mov_b32_e32 v97, v0
	v_mov_b32_e32 v98, v0
	v_mov_b32_e32 v99, v0
	v_mov_b32_e32 v100, v0
	v_mov_b32_e32 v101, v0
	v_mov_b32_e32 v102, v0
	v_mov_b32_e32 v103, v0
	v_mov_b32_e32 v112, v0
	v_mov_b32_e32 v113, v0
	v_mov_b32_e32 v114, v0
	v_mov_b32_e32 v115, v0
	v_mov_b32_e32 v116, v0
	v_mov_b32_e32 v117, v0
	v_mov_b32_e32 v118, v0
	v_mov_b32_e32 v119, v0
	v_mov_b32_e32 v120, v0
	v_mov_b32_e32 v121, v0
	v_mov_b32_e32 v122, v0
	v_mov_b32_e32 v123, v0
	v_mov_b32_e32 v124, v0
	v_mov_b32_e32 v125, v0
	v_mov_b32_e32 v126, v0
	v_mov_b32_e32 v127, v0
	s_cmp_eq_u32 s100, 1
	s_cbranch_scc0 .Lgemm_nobar_1796
	s_mov_b32 s100, 0
	s_barrier
.Lgemm_nobar_1796:
.LBB0_1801:
	ds_read_b128 v[150:153], v147
	ds_read_b128 v[154:157], v147 offset:1024
	ds_read_b128 v[158:161], v147 offset:2048
	ds_read_b128 v[162:165], v147 offset:3072
	ds_read_b128 v[166:169], v148
	ds_read_b128 v[170:173], v148 offset:1024
	ds_read_b128 v[174:177], v148 offset:2048
	ds_read_b128 v[178:181], v148 offset:3072
	s_add_u32 s38, s36, 0xfffc0080
	s_addc_u32 s39, s37, -1
	s_cmp_eq_u32 s61, 12
	s_cselect_b32 s41, s29, s39
	s_cselect_b32 s40, s57, s38
	s_cselect_b32 s39, s27, s60
	s_cselect_b32 s38, s58, s59
	v_lshl_add_u64 v[214:215], s[36:37], 0, v[138:139]
	s_add_i32 m0, s42, 0xc000
	ds_read_b128 v[182:185], v149
	ds_read_b128 v[186:189], v149 offset:1024
	ds_read_b128 v[190:193], v149 offset:2048
	ds_read_b128 v[194:197], v149 offset:3072
	ds_read_b128 v[198:201], v149 offset:4096
	ds_read_b128 v[202:205], v149 offset:5120
	ds_read_b128 v[206:209], v149 offset:6144
	ds_read_b128 v[210:213], v149 offset:7168
	global_load_lds_dwordx4 v[214:215], off
	v_lshl_add_u64 v[214:215], s[36:37], 0, v[136:137]
	s_add_i32 m0, s42, 0xe000
	s_nop 0
	global_load_lds_dwordx4 v[214:215], off
	s_waitcnt vmcnt(8)
	s_waitcnt lgkmcnt(0)
	s_barrier
	s_setprio 1
	s_waitcnt lgkmcnt(0)
	v_mfma_f32_16x16x32_bf16 v[124:127], v[150:153], v[182:185], v[124:127]
	v_mfma_f32_16x16x32_bf16 v[120:123], v[158:161], v[182:185], v[120:123]
	v_mfma_f32_16x16x32_bf16 v[116:119], v[150:153], v[190:193], v[116:119]
	v_mfma_f32_16x16x32_bf16 v[112:115], v[158:161], v[190:193], v[112:115]
	v_mfma_f32_16x16x32_bf16 v[100:103], v[150:153], v[198:201], v[100:103]
	v_mfma_f32_16x16x32_bf16 v[96:99], v[158:161], v[198:201], v[96:99]
	v_mfma_f32_16x16x32_bf16 v[84:87], v[150:153], v[206:209], v[84:87]
	v_mfma_f32_16x16x32_bf16 v[80:83], v[158:161], v[206:209], v[80:83]
	v_mfma_f32_16x16x32_bf16 v[124:127], v[154:157], v[186:189], v[124:127]
	v_mfma_f32_16x16x32_bf16 v[120:123], v[162:165], v[186:189], v[120:123]
	v_mfma_f32_16x16x32_bf16 v[116:119], v[154:157], v[194:197], v[116:119]
	v_mfma_f32_16x16x32_bf16 v[112:115], v[162:165], v[194:197], v[112:115]
	v_mfma_f32_16x16x32_bf16 v[100:103], v[154:157], v[202:205], v[100:103]
	v_mfma_f32_16x16x32_bf16 v[96:99], v[162:165], v[202:205], v[96:99]
	v_mfma_f32_16x16x32_bf16 v[84:87], v[154:157], v[210:213], v[84:87]
	v_mfma_f32_16x16x32_bf16 v[80:83], v[162:165], v[210:213], v[80:83]
	s_setprio 0
	s_setprio 1
	v_mfma_f32_16x16x32_bf16 v[108:111], v[166:169], v[182:185], v[108:111]
	v_mfma_f32_16x16x32_bf16 v[104:107], v[174:177], v[182:185], v[104:107]
	v_mfma_f32_16x16x32_bf16 v[92:95], v[166:169], v[190:193], v[92:95]
	v_mfma_f32_16x16x32_bf16 v[88:91], v[174:177], v[190:193], v[88:91]
	v_mfma_f32_16x16x32_bf16 v[76:79], v[166:169], v[198:201], v[76:79]
	v_mfma_f32_16x16x32_bf16 v[72:75], v[174:177], v[198:201], v[72:75]
	v_mfma_f32_16x16x32_bf16 v[68:71], v[166:169], v[206:209], v[68:71]
	v_mfma_f32_16x16x32_bf16 v[64:67], v[174:177], v[206:209], v[64:67]
	v_mfma_f32_16x16x32_bf16 v[108:111], v[170:173], v[186:189], v[108:111]
	v_mfma_f32_16x16x32_bf16 v[104:107], v[178:181], v[186:189], v[104:107]
	v_mfma_f32_16x16x32_bf16 v[92:95], v[170:173], v[194:197], v[92:95]
	v_mfma_f32_16x16x32_bf16 v[88:91], v[178:181], v[194:197], v[88:91]
	v_mfma_f32_16x16x32_bf16 v[76:79], v[170:173], v[202:205], v[76:79]
	v_mfma_f32_16x16x32_bf16 v[72:75], v[178:181], v[202:205], v[72:75]
	v_mfma_f32_16x16x32_bf16 v[68:71], v[170:173], v[210:213], v[68:71]
	v_mfma_f32_16x16x32_bf16 v[64:67], v[178:181], v[210:213], v[64:67]
	s_setprio 0
	s_barrier
	s_add_i32 s62, s49, s33
	v_lshl_add_u64 v[214:215], s[38:39], 0, v[132:133]
	s_mov_b32 m0, s62
	ds_read_b128 v[182:185], v149 offset:16384
	ds_read_b128 v[186:189], v149 offset:17408
	ds_read_b128 v[190:193], v149 offset:18432
	ds_read_b128 v[194:197], v149 offset:19456
	ds_read_b128 v[198:201], v149 offset:20480
	ds_read_b128 v[202:205], v149 offset:21504
	ds_read_b128 v[206:209], v149 offset:22528
	ds_read_b128 v[210:213], v149 offset:23552
	global_load_lds_dwordx4 v[214:215], off
	s_add_i32 m0, s62, 0x2000
	s_add_u32 s62, s38, 0x40000
	v_lshl_add_u64 v[216:217], s[38:39], 0, v[128:129]
	s_addc_u32 s63, s39, 0
	s_add_i32 s64, s50, s33
	global_load_lds_dwordx4 v[216:217], off
	v_lshl_add_u64 v[218:219], s[62:63], 0, v[132:133]
	s_mov_b32 m0, s64
	v_lshl_add_u64 v[220:221], s[40:41], 0, v[130:131]
	global_load_lds_dwordx4 v[218:219], off
	v_lshl_add_u64 v[218:219], s[62:63], 0, v[128:129]
	s_add_i32 m0, s64, 0x2000
	s_nop 0
	global_load_lds_dwordx4 v[218:219], off
	v_lshl_add_u64 v[218:219], s[40:41], 0, v[134:135]
	s_mov_b32 m0, s42
	s_nop 0
	global_load_lds_dwordx4 v[218:219], off
	s_mov_b32 m0, s43
	s_nop 0
	global_load_lds_dwordx4 v[220:221], off
	s_waitcnt vmcnt(8)
	s_waitcnt lgkmcnt(0)
	s_barrier
	s_setprio 1
	s_waitcnt lgkmcnt(0)
	v_mfma_f32_16x16x32_bf16 v[60:63], v[150:153], v[182:185], v[60:63]
	v_mfma_f32_16x16x32_bf16 v[56:59], v[158:161], v[182:185], v[56:59]
	v_mfma_f32_16x16x32_bf16 v[52:55], v[150:153], v[190:193], v[52:55]
	v_mfma_f32_16x16x32_bf16 v[48:51], v[158:161], v[190:193], v[48:51]
	v_mfma_f32_16x16x32_bf16 v[36:39], v[150:153], v[198:201], v[36:39]
	v_mfma_f32_16x16x32_bf16 v[32:35], v[158:161], v[198:201], v[32:35]
	v_mfma_f32_16x16x32_bf16 v[20:23], v[150:153], v[206:209], v[20:23]
	v_mfma_f32_16x16x32_bf16 v[16:19], v[158:161], v[206:209], v[16:19]
	v_mfma_f32_16x16x32_bf16 v[60:63], v[154:157], v[186:189], v[60:63]
	v_mfma_f32_16x16x32_bf16 v[56:59], v[162:165], v[186:189], v[56:59]
	v_mfma_f32_16x16x32_bf16 v[52:55], v[154:157], v[194:197], v[52:55]
	v_mfma_f32_16x16x32_bf16 v[48:51], v[162:165], v[194:197], v[48:51]
	v_mfma_f32_16x16x32_bf16 v[36:39], v[154:157], v[202:205], v[36:39]
	v_mfma_f32_16x16x32_bf16 v[32:35], v[162:165], v[202:205], v[32:35]
	v_mfma_f32_16x16x32_bf16 v[20:23], v[154:157], v[210:213], v[20:23]
	v_mfma_f32_16x16x32_bf16 v[16:19], v[162:165], v[210:213], v[16:19]
	s_setprio 0
	s_setprio 1
	v_mfma_f32_16x16x32_bf16 v[44:47], v[166:169], v[182:185], v[44:47]
	v_mfma_f32_16x16x32_bf16 v[40:43], v[174:177], v[182:185], v[40:43]
	v_mfma_f32_16x16x32_bf16 v[28:31], v[166:169], v[190:193], v[28:31]
	v_mfma_f32_16x16x32_bf16 v[24:27], v[174:177], v[190:193], v[24:27]
	v_mfma_f32_16x16x32_bf16 v[12:15], v[166:169], v[198:201], v[12:15]
	v_mfma_f32_16x16x32_bf16 v[8:11], v[174:177], v[198:201], v[8:11]
	v_mfma_f32_16x16x32_bf16 v[4:7], v[166:169], v[206:209], v[4:7]
	v_mfma_f32_16x16x32_bf16 v[0:3], v[174:177], v[206:209], v[0:3]
	v_mfma_f32_16x16x32_bf16 v[44:47], v[170:173], v[186:189], v[44:47]
	v_mfma_f32_16x16x32_bf16 v[40:43], v[178:181], v[186:189], v[40:43]
	v_mfma_f32_16x16x32_bf16 v[28:31], v[170:173], v[194:197], v[28:31]
	v_mfma_f32_16x16x32_bf16 v[24:27], v[178:181], v[194:197], v[24:27]
	v_mfma_f32_16x16x32_bf16 v[12:15], v[170:173], v[202:205], v[12:15]
	v_mfma_f32_16x16x32_bf16 v[8:11], v[178:181], v[202:205], v[8:11]
	v_mfma_f32_16x16x32_bf16 v[4:7], v[170:173], v[210:213], v[4:7]
	v_mfma_f32_16x16x32_bf16 v[0:3], v[178:181], v[210:213], v[0:3]
	s_setprio 0
	s_barrier
	s_add_i32 s62, 0, 0x18000
	s_add_i32 s63, 0, 0x1c000
	v_add_u32_e32 v162, s62, v145
	v_add_u32_e32 v178, s63, v145
	ds_read_b128 v[150:153], v162
	ds_read_b128 v[154:157], v162 offset:1024
	ds_read_b128 v[158:161], v162 offset:2048
	ds_read_b128 v[162:165], v162 offset:3072
	ds_read_b128 v[166:169], v178
	ds_read_b128 v[170:173], v178 offset:1024
	ds_read_b128 v[174:177], v178 offset:2048
	ds_read_b128 v[178:181], v178 offset:3072
	s_add_u32 s40, s40, 0x40000
	s_addc_u32 s41, s41, 0
	s_mov_b32 m0, s44
	v_lshl_add_u64 v[222:223], s[40:41], 0, v[134:135]
	ds_read_b128 v[182:185], v149 offset:32768
	ds_read_b128 v[186:189], v149 offset:33792
	ds_read_b128 v[190:193], v149 offset:34816
	ds_read_b128 v[194:197], v149 offset:35840
	ds_read_b128 v[198:201], v149 offset:36864
	ds_read_b128 v[202:205], v149 offset:37888
	ds_read_b128 v[206:209], v149 offset:38912
	ds_read_b128 v[210:213], v149 offset:39936
	global_load_lds_dwordx4 v[222:223], off
	v_lshl_add_u64 v[222:223], s[40:41], 0, v[130:131]
	s_mov_b32 m0, s45
	s_nop 0
	global_load_lds_dwordx4 v[222:223], off
	s_waitcnt vmcnt(8)
	s_waitcnt lgkmcnt(0)
	s_barrier
	s_setprio 1
	s_waitcnt lgkmcnt(0)
	v_mfma_f32_16x16x32_bf16 v[124:127], v[150:153], v[182:185], v[124:127]
	v_mfma_f32_16x16x32_bf16 v[120:123], v[158:161], v[182:185], v[120:123]
	v_mfma_f32_16x16x32_bf16 v[116:119], v[150:153], v[190:193], v[116:119]
	v_mfma_f32_16x16x32_bf16 v[112:115], v[158:161], v[190:193], v[112:115]
	v_mfma_f32_16x16x32_bf16 v[100:103], v[150:153], v[198:201], v[100:103]
	v_mfma_f32_16x16x32_bf16 v[96:99], v[158:161], v[198:201], v[96:99]
	v_mfma_f32_16x16x32_bf16 v[84:87], v[150:153], v[206:209], v[84:87]
	v_mfma_f32_16x16x32_bf16 v[80:83], v[158:161], v[206:209], v[80:83]
	v_mfma_f32_16x16x32_bf16 v[124:127], v[154:157], v[186:189], v[124:127]
	v_mfma_f32_16x16x32_bf16 v[120:123], v[162:165], v[186:189], v[120:123]
	v_mfma_f32_16x16x32_bf16 v[116:119], v[154:157], v[194:197], v[116:119]
	v_mfma_f32_16x16x32_bf16 v[112:115], v[162:165], v[194:197], v[112:115]
	v_mfma_f32_16x16x32_bf16 v[100:103], v[154:157], v[202:205], v[100:103]
	v_mfma_f32_16x16x32_bf16 v[96:99], v[162:165], v[202:205], v[96:99]
	v_mfma_f32_16x16x32_bf16 v[84:87], v[154:157], v[210:213], v[84:87]
	v_mfma_f32_16x16x32_bf16 v[80:83], v[162:165], v[210:213], v[80:83]
	s_setprio 0
	s_setprio 1
	v_mfma_f32_16x16x32_bf16 v[108:111], v[166:169], v[182:185], v[108:111]
	v_mfma_f32_16x16x32_bf16 v[104:107], v[174:177], v[182:185], v[104:107]
	v_mfma_f32_16x16x32_bf16 v[92:95], v[166:169], v[190:193], v[92:95]
	v_mfma_f32_16x16x32_bf16 v[88:91], v[174:177], v[190:193], v[88:91]
	v_mfma_f32_16x16x32_bf16 v[76:79], v[166:169], v[198:201], v[76:79]
	v_mfma_f32_16x16x32_bf16 v[72:75], v[174:177], v[198:201], v[72:75]
	v_mfma_f32_16x16x32_bf16 v[68:71], v[166:169], v[206:209], v[68:71]
	v_mfma_f32_16x16x32_bf16 v[64:67], v[174:177], v[206:209], v[64:67]
	v_mfma_f32_16x16x32_bf16 v[108:111], v[170:173], v[186:189], v[108:111]
	v_mfma_f32_16x16x32_bf16 v[104:107], v[178:181], v[186:189], v[104:107]
	v_mfma_f32_16x16x32_bf16 v[92:95], v[170:173], v[194:197], v[92:95]
	v_mfma_f32_16x16x32_bf16 v[88:91], v[178:181], v[194:197], v[88:91]
	v_mfma_f32_16x16x32_bf16 v[76:79], v[170:173], v[202:205], v[76:79]
	v_mfma_f32_16x16x32_bf16 v[72:75], v[178:181], v[202:205], v[72:75]
	v_mfma_f32_16x16x32_bf16 v[68:71], v[170:173], v[210:213], v[68:71]
	v_mfma_f32_16x16x32_bf16 v[64:67], v[178:181], v[210:213], v[64:67]
	s_setprio 0
	s_barrier
	s_add_i32 s40, s62, s33
	v_lshl_add_u64 v[214:215], v[214:215], 0, s[16:17]
	s_mov_b32 m0, s40
	ds_read_b128 v[182:185], v149 offset:49152
	ds_read_b128 v[186:189], v149 offset:50176
	ds_read_b128 v[190:193], v149 offset:51200
	ds_read_b128 v[194:197], v149 offset:52224
	ds_read_b128 v[198:201], v149 offset:53248
	ds_read_b128 v[202:205], v149 offset:54272
	ds_read_b128 v[206:209], v149 offset:55296
	ds_read_b128 v[210:213], v149 offset:56320
	global_load_lds_dwordx4 v[214:215], off
	s_add_i32 m0, s40, 0x2000
	s_add_u32 s38, s38, 0x40080
	v_lshl_add_u64 v[214:215], v[216:217], 0, s[16:17]
	s_addc_u32 s39, s39, 0
	s_add_i32 s40, s63, s33
	global_load_lds_dwordx4 v[214:215], off
	v_lshl_add_u64 v[214:215], s[38:39], 0, v[132:133]
	s_mov_b32 m0, s40
	s_nop 0
	global_load_lds_dwordx4 v[214:215], off
	v_lshl_add_u64 v[214:215], s[38:39], 0, v[128:129]
	s_add_i32 m0, s40, 0x2000
	s_nop 0
	global_load_lds_dwordx4 v[214:215], off
	v_lshl_add_u64 v[214:215], v[218:219], 0, s[16:17]
	s_mov_b32 m0, s47
	s_nop 0
	global_load_lds_dwordx4 v[214:215], off
	v_lshl_add_u64 v[214:215], v[220:221], 0, s[16:17]
	s_mov_b32 m0, s48
	s_nop 0
	global_load_lds_dwordx4 v[214:215], off
	s_waitcnt vmcnt(8)
	s_waitcnt lgkmcnt(0)
	s_barrier
	s_setprio 1
	s_waitcnt lgkmcnt(0)
	v_mfma_f32_16x16x32_bf16 v[60:63], v[150:153], v[182:185], v[60:63]
	v_mfma_f32_16x16x32_bf16 v[56:59], v[158:161], v[182:185], v[56:59]
	v_mfma_f32_16x16x32_bf16 v[52:55], v[150:153], v[190:193], v[52:55]
	v_mfma_f32_16x16x32_bf16 v[48:51], v[158:161], v[190:193], v[48:51]
	v_mfma_f32_16x16x32_bf16 v[36:39], v[150:153], v[198:201], v[36:39]
	v_mfma_f32_16x16x32_bf16 v[32:35], v[158:161], v[198:201], v[32:35]
	v_mfma_f32_16x16x32_bf16 v[20:23], v[150:153], v[206:209], v[20:23]
	v_mfma_f32_16x16x32_bf16 v[16:19], v[158:161], v[206:209], v[16:19]
	v_mfma_f32_16x16x32_bf16 v[60:63], v[154:157], v[186:189], v[60:63]
	v_mfma_f32_16x16x32_bf16 v[56:59], v[162:165], v[186:189], v[56:59]
	v_mfma_f32_16x16x32_bf16 v[52:55], v[154:157], v[194:197], v[52:55]
	v_mfma_f32_16x16x32_bf16 v[48:51], v[162:165], v[194:197], v[48:51]
	v_mfma_f32_16x16x32_bf16 v[36:39], v[154:157], v[202:205], v[36:39]
	v_mfma_f32_16x16x32_bf16 v[32:35], v[162:165], v[202:205], v[32:35]
	v_mfma_f32_16x16x32_bf16 v[20:23], v[154:157], v[210:213], v[20:23]
	v_mfma_f32_16x16x32_bf16 v[16:19], v[162:165], v[210:213], v[16:19]
	s_setprio 0
	s_setprio 1
	v_mfma_f32_16x16x32_bf16 v[44:47], v[166:169], v[182:185], v[44:47]
	v_mfma_f32_16x16x32_bf16 v[40:43], v[174:177], v[182:185], v[40:43]
	v_mfma_f32_16x16x32_bf16 v[28:31], v[166:169], v[190:193], v[28:31]
	v_mfma_f32_16x16x32_bf16 v[24:27], v[174:177], v[190:193], v[24:27]
	v_mfma_f32_16x16x32_bf16 v[12:15], v[166:169], v[198:201], v[12:15]
	v_mfma_f32_16x16x32_bf16 v[8:11], v[174:177], v[198:201], v[8:11]
	v_mfma_f32_16x16x32_bf16 v[4:7], v[166:169], v[206:209], v[4:7]
	v_mfma_f32_16x16x32_bf16 v[0:3], v[174:177], v[206:209], v[0:3]
	v_mfma_f32_16x16x32_bf16 v[44:47], v[170:173], v[186:189], v[44:47]
	v_mfma_f32_16x16x32_bf16 v[40:43], v[178:181], v[186:189], v[40:43]
	v_mfma_f32_16x16x32_bf16 v[28:31], v[170:173], v[194:197], v[28:31]
	v_mfma_f32_16x16x32_bf16 v[24:27], v[178:181], v[194:197], v[24:27]
	v_mfma_f32_16x16x32_bf16 v[12:15], v[170:173], v[202:205], v[12:15]
	v_mfma_f32_16x16x32_bf16 v[8:11], v[178:181], v[202:205], v[8:11]
	v_mfma_f32_16x16x32_bf16 v[4:7], v[170:173], v[210:213], v[4:7]
	v_mfma_f32_16x16x32_bf16 v[0:3], v[178:181], v[210:213], v[0:3]
	s_setprio 0
	s_barrier
	s_add_i32 s61, s61, 2
	s_add_u32 s59, s59, 0x100
	s_addc_u32 s60, s60, 0
	s_add_u32 s36, s36, 0x100
	s_addc_u32 s37, s37, 0
	s_cmp_gt_u32 s61, 13
	s_cbranch_scc0 .LBB0_1801
	s_and_b64 vcc, exec, s[18:19]
	s_cbranch_vccz .LBB0_1804
	s_barrier
.LBB0_1804:
	v_lshl_or_b32 v150, s55, 8, v146
	v_lshl_add_u32 v152, s56, 8, v144
	s_mov_b64 s[36:37], s[14:15]
	v_ashrrev_i32_e32 v151, 31, v150
	v_ashrrev_i32_e32 v153, 31, v152
	v_lshlrev_b64 v[154:155], 11, v[152:153]
	v_lshl_add_u64 v[150:151], v[150:151], 1, s[36:37]
	v_lshl_add_u64 v[154:155], v[150:151], 0, v[154:155]
	v_cvt_pk_bf16_f32 v60, v60, v61
	v_cvt_pk_bf16_f32 v61, v62, v63
	v_cvt_pk_bf16_f32 v62, v56, v57
	v_add_co_u32_e32 v56, vcc, s51, v154
	v_cvt_pk_bf16_f32 v68, v68, v69
	v_cvt_pk_bf16_f32 v69, v70, v71
	v_cvt_pk_bf16_f32 v70, v64, v65
	v_lshl_add_u64 v[64:65], v[154:155], 0, s[10:11]
	v_addc_co_u32_e32 v57, vcc, 0, v155, vcc
	v_cvt_pk_bf16_f32 v44, v44, v45
	v_cvt_pk_bf16_f32 v45, v46, v47
	v_cvt_pk_bf16_f32 v46, v40, v41
	v_cvt_pk_bf16_f32 v47, v42, v43
	global_store_dwordx4 v[64:65], v[44:47], off offset:256
	v_cvt_pk_bf16_f32 v108, v108, v109
	v_cvt_pk_bf16_f32 v109, v110, v111
	v_add_co_u32_e32 v46, vcc, s52, v154
	v_cvt_pk_bf16_f32 v110, v104, v105
	v_or_b32_e32 v104, 16, v152
	v_lshl_add_u64 v[44:45], v[154:155], 0, s[20:21]
	v_addc_co_u32_e32 v47, vcc, 0, v155, vcc
	v_cvt_pk_bf16_f32 v28, v28, v29
	v_cvt_pk_bf16_f32 v29, v30, v31
	v_cvt_pk_bf16_f32 v30, v24, v25
	v_cvt_pk_bf16_f32 v31, v26, v27
	v_ashrrev_i32_e32 v105, 31, v104
	v_cvt_pk_bf16_f32 v92, v92, v93
	v_cvt_pk_bf16_f32 v93, v94, v95
	v_cvt_pk_bf16_f32 v94, v88, v89
	v_or_b32_e32 v88, 32, v152
	global_store_dwordx4 v[44:45], v[28:31], off offset:256
	v_cvt_pk_bf16_f32 v111, v106, v107
	v_lshlrev_b64 v[104:105], 11, v[104:105]
	v_add_co_u32_e32 v30, vcc, s53, v154
	v_ashrrev_i32_e32 v89, 31, v88
	v_cvt_pk_bf16_f32 v76, v76, v77
	v_cvt_pk_bf16_f32 v77, v78, v79
	v_cvt_pk_bf16_f32 v78, v72, v73
	v_or_b32_e32 v72, 48, v152
	v_lshl_add_u64 v[28:29], v[154:155], 0, s[22:23]
	v_addc_co_u32_e32 v31, vcc, 0, v155, vcc
	v_cvt_pk_bf16_f32 v12, v12, v13
	v_cvt_pk_bf16_f32 v13, v14, v15
	v_cvt_pk_bf16_f32 v14, v8, v9
	v_cvt_pk_bf16_f32 v15, v10, v11
	global_store_dwordx4 v[154:155], v[108:111], off offset:256
	v_cvt_pk_bf16_f32 v95, v90, v91
	v_lshlrev_b64 v[88:89], 11, v[88:89]
	v_lshl_add_u64 v[108:109], v[150:151], 0, v[104:105]
	v_ashrrev_i32_e32 v73, 31, v72
	global_store_dwordx4 v[28:29], v[12:15], off offset:256
	global_store_dwordx4 v[108:109], v[92:95], off offset:256
	v_cvt_pk_bf16_f32 v79, v74, v75
	v_add_co_u32_e32 v14, vcc, s54, v154
	v_lshl_add_u64 v[92:93], v[150:151], 0, v[88:89]
	v_lshlrev_b64 v[72:73], 11, v[72:73]
	v_addc_co_u32_e32 v15, vcc, 0, v155, vcc
	v_cvt_pk_bf16_f32 v124, v124, v125
	v_cvt_pk_bf16_f32 v125, v126, v127
	v_cvt_pk_bf16_f32 v126, v120, v121
	v_cvt_pk_bf16_f32 v127, v122, v123
	v_cvt_pk_bf16_f32 v104, v116, v117
	v_cvt_pk_bf16_f32 v105, v118, v119
	v_cvt_pk_bf16_f32 v106, v112, v113
	v_cvt_pk_bf16_f32 v107, v114, v115
	v_cvt_pk_bf16_f32 v88, v100, v101
	v_cvt_pk_bf16_f32 v89, v102, v103
	v_cvt_pk_bf16_f32 v90, v96, v97
	v_cvt_pk_bf16_f32 v91, v98, v99
	global_store_dwordx4 v[92:93], v[76:79], off offset:256
	v_cvt_pk_bf16_f32 v74, v80, v81
	v_cvt_pk_bf16_f32 v75, v82, v83
	v_lshl_add_u64 v[76:77], v[150:151], 0, v[72:73]
	v_cvt_pk_bf16_f32 v72, v84, v85
	v_cvt_pk_bf16_f32 v73, v86, v87
	v_cvt_pk_bf16_f32 v71, v66, v67
	v_cvt_pk_bf16_f32 v63, v58, v59
	v_cvt_pk_bf16_f32 v40, v52, v53
	v_cvt_pk_bf16_f32 v41, v54, v55
	v_cvt_pk_bf16_f32 v42, v48, v49
	v_cvt_pk_bf16_f32 v43, v50, v51
	v_cvt_pk_bf16_f32 v24, v36, v37
	v_cvt_pk_bf16_f32 v25, v38, v39
	v_cvt_pk_bf16_f32 v26, v32, v33
	v_cvt_pk_bf16_f32 v27, v34, v35
	v_lshl_add_u64 v[12:13], v[154:155], 0, s[24:25]
	v_cvt_pk_bf16_f32 v8, v20, v21
	v_cvt_pk_bf16_f32 v9, v22, v23
	v_cvt_pk_bf16_f32 v10, v16, v17
	v_cvt_pk_bf16_f32 v11, v18, v19
	v_cvt_pk_bf16_f32 v4, v4, v5
	v_cvt_pk_bf16_f32 v5, v6, v7
	v_cvt_pk_bf16_f32 v6, v0, v1
	v_cvt_pk_bf16_f32 v7, v2, v3
	s_andn2_b64 vcc, exec, s[8:9]
	s_mov_b64 s[8:9], -1
	global_store_dwordx4 v[154:155], v[124:127], off
	global_store_dwordx4 v[108:109], v[104:107], off
	global_store_dwordx4 v[92:93], v[88:91], off
	global_store_dwordx4 v[76:77], v[72:75], off
	global_store_dwordx4 v[76:77], v[68:71], off offset:256
	global_store_dwordx4 v[56:57], v[60:63], off
	global_store_dwordx4 v[46:47], v[40:43], off
	global_store_dwordx4 v[30:31], v[24:27], off
	global_store_dwordx4 v[14:15], v[8:11], off
	global_store_dwordx4 v[12:13], v[4:7], off offset:256
	s_cbranch_vccnz .LBB0_1797
	s_andn2_b64 vcc, exec, s[12:13]
	s_cbranch_vccnz .LBB0_1796
	s_mov_b32 s100, 1
	s_branch .LBB0_1796

.LBB0_1943:
	s_add_u32 s12, s8, 0x11800000
	s_addc_u32 s13, s9, 0
	s_lshl_b32 s8, s14, 5
	s_mov_b64 s[14:15], 0x80
	s_and_b32 s19, s8, 0x60
	s_add_i32 m0, s34, 0x18000
	v_lshl_add_u64 v[6:7], v[6:7], 0, s[14:15]
	s_lshl_b32 s18, s17, 13
	s_lshl_b32 s20, s19, 7
	s_waitcnt vmcnt(2)
	s_barrier
	global_load_lds_dwordx4 v[6:7], off
	v_lshl_add_u64 v[4:5], v[4:5], 0, s[14:15]
	s_add_i32 m0, s34, 0x1a000
	s_add_i32 s39, s34, 0x8000
	s_add_i32 s40, s34, 0xa000
	global_load_lds_dwordx4 v[4:5], off
	v_lshl_add_u64 v[0:1], v[0:1], 0, s[14:15]
	s_mov_b32 m0, s39
	s_add_u32 s8, s26, 0x40080
	global_load_lds_dwordx4 v[0:1], off
	v_lshl_add_u64 v[0:1], v[2:3], 0, s[14:15]
	s_mov_b32 m0, s40
	s_addc_u32 s9, s27, 0
	global_load_lds_dwordx4 v[0:1], off
	s_add_i32 m0, s34, 0x1c000
	v_lshl_add_u64 v[0:1], s[8:9], 0, v[132:133]
	global_load_lds_dwordx4 v[0:1], off
	v_lshl_add_u64 v[0:1], s[8:9], 0, v[128:129]
	s_add_i32 m0, s34, 0x1e000
	s_cmpk_lt_u32 s16, 0x100
	global_load_lds_dwordx4 v[0:1], off
	v_lshrrev_b32_e32 v1, 1, v8
	v_and_b32_e32 v1, 24, v1
	v_and_b32_e32 v0, 15, v8
	v_lshlrev_b32_e32 v2, 1, v1
	v_lshl_or_b32 v146, s17, 6, v0
	v_lshl_or_b32 v0, v0, 6, v2
	v_lshlrev_b32_e32 v2, 2, v8
	v_and_b32_e32 v2, 32, v2
	v_bitop3_b32 v3, v0, s18, v2 bitop3:0xde
	v_bitop3_b32 v147, s20, v0, v2 bitop3:0xf6
	v_lshlrev_b32_e32 v0, 14, v9
	v_and_b32_e32 v0, 0xffff8000, v0
	v_or_b32_e32 v148, s19, v1
	v_lshl_add_u32 v0, v10, 11, v0
	v_and_b32_e32 v1, 1, v9
	v_lshl_or_b32 v0, v1, 6, v0
	v_lshl_add_u32 v136, v11, 1, v0
	v_lshlrev_b32_e32 v0, 14, v13
	v_and_b32_e32 v0, 0xffff8000, v0
	s_waitcnt vmcnt(6)
	v_lshl_add_u32 v0, v12, 11, v0
	v_and_b32_e32 v1, 1, v13
	s_cselect_b64 s[16:17], -1, 0
	v_lshl_or_b32 v0, v1, 6, v0
	s_add_i32 s42, 0, 0x10000
	s_add_i32 s43, 0, 0x14000
	v_mov_b32_e32 v137, v133
	v_lshl_add_u32 v138, v14, 1, v0
	v_mov_b32_e32 v139, v133
	v_mov_b64_e32 v[140:141], 0xb00
	v_mov_b64_e32 v[142:143], 0xaff
	s_movk_i32 s41, 0x161
	v_add_u32_e32 v149, s42, v147
	v_add_u32_e32 v150, s43, v147
	v_add_u32_e32 v151, 0, v3
	s_movk_i32 s44, 0x1600
	s_barrier
	s_mov_b32 s100, 0
	s_branch .LBB0_1946

.LBB0_1948:
	s_ashr_i32 s21, s20, 31
	s_lshl_b64 s[22:23], s[20:21], 19
	s_add_u32 s22, s0, s22
	s_addc_u32 s23, s1, s23
	s_and_b64 s[24:25], s[8:9], exec
	s_cselect_b32 s21, s23, s29
	s_cselect_b32 s45, s22, s28
	s_ashr_i32 s19, s18, 31
	s_lshl_b64 s[24:25], s[18:19], 19
	s_add_u32 s24, s4, s24
	s_addc_u32 s25, s5, s25
	s_and_b64 s[30:31], s[8:9], exec
	s_cselect_b32 s19, s25, s27
	s_cselect_b32 s46, s24, s26
	s_add_u32 s47, s26, 0x100
	s_addc_u32 s48, s27, 0
	s_add_u32 s26, s28, 0x40080
	v_mov_b32_e32 v0, 0
	s_addc_u32 s27, s29, 0
	s_mov_b32 s49, -2
	v_mov_b32_e32 v1, v0
	v_mov_b32_e32 v2, v0
	v_mov_b32_e32 v3, v0
	v_mov_b32_e32 v4, v0
	v_mov_b32_e32 v5, v0
	v_mov_b32_e32 v6, v0
	v_mov_b32_e32 v7, v0
	v_mov_b32_e32 v16, v0
	v_mov_b32_e32 v17, v0
	v_mov_b32_e32 v18, v0
	v_mov_b32_e32 v19, v0
	v_mov_b32_e32 v20, v0
	v_mov_b32_e32 v21, v0
	v_mov_b32_e32 v22, v0
	v_mov_b32_e32 v23, v0
	v_mov_b32_e32 v32, v0
	v_mov_b32_e32 v33, v0
	v_mov_b32_e32 v34, v0
	v_mov_b32_e32 v35, v0
	v_mov_b32_e32 v36, v0
	v_mov_b32_e32 v37, v0
	v_mov_b32_e32 v38, v0
	v_mov_b32_e32 v39, v0
	v_mov_b32_e32 v48, v0
	v_mov_b32_e32 v49, v0
	v_mov_b32_e32 v50, v0
	v_mov_b32_e32 v51, v0
	v_mov_b32_e32 v52, v0
	v_mov_b32_e32 v53, v0
	v_mov_b32_e32 v54, v0
	v_mov_b32_e32 v55, v0
	v_mov_b32_e32 v8, v0
	v_mov_b32_e32 v9, v0
	v_mov_b32_e32 v10, v0
	v_mov_b32_e32 v11, v0
	v_mov_b32_e32 v12, v0
	v_mov_b32_e32 v13, v0
	v_mov_b32_e32 v14, v0
	v_mov_b32_e32 v15, v0
	v_mov_b32_e32 v24, v0
	v_mov_b32_e32 v25, v0
	v_mov_b32_e32 v26, v0
	v_mov_b32_e32 v27, v0
	v_mov_b32_e32 v28, v0
	v_mov_b32_e32 v29, v0
	v_mov_b32_e32 v30, v0
	v_mov_b32_e32 v31, v0
	v_mov_b32_e32 v40, v0
	v_mov_b32_e32 v41, v0
	v_mov_b32_e32 v42, v0
	v_mov_b32_e32 v43, v0
	v_mov_b32_e32 v44, v0
	v_mov_b32_e32 v45, v0
	v_mov_b32_e32 v46, v0
	v_mov_b32_e32 v47, v0
	v_mov_b32_e32 v56, v0
	v_mov_b32_e32 v57, v0
	v_mov_b32_e32 v58, v0
	v_mov_b32_e32 v59, v0
	v_mov_b32_e32 v60, v0
	v_mov_b32_e32 v61, v0
	v_mov_b32_e32 v62, v0
	v_mov_b32_e32 v63, v0
	v_mov_b32_e32 v64, v0
	v_mov_b32_e32 v65, v0
	v_mov_b32_e32 v66, v0
	v_mov_b32_e32 v67, v0
	v_mov_b32_e32 v68, v0
	v_mov_b32_e32 v69, v0
	v_mov_b32_e32 v70, v0
	v_mov_b32_e32 v71, v0
	v_mov_b32_e32 v80, v0
	v_mov_b32_e32 v81, v0
	v_mov_b32_e32 v82, v0
	v_mov_b32_e32 v83, v0
	v_mov_b32_e32 v84, v0
	v_mov_b32_e32 v85, v0
	v_mov_b32_e32 v86, v0
	v_mov_b32_e32 v87, v0
	v_mov_b32_e32 v96, v0
	v_mov_b32_e32 v97, v0
	v_mov_b32_e32 v98, v0
	v_mov_b32_e32 v99, v0
	v_mov_b32_e32 v100, v0
	v_mov_b32_e32 v101, v0
	v_mov_b32_e32 v102, v0
	v_mov_b32_e32 v103, v0
	v_mov_b32_e32 v112, v0
	v_mov_b32_e32 v113, v0
	v_mov_b32_e32 v114, v0
	v_mov_b32_e32 v115, v0
	v_mov_b32_e32 v116, v0
	v_mov_b32_e32 v117, v0
	v_mov_b32_e32 v118, v0
	v_mov_b32_e32 v119, v0
	v_mov_b32_e32 v72, v0
	v_mov_b32_e32 v73, v0
	v_mov_b32_e32 v74, v0
	v_mov_b32_e32 v75, v0
	v_mov_b32_e32 v76, v0
	v_mov_b32_e32 v77, v0
	v_mov_b32_e32 v78, v0
	v_mov_b32_e32 v79, v0
	v_mov_b32_e32 v88, v0
	v_mov_b32_e32 v89, v0
	v_mov_b32_e32 v90, v0
	v_mov_b32_e32 v91, v0
	v_mov_b32_e32 v92, v0
	v_mov_b32_e32 v93, v0
	v_mov_b32_e32 v94, v0
	v_mov_b32_e32 v95, v0
	v_mov_b32_e32 v104, v0
	v_mov_b32_e32 v105, v0
	v_mov_b32_e32 v106, v0
	v_mov_b32_e32 v107, v0
	v_mov_b32_e32 v108, v0
	v_mov_b32_e32 v109, v0
	v_mov_b32_e32 v110, v0
	v_mov_b32_e32 v111, v0
	v_mov_b32_e32 v120, v0
	v_mov_b32_e32 v121, v0
	v_mov_b32_e32 v122, v0
	v_mov_b32_e32 v123, v0
	v_mov_b32_e32 v124, v0
	v_mov_b32_e32 v125, v0
	v_mov_b32_e32 v126, v0
	v_mov_b32_e32 v127, v0
	s_cmp_eq_u32 s100, 1
	s_cbranch_scc0 .Lgemm_nobar_1944
	s_mov_b32 s100, 0
	s_barrier
.Lgemm_nobar_1944:
.LBB0_1949:
	ds_read_b128 v[152:155], v149
	ds_read_b128 v[156:159], v149 offset:1024
	ds_read_b128 v[160:163], v149 offset:2048
	ds_read_b128 v[164:167], v149 offset:3072
	ds_read_b128 v[168:171], v150
	ds_read_b128 v[172:175], v150 offset:1024
	ds_read_b128 v[176:179], v150 offset:2048
	ds_read_b128 v[180:183], v150 offset:3072
	s_add_u32 s28, s26, 0xfffc0080
	s_addc_u32 s29, s27, -1
	s_cmp_eq_u32 s49, 12
	s_cselect_b32 s31, s21, s29
	s_cselect_b32 s30, s45, s28
	s_cselect_b32 s29, s19, s48
	s_cselect_b32 s28, s46, s47
	v_lshl_add_u64 v[144:145], s[26:27], 0, v[138:139]
	s_add_i32 m0, s34, 0xc000
	ds_read_b128 v[184:187], v151
	ds_read_b128 v[188:191], v151 offset:1024
	ds_read_b128 v[192:195], v151 offset:2048
	ds_read_b128 v[196:199], v151 offset:3072
	ds_read_b128 v[200:203], v151 offset:4096
	ds_read_b128 v[204:207], v151 offset:5120
	ds_read_b128 v[208:211], v151 offset:6144
	ds_read_b128 v[212:215], v151 offset:7168
	global_load_lds_dwordx4 v[144:145], off
	v_lshl_add_u64 v[144:145], s[26:27], 0, v[136:137]
	s_add_i32 m0, s34, 0xe000
	s_nop 0
	global_load_lds_dwordx4 v[144:145], off
	s_waitcnt vmcnt(8)
	s_waitcnt lgkmcnt(0)
	s_barrier
	s_setprio 1
	s_waitcnt lgkmcnt(0)
	v_mfma_f32_16x16x32_bf16 v[124:127], v[152:155], v[184:187], v[124:127]
	v_mfma_f32_16x16x32_bf16 v[120:123], v[160:163], v[184:187], v[120:123]
	v_mfma_f32_16x16x32_bf16 v[108:111], v[152:155], v[192:195], v[108:111]
	v_mfma_f32_16x16x32_bf16 v[104:107], v[160:163], v[192:195], v[104:107]
	v_mfma_f32_16x16x32_bf16 v[92:95], v[152:155], v[200:203], v[92:95]
	v_mfma_f32_16x16x32_bf16 v[88:91], v[160:163], v[200:203], v[88:91]
	v_mfma_f32_16x16x32_bf16 v[76:79], v[152:155], v[208:211], v[76:79]
	v_mfma_f32_16x16x32_bf16 v[72:75], v[160:163], v[208:211], v[72:75]
	v_mfma_f32_16x16x32_bf16 v[124:127], v[156:159], v[188:191], v[124:127]
	v_mfma_f32_16x16x32_bf16 v[120:123], v[164:167], v[188:191], v[120:123]
	v_mfma_f32_16x16x32_bf16 v[108:111], v[156:159], v[196:199], v[108:111]
	v_mfma_f32_16x16x32_bf16 v[104:107], v[164:167], v[196:199], v[104:107]
	v_mfma_f32_16x16x32_bf16 v[92:95], v[156:159], v[204:207], v[92:95]
	v_mfma_f32_16x16x32_bf16 v[88:91], v[164:167], v[204:207], v[88:91]
	v_mfma_f32_16x16x32_bf16 v[76:79], v[156:159], v[212:215], v[76:79]
	v_mfma_f32_16x16x32_bf16 v[72:75], v[164:167], v[212:215], v[72:75]
	s_setprio 0
	s_setprio 1
	v_mfma_f32_16x16x32_bf16 v[116:119], v[168:171], v[184:187], v[116:119]
	v_mfma_f32_16x16x32_bf16 v[112:115], v[176:179], v[184:187], v[112:115]
	v_mfma_f32_16x16x32_bf16 v[100:103], v[168:171], v[192:195], v[100:103]
	v_mfma_f32_16x16x32_bf16 v[96:99], v[176:179], v[192:195], v[96:99]
	v_mfma_f32_16x16x32_bf16 v[84:87], v[168:171], v[200:203], v[84:87]
	v_mfma_f32_16x16x32_bf16 v[80:83], v[176:179], v[200:203], v[80:83]
	v_mfma_f32_16x16x32_bf16 v[68:71], v[168:171], v[208:211], v[68:71]
	v_mfma_f32_16x16x32_bf16 v[64:67], v[176:179], v[208:211], v[64:67]
	v_mfma_f32_16x16x32_bf16 v[116:119], v[172:175], v[188:191], v[116:119]
	v_mfma_f32_16x16x32_bf16 v[112:115], v[180:183], v[188:191], v[112:115]
	v_mfma_f32_16x16x32_bf16 v[100:103], v[172:175], v[196:199], v[100:103]
	v_mfma_f32_16x16x32_bf16 v[96:99], v[180:183], v[196:199], v[96:99]
	v_mfma_f32_16x16x32_bf16 v[84:87], v[172:175], v[204:207], v[84:87]
	v_mfma_f32_16x16x32_bf16 v[80:83], v[180:183], v[204:207], v[80:83]
	v_mfma_f32_16x16x32_bf16 v[68:71], v[172:175], v[212:215], v[68:71]
	v_mfma_f32_16x16x32_bf16 v[64:67], v[180:183], v[212:215], v[64:67]
	s_setprio 0
	s_barrier
	s_add_i32 s50, s42, s33
	v_lshl_add_u64 v[144:145], s[28:29], 0, v[132:133]
	s_mov_b32 m0, s50
	ds_read_b128 v[184:187], v151 offset:16384
	ds_read_b128 v[188:191], v151 offset:17408
	ds_read_b128 v[192:195], v151 offset:18432
	ds_read_b128 v[196:199], v151 offset:19456
	ds_read_b128 v[200:203], v151 offset:20480
	ds_read_b128 v[204:207], v151 offset:21504
	ds_read_b128 v[208:211], v151 offset:22528
	ds_read_b128 v[212:215], v151 offset:23552
	global_load_lds_dwordx4 v[144:145], off
	s_add_i32 m0, s50, 0x2000
	s_add_u32 s50, s28, 0x40000
	v_lshl_add_u64 v[216:217], s[28:29], 0, v[128:129]
	s_addc_u32 s51, s29, 0
	s_add_i32 s52, s43, s33
	global_load_lds_dwordx4 v[216:217], off
	v_lshl_add_u64 v[218:219], s[50:51], 0, v[132:133]
	s_mov_b32 m0, s52
	v_lshl_add_u64 v[220:221], s[30:31], 0, v[130:131]
	global_load_lds_dwordx4 v[218:219], off
	v_lshl_add_u64 v[218:219], s[50:51], 0, v[128:129]
	s_add_i32 m0, s52, 0x2000
	s_nop 0
	global_load_lds_dwordx4 v[218:219], off
	v_lshl_add_u64 v[218:219], s[30:31], 0, v[134:135]
	s_mov_b32 m0, s34
	s_nop 0
	global_load_lds_dwordx4 v[218:219], off
	s_mov_b32 m0, s35
	s_nop 0
	global_load_lds_dwordx4 v[220:221], off
	s_waitcnt vmcnt(8)
	s_waitcnt lgkmcnt(0)
	s_barrier
	s_setprio 1
	s_waitcnt lgkmcnt(0)
	v_mfma_f32_16x16x32_bf16 v[60:63], v[152:155], v[184:187], v[60:63]
	v_mfma_f32_16x16x32_bf16 v[56:59], v[160:163], v[184:187], v[56:59]
	v_mfma_f32_16x16x32_bf16 v[44:47], v[152:155], v[192:195], v[44:47]
	v_mfma_f32_16x16x32_bf16 v[40:43], v[160:163], v[192:195], v[40:43]
	v_mfma_f32_16x16x32_bf16 v[28:31], v[152:155], v[200:203], v[28:31]
	v_mfma_f32_16x16x32_bf16 v[24:27], v[160:163], v[200:203], v[24:27]
	v_mfma_f32_16x16x32_bf16 v[12:15], v[152:155], v[208:211], v[12:15]
	v_mfma_f32_16x16x32_bf16 v[8:11], v[160:163], v[208:211], v[8:11]
	v_mfma_f32_16x16x32_bf16 v[60:63], v[156:159], v[188:191], v[60:63]
	v_mfma_f32_16x16x32_bf16 v[56:59], v[164:167], v[188:191], v[56:59]
	v_mfma_f32_16x16x32_bf16 v[44:47], v[156:159], v[196:199], v[44:47]
	v_mfma_f32_16x16x32_bf16 v[40:43], v[164:167], v[196:199], v[40:43]
	v_mfma_f32_16x16x32_bf16 v[28:31], v[156:159], v[204:207], v[28:31]
	v_mfma_f32_16x16x32_bf16 v[24:27], v[164:167], v[204:207], v[24:27]
	v_mfma_f32_16x16x32_bf16 v[12:15], v[156:159], v[212:215], v[12:15]
	v_mfma_f32_16x16x32_bf16 v[8:11], v[164:167], v[212:215], v[8:11]
	s_setprio 0
	s_setprio 1
	v_mfma_f32_16x16x32_bf16 v[52:55], v[168:171], v[184:187], v[52:55]
	v_mfma_f32_16x16x32_bf16 v[48:51], v[176:179], v[184:187], v[48:51]
	v_mfma_f32_16x16x32_bf16 v[36:39], v[168:171], v[192:195], v[36:39]
	v_mfma_f32_16x16x32_bf16 v[32:35], v[176:179], v[192:195], v[32:35]
	v_mfma_f32_16x16x32_bf16 v[20:23], v[168:171], v[200:203], v[20:23]
	v_mfma_f32_16x16x32_bf16 v[16:19], v[176:179], v[200:203], v[16:19]
	v_mfma_f32_16x16x32_bf16 v[4:7], v[168:171], v[208:211], v[4:7]
	v_mfma_f32_16x16x32_bf16 v[0:3], v[176:179], v[208:211], v[0:3]
	v_mfma_f32_16x16x32_bf16 v[52:55], v[172:175], v[188:191], v[52:55]
	v_mfma_f32_16x16x32_bf16 v[48:51], v[180:183], v[188:191], v[48:51]
	v_mfma_f32_16x16x32_bf16 v[36:39], v[172:175], v[196:199], v[36:39]
	v_mfma_f32_16x16x32_bf16 v[32:35], v[180:183], v[196:199], v[32:35]
	v_mfma_f32_16x16x32_bf16 v[20:23], v[172:175], v[204:207], v[20:23]
	v_mfma_f32_16x16x32_bf16 v[16:19], v[180:183], v[204:207], v[16:19]
	v_mfma_f32_16x16x32_bf16 v[4:7], v[172:175], v[212:215], v[4:7]
	v_mfma_f32_16x16x32_bf16 v[0:3], v[180:183], v[212:215], v[0:3]
	s_setprio 0
	s_barrier
	s_add_i32 s50, 0, 0x18000
	s_add_i32 s51, 0, 0x1c000
	v_add_u32_e32 v164, s50, v147
	v_add_u32_e32 v180, s51, v147
	ds_read_b128 v[152:155], v164
	ds_read_b128 v[156:159], v164 offset:1024
	ds_read_b128 v[160:163], v164 offset:2048
	ds_read_b128 v[164:167], v164 offset:3072
	ds_read_b128 v[168:171], v180
	ds_read_b128 v[172:175], v180 offset:1024
	ds_read_b128 v[176:179], v180 offset:2048
	ds_read_b128 v[180:183], v180 offset:3072
	s_add_u32 s30, s30, 0x40000
	s_addc_u32 s31, s31, 0
	s_mov_b32 m0, s36
	v_lshl_add_u64 v[222:223], s[30:31], 0, v[134:135]
	ds_read_b128 v[184:187], v151 offset:32768
	ds_read_b128 v[188:191], v151 offset:33792
	ds_read_b128 v[192:195], v151 offset:34816
	ds_read_b128 v[196:199], v151 offset:35840
	ds_read_b128 v[200:203], v151 offset:36864
	ds_read_b128 v[204:207], v151 offset:37888
	ds_read_b128 v[208:211], v151 offset:38912
	ds_read_b128 v[212:215], v151 offset:39936
	global_load_lds_dwordx4 v[222:223], off
	v_lshl_add_u64 v[222:223], s[30:31], 0, v[130:131]
	s_mov_b32 m0, s37
	s_nop 0
	global_load_lds_dwordx4 v[222:223], off
	s_waitcnt vmcnt(8)
	s_waitcnt lgkmcnt(0)
	s_barrier
	s_setprio 1
	s_waitcnt lgkmcnt(0)
	v_mfma_f32_16x16x32_bf16 v[124:127], v[152:155], v[184:187], v[124:127]
	v_mfma_f32_16x16x32_bf16 v[120:123], v[160:163], v[184:187], v[120:123]
	v_mfma_f32_16x16x32_bf16 v[108:111], v[152:155], v[192:195], v[108:111]
	v_mfma_f32_16x16x32_bf16 v[104:107], v[160:163], v[192:195], v[104:107]
	v_mfma_f32_16x16x32_bf16 v[92:95], v[152:155], v[200:203], v[92:95]
	v_mfma_f32_16x16x32_bf16 v[88:91], v[160:163], v[200:203], v[88:91]
	v_mfma_f32_16x16x32_bf16 v[76:79], v[152:155], v[208:211], v[76:79]
	v_mfma_f32_16x16x32_bf16 v[72:75], v[160:163], v[208:211], v[72:75]
	v_mfma_f32_16x16x32_bf16 v[124:127], v[156:159], v[188:191], v[124:127]
	v_mfma_f32_16x16x32_bf16 v[120:123], v[164:167], v[188:191], v[120:123]
	v_mfma_f32_16x16x32_bf16 v[108:111], v[156:159], v[196:199], v[108:111]
	v_mfma_f32_16x16x32_bf16 v[104:107], v[164:167], v[196:199], v[104:107]
	v_mfma_f32_16x16x32_bf16 v[92:95], v[156:159], v[204:207], v[92:95]
	v_mfma_f32_16x16x32_bf16 v[88:91], v[164:167], v[204:207], v[88:91]
	v_mfma_f32_16x16x32_bf16 v[76:79], v[156:159], v[212:215], v[76:79]
	v_mfma_f32_16x16x32_bf16 v[72:75], v[164:167], v[212:215], v[72:75]
	s_setprio 0
	s_setprio 1
	v_mfma_f32_16x16x32_bf16 v[116:119], v[168:171], v[184:187], v[116:119]
	v_mfma_f32_16x16x32_bf16 v[112:115], v[176:179], v[184:187], v[112:115]
	v_mfma_f32_16x16x32_bf16 v[100:103], v[168:171], v[192:195], v[100:103]
	v_mfma_f32_16x16x32_bf16 v[96:99], v[176:179], v[192:195], v[96:99]
	v_mfma_f32_16x16x32_bf16 v[84:87], v[168:171], v[200:203], v[84:87]
	v_mfma_f32_16x16x32_bf16 v[80:83], v[176:179], v[200:203], v[80:83]
	v_mfma_f32_16x16x32_bf16 v[68:71], v[168:171], v[208:211], v[68:71]
	v_mfma_f32_16x16x32_bf16 v[64:67], v[176:179], v[208:211], v[64:67]
	v_mfma_f32_16x16x32_bf16 v[116:119], v[172:175], v[188:191], v[116:119]
	v_mfma_f32_16x16x32_bf16 v[112:115], v[180:183], v[188:191], v[112:115]
	v_mfma_f32_16x16x32_bf16 v[100:103], v[172:175], v[196:199], v[100:103]
	v_mfma_f32_16x16x32_bf16 v[96:99], v[180:183], v[196:199], v[96:99]
	v_mfma_f32_16x16x32_bf16 v[84:87], v[172:175], v[204:207], v[84:87]
	v_mfma_f32_16x16x32_bf16 v[80:83], v[180:183], v[204:207], v[80:83]
	v_mfma_f32_16x16x32_bf16 v[68:71], v[172:175], v[212:215], v[68:71]
	v_mfma_f32_16x16x32_bf16 v[64:67], v[180:183], v[212:215], v[64:67]
	s_setprio 0
	s_barrier
	s_add_i32 s30, s50, s33
	v_lshl_add_u64 v[144:145], v[144:145], 0, s[14:15]
	s_mov_b32 m0, s30
	ds_read_b128 v[184:187], v151 offset:49152
	ds_read_b128 v[188:191], v151 offset:50176
	ds_read_b128 v[192:195], v151 offset:51200
	ds_read_b128 v[196:199], v151 offset:52224
	ds_read_b128 v[200:203], v151 offset:53248
	ds_read_b128 v[204:207], v151 offset:54272
	ds_read_b128 v[208:211], v151 offset:55296
	ds_read_b128 v[212:215], v151 offset:56320
	global_load_lds_dwordx4 v[144:145], off
	s_add_i32 m0, s30, 0x2000
	s_add_u32 s28, s28, 0x40080
	v_lshl_add_u64 v[144:145], v[216:217], 0, s[14:15]
	s_addc_u32 s29, s29, 0
	s_add_i32 s30, s51, s33
	global_load_lds_dwordx4 v[144:145], off
	v_lshl_add_u64 v[144:145], s[28:29], 0, v[132:133]
	s_mov_b32 m0, s30
	s_nop 0
	global_load_lds_dwordx4 v[144:145], off
	v_lshl_add_u64 v[144:145], s[28:29], 0, v[128:129]
	s_add_i32 m0, s30, 0x2000
	s_nop 0
	global_load_lds_dwordx4 v[144:145], off
	v_lshl_add_u64 v[144:145], v[218:219], 0, s[14:15]
	s_mov_b32 m0, s39
	s_nop 0
	global_load_lds_dwordx4 v[144:145], off
	v_lshl_add_u64 v[144:145], v[220:221], 0, s[14:15]
	s_mov_b32 m0, s40
	s_nop 0
	global_load_lds_dwordx4 v[144:145], off
	s_waitcnt vmcnt(8)
	s_waitcnt lgkmcnt(0)
	s_barrier
	s_setprio 1
	s_waitcnt lgkmcnt(0)
	v_mfma_f32_16x16x32_bf16 v[60:63], v[152:155], v[184:187], v[60:63]
	v_mfma_f32_16x16x32_bf16 v[56:59], v[160:163], v[184:187], v[56:59]
	v_mfma_f32_16x16x32_bf16 v[44:47], v[152:155], v[192:195], v[44:47]
	v_mfma_f32_16x16x32_bf16 v[40:43], v[160:163], v[192:195], v[40:43]
	v_mfma_f32_16x16x32_bf16 v[28:31], v[152:155], v[200:203], v[28:31]
	v_mfma_f32_16x16x32_bf16 v[24:27], v[160:163], v[200:203], v[24:27]
	v_mfma_f32_16x16x32_bf16 v[12:15], v[152:155], v[208:211], v[12:15]
	v_mfma_f32_16x16x32_bf16 v[8:11], v[160:163], v[208:211], v[8:11]
	v_mfma_f32_16x16x32_bf16 v[60:63], v[156:159], v[188:191], v[60:63]
	v_mfma_f32_16x16x32_bf16 v[56:59], v[164:167], v[188:191], v[56:59]
	v_mfma_f32_16x16x32_bf16 v[44:47], v[156:159], v[196:199], v[44:47]
	v_mfma_f32_16x16x32_bf16 v[40:43], v[164:167], v[196:199], v[40:43]
	v_mfma_f32_16x16x32_bf16 v[28:31], v[156:159], v[204:207], v[28:31]
	v_mfma_f32_16x16x32_bf16 v[24:27], v[164:167], v[204:207], v[24:27]
	v_mfma_f32_16x16x32_bf16 v[12:15], v[156:159], v[212:215], v[12:15]
	v_mfma_f32_16x16x32_bf16 v[8:11], v[164:167], v[212:215], v[8:11]
	s_setprio 0
	s_setprio 1
	v_mfma_f32_16x16x32_bf16 v[52:55], v[168:171], v[184:187], v[52:55]
	v_mfma_f32_16x16x32_bf16 v[48:51], v[176:179], v[184:187], v[48:51]
	v_mfma_f32_16x16x32_bf16 v[36:39], v[168:171], v[192:195], v[36:39]
	v_mfma_f32_16x16x32_bf16 v[32:35], v[176:179], v[192:195], v[32:35]
	v_mfma_f32_16x16x32_bf16 v[20:23], v[168:171], v[200:203], v[20:23]
	v_mfma_f32_16x16x32_bf16 v[16:19], v[176:179], v[200:203], v[16:19]
	v_mfma_f32_16x16x32_bf16 v[4:7], v[168:171], v[208:211], v[4:7]
	v_mfma_f32_16x16x32_bf16 v[0:3], v[176:179], v[208:211], v[0:3]
	v_mfma_f32_16x16x32_bf16 v[52:55], v[172:175], v[188:191], v[52:55]
	v_mfma_f32_16x16x32_bf16 v[48:51], v[180:183], v[188:191], v[48:51]
	v_mfma_f32_16x16x32_bf16 v[36:39], v[172:175], v[196:199], v[36:39]
	v_mfma_f32_16x16x32_bf16 v[32:35], v[180:183], v[196:199], v[32:35]
	v_mfma_f32_16x16x32_bf16 v[20:23], v[172:175], v[204:207], v[20:23]
	v_mfma_f32_16x16x32_bf16 v[16:19], v[180:183], v[204:207], v[16:19]
	v_mfma_f32_16x16x32_bf16 v[4:7], v[172:175], v[212:215], v[4:7]
	v_mfma_f32_16x16x32_bf16 v[0:3], v[180:183], v[212:215], v[0:3]
	s_setprio 0
	s_barrier
	s_add_i32 s49, s49, 2
	s_add_u32 s47, s47, 0x100
	s_addc_u32 s48, s48, 0
	s_add_u32 s26, s26, 0x100
	s_addc_u32 s27, s27, 0
	s_cmp_gt_u32 s49, 13
	s_cbranch_scc0 .LBB0_1949
	s_and_b64 vcc, exec, s[16:17]
	s_cbranch_vccz .LBB0_1952
	s_barrier
.LBB0_1952:
	v_mul_f32_e32 v153, 0xbfb8aa3b, v124
	v_mul_f32_e32 v154, 0xbfb8aa3b, v120
	v_exp_f32_e32 v153, v153
	v_exp_f32_e32 v155, v154
	v_mul_f32_e32 v154, 0xbfb8aa3b, v125
	v_exp_f32_e32 v156, v154
	v_add_f32_e32 v153, 1.0, v153
	v_rcp_f32_e32 v154, v153
	v_add_f32_e32 v153, 1.0, v155
	v_add_f32_e32 v155, 1.0, v156
	v_rcp_f32_e32 v155, v155
	v_mul_f32_e32 v156, 0xbfb8aa3b, v121
	v_exp_f32_e32 v157, v156
	v_rcp_f32_e32 v156, v153
	v_pk_mul_f32 v[124:125], v[124:125], v[154:155]
	v_mul_f32_e32 v153, 0xbfb8aa3b, v127
	v_pk_mul_f32 v[116:117], v[124:125], v[116:117]
	v_add_f32_e32 v124, 1.0, v157
	v_mul_f32_e32 v125, 0xbfb8aa3b, v122
	v_rcp_f32_e32 v157, v124
	v_mul_f32_e32 v124, 0xbfb8aa3b, v126
	v_exp_f32_e32 v125, v125
	v_exp_f32_e32 v124, v124
	v_exp_f32_e32 v153, v153
	v_mul_f32_e32 v154, 0xbfb8aa3b, v123
	v_exp_f32_e32 v155, v154
	v_add_f32_e32 v125, 1.0, v125
	v_add_f32_e32 v124, 1.0, v124
	v_rcp_f32_e32 v154, v125
	v_add_f32_e32 v125, 1.0, v153
	v_rcp_f32_e32 v124, v124
	v_rcp_f32_e32 v125, v125
	v_add_f32_e32 v153, 1.0, v155
	v_rcp_f32_e32 v155, v153
	v_pk_mul_f32 v[120:121], v[120:121], v[156:157]
	v_lshl_or_b32 v144, s86, 7, v148
	v_pk_mul_f32 v[120:121], v[120:121], v[112:113]
	v_pk_mul_f32 v[112:113], v[126:127], v[124:125]
	s_mov_b64 s[26:27], s[12:13]
	v_ashrrev_i32_e32 v145, 31, v144
	v_pk_mul_f32 v[118:119], v[112:113], v[118:119]
	v_pk_mul_f32 v[112:113], v[122:123], v[154:155]
	v_lshl_add_u32 v152, s88, 8, v146
	v_lshl_add_u64 v[144:145], v[144:145], 1, s[26:27]
	v_pk_mul_f32 v[122:123], v[112:113], v[114:115]
	v_mad_i64_i32 v[124:125], s[26:27], v152, s44, v[144:145]
	v_cvt_pk_bf16_f32 v112, v116, v117
	v_cvt_pk_bf16_f32 v113, v118, v119
	v_cvt_pk_bf16_f32 v114, v120, v121
	v_cvt_pk_bf16_f32 v115, v122, v123
	global_store_dwordx4 v[124:125], v[112:115], off
	v_or_b32_e32 v116, 16, v152
	s_andn2_b64 vcc, exec, s[8:9]
	v_mul_f32_e32 v112, 0xbfb8aa3b, v108
	v_mul_f32_e32 v113, 0xbfb8aa3b, v104
	v_mul_f32_e32 v114, 0xbfb8aa3b, v109
	v_exp_f32_e32 v112, v112
	v_exp_f32_e32 v113, v113
	v_exp_f32_e32 v114, v114
	s_mov_b64 s[8:9], -1
	v_add_f32_e32 v112, 1.0, v112
	v_add_f32_e32 v115, 1.0, v113
	v_add_f32_e32 v113, 1.0, v114
	v_rcp_f32_e32 v112, v112
	v_rcp_f32_e32 v113, v113
	v_mul_f32_e32 v114, 0xbfb8aa3b, v105
	v_exp_f32_e32 v117, v114
	v_rcp_f32_e32 v114, v115
	v_pk_mul_f32 v[108:109], v[108:109], v[112:113]
	v_mul_f32_e32 v112, 0xbfb8aa3b, v111
	v_pk_mul_f32 v[100:101], v[108:109], v[100:101]
	v_add_f32_e32 v108, 1.0, v117
	v_rcp_f32_e32 v115, v108
	v_mul_f32_e32 v109, 0xbfb8aa3b, v106
	v_mul_f32_e32 v108, 0xbfb8aa3b, v110
	v_exp_f32_e32 v109, v109
	v_exp_f32_e32 v108, v108
	v_exp_f32_e32 v113, v112
	v_mul_f32_e32 v112, 0xbfb8aa3b, v107
	v_pk_mul_f32 v[104:105], v[104:105], v[114:115]
	v_exp_f32_e32 v114, v112
	v_add_f32_e32 v109, 1.0, v109
	v_add_f32_e32 v108, 1.0, v108
	v_rcp_f32_e32 v112, v109
	v_add_f32_e32 v109, 1.0, v113
	v_rcp_f32_e32 v108, v108
	v_rcp_f32_e32 v109, v109
	v_add_f32_e32 v113, 1.0, v114
	v_rcp_f32_e32 v113, v113
	v_pk_mul_f32 v[104:105], v[104:105], v[96:97]
	v_pk_mul_f32 v[96:97], v[110:111], v[108:109]
	v_mad_i64_i32 v[108:109], s[26:27], v116, s44, v[144:145]
	v_pk_mul_f32 v[102:103], v[96:97], v[102:103]
	v_pk_mul_f32 v[96:97], v[106:107], v[112:113]
	s_nop 0
	v_pk_mul_f32 v[106:107], v[96:97], v[98:99]
	v_cvt_pk_bf16_f32 v96, v100, v101
	v_cvt_pk_bf16_f32 v97, v102, v103
	v_cvt_pk_bf16_f32 v98, v104, v105
	v_cvt_pk_bf16_f32 v99, v106, v107
	global_store_dwordx4 v[108:109], v[96:99], off
	v_or_b32_e32 v100, 32, v152
	s_nop 0
	v_mul_f32_e32 v96, 0xbfb8aa3b, v92
	v_mul_f32_e32 v97, 0xbfb8aa3b, v88
	v_mul_f32_e32 v98, 0xbfb8aa3b, v93
	v_exp_f32_e32 v96, v96
	v_exp_f32_e32 v97, v97
	v_exp_f32_e32 v98, v98
	v_add_f32_e32 v96, 1.0, v96
	v_add_f32_e32 v99, 1.0, v97
	v_add_f32_e32 v97, 1.0, v98
	v_rcp_f32_e32 v96, v96
	v_rcp_f32_e32 v97, v97
	v_mul_f32_e32 v98, 0xbfb8aa3b, v89
	v_exp_f32_e32 v101, v98
	v_rcp_f32_e32 v98, v99
	v_pk_mul_f32 v[92:93], v[92:93], v[96:97]
	v_mul_f32_e32 v96, 0xbfb8aa3b, v95
	v_pk_mul_f32 v[84:85], v[92:93], v[84:85]
	v_add_f32_e32 v92, 1.0, v101
	v_rcp_f32_e32 v99, v92
	v_mul_f32_e32 v93, 0xbfb8aa3b, v90
	v_mul_f32_e32 v92, 0xbfb8aa3b, v94
	v_exp_f32_e32 v93, v93
	v_exp_f32_e32 v92, v92
	v_exp_f32_e32 v97, v96
	v_mul_f32_e32 v96, 0xbfb8aa3b, v91
	v_pk_mul_f32 v[88:89], v[88:89], v[98:99]
	v_exp_f32_e32 v98, v96
	v_add_f32_e32 v93, 1.0, v93
	v_add_f32_e32 v92, 1.0, v92
	v_rcp_f32_e32 v96, v93
	v_add_f32_e32 v93, 1.0, v97
	v_rcp_f32_e32 v92, v92
	v_rcp_f32_e32 v93, v93
	v_add_f32_e32 v97, 1.0, v98
	v_rcp_f32_e32 v97, v97
	v_pk_mul_f32 v[88:89], v[88:89], v[80:81]
	v_pk_mul_f32 v[80:81], v[94:95], v[92:93]
	v_mad_i64_i32 v[92:93], s[26:27], v100, s44, v[144:145]
	v_pk_mul_f32 v[86:87], v[80:81], v[86:87]
	v_pk_mul_f32 v[80:81], v[90:91], v[96:97]
	s_nop 0
	v_pk_mul_f32 v[90:91], v[80:81], v[82:83]
	v_cvt_pk_bf16_f32 v80, v84, v85
	v_cvt_pk_bf16_f32 v81, v86, v87
	v_cvt_pk_bf16_f32 v82, v88, v89
	v_cvt_pk_bf16_f32 v83, v90, v91
	global_store_dwordx4 v[92:93], v[80:83], off
	v_or_b32_e32 v84, 48, v152
	s_nop 0
	v_mul_f32_e32 v80, 0xbfb8aa3b, v76
	v_mul_f32_e32 v81, 0xbfb8aa3b, v72
	v_mul_f32_e32 v82, 0xbfb8aa3b, v77
	v_exp_f32_e32 v80, v80
	v_exp_f32_e32 v81, v81
	v_exp_f32_e32 v82, v82
	v_add_f32_e32 v80, 1.0, v80
	v_add_f32_e32 v83, 1.0, v81
	v_add_f32_e32 v81, 1.0, v82
	v_rcp_f32_e32 v80, v80
	v_rcp_f32_e32 v81, v81
	v_mul_f32_e32 v82, 0xbfb8aa3b, v73
	v_exp_f32_e32 v85, v82
	v_rcp_f32_e32 v82, v83
	v_pk_mul_f32 v[76:77], v[76:77], v[80:81]
	v_mul_f32_e32 v80, 0xbfb8aa3b, v79
	v_pk_mul_f32 v[68:69], v[76:77], v[68:69]
	v_add_f32_e32 v76, 1.0, v85
	v_rcp_f32_e32 v83, v76
	v_mul_f32_e32 v77, 0xbfb8aa3b, v74
	v_mul_f32_e32 v76, 0xbfb8aa3b, v78
	v_exp_f32_e32 v77, v77
	v_exp_f32_e32 v76, v76
	v_exp_f32_e32 v81, v80
	v_mul_f32_e32 v80, 0xbfb8aa3b, v75
	v_pk_mul_f32 v[72:73], v[72:73], v[82:83]
	v_exp_f32_e32 v82, v80
	v_add_f32_e32 v77, 1.0, v77
	v_add_f32_e32 v76, 1.0, v76
	v_rcp_f32_e32 v80, v77
	v_add_f32_e32 v77, 1.0, v81
	v_rcp_f32_e32 v76, v76
	v_rcp_f32_e32 v77, v77
	v_add_f32_e32 v81, 1.0, v82
	v_rcp_f32_e32 v81, v81
	v_pk_mul_f32 v[72:73], v[72:73], v[64:65]
	v_pk_mul_f32 v[64:65], v[78:79], v[76:77]
	v_mad_i64_i32 v[76:77], s[26:27], v84, s44, v[144:145]
	v_pk_mul_f32 v[70:71], v[64:65], v[70:71]
	v_pk_mul_f32 v[64:65], v[74:75], v[80:81]
	s_nop 0
	v_pk_mul_f32 v[74:75], v[64:65], v[66:67]
	v_cvt_pk_bf16_f32 v64, v68, v69
	v_cvt_pk_bf16_f32 v65, v70, v71
	v_cvt_pk_bf16_f32 v66, v72, v73
	v_cvt_pk_bf16_f32 v67, v74, v75
	global_store_dwordx4 v[76:77], v[64:67], off
	v_add_u32_e32 v68, 0x80, v152
	s_nop 0
	v_mul_f32_e32 v64, 0xbfb8aa3b, v60
	v_mul_f32_e32 v65, 0xbfb8aa3b, v56
	v_mul_f32_e32 v66, 0xbfb8aa3b, v61
	v_exp_f32_e32 v64, v64
	v_exp_f32_e32 v65, v65
	v_exp_f32_e32 v66, v66
	v_add_f32_e32 v64, 1.0, v64
	v_add_f32_e32 v67, 1.0, v65
	v_add_f32_e32 v65, 1.0, v66
	v_rcp_f32_e32 v64, v64
	v_rcp_f32_e32 v65, v65
	v_mul_f32_e32 v66, 0xbfb8aa3b, v57
	v_exp_f32_e32 v69, v66
	v_rcp_f32_e32 v66, v67
	v_pk_mul_f32 v[60:61], v[60:61], v[64:65]
	v_mul_f32_e32 v64, 0xbfb8aa3b, v63
	v_pk_mul_f32 v[52:53], v[60:61], v[52:53]
	v_add_f32_e32 v60, 1.0, v69
	v_rcp_f32_e32 v67, v60
	v_mul_f32_e32 v61, 0xbfb8aa3b, v58
	v_mul_f32_e32 v60, 0xbfb8aa3b, v62
	v_exp_f32_e32 v61, v61
	v_exp_f32_e32 v60, v60
	v_exp_f32_e32 v65, v64
	v_mul_f32_e32 v64, 0xbfb8aa3b, v59
	v_pk_mul_f32 v[56:57], v[56:57], v[66:67]
	v_exp_f32_e32 v66, v64
	v_add_f32_e32 v61, 1.0, v61
	v_add_f32_e32 v60, 1.0, v60
	v_rcp_f32_e32 v64, v61
	v_add_f32_e32 v61, 1.0, v65
	v_rcp_f32_e32 v60, v60
	v_rcp_f32_e32 v61, v61
	v_add_f32_e32 v65, 1.0, v66
	v_rcp_f32_e32 v65, v65
	v_pk_mul_f32 v[56:57], v[56:57], v[48:49]
	v_pk_mul_f32 v[48:49], v[62:63], v[60:61]
	v_mad_i64_i32 v[60:61], s[26:27], v68, s44, v[144:145]
	v_pk_mul_f32 v[54:55], v[48:49], v[54:55]
	v_pk_mul_f32 v[48:49], v[58:59], v[64:65]
	s_nop 0
	v_pk_mul_f32 v[58:59], v[48:49], v[50:51]
	v_cvt_pk_bf16_f32 v48, v52, v53
	v_cvt_pk_bf16_f32 v49, v54, v55
	v_cvt_pk_bf16_f32 v50, v56, v57
	v_cvt_pk_bf16_f32 v51, v58, v59
	global_store_dwordx4 v[60:61], v[48:51], off
	v_add_u32_e32 v52, 0x90, v152
	s_nop 0
	v_mul_f32_e32 v48, 0xbfb8aa3b, v44
	v_mul_f32_e32 v49, 0xbfb8aa3b, v40
	v_mul_f32_e32 v50, 0xbfb8aa3b, v45
	v_exp_f32_e32 v48, v48
	v_exp_f32_e32 v49, v49
	v_exp_f32_e32 v50, v50
	v_add_f32_e32 v48, 1.0, v48
	v_add_f32_e32 v51, 1.0, v49
	v_add_f32_e32 v49, 1.0, v50
	v_rcp_f32_e32 v48, v48
	v_rcp_f32_e32 v49, v49
	v_mul_f32_e32 v50, 0xbfb8aa3b, v41
	v_exp_f32_e32 v53, v50
	v_rcp_f32_e32 v50, v51
	v_pk_mul_f32 v[44:45], v[44:45], v[48:49]
	v_mul_f32_e32 v48, 0xbfb8aa3b, v47
	v_pk_mul_f32 v[36:37], v[44:45], v[36:37]
	v_add_f32_e32 v44, 1.0, v53
	v_rcp_f32_e32 v51, v44
	v_mul_f32_e32 v45, 0xbfb8aa3b, v42
	v_mul_f32_e32 v44, 0xbfb8aa3b, v46
	v_exp_f32_e32 v45, v45
	v_exp_f32_e32 v44, v44
	v_exp_f32_e32 v49, v48
	v_mul_f32_e32 v48, 0xbfb8aa3b, v43
	v_pk_mul_f32 v[40:41], v[40:41], v[50:51]
	v_exp_f32_e32 v50, v48
	v_add_f32_e32 v45, 1.0, v45
	v_add_f32_e32 v44, 1.0, v44
	v_rcp_f32_e32 v48, v45
	v_add_f32_e32 v45, 1.0, v49
	v_rcp_f32_e32 v44, v44
	v_rcp_f32_e32 v45, v45
	v_add_f32_e32 v49, 1.0, v50
	v_rcp_f32_e32 v49, v49
	v_pk_mul_f32 v[40:41], v[40:41], v[32:33]
	v_pk_mul_f32 v[32:33], v[46:47], v[44:45]
	v_mad_i64_i32 v[44:45], s[26:27], v52, s44, v[144:145]
	v_pk_mul_f32 v[38:39], v[32:33], v[38:39]
	v_pk_mul_f32 v[32:33], v[42:43], v[48:49]
	s_nop 0
	v_pk_mul_f32 v[42:43], v[32:33], v[34:35]
	v_cvt_pk_bf16_f32 v32, v36, v37
	v_cvt_pk_bf16_f32 v33, v38, v39
	v_cvt_pk_bf16_f32 v34, v40, v41
	v_cvt_pk_bf16_f32 v35, v42, v43
	global_store_dwordx4 v[44:45], v[32:35], off
	v_add_u32_e32 v36, 0xa0, v152
	s_nop 0
	v_mul_f32_e32 v32, 0xbfb8aa3b, v28
	v_mul_f32_e32 v33, 0xbfb8aa3b, v24
	v_mul_f32_e32 v34, 0xbfb8aa3b, v29
	v_exp_f32_e32 v32, v32
	v_exp_f32_e32 v33, v33
	v_exp_f32_e32 v34, v34
	v_add_f32_e32 v32, 1.0, v32
	v_add_f32_e32 v35, 1.0, v33
	v_add_f32_e32 v33, 1.0, v34
	v_rcp_f32_e32 v32, v32
	v_rcp_f32_e32 v33, v33
	v_mul_f32_e32 v34, 0xbfb8aa3b, v25
	v_exp_f32_e32 v37, v34
	v_rcp_f32_e32 v34, v35
	v_pk_mul_f32 v[28:29], v[28:29], v[32:33]
	v_mul_f32_e32 v32, 0xbfb8aa3b, v31
	v_pk_mul_f32 v[20:21], v[28:29], v[20:21]
	v_add_f32_e32 v28, 1.0, v37
	v_rcp_f32_e32 v35, v28
	v_mul_f32_e32 v29, 0xbfb8aa3b, v26
	v_mul_f32_e32 v28, 0xbfb8aa3b, v30
	v_exp_f32_e32 v29, v29
	v_exp_f32_e32 v28, v28
	v_exp_f32_e32 v33, v32
	v_mul_f32_e32 v32, 0xbfb8aa3b, v27
	v_pk_mul_f32 v[24:25], v[24:25], v[34:35]
	v_exp_f32_e32 v34, v32
	v_add_f32_e32 v29, 1.0, v29
	v_add_f32_e32 v28, 1.0, v28
	v_rcp_f32_e32 v32, v29
	v_add_f32_e32 v29, 1.0, v33
	v_rcp_f32_e32 v28, v28
	v_rcp_f32_e32 v29, v29
	v_add_f32_e32 v33, 1.0, v34
	v_rcp_f32_e32 v33, v33
	v_pk_mul_f32 v[24:25], v[24:25], v[16:17]
	v_pk_mul_f32 v[16:17], v[30:31], v[28:29]
	v_mad_i64_i32 v[28:29], s[26:27], v36, s44, v[144:145]
	v_pk_mul_f32 v[22:23], v[16:17], v[22:23]
	v_pk_mul_f32 v[16:17], v[26:27], v[32:33]
	s_nop 0
	v_pk_mul_f32 v[26:27], v[16:17], v[18:19]
	v_cvt_pk_bf16_f32 v16, v20, v21
	v_cvt_pk_bf16_f32 v17, v22, v23
	v_cvt_pk_bf16_f32 v18, v24, v25
	v_cvt_pk_bf16_f32 v19, v26, v27
	global_store_dwordx4 v[28:29], v[16:19], off
	v_add_u32_e32 v20, 0xb0, v152
	s_nop 0
	v_mul_f32_e32 v16, 0xbfb8aa3b, v12
	v_mul_f32_e32 v17, 0xbfb8aa3b, v8
	v_mul_f32_e32 v18, 0xbfb8aa3b, v13
	v_exp_f32_e32 v16, v16
	v_exp_f32_e32 v17, v17
	v_exp_f32_e32 v18, v18
	v_add_f32_e32 v16, 1.0, v16
	v_add_f32_e32 v19, 1.0, v17
	v_add_f32_e32 v17, 1.0, v18
	v_rcp_f32_e32 v16, v16
	v_rcp_f32_e32 v17, v17
	v_mul_f32_e32 v18, 0xbfb8aa3b, v9
	v_exp_f32_e32 v21, v18
	v_rcp_f32_e32 v18, v19
	v_pk_mul_f32 v[12:13], v[12:13], v[16:17]
	v_mul_f32_e32 v16, 0xbfb8aa3b, v15
	v_pk_mul_f32 v[4:5], v[12:13], v[4:5]
	v_add_f32_e32 v12, 1.0, v21
	v_rcp_f32_e32 v19, v12
	v_mul_f32_e32 v13, 0xbfb8aa3b, v10
	v_mul_f32_e32 v12, 0xbfb8aa3b, v14
	v_exp_f32_e32 v13, v13
	v_exp_f32_e32 v12, v12
	v_exp_f32_e32 v17, v16
	v_mul_f32_e32 v16, 0xbfb8aa3b, v11
	v_pk_mul_f32 v[8:9], v[8:9], v[18:19]
	v_exp_f32_e32 v18, v16
	v_add_f32_e32 v13, 1.0, v13
	v_add_f32_e32 v12, 1.0, v12
	v_rcp_f32_e32 v16, v13
	v_add_f32_e32 v13, 1.0, v17
	v_rcp_f32_e32 v12, v12
	v_rcp_f32_e32 v13, v13
	v_add_f32_e32 v17, 1.0, v18
	v_rcp_f32_e32 v17, v17
	v_pk_mul_f32 v[8:9], v[8:9], v[0:1]
	v_pk_mul_f32 v[0:1], v[14:15], v[12:13]
	v_mad_i64_i32 v[12:13], s[26:27], v20, s44, v[144:145]
	v_pk_mul_f32 v[6:7], v[0:1], v[6:7]
	v_pk_mul_f32 v[0:1], v[10:11], v[16:17]
	s_nop 0
	v_pk_mul_f32 v[10:11], v[0:1], v[2:3]
	v_cvt_pk_bf16_f32 v0, v4, v5
	v_cvt_pk_bf16_f32 v1, v6, v7
	v_cvt_pk_bf16_f32 v2, v8, v9
	v_cvt_pk_bf16_f32 v3, v10, v11
	global_store_dwordx4 v[12:13], v[0:3], off
	s_cbranch_vccnz .LBB0_1945
	s_andn2_b64 vcc, exec, s[10:11]
	s_cbranch_vccnz .LBB0_1944
	s_mov_b32 s100, 1
	s_branch .LBB0_1944

.LBB0_2011:
	s_add_u32 s14, s8, 0xd800000
	s_addc_u32 s15, s9, 0
	s_lshl_b32 s8, s16, 5
	s_mov_b64 s[16:17], 0x80
	s_and_b32 s21, s8, 0x60
	s_add_i32 m0, s40, 0x18000
	v_lshl_add_u64 v[6:7], v[6:7], 0, s[16:17]
	s_lshl_b32 s18, s11, 13
	s_lshl_b32 s19, s21, 7
	s_waitcnt vmcnt(2)
	s_barrier
	global_load_lds_dwordx4 v[6:7], off
	v_lshl_add_u64 v[4:5], v[4:5], 0, s[16:17]
	s_add_i32 m0, s40, 0x1a000
	s_add_i32 s45, s40, 0x8000
	s_add_i32 s46, s40, 0xa000
	global_load_lds_dwordx4 v[4:5], off
	v_lshl_add_u64 v[0:1], v[0:1], 0, s[16:17]
	s_mov_b32 m0, s45
	s_add_u32 s8, s34, 0xb0080
	global_load_lds_dwordx4 v[0:1], off
	v_lshl_add_u64 v[0:1], v[2:3], 0, s[16:17]
	s_mov_b32 m0, s46
	s_addc_u32 s9, s35, 0
	global_load_lds_dwordx4 v[0:1], off
	s_add_i32 m0, s40, 0x1c000
	v_lshl_add_u64 v[0:1], s[8:9], 0, v[132:133]
	global_load_lds_dwordx4 v[0:1], off
	v_lshl_add_u64 v[0:1], s[8:9], 0, v[128:129]
	s_add_i32 m0, s40, 0x1e000
	s_cmpk_lt_u32 s10, 0x100
	global_load_lds_dwordx4 v[0:1], off
	v_lshrrev_b32_e32 v1, 1, v8
	v_and_b32_e32 v1, 24, v1
	v_and_b32_e32 v0, 15, v8
	v_lshlrev_b32_e32 v2, 1, v1
	v_lshl_or_b32 v144, s11, 6, v0
	v_lshl_or_b32 v0, v0, 6, v2
	v_lshlrev_b32_e32 v2, 2, v8
	v_and_b32_e32 v2, 32, v2
	v_bitop3_b32 v3, v0, s18, v2 bitop3:0xde
	v_bitop3_b32 v145, s19, v0, v2 bitop3:0xf6
	v_or_b32_e32 v146, s21, v1
	v_lshrrev_b32_e32 v1, 1, v9
	v_mul_lo_u32 v0, v10, s20
	s_mov_b32 s21, 0xb000
	v_mad_u64_u32 v[0:1], s[10:11], v1, s21, v[0:1]
	v_or_b32_e32 v0, v0, v11
	s_mov_b64 s[8:9], 0xb0080
	v_add_lshl_u32 v0, v0, v12, 1
	v_mov_b32_e32 v1, v133
	v_lshl_add_u64 v[136:137], v[0:1], 0, s[8:9]
	v_lshrrev_b32_e32 v1, 1, v14
	v_mul_lo_u32 v0, v13, s20
	v_mad_u64_u32 v[0:1], s[10:11], v1, s21, v[0:1]
	s_waitcnt vmcnt(6)
	v_or_b32_e32 v0, v0, v15
	s_cselect_b64 s[18:19], -1, 0
	v_add_lshl_u32 v0, v0, v16, 1
	v_mov_b32_e32 v1, v133
	s_add_i32 s47, 0, 0x10000
	s_add_i32 s48, 0, 0x14000
	v_lshl_add_u64 v[138:139], v[0:1], 0, s[8:9]
	v_mov_b64_e32 v[140:141], 0x200
	v_mov_b64_e32 v[142:143], 0x1ff
	v_add_u32_e32 v147, s47, v145
	v_add_u32_e32 v148, s48, v145
	v_add_u32_e32 v149, 0, v3
	s_mov_b64 s[20:21], 0x40000
	s_mov_b32 s49, 0x40000
	s_mov_b64 s[22:23], 0x48000
	s_mov_b32 s50, 0x48000
	s_mov_b64 s[24:25], 0x50000
	s_mov_b32 s51, 0x50000
	s_mov_b64 s[26:27], 0x58000
	s_mov_b32 s52, 0x58000
	s_barrier
	s_mov_b32 s100, 0
	s_branch .LBB0_2014

.LBB0_2020:
	s_add_u32 s55, s34, 0x100
	v_mov_b32_e32 v0, 0
	s_addc_u32 s56, s35, 0
	s_mov_b32 s57, -2
	v_mov_b32_e32 v1, v0
	v_mov_b32_e32 v2, v0
	v_mov_b32_e32 v3, v0
	v_mov_b32_e32 v4, v0
	v_mov_b32_e32 v5, v0
	v_mov_b32_e32 v6, v0
	v_mov_b32_e32 v7, v0
	v_mov_b32_e32 v8, v0
	v_mov_b32_e32 v9, v0
	v_mov_b32_e32 v10, v0
	v_mov_b32_e32 v11, v0
	v_mov_b32_e32 v12, v0
	v_mov_b32_e32 v13, v0
	v_mov_b32_e32 v14, v0
	v_mov_b32_e32 v15, v0
	v_mov_b32_e32 v24, v0
	v_mov_b32_e32 v25, v0
	v_mov_b32_e32 v26, v0
	v_mov_b32_e32 v27, v0
	v_mov_b32_e32 v28, v0
	v_mov_b32_e32 v29, v0
	v_mov_b32_e32 v30, v0
	v_mov_b32_e32 v31, v0
	v_mov_b32_e32 v40, v0
	v_mov_b32_e32 v41, v0
	v_mov_b32_e32 v42, v0
	v_mov_b32_e32 v43, v0
	v_mov_b32_e32 v44, v0
	v_mov_b32_e32 v45, v0
	v_mov_b32_e32 v46, v0
	v_mov_b32_e32 v47, v0
	v_mov_b32_e32 v16, v0
	v_mov_b32_e32 v17, v0
	v_mov_b32_e32 v18, v0
	v_mov_b32_e32 v19, v0
	v_mov_b32_e32 v20, v0
	v_mov_b32_e32 v21, v0
	v_mov_b32_e32 v22, v0
	v_mov_b32_e32 v23, v0
	v_mov_b32_e32 v32, v0
	v_mov_b32_e32 v33, v0
	v_mov_b32_e32 v34, v0
	v_mov_b32_e32 v35, v0
	v_mov_b32_e32 v36, v0
	v_mov_b32_e32 v37, v0
	v_mov_b32_e32 v38, v0
	v_mov_b32_e32 v39, v0
	v_mov_b32_e32 v48, v0
	v_mov_b32_e32 v49, v0
	v_mov_b32_e32 v50, v0
	v_mov_b32_e32 v51, v0
	v_mov_b32_e32 v52, v0
	v_mov_b32_e32 v53, v0
	v_mov_b32_e32 v54, v0
	v_mov_b32_e32 v55, v0
	v_mov_b32_e32 v56, v0
	v_mov_b32_e32 v57, v0
	v_mov_b32_e32 v58, v0
	v_mov_b32_e32 v59, v0
	v_mov_b32_e32 v60, v0
	v_mov_b32_e32 v61, v0
	v_mov_b32_e32 v62, v0
	v_mov_b32_e32 v63, v0
	v_mov_b32_e32 v64, v0
	v_mov_b32_e32 v65, v0
	v_mov_b32_e32 v66, v0
	v_mov_b32_e32 v67, v0
	v_mov_b32_e32 v68, v0
	v_mov_b32_e32 v69, v0
	v_mov_b32_e32 v70, v0
	v_mov_b32_e32 v71, v0
	v_mov_b32_e32 v72, v0
	v_mov_b32_e32 v73, v0
	v_mov_b32_e32 v74, v0
	v_mov_b32_e32 v75, v0
	v_mov_b32_e32 v76, v0
	v_mov_b32_e32 v77, v0
	v_mov_b32_e32 v78, v0
	v_mov_b32_e32 v79, v0
	v_mov_b32_e32 v88, v0
	v_mov_b32_e32 v89, v0
	v_mov_b32_e32 v90, v0
	v_mov_b32_e32 v91, v0
	v_mov_b32_e32 v92, v0
	v_mov_b32_e32 v93, v0
	v_mov_b32_e32 v94, v0
	v_mov_b32_e32 v95, v0
	v_mov_b32_e32 v104, v0
	v_mov_b32_e32 v105, v0
	v_mov_b32_e32 v106, v0
	v_mov_b32_e32 v107, v0
	v_mov_b32_e32 v108, v0
	v_mov_b32_e32 v109, v0
	v_mov_b32_e32 v110, v0
	v_mov_b32_e32 v111, v0
	v_mov_b32_e32 v80, v0
	v_mov_b32_e32 v81, v0
	v_mov_b32_e32 v82, v0
	v_mov_b32_e32 v83, v0
	v_mov_b32_e32 v84, v0
	v_mov_b32_e32 v85, v0
	v_mov_b32_e32 v86, v0
	v_mov_b32_e32 v87, v0
	v_mov_b32_e32 v96, v0
	v_mov_b32_e32 v97, v0
	v_mov_b32_e32 v98, v0
	v_mov_b32_e32 v99, v0
	v_mov_b32_e32 v100, v0
	v_mov_b32_e32 v101, v0
	v_mov_b32_e32 v102, v0
	v_mov_b32_e32 v103, v0
	v_mov_b32_e32 v112, v0
	v_mov_b32_e32 v113, v0
	v_mov_b32_e32 v114, v0
	v_mov_b32_e32 v115, v0
	v_mov_b32_e32 v116, v0
	v_mov_b32_e32 v117, v0
	v_mov_b32_e32 v118, v0
	v_mov_b32_e32 v119, v0
	v_mov_b32_e32 v120, v0
	v_mov_b32_e32 v121, v0
	v_mov_b32_e32 v122, v0
	v_mov_b32_e32 v123, v0
	v_mov_b32_e32 v124, v0
	v_mov_b32_e32 v125, v0
	v_mov_b32_e32 v126, v0
	v_mov_b32_e32 v127, v0
	s_cmp_eq_u32 s100, 1
	s_cbranch_scc0 .Lgemm_nobar_2012
	s_mov_b32 s100, 0
	s_barrier
.Lgemm_nobar_2012:
.LBB0_2021:
	ds_read_b128 v[150:153], v147
	ds_read_b128 v[154:157], v147 offset:1024
	ds_read_b128 v[158:161], v147 offset:2048
	ds_read_b128 v[162:165], v147 offset:3072
	ds_read_b128 v[166:169], v148
	ds_read_b128 v[170:173], v148 offset:1024
	ds_read_b128 v[174:177], v148 offset:2048
	ds_read_b128 v[178:181], v148 offset:3072
	s_add_u32 s34, s30, 0x100
	s_addc_u32 s35, s31, 0
	s_cmp_eq_u32 s57, 40
	s_cselect_b32 s39, s11, s35
	s_cselect_b32 s38, s10, s34
	s_cselect_b32 s37, s29, s56
	s_cselect_b32 s36, s28, s55
	v_lshl_add_u64 v[214:215], s[30:31], 0, v[138:139]
	s_add_i32 m0, s40, 0xc000
	ds_read_b128 v[182:185], v149
	ds_read_b128 v[186:189], v149 offset:1024
	ds_read_b128 v[190:193], v149 offset:2048
	ds_read_b128 v[194:197], v149 offset:3072
	ds_read_b128 v[198:201], v149 offset:4096
	ds_read_b128 v[202:205], v149 offset:5120
	ds_read_b128 v[206:209], v149 offset:6144
	ds_read_b128 v[210:213], v149 offset:7168
	global_load_lds_dwordx4 v[214:215], off
	v_lshl_add_u64 v[214:215], s[30:31], 0, v[136:137]
	s_add_i32 m0, s40, 0xe000
	s_nop 0
	global_load_lds_dwordx4 v[214:215], off
	s_waitcnt vmcnt(8)
	s_waitcnt lgkmcnt(0)
	s_barrier
	s_setprio 1
	s_waitcnt lgkmcnt(0)
	v_mfma_f32_16x16x32_bf16 v[124:127], v[150:153], v[182:185], v[124:127]
	v_mfma_f32_16x16x32_bf16 v[120:123], v[158:161], v[182:185], v[120:123]
	v_mfma_f32_16x16x32_bf16 v[116:119], v[150:153], v[190:193], v[116:119]
	v_mfma_f32_16x16x32_bf16 v[112:115], v[158:161], v[190:193], v[112:115]
	v_mfma_f32_16x16x32_bf16 v[100:103], v[150:153], v[198:201], v[100:103]
	v_mfma_f32_16x16x32_bf16 v[96:99], v[158:161], v[198:201], v[96:99]
	v_mfma_f32_16x16x32_bf16 v[84:87], v[150:153], v[206:209], v[84:87]
	v_mfma_f32_16x16x32_bf16 v[80:83], v[158:161], v[206:209], v[80:83]
	v_mfma_f32_16x16x32_bf16 v[124:127], v[154:157], v[186:189], v[124:127]
	v_mfma_f32_16x16x32_bf16 v[120:123], v[162:165], v[186:189], v[120:123]
	v_mfma_f32_16x16x32_bf16 v[116:119], v[154:157], v[194:197], v[116:119]
	v_mfma_f32_16x16x32_bf16 v[112:115], v[162:165], v[194:197], v[112:115]
	v_mfma_f32_16x16x32_bf16 v[100:103], v[154:157], v[202:205], v[100:103]
	v_mfma_f32_16x16x32_bf16 v[96:99], v[162:165], v[202:205], v[96:99]
	v_mfma_f32_16x16x32_bf16 v[84:87], v[154:157], v[210:213], v[84:87]
	v_mfma_f32_16x16x32_bf16 v[80:83], v[162:165], v[210:213], v[80:83]
	s_setprio 0
	s_setprio 1
	v_mfma_f32_16x16x32_bf16 v[108:111], v[166:169], v[182:185], v[108:111]
	v_mfma_f32_16x16x32_bf16 v[104:107], v[174:177], v[182:185], v[104:107]
	v_mfma_f32_16x16x32_bf16 v[92:95], v[166:169], v[190:193], v[92:95]
	v_mfma_f32_16x16x32_bf16 v[88:91], v[174:177], v[190:193], v[88:91]
	v_mfma_f32_16x16x32_bf16 v[76:79], v[166:169], v[198:201], v[76:79]
	v_mfma_f32_16x16x32_bf16 v[72:75], v[174:177], v[198:201], v[72:75]
	v_mfma_f32_16x16x32_bf16 v[68:71], v[166:169], v[206:209], v[68:71]
	v_mfma_f32_16x16x32_bf16 v[64:67], v[174:177], v[206:209], v[64:67]
	v_mfma_f32_16x16x32_bf16 v[108:111], v[170:173], v[186:189], v[108:111]
	v_mfma_f32_16x16x32_bf16 v[104:107], v[178:181], v[186:189], v[104:107]
	v_mfma_f32_16x16x32_bf16 v[92:95], v[170:173], v[194:197], v[92:95]
	v_mfma_f32_16x16x32_bf16 v[88:91], v[178:181], v[194:197], v[88:91]
	v_mfma_f32_16x16x32_bf16 v[76:79], v[170:173], v[202:205], v[76:79]
	v_mfma_f32_16x16x32_bf16 v[72:75], v[178:181], v[202:205], v[72:75]
	v_mfma_f32_16x16x32_bf16 v[68:71], v[170:173], v[210:213], v[68:71]
	v_mfma_f32_16x16x32_bf16 v[64:67], v[178:181], v[210:213], v[64:67]
	s_setprio 0
	s_barrier
	s_add_i32 s30, s47, s33
	v_lshl_add_u64 v[214:215], s[36:37], 0, v[132:133]
	s_mov_b32 m0, s30
	ds_read_b128 v[182:185], v149 offset:16384
	ds_read_b128 v[186:189], v149 offset:17408
	ds_read_b128 v[190:193], v149 offset:18432
	ds_read_b128 v[194:197], v149 offset:19456
	ds_read_b128 v[198:201], v149 offset:20480
	ds_read_b128 v[202:205], v149 offset:21504
	ds_read_b128 v[206:209], v149 offset:22528
	ds_read_b128 v[210:213], v149 offset:23552
	global_load_lds_dwordx4 v[214:215], off
	s_add_i32 m0, s30, 0x2000
	s_add_u32 s30, s36, 0xb0000
	v_lshl_add_u64 v[216:217], s[36:37], 0, v[128:129]
	s_addc_u32 s31, s37, 0
	s_add_i32 s58, s48, s33
	global_load_lds_dwordx4 v[216:217], off
	v_lshl_add_u64 v[218:219], s[30:31], 0, v[132:133]
	s_mov_b32 m0, s58
	v_lshl_add_u64 v[220:221], s[38:39], 0, v[130:131]
	global_load_lds_dwordx4 v[218:219], off
	v_lshl_add_u64 v[218:219], s[30:31], 0, v[128:129]
	s_add_i32 m0, s58, 0x2000
	s_nop 0
	global_load_lds_dwordx4 v[218:219], off
	v_lshl_add_u64 v[218:219], s[38:39], 0, v[134:135]
	s_mov_b32 m0, s40
	s_nop 0
	global_load_lds_dwordx4 v[218:219], off
	s_mov_b32 m0, s41
	s_nop 0
	global_load_lds_dwordx4 v[220:221], off
	s_waitcnt vmcnt(8)
	s_waitcnt lgkmcnt(0)
	s_barrier
	s_setprio 1
	s_waitcnt lgkmcnt(0)
	v_mfma_f32_16x16x32_bf16 v[60:63], v[150:153], v[182:185], v[60:63]
	v_mfma_f32_16x16x32_bf16 v[56:59], v[158:161], v[182:185], v[56:59]
	v_mfma_f32_16x16x32_bf16 v[52:55], v[150:153], v[190:193], v[52:55]
	v_mfma_f32_16x16x32_bf16 v[48:51], v[158:161], v[190:193], v[48:51]
	v_mfma_f32_16x16x32_bf16 v[36:39], v[150:153], v[198:201], v[36:39]
	v_mfma_f32_16x16x32_bf16 v[32:35], v[158:161], v[198:201], v[32:35]
	v_mfma_f32_16x16x32_bf16 v[20:23], v[150:153], v[206:209], v[20:23]
	v_mfma_f32_16x16x32_bf16 v[16:19], v[158:161], v[206:209], v[16:19]
	v_mfma_f32_16x16x32_bf16 v[60:63], v[154:157], v[186:189], v[60:63]
	v_mfma_f32_16x16x32_bf16 v[56:59], v[162:165], v[186:189], v[56:59]
	v_mfma_f32_16x16x32_bf16 v[52:55], v[154:157], v[194:197], v[52:55]
	v_mfma_f32_16x16x32_bf16 v[48:51], v[162:165], v[194:197], v[48:51]
	v_mfma_f32_16x16x32_bf16 v[36:39], v[154:157], v[202:205], v[36:39]
	v_mfma_f32_16x16x32_bf16 v[32:35], v[162:165], v[202:205], v[32:35]
	v_mfma_f32_16x16x32_bf16 v[20:23], v[154:157], v[210:213], v[20:23]
	v_mfma_f32_16x16x32_bf16 v[16:19], v[162:165], v[210:213], v[16:19]
	s_setprio 0
	s_setprio 1
	v_mfma_f32_16x16x32_bf16 v[44:47], v[166:169], v[182:185], v[44:47]
	v_mfma_f32_16x16x32_bf16 v[40:43], v[174:177], v[182:185], v[40:43]
	v_mfma_f32_16x16x32_bf16 v[28:31], v[166:169], v[190:193], v[28:31]
	v_mfma_f32_16x16x32_bf16 v[24:27], v[174:177], v[190:193], v[24:27]
	v_mfma_f32_16x16x32_bf16 v[12:15], v[166:169], v[198:201], v[12:15]
	v_mfma_f32_16x16x32_bf16 v[8:11], v[174:177], v[198:201], v[8:11]
	v_mfma_f32_16x16x32_bf16 v[4:7], v[166:169], v[206:209], v[4:7]
	v_mfma_f32_16x16x32_bf16 v[0:3], v[174:177], v[206:209], v[0:3]
	v_mfma_f32_16x16x32_bf16 v[44:47], v[170:173], v[186:189], v[44:47]
	v_mfma_f32_16x16x32_bf16 v[40:43], v[178:181], v[186:189], v[40:43]
	v_mfma_f32_16x16x32_bf16 v[28:31], v[170:173], v[194:197], v[28:31]
	v_mfma_f32_16x16x32_bf16 v[24:27], v[178:181], v[194:197], v[24:27]
	v_mfma_f32_16x16x32_bf16 v[12:15], v[170:173], v[202:205], v[12:15]
	v_mfma_f32_16x16x32_bf16 v[8:11], v[178:181], v[202:205], v[8:11]
	v_mfma_f32_16x16x32_bf16 v[4:7], v[170:173], v[210:213], v[4:7]
	v_mfma_f32_16x16x32_bf16 v[0:3], v[178:181], v[210:213], v[0:3]
	s_setprio 0
	s_barrier
	s_add_i32 s58, 0, 0x18000
	s_add_i32 s59, 0, 0x1c000
	v_add_u32_e32 v162, s58, v145
	v_add_u32_e32 v178, s59, v145
	ds_read_b128 v[150:153], v162
	ds_read_b128 v[154:157], v162 offset:1024
	ds_read_b128 v[158:161], v162 offset:2048
	ds_read_b128 v[162:165], v162 offset:3072
	ds_read_b128 v[166:169], v178
	ds_read_b128 v[170:173], v178 offset:1024
	ds_read_b128 v[174:177], v178 offset:2048
	ds_read_b128 v[178:181], v178 offset:3072
	s_add_u32 s30, s38, 0xb0000
	s_addc_u32 s31, s39, 0
	s_mov_b32 m0, s42
	v_lshl_add_u64 v[222:223], s[30:31], 0, v[134:135]
	ds_read_b128 v[182:185], v149 offset:32768
	ds_read_b128 v[186:189], v149 offset:33792
	ds_read_b128 v[190:193], v149 offset:34816
	ds_read_b128 v[194:197], v149 offset:35840
	ds_read_b128 v[198:201], v149 offset:36864
	ds_read_b128 v[202:205], v149 offset:37888
	ds_read_b128 v[206:209], v149 offset:38912
	ds_read_b128 v[210:213], v149 offset:39936
	global_load_lds_dwordx4 v[222:223], off
	v_lshl_add_u64 v[222:223], s[30:31], 0, v[130:131]
	s_mov_b32 m0, s43
	s_nop 0
	global_load_lds_dwordx4 v[222:223], off
	s_waitcnt vmcnt(8)
	s_waitcnt lgkmcnt(0)
	s_barrier
	s_setprio 1
	s_waitcnt lgkmcnt(0)
	v_mfma_f32_16x16x32_bf16 v[124:127], v[150:153], v[182:185], v[124:127]
	v_mfma_f32_16x16x32_bf16 v[120:123], v[158:161], v[182:185], v[120:123]
	v_mfma_f32_16x16x32_bf16 v[116:119], v[150:153], v[190:193], v[116:119]
	v_mfma_f32_16x16x32_bf16 v[112:115], v[158:161], v[190:193], v[112:115]
	v_mfma_f32_16x16x32_bf16 v[100:103], v[150:153], v[198:201], v[100:103]
	v_mfma_f32_16x16x32_bf16 v[96:99], v[158:161], v[198:201], v[96:99]
	v_mfma_f32_16x16x32_bf16 v[84:87], v[150:153], v[206:209], v[84:87]
	v_mfma_f32_16x16x32_bf16 v[80:83], v[158:161], v[206:209], v[80:83]
	v_mfma_f32_16x16x32_bf16 v[124:127], v[154:157], v[186:189], v[124:127]
	v_mfma_f32_16x16x32_bf16 v[120:123], v[162:165], v[186:189], v[120:123]
	v_mfma_f32_16x16x32_bf16 v[116:119], v[154:157], v[194:197], v[116:119]
	v_mfma_f32_16x16x32_bf16 v[112:115], v[162:165], v[194:197], v[112:115]
	v_mfma_f32_16x16x32_bf16 v[100:103], v[154:157], v[202:205], v[100:103]
	v_mfma_f32_16x16x32_bf16 v[96:99], v[162:165], v[202:205], v[96:99]
	v_mfma_f32_16x16x32_bf16 v[84:87], v[154:157], v[210:213], v[84:87]
	v_mfma_f32_16x16x32_bf16 v[80:83], v[162:165], v[210:213], v[80:83]
	s_setprio 0
	s_setprio 1
	v_mfma_f32_16x16x32_bf16 v[108:111], v[166:169], v[182:185], v[108:111]
	v_mfma_f32_16x16x32_bf16 v[104:107], v[174:177], v[182:185], v[104:107]
	v_mfma_f32_16x16x32_bf16 v[92:95], v[166:169], v[190:193], v[92:95]
	v_mfma_f32_16x16x32_bf16 v[88:91], v[174:177], v[190:193], v[88:91]
	v_mfma_f32_16x16x32_bf16 v[76:79], v[166:169], v[198:201], v[76:79]
	v_mfma_f32_16x16x32_bf16 v[72:75], v[174:177], v[198:201], v[72:75]
	v_mfma_f32_16x16x32_bf16 v[68:71], v[166:169], v[206:209], v[68:71]
	v_mfma_f32_16x16x32_bf16 v[64:67], v[174:177], v[206:209], v[64:67]
	v_mfma_f32_16x16x32_bf16 v[108:111], v[170:173], v[186:189], v[108:111]
	v_mfma_f32_16x16x32_bf16 v[104:107], v[178:181], v[186:189], v[104:107]
	v_mfma_f32_16x16x32_bf16 v[92:95], v[170:173], v[194:197], v[92:95]
	v_mfma_f32_16x16x32_bf16 v[88:91], v[178:181], v[194:197], v[88:91]
	v_mfma_f32_16x16x32_bf16 v[76:79], v[170:173], v[202:205], v[76:79]
	v_mfma_f32_16x16x32_bf16 v[72:75], v[178:181], v[202:205], v[72:75]
	v_mfma_f32_16x16x32_bf16 v[68:71], v[170:173], v[210:213], v[68:71]
	v_mfma_f32_16x16x32_bf16 v[64:67], v[178:181], v[210:213], v[64:67]
	s_setprio 0
	s_barrier
	s_add_i32 s30, s58, s33
	v_lshl_add_u64 v[214:215], v[214:215], 0, s[16:17]
	s_mov_b32 m0, s30
	ds_read_b128 v[182:185], v149 offset:49152
	ds_read_b128 v[186:189], v149 offset:50176
	ds_read_b128 v[190:193], v149 offset:51200
	ds_read_b128 v[194:197], v149 offset:52224
	ds_read_b128 v[198:201], v149 offset:53248
	ds_read_b128 v[202:205], v149 offset:54272
	ds_read_b128 v[206:209], v149 offset:55296
	ds_read_b128 v[210:213], v149 offset:56320
	global_load_lds_dwordx4 v[214:215], off
	s_add_i32 m0, s30, 0x2000
	s_add_u32 s30, s36, 0xb0080
	v_lshl_add_u64 v[214:215], v[216:217], 0, s[16:17]
	s_addc_u32 s31, s37, 0
	s_add_i32 s36, s59, s33
	global_load_lds_dwordx4 v[214:215], off
	v_lshl_add_u64 v[214:215], s[30:31], 0, v[132:133]
	s_mov_b32 m0, s36
	s_nop 0
	global_load_lds_dwordx4 v[214:215], off
	v_lshl_add_u64 v[214:215], s[30:31], 0, v[128:129]
	s_add_i32 m0, s36, 0x2000
	s_nop 0
	global_load_lds_dwordx4 v[214:215], off
	v_lshl_add_u64 v[214:215], v[218:219], 0, s[16:17]
	s_mov_b32 m0, s45
	s_nop 0
	global_load_lds_dwordx4 v[214:215], off
	v_lshl_add_u64 v[214:215], v[220:221], 0, s[16:17]
	s_mov_b32 m0, s46
	s_nop 0
	global_load_lds_dwordx4 v[214:215], off
	s_waitcnt vmcnt(8)
	s_waitcnt lgkmcnt(0)
	s_barrier
	s_setprio 1
	s_waitcnt lgkmcnt(0)
	v_mfma_f32_16x16x32_bf16 v[60:63], v[150:153], v[182:185], v[60:63]
	v_mfma_f32_16x16x32_bf16 v[56:59], v[158:161], v[182:185], v[56:59]
	v_mfma_f32_16x16x32_bf16 v[52:55], v[150:153], v[190:193], v[52:55]
	v_mfma_f32_16x16x32_bf16 v[48:51], v[158:161], v[190:193], v[48:51]
	v_mfma_f32_16x16x32_bf16 v[36:39], v[150:153], v[198:201], v[36:39]
	v_mfma_f32_16x16x32_bf16 v[32:35], v[158:161], v[198:201], v[32:35]
	v_mfma_f32_16x16x32_bf16 v[20:23], v[150:153], v[206:209], v[20:23]
	v_mfma_f32_16x16x32_bf16 v[16:19], v[158:161], v[206:209], v[16:19]
	v_mfma_f32_16x16x32_bf16 v[60:63], v[154:157], v[186:189], v[60:63]
	v_mfma_f32_16x16x32_bf16 v[56:59], v[162:165], v[186:189], v[56:59]
	v_mfma_f32_16x16x32_bf16 v[52:55], v[154:157], v[194:197], v[52:55]
	v_mfma_f32_16x16x32_bf16 v[48:51], v[162:165], v[194:197], v[48:51]
	v_mfma_f32_16x16x32_bf16 v[36:39], v[154:157], v[202:205], v[36:39]
	v_mfma_f32_16x16x32_bf16 v[32:35], v[162:165], v[202:205], v[32:35]
	v_mfma_f32_16x16x32_bf16 v[20:23], v[154:157], v[210:213], v[20:23]
	v_mfma_f32_16x16x32_bf16 v[16:19], v[162:165], v[210:213], v[16:19]
	s_setprio 0
	s_setprio 1
	v_mfma_f32_16x16x32_bf16 v[44:47], v[166:169], v[182:185], v[44:47]
	v_mfma_f32_16x16x32_bf16 v[40:43], v[174:177], v[182:185], v[40:43]
	v_mfma_f32_16x16x32_bf16 v[28:31], v[166:169], v[190:193], v[28:31]
	v_mfma_f32_16x16x32_bf16 v[24:27], v[174:177], v[190:193], v[24:27]
	v_mfma_f32_16x16x32_bf16 v[12:15], v[166:169], v[198:201], v[12:15]
	v_mfma_f32_16x16x32_bf16 v[8:11], v[174:177], v[198:201], v[8:11]
	v_mfma_f32_16x16x32_bf16 v[4:7], v[166:169], v[206:209], v[4:7]
	v_mfma_f32_16x16x32_bf16 v[0:3], v[174:177], v[206:209], v[0:3]
	v_mfma_f32_16x16x32_bf16 v[44:47], v[170:173], v[186:189], v[44:47]
	v_mfma_f32_16x16x32_bf16 v[40:43], v[178:181], v[186:189], v[40:43]
	v_mfma_f32_16x16x32_bf16 v[28:31], v[170:173], v[194:197], v[28:31]
	v_mfma_f32_16x16x32_bf16 v[24:27], v[178:181], v[194:197], v[24:27]
	v_mfma_f32_16x16x32_bf16 v[12:15], v[170:173], v[202:205], v[12:15]
	v_mfma_f32_16x16x32_bf16 v[8:11], v[178:181], v[202:205], v[8:11]
	v_mfma_f32_16x16x32_bf16 v[4:7], v[170:173], v[210:213], v[4:7]
	v_mfma_f32_16x16x32_bf16 v[0:3], v[178:181], v[210:213], v[0:3]
	s_setprio 0
	s_barrier
	s_add_i32 s57, s57, 2
	s_add_u32 s55, s55, 0x100
	s_addc_u32 s56, s56, 0
	s_cmp_gt_u32 s57, 41
	s_mov_b64 s[30:31], s[34:35]
	s_cbranch_scc0 .LBB0_2021
	s_and_b64 vcc, exec, s[18:19]
	s_cbranch_vccz .LBB0_2024
	s_barrier
.LBB0_2024:
	v_lshl_or_b32 v150, s60, 8, v146
	v_lshl_add_u32 v152, s92, 8, v144
	s_mov_b64 s[30:31], s[14:15]
	v_ashrrev_i32_e32 v151, 31, v150
	v_ashrrev_i32_e32 v153, 31, v152
	v_lshlrev_b64 v[154:155], 11, v[152:153]
	v_lshl_add_u64 v[150:151], v[150:151], 1, s[30:31]
	v_lshl_add_u64 v[154:155], v[150:151], 0, v[154:155]
	v_cvt_pk_bf16_f32 v60, v60, v61
	v_cvt_pk_bf16_f32 v61, v62, v63
	v_cvt_pk_bf16_f32 v62, v56, v57
	v_add_co_u32_e32 v56, vcc, s49, v154
	v_cvt_pk_bf16_f32 v68, v68, v69
	v_cvt_pk_bf16_f32 v69, v70, v71
	v_cvt_pk_bf16_f32 v70, v64, v65
	v_lshl_add_u64 v[64:65], v[154:155], 0, s[20:21]
	v_addc_co_u32_e32 v57, vcc, 0, v155, vcc
	v_cvt_pk_bf16_f32 v44, v44, v45
	v_cvt_pk_bf16_f32 v45, v46, v47
	v_cvt_pk_bf16_f32 v46, v40, v41
	v_cvt_pk_bf16_f32 v47, v42, v43
	global_store_dwordx4 v[64:65], v[44:47], off offset:256
	v_cvt_pk_bf16_f32 v108, v108, v109
	v_cvt_pk_bf16_f32 v109, v110, v111
	v_add_co_u32_e32 v46, vcc, s50, v154
	v_cvt_pk_bf16_f32 v110, v104, v105
	v_or_b32_e32 v104, 16, v152
	v_lshl_add_u64 v[44:45], v[154:155], 0, s[22:23]
	v_addc_co_u32_e32 v47, vcc, 0, v155, vcc
	v_cvt_pk_bf16_f32 v28, v28, v29
	v_cvt_pk_bf16_f32 v29, v30, v31
	v_cvt_pk_bf16_f32 v30, v24, v25
	v_cvt_pk_bf16_f32 v31, v26, v27
	v_ashrrev_i32_e32 v105, 31, v104
	v_cvt_pk_bf16_f32 v92, v92, v93
	v_cvt_pk_bf16_f32 v93, v94, v95
	v_cvt_pk_bf16_f32 v94, v88, v89
	v_or_b32_e32 v88, 32, v152
	global_store_dwordx4 v[44:45], v[28:31], off offset:256
	v_cvt_pk_bf16_f32 v111, v106, v107
	v_lshlrev_b64 v[104:105], 11, v[104:105]
	v_add_co_u32_e32 v30, vcc, s51, v154
	v_ashrrev_i32_e32 v89, 31, v88
	v_cvt_pk_bf16_f32 v76, v76, v77
	v_cvt_pk_bf16_f32 v77, v78, v79
	v_cvt_pk_bf16_f32 v78, v72, v73
	v_or_b32_e32 v72, 48, v152
	v_lshl_add_u64 v[28:29], v[154:155], 0, s[24:25]
	v_addc_co_u32_e32 v31, vcc, 0, v155, vcc
	v_cvt_pk_bf16_f32 v12, v12, v13
	v_cvt_pk_bf16_f32 v13, v14, v15
	v_cvt_pk_bf16_f32 v14, v8, v9
	v_cvt_pk_bf16_f32 v15, v10, v11
	global_store_dwordx4 v[154:155], v[108:111], off offset:256
	v_cvt_pk_bf16_f32 v95, v90, v91
	v_lshlrev_b64 v[88:89], 11, v[88:89]
	v_lshl_add_u64 v[108:109], v[150:151], 0, v[104:105]
	v_ashrrev_i32_e32 v73, 31, v72
	global_store_dwordx4 v[28:29], v[12:15], off offset:256
	global_store_dwordx4 v[108:109], v[92:95], off offset:256
	v_cvt_pk_bf16_f32 v79, v74, v75
	v_add_co_u32_e32 v14, vcc, s52, v154
	v_lshl_add_u64 v[92:93], v[150:151], 0, v[88:89]
	v_lshlrev_b64 v[72:73], 11, v[72:73]
	v_addc_co_u32_e32 v15, vcc, 0, v155, vcc
	v_cvt_pk_bf16_f32 v124, v124, v125
	v_cvt_pk_bf16_f32 v125, v126, v127
	v_cvt_pk_bf16_f32 v126, v120, v121
	v_cvt_pk_bf16_f32 v127, v122, v123
	v_cvt_pk_bf16_f32 v104, v116, v117
	v_cvt_pk_bf16_f32 v105, v118, v119
	v_cvt_pk_bf16_f32 v106, v112, v113
	v_cvt_pk_bf16_f32 v107, v114, v115
	v_cvt_pk_bf16_f32 v88, v100, v101
	v_cvt_pk_bf16_f32 v89, v102, v103
	v_cvt_pk_bf16_f32 v90, v96, v97
	v_cvt_pk_bf16_f32 v91, v98, v99
	global_store_dwordx4 v[92:93], v[76:79], off offset:256
	v_cvt_pk_bf16_f32 v74, v80, v81
	v_cvt_pk_bf16_f32 v75, v82, v83
	v_lshl_add_u64 v[76:77], v[150:151], 0, v[72:73]
	v_cvt_pk_bf16_f32 v72, v84, v85
	v_cvt_pk_bf16_f32 v73, v86, v87
	v_cvt_pk_bf16_f32 v71, v66, v67
	v_cvt_pk_bf16_f32 v63, v58, v59
	v_cvt_pk_bf16_f32 v40, v52, v53
	v_cvt_pk_bf16_f32 v41, v54, v55
	v_cvt_pk_bf16_f32 v42, v48, v49
	v_cvt_pk_bf16_f32 v43, v50, v51
	v_cvt_pk_bf16_f32 v24, v36, v37
	v_cvt_pk_bf16_f32 v25, v38, v39
	v_cvt_pk_bf16_f32 v26, v32, v33
	v_cvt_pk_bf16_f32 v27, v34, v35
	v_lshl_add_u64 v[12:13], v[154:155], 0, s[26:27]
	v_cvt_pk_bf16_f32 v8, v20, v21
	v_cvt_pk_bf16_f32 v9, v22, v23
	v_cvt_pk_bf16_f32 v10, v16, v17
	v_cvt_pk_bf16_f32 v11, v18, v19
	v_cvt_pk_bf16_f32 v4, v4, v5
	v_cvt_pk_bf16_f32 v5, v6, v7
	v_cvt_pk_bf16_f32 v6, v0, v1
	v_cvt_pk_bf16_f32 v7, v2, v3
	s_and_b64 vcc, exec, s[8:9]
	s_mov_b64 s[8:9], -1
	global_store_dwordx4 v[154:155], v[124:127], off
	global_store_dwordx4 v[108:109], v[104:107], off
	global_store_dwordx4 v[92:93], v[88:91], off
	global_store_dwordx4 v[76:77], v[72:75], off
	global_store_dwordx4 v[76:77], v[68:71], off offset:256
	global_store_dwordx4 v[56:57], v[60:63], off
	global_store_dwordx4 v[46:47], v[40:43], off
	global_store_dwordx4 v[30:31], v[24:27], off
	global_store_dwordx4 v[14:15], v[8:11], off
	global_store_dwordx4 v[12:13], v[4:7], off offset:256
	s_cbranch_vccnz .LBB0_2013
	s_andn2_b64 vcc, exec, s[12:13]
	s_cbranch_vccnz .LBB0_2012
	s_mov_b32 s100, 1
	s_branch .LBB0_2012

	.amdhsa_kernel _Z8yoco_fwd4Args
		.amdhsa_group_segment_fixed_size 0
		.amdhsa_private_segment_fixed_size 0
		.amdhsa_kernarg_size 408
		.amdhsa_user_sgpr_count 2
		.amdhsa_user_sgpr_dispatch_ptr 0
		.amdhsa_user_sgpr_queue_ptr 0
		.amdhsa_user_sgpr_kernarg_segment_ptr 1
		.amdhsa_user_sgpr_dispatch_id 0
		.amdhsa_user_sgpr_kernarg_preload_length 0
		.amdhsa_user_sgpr_kernarg_preload_offset 0
		.amdhsa_user_sgpr_private_segment_size 0
		.amdhsa_uses_dynamic_stack 0
		.amdhsa_enable_private_segment 0
		.amdhsa_system_sgpr_workgroup_id_x 1
		.amdhsa_system_sgpr_workgroup_id_y 0
		.amdhsa_system_sgpr_workgroup_id_z 0
		.amdhsa_system_sgpr_workgroup_info 0
		.amdhsa_system_vgpr_workitem_id 2
		.amdhsa_next_free_vgpr 256
		.amdhsa_next_free_sgpr 102
		.amdhsa_accum_offset 256
		.amdhsa_reserve_vcc 1
		.amdhsa_float_round_mode_32 0
		.amdhsa_float_round_mode_16_64 0
		.amdhsa_float_denorm_mode_32 3
		.amdhsa_float_denorm_mode_16_64 3
		.amdhsa_dx10_clamp 1
		.amdhsa_ieee_mode 1
		.amdhsa_fp16_overflow 0
		.amdhsa_tg_split 0
		.amdhsa_exception_fp_ieee_invalid_op 0
		.amdhsa_exception_fp_denorm_src 0
		.amdhsa_exception_fp_ieee_div_zero 0
		.amdhsa_exception_fp_ieee_overflow 0
		.amdhsa_exception_fp_ieee_underflow 0
		.amdhsa_exception_fp_ieee_inexact 0
		.amdhsa_exception_int_div_zero 0
	.end_amdhsa_kernel

amdhsa.kernels:
  - .agpr_count:     0
    .args:
      - .offset:         0
        .size:           152
        .value_kind:     by_value
      - .offset:         152
        .size:           4
        .value_kind:     hidden_block_count_x
      - .offset:         156
        .size:           4
        .value_kind:     hidden_block_count_y
      - .offset:         160
        .size:           4
        .value_kind:     hidden_block_count_z
      - .offset:         164
        .size:           2
        .value_kind:     hidden_group_size_x
      - .offset:         166
        .size:           2
        .value_kind:     hidden_group_size_y
      - .offset:         168
        .size:           2
        .value_kind:     hidden_group_size_z
      - .offset:         170
        .size:           2
        .value_kind:     hidden_remainder_x
      - .offset:         172
        .size:           2
        .value_kind:     hidden_remainder_y
      - .offset:         174
        .size:           2
        .value_kind:     hidden_remainder_z
      - .offset:         192
        .size:           8
        .value_kind:     hidden_global_offset_x
      - .offset:         200
        .size:           8
        .value_kind:     hidden_global_offset_y
      - .offset:         208
        .size:           8
        .value_kind:     hidden_global_offset_z
      - .offset:         216
        .size:           2
        .value_kind:     hidden_grid_dims
      - .offset:         240
        .size:           8
        .value_kind:     hidden_multigrid_sync_arg
      - .offset:         272
        .size:           4
        .value_kind:     hidden_dynamic_lds_size
    .group_segment_fixed_size: 0
    .kernarg_segment_align: 8
    .kernarg_segment_size: 408
    .language:       OpenCL C
    .language_version:
      - 2
      - 0
    .max_flat_workgroup_size: 512
    .name:           _Z8yoco_fwd4Args
    .private_segment_fixed_size: 0
    .sgpr_count:     108
    .sgpr_spill_count: 71
    .symbol:         _Z8yoco_fwd4Args.kd
    .uniform_work_group_size: 1
    .uses_dynamic_stack: false
    .vgpr_count:     256
    .vgpr_spill_count: 0
    .wavefront_size: 64
